# GEMM units: first K-tile peeled with srcC=0 MFMAs, 128 v_mov accumulator zeroing per unit removed (all 13 GEMM loops)
# speedup vs baseline: 1.0239x; 1.0239x over previous
.LBB0_183:
	s_ashr_i32 s13, s12, 31
	s_lshl_b64 s[24:25], s[12:13], 19
	s_add_u32 s24, s80, s24
	s_addc_u32 s25, s81, s25
	s_and_b64 s[30:31], s[4:5], exec
	s_cselect_b32 s13, s25, s45
	s_cselect_b32 s66, s24, s44
	s_ashr_i32 s11, s10, 31
	s_lshl_b64 s[30:31], s[10:11], 19
	s_add_u32 s30, s52, s30
	s_addc_u32 s31, s53, s31
	s_and_b64 s[48:49], s[4:5], exec
	s_cselect_b32 s11, s31, s47
	s_cselect_b32 s67, s30, s46
	s_add_u32 s44, s44, 0x40080
	s_addc_u32 s45, s45, 0
	s_add_u32 s68, s46, 0x100
	s_addc_u32 s69, s47, 0
	s_mov_b32 s70, -2
	ds_read_b128 v[140:143], v147
	ds_read_b128 v[150:153], v147 offset:1024
	ds_read_b128 v[154:157], v147 offset:2048
	ds_read_b128 v[158:161], v147 offset:3072
	ds_read_b128 v[162:165], v148
	ds_read_b128 v[166:169], v148 offset:1024
	ds_read_b128 v[170:173], v148 offset:2048
	ds_read_b128 v[174:177], v148 offset:3072
	s_add_u32 s18, s44, 0xfffc0080
	s_addc_u32 s19, s45, -1
	s_cmp_eq_u32 s70, 12
	s_cselect_b32 s49, s13, s19
	s_cselect_b32 s48, s66, s18
	s_cselect_b32 s47, s11, s69
	s_cselect_b32 s46, s67, s68
	v_lshl_add_u64 v[178:179], s[44:45], 0, v[132:133]
	s_add_i32 m0, s37, 0xc000
	ds_read_b128 v[184:187], v149
	ds_read_b128 v[188:191], v149 offset:1024
	ds_read_b128 v[192:195], v149 offset:2048
	ds_read_b128 v[196:199], v149 offset:3072
	ds_read_b128 v[200:203], v149 offset:4096
	ds_read_b128 v[204:207], v149 offset:5120
	ds_read_b128 v[208:211], v149 offset:6144
	ds_read_b128 v[212:215], v149 offset:7168
	global_load_lds_dwordx4 v[178:179], off
	v_lshl_add_u64 v[178:179], s[44:45], 0, v[134:135]
	s_add_i32 m0, s37, 0xe000
	s_nop 0
	global_load_lds_dwordx4 v[178:179], off
	s_waitcnt vmcnt(8)
	s_waitcnt lgkmcnt(0)
	s_barrier
	s_setprio 1
	s_waitcnt lgkmcnt(0)
	v_mfma_f32_16x16x32_bf16 v[124:127], v[140:143], v[184:187], 0
	v_mfma_f32_16x16x32_bf16 v[120:123], v[154:157], v[184:187], 0
	v_mfma_f32_16x16x32_bf16 v[108:111], v[140:143], v[192:195], 0
	v_mfma_f32_16x16x32_bf16 v[104:107], v[154:157], v[192:195], 0
	v_mfma_f32_16x16x32_bf16 v[92:95], v[140:143], v[200:203], 0
	v_mfma_f32_16x16x32_bf16 v[88:91], v[154:157], v[200:203], 0
	v_mfma_f32_16x16x32_bf16 v[76:79], v[140:143], v[208:211], 0
	v_mfma_f32_16x16x32_bf16 v[72:75], v[154:157], v[208:211], 0
	v_mfma_f32_16x16x32_bf16 v[124:127], v[150:153], v[188:191], v[124:127]
	v_mfma_f32_16x16x32_bf16 v[120:123], v[158:161], v[188:191], v[120:123]
	v_mfma_f32_16x16x32_bf16 v[108:111], v[150:153], v[196:199], v[108:111]
	v_mfma_f32_16x16x32_bf16 v[104:107], v[158:161], v[196:199], v[104:107]
	v_mfma_f32_16x16x32_bf16 v[92:95], v[150:153], v[204:207], v[92:95]
	v_mfma_f32_16x16x32_bf16 v[88:91], v[158:161], v[204:207], v[88:91]
	v_mfma_f32_16x16x32_bf16 v[76:79], v[150:153], v[212:215], v[76:79]
	v_mfma_f32_16x16x32_bf16 v[72:75], v[158:161], v[212:215], v[72:75]
	s_setprio 0
	s_setprio 1
	v_mfma_f32_16x16x32_bf16 v[116:119], v[162:165], v[184:187], 0
	v_mfma_f32_16x16x32_bf16 v[112:115], v[170:173], v[184:187], 0
	v_mfma_f32_16x16x32_bf16 v[100:103], v[162:165], v[192:195], 0
	v_mfma_f32_16x16x32_bf16 v[96:99], v[170:173], v[192:195], 0
	v_mfma_f32_16x16x32_bf16 v[84:87], v[162:165], v[200:203], 0
	v_mfma_f32_16x16x32_bf16 v[80:83], v[170:173], v[200:203], 0
	v_mfma_f32_16x16x32_bf16 v[68:71], v[162:165], v[208:211], 0
	v_mfma_f32_16x16x32_bf16 v[64:67], v[170:173], v[208:211], 0
	v_mfma_f32_16x16x32_bf16 v[116:119], v[166:169], v[188:191], v[116:119]
	v_mfma_f32_16x16x32_bf16 v[112:115], v[174:177], v[188:191], v[112:115]
	v_mfma_f32_16x16x32_bf16 v[100:103], v[166:169], v[196:199], v[100:103]
	v_mfma_f32_16x16x32_bf16 v[96:99], v[174:177], v[196:199], v[96:99]
	v_mfma_f32_16x16x32_bf16 v[84:87], v[166:169], v[204:207], v[84:87]
	v_mfma_f32_16x16x32_bf16 v[80:83], v[174:177], v[204:207], v[80:83]
	v_mfma_f32_16x16x32_bf16 v[68:71], v[166:169], v[212:215], v[68:71]
	v_mfma_f32_16x16x32_bf16 v[64:67], v[174:177], v[212:215], v[64:67]
	s_setprio 0
	s_barrier
	s_add_i32 s18, s62, s54
	v_lshl_add_u64 v[178:179], s[46:47], 0, v[130:131]
	s_mov_b32 m0, s18
	ds_read_b128 v[184:187], v149 offset:16384
	ds_read_b128 v[188:191], v149 offset:17408
	ds_read_b128 v[192:195], v149 offset:18432
	ds_read_b128 v[196:199], v149 offset:19456
	ds_read_b128 v[200:203], v149 offset:20480
	ds_read_b128 v[204:207], v149 offset:21504
	ds_read_b128 v[208:211], v149 offset:22528
	ds_read_b128 v[212:215], v149 offset:23552
	global_load_lds_dwordx4 v[178:179], off
	s_add_i32 m0, s18, 0x2000
	s_add_u32 s72, s46, 0x40000
	v_lshl_add_u64 v[216:217], s[46:47], 0, v[128:129]
	s_addc_u32 s73, s47, 0
	s_add_i32 s18, s63, s54
	global_load_lds_dwordx4 v[216:217], off
	v_lshl_add_u64 v[218:219], s[72:73], 0, v[130:131]
	s_mov_b32 m0, s18
	v_lshl_add_u64 v[220:221], s[48:49], 0, v[128:129]
	global_load_lds_dwordx4 v[218:219], off
	v_lshl_add_u64 v[218:219], s[72:73], 0, v[128:129]
	s_add_i32 m0, s18, 0x2000
	s_nop 0
	global_load_lds_dwordx4 v[218:219], off
	v_lshl_add_u64 v[218:219], s[48:49], 0, v[130:131]
	s_mov_b32 m0, s37
	s_nop 0
	global_load_lds_dwordx4 v[218:219], off
	s_mov_b32 m0, s56
	s_nop 0
	global_load_lds_dwordx4 v[220:221], off
	s_waitcnt vmcnt(8)
	s_waitcnt lgkmcnt(0)
	s_barrier
	s_setprio 1
	s_waitcnt lgkmcnt(0)
	v_mfma_f32_16x16x32_bf16 v[60:63], v[140:143], v[184:187], 0
	v_mfma_f32_16x16x32_bf16 v[56:59], v[154:157], v[184:187], 0
	v_mfma_f32_16x16x32_bf16 v[44:47], v[140:143], v[192:195], 0
	v_mfma_f32_16x16x32_bf16 v[40:43], v[154:157], v[192:195], 0
	v_mfma_f32_16x16x32_bf16 v[28:31], v[140:143], v[200:203], 0
	v_mfma_f32_16x16x32_bf16 v[24:27], v[154:157], v[200:203], 0
	v_mfma_f32_16x16x32_bf16 v[12:15], v[140:143], v[208:211], 0
	v_mfma_f32_16x16x32_bf16 v[8:11], v[154:157], v[208:211], 0
	v_mfma_f32_16x16x32_bf16 v[60:63], v[150:153], v[188:191], v[60:63]
	v_mfma_f32_16x16x32_bf16 v[56:59], v[158:161], v[188:191], v[56:59]
	v_mfma_f32_16x16x32_bf16 v[44:47], v[150:153], v[196:199], v[44:47]
	v_mfma_f32_16x16x32_bf16 v[40:43], v[158:161], v[196:199], v[40:43]
	v_mfma_f32_16x16x32_bf16 v[28:31], v[150:153], v[204:207], v[28:31]
	v_mfma_f32_16x16x32_bf16 v[24:27], v[158:161], v[204:207], v[24:27]
	v_mfma_f32_16x16x32_bf16 v[12:15], v[150:153], v[212:215], v[12:15]
	v_mfma_f32_16x16x32_bf16 v[8:11], v[158:161], v[212:215], v[8:11]
	s_setprio 0
	s_setprio 1
	v_mfma_f32_16x16x32_bf16 v[52:55], v[162:165], v[184:187], 0
	v_mfma_f32_16x16x32_bf16 v[48:51], v[170:173], v[184:187], 0
	v_mfma_f32_16x16x32_bf16 v[36:39], v[162:165], v[192:195], 0
	v_mfma_f32_16x16x32_bf16 v[32:35], v[170:173], v[192:195], 0
	v_mfma_f32_16x16x32_bf16 v[20:23], v[162:165], v[200:203], 0
	v_mfma_f32_16x16x32_bf16 v[16:19], v[170:173], v[200:203], 0
	v_mfma_f32_16x16x32_bf16 v[4:7], v[162:165], v[208:211], 0
	v_mfma_f32_16x16x32_bf16 v[0:3], v[170:173], v[208:211], 0
	v_mfma_f32_16x16x32_bf16 v[52:55], v[166:169], v[188:191], v[52:55]
	v_mfma_f32_16x16x32_bf16 v[48:51], v[174:177], v[188:191], v[48:51]
	v_mfma_f32_16x16x32_bf16 v[36:39], v[166:169], v[196:199], v[36:39]
	v_mfma_f32_16x16x32_bf16 v[32:35], v[174:177], v[196:199], v[32:35]
	v_mfma_f32_16x16x32_bf16 v[20:23], v[166:169], v[204:207], v[20:23]
	v_mfma_f32_16x16x32_bf16 v[16:19], v[174:177], v[204:207], v[16:19]
	v_mfma_f32_16x16x32_bf16 v[4:7], v[166:169], v[212:215], v[4:7]
	v_mfma_f32_16x16x32_bf16 v[0:3], v[174:177], v[212:215], v[0:3]
	s_setprio 0
	s_barrier
	s_branch .Lmid_gemm0
.LBB0_184:
	ds_read_b128 v[140:143], v147
	ds_read_b128 v[150:153], v147 offset:1024
	ds_read_b128 v[154:157], v147 offset:2048
	ds_read_b128 v[158:161], v147 offset:3072
	ds_read_b128 v[162:165], v148
	ds_read_b128 v[166:169], v148 offset:1024
	ds_read_b128 v[170:173], v148 offset:2048
	ds_read_b128 v[174:177], v148 offset:3072
	s_add_u32 s18, s44, 0xfffc0080
	s_addc_u32 s19, s45, -1
	s_cmp_eq_u32 s70, 12
	s_cselect_b32 s49, s13, s19
	s_cselect_b32 s48, s66, s18
	s_cselect_b32 s47, s11, s69
	s_cselect_b32 s46, s67, s68
	v_lshl_add_u64 v[178:179], s[44:45], 0, v[132:133]
	s_add_i32 m0, s37, 0xc000
	ds_read_b128 v[184:187], v149
	ds_read_b128 v[188:191], v149 offset:1024
	ds_read_b128 v[192:195], v149 offset:2048
	ds_read_b128 v[196:199], v149 offset:3072
	ds_read_b128 v[200:203], v149 offset:4096
	ds_read_b128 v[204:207], v149 offset:5120
	ds_read_b128 v[208:211], v149 offset:6144
	ds_read_b128 v[212:215], v149 offset:7168
	global_load_lds_dwordx4 v[178:179], off
	v_lshl_add_u64 v[178:179], s[44:45], 0, v[134:135]
	s_add_i32 m0, s37, 0xe000
	s_nop 0
	global_load_lds_dwordx4 v[178:179], off
	s_waitcnt vmcnt(8)
	s_waitcnt lgkmcnt(0)
	s_barrier
	s_setprio 1
	s_waitcnt lgkmcnt(0)
	v_mfma_f32_16x16x32_bf16 v[124:127], v[140:143], v[184:187], v[124:127]
	v_mfma_f32_16x16x32_bf16 v[120:123], v[154:157], v[184:187], v[120:123]
	v_mfma_f32_16x16x32_bf16 v[108:111], v[140:143], v[192:195], v[108:111]
	v_mfma_f32_16x16x32_bf16 v[104:107], v[154:157], v[192:195], v[104:107]
	v_mfma_f32_16x16x32_bf16 v[92:95], v[140:143], v[200:203], v[92:95]
	v_mfma_f32_16x16x32_bf16 v[88:91], v[154:157], v[200:203], v[88:91]
	v_mfma_f32_16x16x32_bf16 v[76:79], v[140:143], v[208:211], v[76:79]
	v_mfma_f32_16x16x32_bf16 v[72:75], v[154:157], v[208:211], v[72:75]
	v_mfma_f32_16x16x32_bf16 v[124:127], v[150:153], v[188:191], v[124:127]
	v_mfma_f32_16x16x32_bf16 v[120:123], v[158:161], v[188:191], v[120:123]
	v_mfma_f32_16x16x32_bf16 v[108:111], v[150:153], v[196:199], v[108:111]
	v_mfma_f32_16x16x32_bf16 v[104:107], v[158:161], v[196:199], v[104:107]
	v_mfma_f32_16x16x32_bf16 v[92:95], v[150:153], v[204:207], v[92:95]
	v_mfma_f32_16x16x32_bf16 v[88:91], v[158:161], v[204:207], v[88:91]
	v_mfma_f32_16x16x32_bf16 v[76:79], v[150:153], v[212:215], v[76:79]
	v_mfma_f32_16x16x32_bf16 v[72:75], v[158:161], v[212:215], v[72:75]
	s_setprio 0
	s_setprio 1
	v_mfma_f32_16x16x32_bf16 v[116:119], v[162:165], v[184:187], v[116:119]
	v_mfma_f32_16x16x32_bf16 v[112:115], v[170:173], v[184:187], v[112:115]
	v_mfma_f32_16x16x32_bf16 v[100:103], v[162:165], v[192:195], v[100:103]
	v_mfma_f32_16x16x32_bf16 v[96:99], v[170:173], v[192:195], v[96:99]
	v_mfma_f32_16x16x32_bf16 v[84:87], v[162:165], v[200:203], v[84:87]
	v_mfma_f32_16x16x32_bf16 v[80:83], v[170:173], v[200:203], v[80:83]
	v_mfma_f32_16x16x32_bf16 v[68:71], v[162:165], v[208:211], v[68:71]
	v_mfma_f32_16x16x32_bf16 v[64:67], v[170:173], v[208:211], v[64:67]
	v_mfma_f32_16x16x32_bf16 v[116:119], v[166:169], v[188:191], v[116:119]
	v_mfma_f32_16x16x32_bf16 v[112:115], v[174:177], v[188:191], v[112:115]
	v_mfma_f32_16x16x32_bf16 v[100:103], v[166:169], v[196:199], v[100:103]
	v_mfma_f32_16x16x32_bf16 v[96:99], v[174:177], v[196:199], v[96:99]
	v_mfma_f32_16x16x32_bf16 v[84:87], v[166:169], v[204:207], v[84:87]
	v_mfma_f32_16x16x32_bf16 v[80:83], v[174:177], v[204:207], v[80:83]
	v_mfma_f32_16x16x32_bf16 v[68:71], v[166:169], v[212:215], v[68:71]
	v_mfma_f32_16x16x32_bf16 v[64:67], v[174:177], v[212:215], v[64:67]
	s_setprio 0
	s_barrier
	s_add_i32 s18, s62, s54
	v_lshl_add_u64 v[178:179], s[46:47], 0, v[130:131]
	s_mov_b32 m0, s18
	ds_read_b128 v[184:187], v149 offset:16384
	ds_read_b128 v[188:191], v149 offset:17408
	ds_read_b128 v[192:195], v149 offset:18432
	ds_read_b128 v[196:199], v149 offset:19456
	ds_read_b128 v[200:203], v149 offset:20480
	ds_read_b128 v[204:207], v149 offset:21504
	ds_read_b128 v[208:211], v149 offset:22528
	ds_read_b128 v[212:215], v149 offset:23552
	global_load_lds_dwordx4 v[178:179], off
	s_add_i32 m0, s18, 0x2000
	s_add_u32 s72, s46, 0x40000
	v_lshl_add_u64 v[216:217], s[46:47], 0, v[128:129]
	s_addc_u32 s73, s47, 0
	s_add_i32 s18, s63, s54
	global_load_lds_dwordx4 v[216:217], off
	v_lshl_add_u64 v[218:219], s[72:73], 0, v[130:131]
	s_mov_b32 m0, s18
	v_lshl_add_u64 v[220:221], s[48:49], 0, v[128:129]
	global_load_lds_dwordx4 v[218:219], off
	v_lshl_add_u64 v[218:219], s[72:73], 0, v[128:129]
	s_add_i32 m0, s18, 0x2000
	s_nop 0
	global_load_lds_dwordx4 v[218:219], off
	v_lshl_add_u64 v[218:219], s[48:49], 0, v[130:131]
	s_mov_b32 m0, s37
	s_nop 0
	global_load_lds_dwordx4 v[218:219], off
	s_mov_b32 m0, s56
	s_nop 0
	global_load_lds_dwordx4 v[220:221], off
	s_waitcnt vmcnt(8)
	s_waitcnt lgkmcnt(0)
	s_barrier
	s_setprio 1
	s_waitcnt lgkmcnt(0)
	v_mfma_f32_16x16x32_bf16 v[60:63], v[140:143], v[184:187], v[60:63]
	v_mfma_f32_16x16x32_bf16 v[56:59], v[154:157], v[184:187], v[56:59]
	v_mfma_f32_16x16x32_bf16 v[44:47], v[140:143], v[192:195], v[44:47]
	v_mfma_f32_16x16x32_bf16 v[40:43], v[154:157], v[192:195], v[40:43]
	v_mfma_f32_16x16x32_bf16 v[28:31], v[140:143], v[200:203], v[28:31]
	v_mfma_f32_16x16x32_bf16 v[24:27], v[154:157], v[200:203], v[24:27]
	v_mfma_f32_16x16x32_bf16 v[12:15], v[140:143], v[208:211], v[12:15]
	v_mfma_f32_16x16x32_bf16 v[8:11], v[154:157], v[208:211], v[8:11]
	v_mfma_f32_16x16x32_bf16 v[60:63], v[150:153], v[188:191], v[60:63]
	v_mfma_f32_16x16x32_bf16 v[56:59], v[158:161], v[188:191], v[56:59]
	v_mfma_f32_16x16x32_bf16 v[44:47], v[150:153], v[196:199], v[44:47]
	v_mfma_f32_16x16x32_bf16 v[40:43], v[158:161], v[196:199], v[40:43]
	v_mfma_f32_16x16x32_bf16 v[28:31], v[150:153], v[204:207], v[28:31]
	v_mfma_f32_16x16x32_bf16 v[24:27], v[158:161], v[204:207], v[24:27]
	v_mfma_f32_16x16x32_bf16 v[12:15], v[150:153], v[212:215], v[12:15]
	v_mfma_f32_16x16x32_bf16 v[8:11], v[158:161], v[212:215], v[8:11]
	s_setprio 0
	s_setprio 1
	v_mfma_f32_16x16x32_bf16 v[52:55], v[162:165], v[184:187], v[52:55]
	v_mfma_f32_16x16x32_bf16 v[48:51], v[170:173], v[184:187], v[48:51]
	v_mfma_f32_16x16x32_bf16 v[36:39], v[162:165], v[192:195], v[36:39]
	v_mfma_f32_16x16x32_bf16 v[32:35], v[170:173], v[192:195], v[32:35]
	v_mfma_f32_16x16x32_bf16 v[20:23], v[162:165], v[200:203], v[20:23]
	v_mfma_f32_16x16x32_bf16 v[16:19], v[170:173], v[200:203], v[16:19]
	v_mfma_f32_16x16x32_bf16 v[4:7], v[162:165], v[208:211], v[4:7]
	v_mfma_f32_16x16x32_bf16 v[0:3], v[170:173], v[208:211], v[0:3]
	v_mfma_f32_16x16x32_bf16 v[52:55], v[166:169], v[188:191], v[52:55]
	v_mfma_f32_16x16x32_bf16 v[48:51], v[174:177], v[188:191], v[48:51]
	v_mfma_f32_16x16x32_bf16 v[36:39], v[166:169], v[196:199], v[36:39]
	v_mfma_f32_16x16x32_bf16 v[32:35], v[174:177], v[196:199], v[32:35]
	v_mfma_f32_16x16x32_bf16 v[20:23], v[166:169], v[204:207], v[20:23]
	v_mfma_f32_16x16x32_bf16 v[16:19], v[174:177], v[204:207], v[16:19]
	v_mfma_f32_16x16x32_bf16 v[4:7], v[166:169], v[212:215], v[4:7]
	v_mfma_f32_16x16x32_bf16 v[0:3], v[174:177], v[212:215], v[0:3]
	s_setprio 0
	s_barrier
.Lmid_gemm0:
	s_add_i32 s18, 0, 0x18000
	s_add_i32 s19, 0, 0x1c000
	v_add_u32_e32 v158, s18, v145
	v_add_u32_e32 v174, s19, v145
	ds_read_b128 v[140:143], v158
	ds_read_b128 v[150:153], v158 offset:1024
	ds_read_b128 v[154:157], v158 offset:2048
	ds_read_b128 v[158:161], v158 offset:3072
	ds_read_b128 v[162:165], v174
	ds_read_b128 v[166:169], v174 offset:1024
	ds_read_b128 v[170:173], v174 offset:2048
	ds_read_b128 v[174:177], v174 offset:3072
	s_add_u32 s48, s48, 0x40000
	s_addc_u32 s49, s49, 0
	s_mov_b32 m0, s57
	v_lshl_add_u64 v[222:223], s[48:49], 0, v[130:131]
	ds_read_b128 v[184:187], v149 offset:32768
	ds_read_b128 v[188:191], v149 offset:33792
	ds_read_b128 v[192:195], v149 offset:34816
	ds_read_b128 v[196:199], v149 offset:35840
	ds_read_b128 v[200:203], v149 offset:36864
	ds_read_b128 v[204:207], v149 offset:37888
	ds_read_b128 v[208:211], v149 offset:38912
	ds_read_b128 v[212:215], v149 offset:39936
	global_load_lds_dwordx4 v[222:223], off
	v_lshl_add_u64 v[222:223], s[48:49], 0, v[128:129]
	s_mov_b32 m0, s58
	s_nop 0
	global_load_lds_dwordx4 v[222:223], off
	s_waitcnt vmcnt(8)
	s_waitcnt lgkmcnt(0)
	s_barrier
	s_setprio 1
	s_waitcnt lgkmcnt(0)
	v_mfma_f32_16x16x32_bf16 v[124:127], v[140:143], v[184:187], v[124:127]
	v_mfma_f32_16x16x32_bf16 v[120:123], v[154:157], v[184:187], v[120:123]
	v_mfma_f32_16x16x32_bf16 v[108:111], v[140:143], v[192:195], v[108:111]
	v_mfma_f32_16x16x32_bf16 v[104:107], v[154:157], v[192:195], v[104:107]
	v_mfma_f32_16x16x32_bf16 v[92:95], v[140:143], v[200:203], v[92:95]
	v_mfma_f32_16x16x32_bf16 v[88:91], v[154:157], v[200:203], v[88:91]
	v_mfma_f32_16x16x32_bf16 v[76:79], v[140:143], v[208:211], v[76:79]
	v_mfma_f32_16x16x32_bf16 v[72:75], v[154:157], v[208:211], v[72:75]
	v_mfma_f32_16x16x32_bf16 v[124:127], v[150:153], v[188:191], v[124:127]
	v_mfma_f32_16x16x32_bf16 v[120:123], v[158:161], v[188:191], v[120:123]
	v_mfma_f32_16x16x32_bf16 v[108:111], v[150:153], v[196:199], v[108:111]
	v_mfma_f32_16x16x32_bf16 v[104:107], v[158:161], v[196:199], v[104:107]
	v_mfma_f32_16x16x32_bf16 v[92:95], v[150:153], v[204:207], v[92:95]
	v_mfma_f32_16x16x32_bf16 v[88:91], v[158:161], v[204:207], v[88:91]
	v_mfma_f32_16x16x32_bf16 v[76:79], v[150:153], v[212:215], v[76:79]
	v_mfma_f32_16x16x32_bf16 v[72:75], v[158:161], v[212:215], v[72:75]
	s_setprio 0
	s_setprio 1
	v_mfma_f32_16x16x32_bf16 v[116:119], v[162:165], v[184:187], v[116:119]
	v_mfma_f32_16x16x32_bf16 v[112:115], v[170:173], v[184:187], v[112:115]
	v_mfma_f32_16x16x32_bf16 v[100:103], v[162:165], v[192:195], v[100:103]
	v_mfma_f32_16x16x32_bf16 v[96:99], v[170:173], v[192:195], v[96:99]
	v_mfma_f32_16x16x32_bf16 v[84:87], v[162:165], v[200:203], v[84:87]
	v_mfma_f32_16x16x32_bf16 v[80:83], v[170:173], v[200:203], v[80:83]
	v_mfma_f32_16x16x32_bf16 v[68:71], v[162:165], v[208:211], v[68:71]
	v_mfma_f32_16x16x32_bf16 v[64:67], v[170:173], v[208:211], v[64:67]
	v_mfma_f32_16x16x32_bf16 v[116:119], v[166:169], v[188:191], v[116:119]
	v_mfma_f32_16x16x32_bf16 v[112:115], v[174:177], v[188:191], v[112:115]
	v_mfma_f32_16x16x32_bf16 v[100:103], v[166:169], v[196:199], v[100:103]
	v_mfma_f32_16x16x32_bf16 v[96:99], v[174:177], v[196:199], v[96:99]
	v_mfma_f32_16x16x32_bf16 v[84:87], v[166:169], v[204:207], v[84:87]
	v_mfma_f32_16x16x32_bf16 v[80:83], v[174:177], v[204:207], v[80:83]
	v_mfma_f32_16x16x32_bf16 v[68:71], v[166:169], v[212:215], v[68:71]
	v_mfma_f32_16x16x32_bf16 v[64:67], v[174:177], v[212:215], v[64:67]
	s_setprio 0
	s_barrier
	s_add_i32 s18, s18, s54
	v_lshl_add_u64 v[178:179], v[178:179], 0, s[6:7]
	s_mov_b32 m0, s18
	ds_read_b128 v[184:187], v149 offset:49152
	ds_read_b128 v[188:191], v149 offset:50176
	ds_read_b128 v[192:195], v149 offset:51200
	ds_read_b128 v[196:199], v149 offset:52224
	ds_read_b128 v[200:203], v149 offset:53248
	ds_read_b128 v[204:207], v149 offset:54272
	ds_read_b128 v[208:211], v149 offset:55296
	ds_read_b128 v[212:215], v149 offset:56320
	global_load_lds_dwordx4 v[178:179], off
	s_add_i32 m0, s18, 0x2000
	s_add_u32 s46, s46, 0x40080
	v_lshl_add_u64 v[178:179], v[216:217], 0, s[6:7]
	s_addc_u32 s47, s47, 0
	s_add_i32 s18, s19, s54
	global_load_lds_dwordx4 v[178:179], off
	v_lshl_add_u64 v[178:179], s[46:47], 0, v[130:131]
	s_mov_b32 m0, s18
	s_nop 0
	global_load_lds_dwordx4 v[178:179], off
	v_lshl_add_u64 v[178:179], s[46:47], 0, v[128:129]
	s_add_i32 m0, s18, 0x2000
	s_nop 0
	global_load_lds_dwordx4 v[178:179], off
	v_lshl_add_u64 v[178:179], v[218:219], 0, s[6:7]
	s_mov_b32 m0, s60
	s_nop 0
	global_load_lds_dwordx4 v[178:179], off
	v_lshl_add_u64 v[178:179], v[220:221], 0, s[6:7]
	s_mov_b32 m0, s61
	s_nop 0
	global_load_lds_dwordx4 v[178:179], off
	s_waitcnt vmcnt(8)
	s_waitcnt lgkmcnt(0)
	s_barrier
	s_setprio 1
	s_waitcnt lgkmcnt(0)
	v_mfma_f32_16x16x32_bf16 v[60:63], v[140:143], v[184:187], v[60:63]
	v_mfma_f32_16x16x32_bf16 v[56:59], v[154:157], v[184:187], v[56:59]
	v_mfma_f32_16x16x32_bf16 v[44:47], v[140:143], v[192:195], v[44:47]
	v_mfma_f32_16x16x32_bf16 v[40:43], v[154:157], v[192:195], v[40:43]
	v_mfma_f32_16x16x32_bf16 v[28:31], v[140:143], v[200:203], v[28:31]
	v_mfma_f32_16x16x32_bf16 v[24:27], v[154:157], v[200:203], v[24:27]
	v_mfma_f32_16x16x32_bf16 v[12:15], v[140:143], v[208:211], v[12:15]
	v_mfma_f32_16x16x32_bf16 v[8:11], v[154:157], v[208:211], v[8:11]
	v_mfma_f32_16x16x32_bf16 v[60:63], v[150:153], v[188:191], v[60:63]
	v_mfma_f32_16x16x32_bf16 v[56:59], v[158:161], v[188:191], v[56:59]
	v_mfma_f32_16x16x32_bf16 v[44:47], v[150:153], v[196:199], v[44:47]
	v_mfma_f32_16x16x32_bf16 v[40:43], v[158:161], v[196:199], v[40:43]
	v_mfma_f32_16x16x32_bf16 v[28:31], v[150:153], v[204:207], v[28:31]
	v_mfma_f32_16x16x32_bf16 v[24:27], v[158:161], v[204:207], v[24:27]
	v_mfma_f32_16x16x32_bf16 v[12:15], v[150:153], v[212:215], v[12:15]
	v_mfma_f32_16x16x32_bf16 v[8:11], v[158:161], v[212:215], v[8:11]
	s_setprio 0
	s_setprio 1
	v_mfma_f32_16x16x32_bf16 v[52:55], v[162:165], v[184:187], v[52:55]
	v_mfma_f32_16x16x32_bf16 v[48:51], v[170:173], v[184:187], v[48:51]
	v_mfma_f32_16x16x32_bf16 v[36:39], v[162:165], v[192:195], v[36:39]
	v_mfma_f32_16x16x32_bf16 v[32:35], v[170:173], v[192:195], v[32:35]
	v_mfma_f32_16x16x32_bf16 v[20:23], v[162:165], v[200:203], v[20:23]
	v_mfma_f32_16x16x32_bf16 v[16:19], v[170:173], v[200:203], v[16:19]
	v_mfma_f32_16x16x32_bf16 v[4:7], v[162:165], v[208:211], v[4:7]
	v_mfma_f32_16x16x32_bf16 v[0:3], v[170:173], v[208:211], v[0:3]
	v_mfma_f32_16x16x32_bf16 v[52:55], v[166:169], v[188:191], v[52:55]
	v_mfma_f32_16x16x32_bf16 v[48:51], v[174:177], v[188:191], v[48:51]
	v_mfma_f32_16x16x32_bf16 v[36:39], v[166:169], v[196:199], v[36:39]
	v_mfma_f32_16x16x32_bf16 v[32:35], v[174:177], v[196:199], v[32:35]
	v_mfma_f32_16x16x32_bf16 v[20:23], v[166:169], v[204:207], v[20:23]
	v_mfma_f32_16x16x32_bf16 v[16:19], v[174:177], v[204:207], v[16:19]
	v_mfma_f32_16x16x32_bf16 v[4:7], v[166:169], v[212:215], v[4:7]
	v_mfma_f32_16x16x32_bf16 v[0:3], v[174:177], v[212:215], v[0:3]
	s_setprio 0
	s_barrier
	s_add_i32 s70, s70, 2
	s_add_u32 s44, s44, 0x100
	s_addc_u32 s45, s45, 0
	s_add_u32 s68, s68, 0x100
	s_addc_u32 s69, s69, 0
	s_cmp_gt_u32 s70, 13
	s_cbranch_scc0 .LBB0_184
	s_and_b64 vcc, exec, s[8:9]
	s_cbranch_vccz .LBB0_187
	s_barrier

.LBB0_263:
	s_add_u32 s84, s54, 0x100
	s_addc_u32 s85, s55, 0
	s_mov_b32 s86, -2
	ds_read_b128 v[152:155], v149
	ds_read_b128 v[156:159], v149 offset:1024
	ds_read_b128 v[160:163], v149 offset:2048
	ds_read_b128 v[164:167], v149 offset:3072
	ds_read_b128 v[168:171], v150
	ds_read_b128 v[172:175], v150 offset:1024
	ds_read_b128 v[176:179], v150 offset:2048
	ds_read_b128 v[184:187], v150 offset:3072
	s_add_u32 s54, s52, 0x100
	s_addc_u32 s55, s53, 0
	s_cmp_eq_u32 s86, 40
	s_cselect_b32 s59, s7, s55
	s_cselect_b32 s58, s6, s54
	s_cselect_b32 s57, s49, s85
	s_cselect_b32 s56, s48, s84
	v_lshl_add_u64 v[144:145], s[52:53], 0, v[136:137]
	s_add_i32 m0, s63, 0xc000
	ds_read_b128 v[188:191], v151
	ds_read_b128 v[192:195], v151 offset:1024
	ds_read_b128 v[196:199], v151 offset:2048
	ds_read_b128 v[200:203], v151 offset:3072
	ds_read_b128 v[204:207], v151 offset:4096
	ds_read_b128 v[208:211], v151 offset:5120
	ds_read_b128 v[212:215], v151 offset:6144
	ds_read_b128 v[216:219], v151 offset:7168
	global_load_lds_dwordx4 v[144:145], off
	v_lshl_add_u64 v[144:145], s[52:53], 0, v[138:139]
	s_add_i32 m0, s63, 0xe000
	s_nop 0
	global_load_lds_dwordx4 v[144:145], off
	s_waitcnt vmcnt(8)
	s_waitcnt lgkmcnt(0)
	s_barrier
	s_setprio 1
	s_waitcnt lgkmcnt(0)
	v_mfma_f32_16x16x32_bf16 v[124:127], v[152:155], v[188:191], 0
	v_mfma_f32_16x16x32_bf16 v[120:123], v[160:163], v[188:191], 0
	v_mfma_f32_16x16x32_bf16 v[116:119], v[152:155], v[196:199], 0
	v_mfma_f32_16x16x32_bf16 v[108:111], v[160:163], v[196:199], 0
	v_mfma_f32_16x16x32_bf16 v[100:103], v[152:155], v[204:207], 0
	v_mfma_f32_16x16x32_bf16 v[92:95], v[160:163], v[204:207], 0
	v_mfma_f32_16x16x32_bf16 v[84:87], v[152:155], v[212:215], 0
	v_mfma_f32_16x16x32_bf16 v[76:79], v[160:163], v[212:215], 0
	v_mfma_f32_16x16x32_bf16 v[124:127], v[156:159], v[192:195], v[124:127]
	v_mfma_f32_16x16x32_bf16 v[120:123], v[164:167], v[192:195], v[120:123]
	v_mfma_f32_16x16x32_bf16 v[116:119], v[156:159], v[200:203], v[116:119]
	v_mfma_f32_16x16x32_bf16 v[108:111], v[164:167], v[200:203], v[108:111]
	v_mfma_f32_16x16x32_bf16 v[100:103], v[156:159], v[208:211], v[100:103]
	v_mfma_f32_16x16x32_bf16 v[92:95], v[164:167], v[208:211], v[92:95]
	v_mfma_f32_16x16x32_bf16 v[84:87], v[156:159], v[216:219], v[84:87]
	v_mfma_f32_16x16x32_bf16 v[76:79], v[164:167], v[216:219], v[76:79]
	s_setprio 0
	s_setprio 1
	v_mfma_f32_16x16x32_bf16 v[112:115], v[168:171], v[188:191], 0
	v_mfma_f32_16x16x32_bf16 v[104:107], v[176:179], v[188:191], 0
	v_mfma_f32_16x16x32_bf16 v[96:99], v[168:171], v[196:199], 0
	v_mfma_f32_16x16x32_bf16 v[88:91], v[176:179], v[196:199], 0
	v_mfma_f32_16x16x32_bf16 v[80:83], v[168:171], v[204:207], 0
	v_mfma_f32_16x16x32_bf16 v[72:75], v[176:179], v[204:207], 0
	v_mfma_f32_16x16x32_bf16 v[68:71], v[168:171], v[212:215], 0
	v_mfma_f32_16x16x32_bf16 v[64:67], v[176:179], v[212:215], 0
	v_mfma_f32_16x16x32_bf16 v[112:115], v[172:175], v[192:195], v[112:115]
	v_mfma_f32_16x16x32_bf16 v[104:107], v[184:187], v[192:195], v[104:107]
	v_mfma_f32_16x16x32_bf16 v[96:99], v[172:175], v[200:203], v[96:99]
	v_mfma_f32_16x16x32_bf16 v[88:91], v[184:187], v[200:203], v[88:91]
	v_mfma_f32_16x16x32_bf16 v[80:83], v[172:175], v[208:211], v[80:83]
	v_mfma_f32_16x16x32_bf16 v[72:75], v[184:187], v[208:211], v[72:75]
	v_mfma_f32_16x16x32_bf16 v[68:71], v[172:175], v[216:219], v[68:71]
	v_mfma_f32_16x16x32_bf16 v[64:67], v[184:187], v[216:219], v[64:67]
	s_setprio 0
	s_barrier
	s_add_i32 s18, s70, s62
	v_lshl_add_u64 v[144:145], s[56:57], 0, v[130:131]
	s_mov_b32 m0, s18
	ds_read_b128 v[188:191], v151 offset:16384
	ds_read_b128 v[192:195], v151 offset:17408
	ds_read_b128 v[196:199], v151 offset:18432
	ds_read_b128 v[200:203], v151 offset:19456
	ds_read_b128 v[204:207], v151 offset:20480
	ds_read_b128 v[208:211], v151 offset:21504
	ds_read_b128 v[212:215], v151 offset:22528
	ds_read_b128 v[216:219], v151 offset:23552
	global_load_lds_dwordx4 v[144:145], off
	s_add_i32 m0, s18, 0x2000
	s_add_u32 s52, s56, 0xb0000
	v_lshl_add_u64 v[220:221], s[56:57], 0, v[134:135]
	s_addc_u32 s53, s57, 0
	s_add_i32 s18, s71, s62
	global_load_lds_dwordx4 v[220:221], off
	v_lshl_add_u64 v[222:223], s[52:53], 0, v[130:131]
	s_mov_b32 m0, s18
	v_lshl_add_u64 v[224:225], s[58:59], 0, v[132:133]
	global_load_lds_dwordx4 v[222:223], off
	v_lshl_add_u64 v[222:223], s[52:53], 0, v[134:135]
	s_add_i32 m0, s18, 0x2000
	s_nop 0
	global_load_lds_dwordx4 v[222:223], off
	v_lshl_add_u64 v[222:223], s[58:59], 0, v[128:129]
	s_mov_b32 m0, s63
	s_nop 0
	global_load_lds_dwordx4 v[222:223], off
	s_mov_b32 m0, s64
	s_nop 0
	global_load_lds_dwordx4 v[224:225], off
	s_waitcnt vmcnt(8)
	s_waitcnt lgkmcnt(0)
	s_barrier
	s_setprio 1
	s_waitcnt lgkmcnt(0)
	v_mfma_f32_16x16x32_bf16 v[60:63], v[152:155], v[188:191], 0
	v_mfma_f32_16x16x32_bf16 v[56:59], v[160:163], v[188:191], 0
	v_mfma_f32_16x16x32_bf16 v[52:55], v[152:155], v[196:199], 0
	v_mfma_f32_16x16x32_bf16 v[44:47], v[160:163], v[196:199], 0
	v_mfma_f32_16x16x32_bf16 v[36:39], v[152:155], v[204:207], 0
	v_mfma_f32_16x16x32_bf16 v[28:31], v[160:163], v[204:207], 0
	v_mfma_f32_16x16x32_bf16 v[20:23], v[152:155], v[212:215], 0
	v_mfma_f32_16x16x32_bf16 v[12:15], v[160:163], v[212:215], 0
	v_mfma_f32_16x16x32_bf16 v[60:63], v[156:159], v[192:195], v[60:63]
	v_mfma_f32_16x16x32_bf16 v[56:59], v[164:167], v[192:195], v[56:59]
	v_mfma_f32_16x16x32_bf16 v[52:55], v[156:159], v[200:203], v[52:55]
	v_mfma_f32_16x16x32_bf16 v[44:47], v[164:167], v[200:203], v[44:47]
	v_mfma_f32_16x16x32_bf16 v[36:39], v[156:159], v[208:211], v[36:39]
	v_mfma_f32_16x16x32_bf16 v[28:31], v[164:167], v[208:211], v[28:31]
	v_mfma_f32_16x16x32_bf16 v[20:23], v[156:159], v[216:219], v[20:23]
	v_mfma_f32_16x16x32_bf16 v[12:15], v[164:167], v[216:219], v[12:15]
	s_setprio 0
	s_setprio 1
	v_mfma_f32_16x16x32_bf16 v[48:51], v[168:171], v[188:191], 0
	v_mfma_f32_16x16x32_bf16 v[40:43], v[176:179], v[188:191], 0
	v_mfma_f32_16x16x32_bf16 v[32:35], v[168:171], v[196:199], 0
	v_mfma_f32_16x16x32_bf16 v[24:27], v[176:179], v[196:199], 0
	v_mfma_f32_16x16x32_bf16 v[16:19], v[168:171], v[204:207], 0
	v_mfma_f32_16x16x32_bf16 v[8:11], v[176:179], v[204:207], 0
	v_mfma_f32_16x16x32_bf16 v[4:7], v[168:171], v[212:215], 0
	v_mfma_f32_16x16x32_bf16 v[0:3], v[176:179], v[212:215], 0
	v_mfma_f32_16x16x32_bf16 v[48:51], v[172:175], v[192:195], v[48:51]
	v_mfma_f32_16x16x32_bf16 v[40:43], v[184:187], v[192:195], v[40:43]
	v_mfma_f32_16x16x32_bf16 v[32:35], v[172:175], v[200:203], v[32:35]
	v_mfma_f32_16x16x32_bf16 v[24:27], v[184:187], v[200:203], v[24:27]
	v_mfma_f32_16x16x32_bf16 v[16:19], v[172:175], v[208:211], v[16:19]
	v_mfma_f32_16x16x32_bf16 v[8:11], v[184:187], v[208:211], v[8:11]
	v_mfma_f32_16x16x32_bf16 v[4:7], v[172:175], v[216:219], v[4:7]
	v_mfma_f32_16x16x32_bf16 v[0:3], v[184:187], v[216:219], v[0:3]
	s_setprio 0
	s_barrier
	s_branch .Lmid_gemm1
.LBB0_264:
	ds_read_b128 v[152:155], v149
	ds_read_b128 v[156:159], v149 offset:1024
	ds_read_b128 v[160:163], v149 offset:2048
	ds_read_b128 v[164:167], v149 offset:3072
	ds_read_b128 v[168:171], v150
	ds_read_b128 v[172:175], v150 offset:1024
	ds_read_b128 v[176:179], v150 offset:2048
	ds_read_b128 v[184:187], v150 offset:3072
	s_add_u32 s54, s52, 0x100
	s_addc_u32 s55, s53, 0
	s_cmp_eq_u32 s86, 40
	s_cselect_b32 s59, s7, s55
	s_cselect_b32 s58, s6, s54
	s_cselect_b32 s57, s49, s85
	s_cselect_b32 s56, s48, s84
	v_lshl_add_u64 v[144:145], s[52:53], 0, v[136:137]
	s_add_i32 m0, s63, 0xc000
	ds_read_b128 v[188:191], v151
	ds_read_b128 v[192:195], v151 offset:1024
	ds_read_b128 v[196:199], v151 offset:2048
	ds_read_b128 v[200:203], v151 offset:3072
	ds_read_b128 v[204:207], v151 offset:4096
	ds_read_b128 v[208:211], v151 offset:5120
	ds_read_b128 v[212:215], v151 offset:6144
	ds_read_b128 v[216:219], v151 offset:7168
	global_load_lds_dwordx4 v[144:145], off
	v_lshl_add_u64 v[144:145], s[52:53], 0, v[138:139]
	s_add_i32 m0, s63, 0xe000
	s_nop 0
	global_load_lds_dwordx4 v[144:145], off
	s_waitcnt vmcnt(8)
	s_waitcnt lgkmcnt(0)
	s_barrier
	s_setprio 1
	s_waitcnt lgkmcnt(0)
	v_mfma_f32_16x16x32_bf16 v[124:127], v[152:155], v[188:191], v[124:127]
	v_mfma_f32_16x16x32_bf16 v[120:123], v[160:163], v[188:191], v[120:123]
	v_mfma_f32_16x16x32_bf16 v[116:119], v[152:155], v[196:199], v[116:119]
	v_mfma_f32_16x16x32_bf16 v[108:111], v[160:163], v[196:199], v[108:111]
	v_mfma_f32_16x16x32_bf16 v[100:103], v[152:155], v[204:207], v[100:103]
	v_mfma_f32_16x16x32_bf16 v[92:95], v[160:163], v[204:207], v[92:95]
	v_mfma_f32_16x16x32_bf16 v[84:87], v[152:155], v[212:215], v[84:87]
	v_mfma_f32_16x16x32_bf16 v[76:79], v[160:163], v[212:215], v[76:79]
	v_mfma_f32_16x16x32_bf16 v[124:127], v[156:159], v[192:195], v[124:127]
	v_mfma_f32_16x16x32_bf16 v[120:123], v[164:167], v[192:195], v[120:123]
	v_mfma_f32_16x16x32_bf16 v[116:119], v[156:159], v[200:203], v[116:119]
	v_mfma_f32_16x16x32_bf16 v[108:111], v[164:167], v[200:203], v[108:111]
	v_mfma_f32_16x16x32_bf16 v[100:103], v[156:159], v[208:211], v[100:103]
	v_mfma_f32_16x16x32_bf16 v[92:95], v[164:167], v[208:211], v[92:95]
	v_mfma_f32_16x16x32_bf16 v[84:87], v[156:159], v[216:219], v[84:87]
	v_mfma_f32_16x16x32_bf16 v[76:79], v[164:167], v[216:219], v[76:79]
	s_setprio 0
	s_setprio 1
	v_mfma_f32_16x16x32_bf16 v[112:115], v[168:171], v[188:191], v[112:115]
	v_mfma_f32_16x16x32_bf16 v[104:107], v[176:179], v[188:191], v[104:107]
	v_mfma_f32_16x16x32_bf16 v[96:99], v[168:171], v[196:199], v[96:99]
	v_mfma_f32_16x16x32_bf16 v[88:91], v[176:179], v[196:199], v[88:91]
	v_mfma_f32_16x16x32_bf16 v[80:83], v[168:171], v[204:207], v[80:83]
	v_mfma_f32_16x16x32_bf16 v[72:75], v[176:179], v[204:207], v[72:75]
	v_mfma_f32_16x16x32_bf16 v[68:71], v[168:171], v[212:215], v[68:71]
	v_mfma_f32_16x16x32_bf16 v[64:67], v[176:179], v[212:215], v[64:67]
	v_mfma_f32_16x16x32_bf16 v[112:115], v[172:175], v[192:195], v[112:115]
	v_mfma_f32_16x16x32_bf16 v[104:107], v[184:187], v[192:195], v[104:107]
	v_mfma_f32_16x16x32_bf16 v[96:99], v[172:175], v[200:203], v[96:99]
	v_mfma_f32_16x16x32_bf16 v[88:91], v[184:187], v[200:203], v[88:91]
	v_mfma_f32_16x16x32_bf16 v[80:83], v[172:175], v[208:211], v[80:83]
	v_mfma_f32_16x16x32_bf16 v[72:75], v[184:187], v[208:211], v[72:75]
	v_mfma_f32_16x16x32_bf16 v[68:71], v[172:175], v[216:219], v[68:71]
	v_mfma_f32_16x16x32_bf16 v[64:67], v[184:187], v[216:219], v[64:67]
	s_setprio 0
	s_barrier
	s_add_i32 s18, s70, s62
	v_lshl_add_u64 v[144:145], s[56:57], 0, v[130:131]
	s_mov_b32 m0, s18
	ds_read_b128 v[188:191], v151 offset:16384
	ds_read_b128 v[192:195], v151 offset:17408
	ds_read_b128 v[196:199], v151 offset:18432
	ds_read_b128 v[200:203], v151 offset:19456
	ds_read_b128 v[204:207], v151 offset:20480
	ds_read_b128 v[208:211], v151 offset:21504
	ds_read_b128 v[212:215], v151 offset:22528
	ds_read_b128 v[216:219], v151 offset:23552
	global_load_lds_dwordx4 v[144:145], off
	s_add_i32 m0, s18, 0x2000
	s_add_u32 s52, s56, 0xb0000
	v_lshl_add_u64 v[220:221], s[56:57], 0, v[134:135]
	s_addc_u32 s53, s57, 0
	s_add_i32 s18, s71, s62
	global_load_lds_dwordx4 v[220:221], off
	v_lshl_add_u64 v[222:223], s[52:53], 0, v[130:131]
	s_mov_b32 m0, s18
	v_lshl_add_u64 v[224:225], s[58:59], 0, v[132:133]
	global_load_lds_dwordx4 v[222:223], off
	v_lshl_add_u64 v[222:223], s[52:53], 0, v[134:135]
	s_add_i32 m0, s18, 0x2000
	s_nop 0
	global_load_lds_dwordx4 v[222:223], off
	v_lshl_add_u64 v[222:223], s[58:59], 0, v[128:129]
	s_mov_b32 m0, s63
	s_nop 0
	global_load_lds_dwordx4 v[222:223], off
	s_mov_b32 m0, s64
	s_nop 0
	global_load_lds_dwordx4 v[224:225], off
	s_waitcnt vmcnt(8)
	s_waitcnt lgkmcnt(0)
	s_barrier
	s_setprio 1
	s_waitcnt lgkmcnt(0)
	v_mfma_f32_16x16x32_bf16 v[60:63], v[152:155], v[188:191], v[60:63]
	v_mfma_f32_16x16x32_bf16 v[56:59], v[160:163], v[188:191], v[56:59]
	v_mfma_f32_16x16x32_bf16 v[52:55], v[152:155], v[196:199], v[52:55]
	v_mfma_f32_16x16x32_bf16 v[44:47], v[160:163], v[196:199], v[44:47]
	v_mfma_f32_16x16x32_bf16 v[36:39], v[152:155], v[204:207], v[36:39]
	v_mfma_f32_16x16x32_bf16 v[28:31], v[160:163], v[204:207], v[28:31]
	v_mfma_f32_16x16x32_bf16 v[20:23], v[152:155], v[212:215], v[20:23]
	v_mfma_f32_16x16x32_bf16 v[12:15], v[160:163], v[212:215], v[12:15]
	v_mfma_f32_16x16x32_bf16 v[60:63], v[156:159], v[192:195], v[60:63]
	v_mfma_f32_16x16x32_bf16 v[56:59], v[164:167], v[192:195], v[56:59]
	v_mfma_f32_16x16x32_bf16 v[52:55], v[156:159], v[200:203], v[52:55]
	v_mfma_f32_16x16x32_bf16 v[44:47], v[164:167], v[200:203], v[44:47]
	v_mfma_f32_16x16x32_bf16 v[36:39], v[156:159], v[208:211], v[36:39]
	v_mfma_f32_16x16x32_bf16 v[28:31], v[164:167], v[208:211], v[28:31]
	v_mfma_f32_16x16x32_bf16 v[20:23], v[156:159], v[216:219], v[20:23]
	v_mfma_f32_16x16x32_bf16 v[12:15], v[164:167], v[216:219], v[12:15]
	s_setprio 0
	s_setprio 1
	v_mfma_f32_16x16x32_bf16 v[48:51], v[168:171], v[188:191], v[48:51]
	v_mfma_f32_16x16x32_bf16 v[40:43], v[176:179], v[188:191], v[40:43]
	v_mfma_f32_16x16x32_bf16 v[32:35], v[168:171], v[196:199], v[32:35]
	v_mfma_f32_16x16x32_bf16 v[24:27], v[176:179], v[196:199], v[24:27]
	v_mfma_f32_16x16x32_bf16 v[16:19], v[168:171], v[204:207], v[16:19]
	v_mfma_f32_16x16x32_bf16 v[8:11], v[176:179], v[204:207], v[8:11]
	v_mfma_f32_16x16x32_bf16 v[4:7], v[168:171], v[212:215], v[4:7]
	v_mfma_f32_16x16x32_bf16 v[0:3], v[176:179], v[212:215], v[0:3]
	v_mfma_f32_16x16x32_bf16 v[48:51], v[172:175], v[192:195], v[48:51]
	v_mfma_f32_16x16x32_bf16 v[40:43], v[184:187], v[192:195], v[40:43]
	v_mfma_f32_16x16x32_bf16 v[32:35], v[172:175], v[200:203], v[32:35]
	v_mfma_f32_16x16x32_bf16 v[24:27], v[184:187], v[200:203], v[24:27]
	v_mfma_f32_16x16x32_bf16 v[16:19], v[172:175], v[208:211], v[16:19]
	v_mfma_f32_16x16x32_bf16 v[8:11], v[184:187], v[208:211], v[8:11]
	v_mfma_f32_16x16x32_bf16 v[4:7], v[172:175], v[216:219], v[4:7]
	v_mfma_f32_16x16x32_bf16 v[0:3], v[184:187], v[216:219], v[0:3]
	s_setprio 0
	s_barrier
.Lmid_gemm1:
	s_add_i32 s18, 0, 0x18000
	s_add_i32 s19, 0, 0x1c000
	v_add_u32_e32 v164, s18, v147
	v_add_u32_e32 v181, s19, v147
	ds_read_b128 v[152:155], v164
	ds_read_b128 v[156:159], v164 offset:1024
	ds_read_b128 v[160:163], v164 offset:2048
	ds_read_b128 v[164:167], v164 offset:3072
	ds_read_b128 v[168:171], v181
	ds_read_b128 v[172:175], v181 offset:1024
	ds_read_b128 v[176:179], v181 offset:2048
	ds_read_b128 v[184:187], v181 offset:3072
	s_add_u32 s52, s58, 0xb0000
	s_addc_u32 s53, s59, 0
	s_mov_b32 m0, s65
	v_lshl_add_u64 v[226:227], s[52:53], 0, v[128:129]
	ds_read_b128 v[188:191], v151 offset:32768
	ds_read_b128 v[192:195], v151 offset:33792
	ds_read_b128 v[196:199], v151 offset:34816
	ds_read_b128 v[200:203], v151 offset:35840
	ds_read_b128 v[204:207], v151 offset:36864
	ds_read_b128 v[208:211], v151 offset:37888
	ds_read_b128 v[212:215], v151 offset:38912
	ds_read_b128 v[216:219], v151 offset:39936
	global_load_lds_dwordx4 v[226:227], off
	v_lshl_add_u64 v[226:227], s[52:53], 0, v[132:133]
	s_mov_b32 m0, s66
	s_nop 0
	global_load_lds_dwordx4 v[226:227], off
	s_waitcnt vmcnt(8)
	s_waitcnt lgkmcnt(0)
	s_barrier
	s_setprio 1
	s_waitcnt lgkmcnt(0)
	v_mfma_f32_16x16x32_bf16 v[124:127], v[152:155], v[188:191], v[124:127]
	v_mfma_f32_16x16x32_bf16 v[120:123], v[160:163], v[188:191], v[120:123]
	v_mfma_f32_16x16x32_bf16 v[116:119], v[152:155], v[196:199], v[116:119]
	v_mfma_f32_16x16x32_bf16 v[108:111], v[160:163], v[196:199], v[108:111]
	v_mfma_f32_16x16x32_bf16 v[100:103], v[152:155], v[204:207], v[100:103]
	v_mfma_f32_16x16x32_bf16 v[92:95], v[160:163], v[204:207], v[92:95]
	v_mfma_f32_16x16x32_bf16 v[84:87], v[152:155], v[212:215], v[84:87]
	v_mfma_f32_16x16x32_bf16 v[76:79], v[160:163], v[212:215], v[76:79]
	v_mfma_f32_16x16x32_bf16 v[124:127], v[156:159], v[192:195], v[124:127]
	v_mfma_f32_16x16x32_bf16 v[120:123], v[164:167], v[192:195], v[120:123]
	v_mfma_f32_16x16x32_bf16 v[116:119], v[156:159], v[200:203], v[116:119]
	v_mfma_f32_16x16x32_bf16 v[108:111], v[164:167], v[200:203], v[108:111]
	v_mfma_f32_16x16x32_bf16 v[100:103], v[156:159], v[208:211], v[100:103]
	v_mfma_f32_16x16x32_bf16 v[92:95], v[164:167], v[208:211], v[92:95]
	v_mfma_f32_16x16x32_bf16 v[84:87], v[156:159], v[216:219], v[84:87]
	v_mfma_f32_16x16x32_bf16 v[76:79], v[164:167], v[216:219], v[76:79]
	s_setprio 0
	s_setprio 1
	v_mfma_f32_16x16x32_bf16 v[112:115], v[168:171], v[188:191], v[112:115]
	v_mfma_f32_16x16x32_bf16 v[104:107], v[176:179], v[188:191], v[104:107]
	v_mfma_f32_16x16x32_bf16 v[96:99], v[168:171], v[196:199], v[96:99]
	v_mfma_f32_16x16x32_bf16 v[88:91], v[176:179], v[196:199], v[88:91]
	v_mfma_f32_16x16x32_bf16 v[80:83], v[168:171], v[204:207], v[80:83]
	v_mfma_f32_16x16x32_bf16 v[72:75], v[176:179], v[204:207], v[72:75]
	v_mfma_f32_16x16x32_bf16 v[68:71], v[168:171], v[212:215], v[68:71]
	v_mfma_f32_16x16x32_bf16 v[64:67], v[176:179], v[212:215], v[64:67]
	v_mfma_f32_16x16x32_bf16 v[112:115], v[172:175], v[192:195], v[112:115]
	v_mfma_f32_16x16x32_bf16 v[104:107], v[184:187], v[192:195], v[104:107]
	v_mfma_f32_16x16x32_bf16 v[96:99], v[172:175], v[200:203], v[96:99]
	v_mfma_f32_16x16x32_bf16 v[88:91], v[184:187], v[200:203], v[88:91]
	v_mfma_f32_16x16x32_bf16 v[80:83], v[172:175], v[208:211], v[80:83]
	v_mfma_f32_16x16x32_bf16 v[72:75], v[184:187], v[208:211], v[72:75]
	v_mfma_f32_16x16x32_bf16 v[68:71], v[172:175], v[216:219], v[68:71]
	v_mfma_f32_16x16x32_bf16 v[64:67], v[184:187], v[216:219], v[64:67]
	s_setprio 0
	s_barrier
	s_add_i32 s18, s18, s62
	v_lshl_add_u64 v[144:145], v[144:145], 0, s[8:9]
	s_mov_b32 m0, s18
	ds_read_b128 v[188:191], v151 offset:49152
	ds_read_b128 v[192:195], v151 offset:50176
	ds_read_b128 v[196:199], v151 offset:51200
	ds_read_b128 v[200:203], v151 offset:52224
	ds_read_b128 v[204:207], v151 offset:53248
	ds_read_b128 v[208:211], v151 offset:54272
	ds_read_b128 v[212:215], v151 offset:55296
	ds_read_b128 v[216:219], v151 offset:56320
	global_load_lds_dwordx4 v[144:145], off
	s_add_i32 m0, s18, 0x2000
	s_add_u32 s52, s56, 0xb0080
	v_lshl_add_u64 v[144:145], v[220:221], 0, s[8:9]
	s_addc_u32 s53, s57, 0
	s_add_i32 s18, s19, s62
	global_load_lds_dwordx4 v[144:145], off
	v_lshl_add_u64 v[144:145], s[52:53], 0, v[130:131]
	s_mov_b32 m0, s18
	s_nop 0
	global_load_lds_dwordx4 v[144:145], off
	v_lshl_add_u64 v[144:145], s[52:53], 0, v[134:135]
	s_add_i32 m0, s18, 0x2000
	s_nop 0
	global_load_lds_dwordx4 v[144:145], off
	v_lshl_add_u64 v[144:145], v[222:223], 0, s[8:9]
	s_mov_b32 m0, s68
	s_nop 0
	global_load_lds_dwordx4 v[144:145], off
	v_lshl_add_u64 v[144:145], v[224:225], 0, s[8:9]
	s_mov_b32 m0, s69
	s_nop 0
	global_load_lds_dwordx4 v[144:145], off
	s_waitcnt vmcnt(8)
	s_waitcnt lgkmcnt(0)
	s_barrier
	s_setprio 1
	s_waitcnt lgkmcnt(0)
	v_mfma_f32_16x16x32_bf16 v[60:63], v[152:155], v[188:191], v[60:63]
	v_mfma_f32_16x16x32_bf16 v[56:59], v[160:163], v[188:191], v[56:59]
	v_mfma_f32_16x16x32_bf16 v[52:55], v[152:155], v[196:199], v[52:55]
	v_mfma_f32_16x16x32_bf16 v[44:47], v[160:163], v[196:199], v[44:47]
	v_mfma_f32_16x16x32_bf16 v[36:39], v[152:155], v[204:207], v[36:39]
	v_mfma_f32_16x16x32_bf16 v[28:31], v[160:163], v[204:207], v[28:31]
	v_mfma_f32_16x16x32_bf16 v[20:23], v[152:155], v[212:215], v[20:23]
	v_mfma_f32_16x16x32_bf16 v[12:15], v[160:163], v[212:215], v[12:15]
	v_mfma_f32_16x16x32_bf16 v[60:63], v[156:159], v[192:195], v[60:63]
	v_mfma_f32_16x16x32_bf16 v[56:59], v[164:167], v[192:195], v[56:59]
	v_mfma_f32_16x16x32_bf16 v[52:55], v[156:159], v[200:203], v[52:55]
	v_mfma_f32_16x16x32_bf16 v[44:47], v[164:167], v[200:203], v[44:47]
	v_mfma_f32_16x16x32_bf16 v[36:39], v[156:159], v[208:211], v[36:39]
	v_mfma_f32_16x16x32_bf16 v[28:31], v[164:167], v[208:211], v[28:31]
	v_mfma_f32_16x16x32_bf16 v[20:23], v[156:159], v[216:219], v[20:23]
	v_mfma_f32_16x16x32_bf16 v[12:15], v[164:167], v[216:219], v[12:15]
	s_setprio 0
	s_setprio 1
	v_mfma_f32_16x16x32_bf16 v[48:51], v[168:171], v[188:191], v[48:51]
	v_mfma_f32_16x16x32_bf16 v[40:43], v[176:179], v[188:191], v[40:43]
	v_mfma_f32_16x16x32_bf16 v[32:35], v[168:171], v[196:199], v[32:35]
	v_mfma_f32_16x16x32_bf16 v[24:27], v[176:179], v[196:199], v[24:27]
	v_mfma_f32_16x16x32_bf16 v[16:19], v[168:171], v[204:207], v[16:19]
	v_mfma_f32_16x16x32_bf16 v[8:11], v[176:179], v[204:207], v[8:11]
	v_mfma_f32_16x16x32_bf16 v[4:7], v[168:171], v[212:215], v[4:7]
	v_mfma_f32_16x16x32_bf16 v[0:3], v[176:179], v[212:215], v[0:3]
	v_mfma_f32_16x16x32_bf16 v[48:51], v[172:175], v[192:195], v[48:51]
	v_mfma_f32_16x16x32_bf16 v[40:43], v[184:187], v[192:195], v[40:43]
	v_mfma_f32_16x16x32_bf16 v[32:35], v[172:175], v[200:203], v[32:35]
	v_mfma_f32_16x16x32_bf16 v[24:27], v[184:187], v[200:203], v[24:27]
	v_mfma_f32_16x16x32_bf16 v[16:19], v[172:175], v[208:211], v[16:19]
	v_mfma_f32_16x16x32_bf16 v[8:11], v[184:187], v[208:211], v[8:11]
	v_mfma_f32_16x16x32_bf16 v[4:7], v[172:175], v[216:219], v[4:7]
	v_mfma_f32_16x16x32_bf16 v[0:3], v[184:187], v[216:219], v[0:3]
	s_setprio 0
	s_barrier
	s_add_i32 s86, s86, 2
	s_add_u32 s84, s84, 0x100
	s_addc_u32 s85, s85, 0
	s_cmp_gt_u32 s86, 41
	s_mov_b64 s[52:53], s[54:55]
	s_cbranch_scc0 .LBB0_264
	s_and_b64 vcc, exec, s[10:11]
	s_cbranch_vccz .LBB0_267
	s_barrier

.LBB0_386:
	s_ashr_i32 s49, s48, 31
	s_lshl_b64 s[52:53], s[48:49], 19
	s_add_u32 s52, s80, s52
	s_addc_u32 s53, s81, s53
	s_and_b64 s[54:55], s[4:5], exec
	s_cselect_b32 s49, s53, s59
	s_cselect_b32 s82, s52, s58
	s_ashr_i32 s47, s46, 31
	s_lshl_b64 s[54:55], s[46:47], 19
	s_add_u32 s54, s64, s54
	s_addc_u32 s55, s65, s55
	s_and_b64 s[62:63], s[4:5], exec
	s_cselect_b32 s47, s55, s61
	s_cselect_b32 s83, s54, s60
	s_add_u32 s58, s58, 0x40080
	s_addc_u32 s59, s59, 0
	s_add_u32 s84, s60, 0x100
	s_addc_u32 s85, s61, 0
	s_mov_b32 s86, -2
	ds_read_b128 v[152:155], v148
	ds_read_b128 v[156:159], v148 offset:1024
	ds_read_b128 v[160:163], v148 offset:2048
	ds_read_b128 v[164:167], v148 offset:3072
	ds_read_b128 v[168:171], v149
	ds_read_b128 v[172:175], v149 offset:1024
	ds_read_b128 v[176:179], v149 offset:2048
	ds_read_b128 v[184:187], v149 offset:3072
	s_add_u32 s18, s58, 0xfffc0080
	s_addc_u32 s19, s59, -1
	s_cmp_eq_u32 s86, 12
	s_cselect_b32 s63, s49, s19
	s_cselect_b32 s62, s82, s18
	s_cselect_b32 s61, s47, s85
	s_cselect_b32 s60, s83, s84
	v_lshl_add_u64 v[220:221], s[58:59], 0, v[138:139]
	s_add_i32 m0, s68, 0xc000
	ds_read_b128 v[188:191], v150
	ds_read_b128 v[192:195], v150 offset:1024
	ds_read_b128 v[196:199], v150 offset:2048
	ds_read_b128 v[200:203], v150 offset:3072
	ds_read_b128 v[204:207], v150 offset:4096
	ds_read_b128 v[208:211], v150 offset:5120
	ds_read_b128 v[212:215], v150 offset:6144
	ds_read_b128 v[216:219], v150 offset:7168
	global_load_lds_dwordx4 v[220:221], off
	v_lshl_add_u64 v[220:221], s[58:59], 0, v[140:141]
	s_add_i32 m0, s68, 0xe000
	s_nop 0
	global_load_lds_dwordx4 v[220:221], off
	s_waitcnt vmcnt(8)
	s_waitcnt lgkmcnt(0)
	s_barrier
	s_setprio 1
	s_waitcnt lgkmcnt(0)
	v_mfma_f32_16x16x32_bf16 v[124:127], v[152:155], v[188:191], 0
	v_mfma_f32_16x16x32_bf16 v[120:123], v[160:163], v[188:191], 0
	v_mfma_f32_16x16x32_bf16 v[116:119], v[152:155], v[196:199], 0
	v_mfma_f32_16x16x32_bf16 v[112:115], v[160:163], v[196:199], 0
	v_mfma_f32_16x16x32_bf16 v[108:111], v[152:155], v[204:207], 0
	v_mfma_f32_16x16x32_bf16 v[104:107], v[160:163], v[204:207], 0
	v_mfma_f32_16x16x32_bf16 v[100:103], v[152:155], v[212:215], 0
	v_mfma_f32_16x16x32_bf16 v[96:99], v[160:163], v[212:215], 0
	v_mfma_f32_16x16x32_bf16 v[124:127], v[156:159], v[192:195], v[124:127]
	v_mfma_f32_16x16x32_bf16 v[120:123], v[164:167], v[192:195], v[120:123]
	v_mfma_f32_16x16x32_bf16 v[116:119], v[156:159], v[200:203], v[116:119]
	v_mfma_f32_16x16x32_bf16 v[112:115], v[164:167], v[200:203], v[112:115]
	v_mfma_f32_16x16x32_bf16 v[108:111], v[156:159], v[208:211], v[108:111]
	v_mfma_f32_16x16x32_bf16 v[104:107], v[164:167], v[208:211], v[104:107]
	v_mfma_f32_16x16x32_bf16 v[100:103], v[156:159], v[216:219], v[100:103]
	v_mfma_f32_16x16x32_bf16 v[96:99], v[164:167], v[216:219], v[96:99]
	s_setprio 0
	s_setprio 1
	v_mfma_f32_16x16x32_bf16 v[68:71], v[168:171], v[188:191], 0
	v_mfma_f32_16x16x32_bf16 v[64:67], v[176:179], v[188:191], 0
	v_mfma_f32_16x16x32_bf16 v[52:55], v[168:171], v[196:199], 0
	v_mfma_f32_16x16x32_bf16 v[48:51], v[176:179], v[196:199], 0
	v_mfma_f32_16x16x32_bf16 v[44:47], v[168:171], v[204:207], 0
	v_mfma_f32_16x16x32_bf16 v[40:43], v[176:179], v[204:207], 0
	v_mfma_f32_16x16x32_bf16 v[36:39], v[168:171], v[212:215], 0
	v_mfma_f32_16x16x32_bf16 v[32:35], v[176:179], v[212:215], 0
	v_mfma_f32_16x16x32_bf16 v[68:71], v[172:175], v[192:195], v[68:71]
	v_mfma_f32_16x16x32_bf16 v[64:67], v[184:187], v[192:195], v[64:67]
	v_mfma_f32_16x16x32_bf16 v[52:55], v[172:175], v[200:203], v[52:55]
	v_mfma_f32_16x16x32_bf16 v[48:51], v[184:187], v[200:203], v[48:51]
	v_mfma_f32_16x16x32_bf16 v[44:47], v[172:175], v[208:211], v[44:47]
	v_mfma_f32_16x16x32_bf16 v[40:43], v[184:187], v[208:211], v[40:43]
	v_mfma_f32_16x16x32_bf16 v[36:39], v[172:175], v[216:219], v[36:39]
	v_mfma_f32_16x16x32_bf16 v[32:35], v[184:187], v[216:219], v[32:35]
	s_setprio 0
	s_barrier
	s_add_i32 s18, s76, s66
	v_lshl_add_u64 v[220:221], s[60:61], 0, v[132:133]
	s_mov_b32 m0, s18
	ds_read_b128 v[188:191], v150 offset:16384
	ds_read_b128 v[192:195], v150 offset:17408
	ds_read_b128 v[196:199], v150 offset:18432
	ds_read_b128 v[200:203], v150 offset:19456
	ds_read_b128 v[204:207], v150 offset:20480
	ds_read_b128 v[208:211], v150 offset:21504
	ds_read_b128 v[212:215], v150 offset:22528
	ds_read_b128 v[216:219], v150 offset:23552
	global_load_lds_dwordx4 v[220:221], off
	s_add_i32 m0, s18, 0x2000
	s_add_u32 s88, s60, 0x40000
	v_lshl_add_u64 v[222:223], s[60:61], 0, v[128:129]
	s_addc_u32 s89, s61, 0
	s_add_i32 s18, s77, s66
	global_load_lds_dwordx4 v[222:223], off
	v_lshl_add_u64 v[224:225], s[88:89], 0, v[132:133]
	s_mov_b32 m0, s18
	v_lshl_add_u64 v[226:227], s[62:63], 0, v[130:131]
	global_load_lds_dwordx4 v[224:225], off
	v_lshl_add_u64 v[224:225], s[88:89], 0, v[128:129]
	s_add_i32 m0, s18, 0x2000
	s_nop 0
	global_load_lds_dwordx4 v[224:225], off
	v_lshl_add_u64 v[224:225], s[62:63], 0, v[134:135]
	s_mov_b32 m0, s68
	s_nop 0
	global_load_lds_dwordx4 v[224:225], off
	s_mov_b32 m0, s69
	s_nop 0
	global_load_lds_dwordx4 v[226:227], off
	s_waitcnt vmcnt(8)
	s_waitcnt lgkmcnt(0)
	s_barrier
	s_setprio 1
	s_waitcnt lgkmcnt(0)
	v_mfma_f32_16x16x32_bf16 v[92:95], v[152:155], v[188:191], 0
	v_mfma_f32_16x16x32_bf16 v[88:91], v[160:163], v[188:191], 0
	v_mfma_f32_16x16x32_bf16 v[84:87], v[152:155], v[196:199], 0
	v_mfma_f32_16x16x32_bf16 v[80:83], v[160:163], v[196:199], 0
	v_mfma_f32_16x16x32_bf16 v[76:79], v[152:155], v[204:207], 0
	v_mfma_f32_16x16x32_bf16 v[72:75], v[160:163], v[204:207], 0
	v_mfma_f32_16x16x32_bf16 v[60:63], v[152:155], v[212:215], 0
	v_mfma_f32_16x16x32_bf16 v[56:59], v[160:163], v[212:215], 0
	v_mfma_f32_16x16x32_bf16 v[92:95], v[156:159], v[192:195], v[92:95]
	v_mfma_f32_16x16x32_bf16 v[88:91], v[164:167], v[192:195], v[88:91]
	v_mfma_f32_16x16x32_bf16 v[84:87], v[156:159], v[200:203], v[84:87]
	v_mfma_f32_16x16x32_bf16 v[80:83], v[164:167], v[200:203], v[80:83]
	v_mfma_f32_16x16x32_bf16 v[76:79], v[156:159], v[208:211], v[76:79]
	v_mfma_f32_16x16x32_bf16 v[72:75], v[164:167], v[208:211], v[72:75]
	v_mfma_f32_16x16x32_bf16 v[60:63], v[156:159], v[216:219], v[60:63]
	v_mfma_f32_16x16x32_bf16 v[56:59], v[164:167], v[216:219], v[56:59]
	s_setprio 0
	s_setprio 1
	v_mfma_f32_16x16x32_bf16 v[28:31], v[168:171], v[188:191], 0
	v_mfma_f32_16x16x32_bf16 v[24:27], v[176:179], v[188:191], 0
	v_mfma_f32_16x16x32_bf16 v[20:23], v[168:171], v[196:199], 0
	v_mfma_f32_16x16x32_bf16 v[16:19], v[176:179], v[196:199], 0
	v_mfma_f32_16x16x32_bf16 v[12:15], v[168:171], v[204:207], 0
	v_mfma_f32_16x16x32_bf16 v[8:11], v[176:179], v[204:207], 0
	v_mfma_f32_16x16x32_bf16 v[4:7], v[168:171], v[212:215], 0
	v_mfma_f32_16x16x32_bf16 v[0:3], v[176:179], v[212:215], 0
	v_mfma_f32_16x16x32_bf16 v[28:31], v[172:175], v[192:195], v[28:31]
	v_mfma_f32_16x16x32_bf16 v[24:27], v[184:187], v[192:195], v[24:27]
	v_mfma_f32_16x16x32_bf16 v[20:23], v[172:175], v[200:203], v[20:23]
	v_mfma_f32_16x16x32_bf16 v[16:19], v[184:187], v[200:203], v[16:19]
	v_mfma_f32_16x16x32_bf16 v[12:15], v[172:175], v[208:211], v[12:15]
	v_mfma_f32_16x16x32_bf16 v[8:11], v[184:187], v[208:211], v[8:11]
	v_mfma_f32_16x16x32_bf16 v[4:7], v[172:175], v[216:219], v[4:7]
	v_mfma_f32_16x16x32_bf16 v[0:3], v[184:187], v[216:219], v[0:3]
	s_setprio 0
	s_barrier
	s_branch .Lmid_gemm2
.LBB0_387:
	ds_read_b128 v[152:155], v148
	ds_read_b128 v[156:159], v148 offset:1024
	ds_read_b128 v[160:163], v148 offset:2048
	ds_read_b128 v[164:167], v148 offset:3072
	ds_read_b128 v[168:171], v149
	ds_read_b128 v[172:175], v149 offset:1024
	ds_read_b128 v[176:179], v149 offset:2048
	ds_read_b128 v[184:187], v149 offset:3072
	s_add_u32 s18, s58, 0xfffc0080
	s_addc_u32 s19, s59, -1
	s_cmp_eq_u32 s86, 12
	s_cselect_b32 s63, s49, s19
	s_cselect_b32 s62, s82, s18
	s_cselect_b32 s61, s47, s85
	s_cselect_b32 s60, s83, s84
	v_lshl_add_u64 v[220:221], s[58:59], 0, v[138:139]
	s_add_i32 m0, s68, 0xc000
	ds_read_b128 v[188:191], v150
	ds_read_b128 v[192:195], v150 offset:1024
	ds_read_b128 v[196:199], v150 offset:2048
	ds_read_b128 v[200:203], v150 offset:3072
	ds_read_b128 v[204:207], v150 offset:4096
	ds_read_b128 v[208:211], v150 offset:5120
	ds_read_b128 v[212:215], v150 offset:6144
	ds_read_b128 v[216:219], v150 offset:7168
	global_load_lds_dwordx4 v[220:221], off
	v_lshl_add_u64 v[220:221], s[58:59], 0, v[140:141]
	s_add_i32 m0, s68, 0xe000
	s_nop 0
	global_load_lds_dwordx4 v[220:221], off
	s_waitcnt vmcnt(8)
	s_waitcnt lgkmcnt(0)
	s_barrier
	s_setprio 1
	s_waitcnt lgkmcnt(0)
	v_mfma_f32_16x16x32_bf16 v[124:127], v[152:155], v[188:191], v[124:127]
	v_mfma_f32_16x16x32_bf16 v[120:123], v[160:163], v[188:191], v[120:123]
	v_mfma_f32_16x16x32_bf16 v[116:119], v[152:155], v[196:199], v[116:119]
	v_mfma_f32_16x16x32_bf16 v[112:115], v[160:163], v[196:199], v[112:115]
	v_mfma_f32_16x16x32_bf16 v[108:111], v[152:155], v[204:207], v[108:111]
	v_mfma_f32_16x16x32_bf16 v[104:107], v[160:163], v[204:207], v[104:107]
	v_mfma_f32_16x16x32_bf16 v[100:103], v[152:155], v[212:215], v[100:103]
	v_mfma_f32_16x16x32_bf16 v[96:99], v[160:163], v[212:215], v[96:99]
	v_mfma_f32_16x16x32_bf16 v[124:127], v[156:159], v[192:195], v[124:127]
	v_mfma_f32_16x16x32_bf16 v[120:123], v[164:167], v[192:195], v[120:123]
	v_mfma_f32_16x16x32_bf16 v[116:119], v[156:159], v[200:203], v[116:119]
	v_mfma_f32_16x16x32_bf16 v[112:115], v[164:167], v[200:203], v[112:115]
	v_mfma_f32_16x16x32_bf16 v[108:111], v[156:159], v[208:211], v[108:111]
	v_mfma_f32_16x16x32_bf16 v[104:107], v[164:167], v[208:211], v[104:107]
	v_mfma_f32_16x16x32_bf16 v[100:103], v[156:159], v[216:219], v[100:103]
	v_mfma_f32_16x16x32_bf16 v[96:99], v[164:167], v[216:219], v[96:99]
	s_setprio 0
	s_setprio 1
	v_mfma_f32_16x16x32_bf16 v[68:71], v[168:171], v[188:191], v[68:71]
	v_mfma_f32_16x16x32_bf16 v[64:67], v[176:179], v[188:191], v[64:67]
	v_mfma_f32_16x16x32_bf16 v[52:55], v[168:171], v[196:199], v[52:55]
	v_mfma_f32_16x16x32_bf16 v[48:51], v[176:179], v[196:199], v[48:51]
	v_mfma_f32_16x16x32_bf16 v[44:47], v[168:171], v[204:207], v[44:47]
	v_mfma_f32_16x16x32_bf16 v[40:43], v[176:179], v[204:207], v[40:43]
	v_mfma_f32_16x16x32_bf16 v[36:39], v[168:171], v[212:215], v[36:39]
	v_mfma_f32_16x16x32_bf16 v[32:35], v[176:179], v[212:215], v[32:35]
	v_mfma_f32_16x16x32_bf16 v[68:71], v[172:175], v[192:195], v[68:71]
	v_mfma_f32_16x16x32_bf16 v[64:67], v[184:187], v[192:195], v[64:67]
	v_mfma_f32_16x16x32_bf16 v[52:55], v[172:175], v[200:203], v[52:55]
	v_mfma_f32_16x16x32_bf16 v[48:51], v[184:187], v[200:203], v[48:51]
	v_mfma_f32_16x16x32_bf16 v[44:47], v[172:175], v[208:211], v[44:47]
	v_mfma_f32_16x16x32_bf16 v[40:43], v[184:187], v[208:211], v[40:43]
	v_mfma_f32_16x16x32_bf16 v[36:39], v[172:175], v[216:219], v[36:39]
	v_mfma_f32_16x16x32_bf16 v[32:35], v[184:187], v[216:219], v[32:35]
	s_setprio 0
	s_barrier
	s_add_i32 s18, s76, s66
	v_lshl_add_u64 v[220:221], s[60:61], 0, v[132:133]
	s_mov_b32 m0, s18
	ds_read_b128 v[188:191], v150 offset:16384
	ds_read_b128 v[192:195], v150 offset:17408
	ds_read_b128 v[196:199], v150 offset:18432
	ds_read_b128 v[200:203], v150 offset:19456
	ds_read_b128 v[204:207], v150 offset:20480
	ds_read_b128 v[208:211], v150 offset:21504
	ds_read_b128 v[212:215], v150 offset:22528
	ds_read_b128 v[216:219], v150 offset:23552
	global_load_lds_dwordx4 v[220:221], off
	s_add_i32 m0, s18, 0x2000
	s_add_u32 s88, s60, 0x40000
	v_lshl_add_u64 v[222:223], s[60:61], 0, v[128:129]
	s_addc_u32 s89, s61, 0
	s_add_i32 s18, s77, s66
	global_load_lds_dwordx4 v[222:223], off
	v_lshl_add_u64 v[224:225], s[88:89], 0, v[132:133]
	s_mov_b32 m0, s18
	v_lshl_add_u64 v[226:227], s[62:63], 0, v[130:131]
	global_load_lds_dwordx4 v[224:225], off
	v_lshl_add_u64 v[224:225], s[88:89], 0, v[128:129]
	s_add_i32 m0, s18, 0x2000
	s_nop 0
	global_load_lds_dwordx4 v[224:225], off
	v_lshl_add_u64 v[224:225], s[62:63], 0, v[134:135]
	s_mov_b32 m0, s68
	s_nop 0
	global_load_lds_dwordx4 v[224:225], off
	s_mov_b32 m0, s69
	s_nop 0
	global_load_lds_dwordx4 v[226:227], off
	s_waitcnt vmcnt(8)
	s_waitcnt lgkmcnt(0)
	s_barrier
	s_setprio 1
	s_waitcnt lgkmcnt(0)
	v_mfma_f32_16x16x32_bf16 v[92:95], v[152:155], v[188:191], v[92:95]
	v_mfma_f32_16x16x32_bf16 v[88:91], v[160:163], v[188:191], v[88:91]
	v_mfma_f32_16x16x32_bf16 v[84:87], v[152:155], v[196:199], v[84:87]
	v_mfma_f32_16x16x32_bf16 v[80:83], v[160:163], v[196:199], v[80:83]
	v_mfma_f32_16x16x32_bf16 v[76:79], v[152:155], v[204:207], v[76:79]
	v_mfma_f32_16x16x32_bf16 v[72:75], v[160:163], v[204:207], v[72:75]
	v_mfma_f32_16x16x32_bf16 v[60:63], v[152:155], v[212:215], v[60:63]
	v_mfma_f32_16x16x32_bf16 v[56:59], v[160:163], v[212:215], v[56:59]
	v_mfma_f32_16x16x32_bf16 v[92:95], v[156:159], v[192:195], v[92:95]
	v_mfma_f32_16x16x32_bf16 v[88:91], v[164:167], v[192:195], v[88:91]
	v_mfma_f32_16x16x32_bf16 v[84:87], v[156:159], v[200:203], v[84:87]
	v_mfma_f32_16x16x32_bf16 v[80:83], v[164:167], v[200:203], v[80:83]
	v_mfma_f32_16x16x32_bf16 v[76:79], v[156:159], v[208:211], v[76:79]
	v_mfma_f32_16x16x32_bf16 v[72:75], v[164:167], v[208:211], v[72:75]
	v_mfma_f32_16x16x32_bf16 v[60:63], v[156:159], v[216:219], v[60:63]
	v_mfma_f32_16x16x32_bf16 v[56:59], v[164:167], v[216:219], v[56:59]
	s_setprio 0
	s_setprio 1
	v_mfma_f32_16x16x32_bf16 v[28:31], v[168:171], v[188:191], v[28:31]
	v_mfma_f32_16x16x32_bf16 v[24:27], v[176:179], v[188:191], v[24:27]
	v_mfma_f32_16x16x32_bf16 v[20:23], v[168:171], v[196:199], v[20:23]
	v_mfma_f32_16x16x32_bf16 v[16:19], v[176:179], v[196:199], v[16:19]
	v_mfma_f32_16x16x32_bf16 v[12:15], v[168:171], v[204:207], v[12:15]
	v_mfma_f32_16x16x32_bf16 v[8:11], v[176:179], v[204:207], v[8:11]
	v_mfma_f32_16x16x32_bf16 v[4:7], v[168:171], v[212:215], v[4:7]
	v_mfma_f32_16x16x32_bf16 v[0:3], v[176:179], v[212:215], v[0:3]
	v_mfma_f32_16x16x32_bf16 v[28:31], v[172:175], v[192:195], v[28:31]
	v_mfma_f32_16x16x32_bf16 v[24:27], v[184:187], v[192:195], v[24:27]
	v_mfma_f32_16x16x32_bf16 v[20:23], v[172:175], v[200:203], v[20:23]
	v_mfma_f32_16x16x32_bf16 v[16:19], v[184:187], v[200:203], v[16:19]
	v_mfma_f32_16x16x32_bf16 v[12:15], v[172:175], v[208:211], v[12:15]
	v_mfma_f32_16x16x32_bf16 v[8:11], v[184:187], v[208:211], v[8:11]
	v_mfma_f32_16x16x32_bf16 v[4:7], v[172:175], v[216:219], v[4:7]
	v_mfma_f32_16x16x32_bf16 v[0:3], v[184:187], v[216:219], v[0:3]
	s_setprio 0
	s_barrier
.Lmid_gemm2:
	s_add_i32 s18, 0, 0x18000
	s_add_i32 s19, 0, 0x1c000
	v_add_u32_e32 v164, s18, v147
	v_add_u32_e32 v181, s19, v147
	ds_read_b128 v[152:155], v164
	ds_read_b128 v[156:159], v164 offset:1024
	ds_read_b128 v[160:163], v164 offset:2048
	ds_read_b128 v[164:167], v164 offset:3072
	ds_read_b128 v[168:171], v181
	ds_read_b128 v[172:175], v181 offset:1024
	ds_read_b128 v[176:179], v181 offset:2048
	ds_read_b128 v[184:187], v181 offset:3072
	s_add_u32 s62, s62, 0x40000
	s_addc_u32 s63, s63, 0
	s_mov_b32 m0, s70
	v_lshl_add_u64 v[228:229], s[62:63], 0, v[134:135]
	ds_read_b128 v[188:191], v150 offset:32768
	ds_read_b128 v[192:195], v150 offset:33792
	ds_read_b128 v[196:199], v150 offset:34816
	ds_read_b128 v[200:203], v150 offset:35840
	ds_read_b128 v[204:207], v150 offset:36864
	ds_read_b128 v[208:211], v150 offset:37888
	ds_read_b128 v[212:215], v150 offset:38912
	ds_read_b128 v[216:219], v150 offset:39936
	global_load_lds_dwordx4 v[228:229], off
	v_lshl_add_u64 v[228:229], s[62:63], 0, v[130:131]
	s_mov_b32 m0, s71
	s_nop 0
	global_load_lds_dwordx4 v[228:229], off
	s_waitcnt vmcnt(8)
	s_waitcnt lgkmcnt(0)
	s_barrier
	s_setprio 1
	s_waitcnt lgkmcnt(0)
	v_mfma_f32_16x16x32_bf16 v[124:127], v[152:155], v[188:191], v[124:127]
	v_mfma_f32_16x16x32_bf16 v[120:123], v[160:163], v[188:191], v[120:123]
	v_mfma_f32_16x16x32_bf16 v[116:119], v[152:155], v[196:199], v[116:119]
	v_mfma_f32_16x16x32_bf16 v[112:115], v[160:163], v[196:199], v[112:115]
	v_mfma_f32_16x16x32_bf16 v[108:111], v[152:155], v[204:207], v[108:111]
	v_mfma_f32_16x16x32_bf16 v[104:107], v[160:163], v[204:207], v[104:107]
	v_mfma_f32_16x16x32_bf16 v[100:103], v[152:155], v[212:215], v[100:103]
	v_mfma_f32_16x16x32_bf16 v[96:99], v[160:163], v[212:215], v[96:99]
	v_mfma_f32_16x16x32_bf16 v[124:127], v[156:159], v[192:195], v[124:127]
	v_mfma_f32_16x16x32_bf16 v[120:123], v[164:167], v[192:195], v[120:123]
	v_mfma_f32_16x16x32_bf16 v[116:119], v[156:159], v[200:203], v[116:119]
	v_mfma_f32_16x16x32_bf16 v[112:115], v[164:167], v[200:203], v[112:115]
	v_mfma_f32_16x16x32_bf16 v[108:111], v[156:159], v[208:211], v[108:111]
	v_mfma_f32_16x16x32_bf16 v[104:107], v[164:167], v[208:211], v[104:107]
	v_mfma_f32_16x16x32_bf16 v[100:103], v[156:159], v[216:219], v[100:103]
	v_mfma_f32_16x16x32_bf16 v[96:99], v[164:167], v[216:219], v[96:99]
	s_setprio 0
	s_setprio 1
	v_mfma_f32_16x16x32_bf16 v[68:71], v[168:171], v[188:191], v[68:71]
	v_mfma_f32_16x16x32_bf16 v[64:67], v[176:179], v[188:191], v[64:67]
	v_mfma_f32_16x16x32_bf16 v[52:55], v[168:171], v[196:199], v[52:55]
	v_mfma_f32_16x16x32_bf16 v[48:51], v[176:179], v[196:199], v[48:51]
	v_mfma_f32_16x16x32_bf16 v[44:47], v[168:171], v[204:207], v[44:47]
	v_mfma_f32_16x16x32_bf16 v[40:43], v[176:179], v[204:207], v[40:43]
	v_mfma_f32_16x16x32_bf16 v[36:39], v[168:171], v[212:215], v[36:39]
	v_mfma_f32_16x16x32_bf16 v[32:35], v[176:179], v[212:215], v[32:35]
	v_mfma_f32_16x16x32_bf16 v[68:71], v[172:175], v[192:195], v[68:71]
	v_mfma_f32_16x16x32_bf16 v[64:67], v[184:187], v[192:195], v[64:67]
	v_mfma_f32_16x16x32_bf16 v[52:55], v[172:175], v[200:203], v[52:55]
	v_mfma_f32_16x16x32_bf16 v[48:51], v[184:187], v[200:203], v[48:51]
	v_mfma_f32_16x16x32_bf16 v[44:47], v[172:175], v[208:211], v[44:47]
	v_mfma_f32_16x16x32_bf16 v[40:43], v[184:187], v[208:211], v[40:43]
	v_mfma_f32_16x16x32_bf16 v[36:39], v[172:175], v[216:219], v[36:39]
	v_mfma_f32_16x16x32_bf16 v[32:35], v[184:187], v[216:219], v[32:35]
	s_setprio 0
	s_barrier
	s_add_i32 s18, s18, s66
	v_lshl_add_u64 v[220:221], v[220:221], 0, s[6:7]
	s_mov_b32 m0, s18
	ds_read_b128 v[188:191], v150 offset:49152
	ds_read_b128 v[192:195], v150 offset:50176
	ds_read_b128 v[196:199], v150 offset:51200
	ds_read_b128 v[200:203], v150 offset:52224
	ds_read_b128 v[204:207], v150 offset:53248
	ds_read_b128 v[208:211], v150 offset:54272
	ds_read_b128 v[212:215], v150 offset:55296
	ds_read_b128 v[216:219], v150 offset:56320
	global_load_lds_dwordx4 v[220:221], off
	s_add_i32 m0, s18, 0x2000
	s_add_u32 s60, s60, 0x40080
	v_lshl_add_u64 v[220:221], v[222:223], 0, s[6:7]
	s_addc_u32 s61, s61, 0
	s_add_i32 s18, s19, s66
	global_load_lds_dwordx4 v[220:221], off
	v_lshl_add_u64 v[220:221], s[60:61], 0, v[132:133]
	s_mov_b32 m0, s18
	s_nop 0
	global_load_lds_dwordx4 v[220:221], off
	v_lshl_add_u64 v[220:221], s[60:61], 0, v[128:129]
	s_add_i32 m0, s18, 0x2000
	s_nop 0
	global_load_lds_dwordx4 v[220:221], off
	v_lshl_add_u64 v[220:221], v[224:225], 0, s[6:7]
	s_mov_b32 m0, s74
	s_nop 0
	global_load_lds_dwordx4 v[220:221], off
	v_lshl_add_u64 v[220:221], v[226:227], 0, s[6:7]
	s_mov_b32 m0, s75
	s_nop 0
	global_load_lds_dwordx4 v[220:221], off
	s_waitcnt vmcnt(8)
	s_waitcnt lgkmcnt(0)
	s_barrier
	s_setprio 1
	s_waitcnt lgkmcnt(0)
	v_mfma_f32_16x16x32_bf16 v[92:95], v[152:155], v[188:191], v[92:95]
	v_mfma_f32_16x16x32_bf16 v[88:91], v[160:163], v[188:191], v[88:91]
	v_mfma_f32_16x16x32_bf16 v[84:87], v[152:155], v[196:199], v[84:87]
	v_mfma_f32_16x16x32_bf16 v[80:83], v[160:163], v[196:199], v[80:83]
	v_mfma_f32_16x16x32_bf16 v[76:79], v[152:155], v[204:207], v[76:79]
	v_mfma_f32_16x16x32_bf16 v[72:75], v[160:163], v[204:207], v[72:75]
	v_mfma_f32_16x16x32_bf16 v[60:63], v[152:155], v[212:215], v[60:63]
	v_mfma_f32_16x16x32_bf16 v[56:59], v[160:163], v[212:215], v[56:59]
	v_mfma_f32_16x16x32_bf16 v[92:95], v[156:159], v[192:195], v[92:95]
	v_mfma_f32_16x16x32_bf16 v[88:91], v[164:167], v[192:195], v[88:91]
	v_mfma_f32_16x16x32_bf16 v[84:87], v[156:159], v[200:203], v[84:87]
	v_mfma_f32_16x16x32_bf16 v[80:83], v[164:167], v[200:203], v[80:83]
	v_mfma_f32_16x16x32_bf16 v[76:79], v[156:159], v[208:211], v[76:79]
	v_mfma_f32_16x16x32_bf16 v[72:75], v[164:167], v[208:211], v[72:75]
	v_mfma_f32_16x16x32_bf16 v[60:63], v[156:159], v[216:219], v[60:63]
	v_mfma_f32_16x16x32_bf16 v[56:59], v[164:167], v[216:219], v[56:59]
	s_setprio 0
	s_setprio 1
	v_mfma_f32_16x16x32_bf16 v[28:31], v[168:171], v[188:191], v[28:31]
	v_mfma_f32_16x16x32_bf16 v[24:27], v[176:179], v[188:191], v[24:27]
	v_mfma_f32_16x16x32_bf16 v[20:23], v[168:171], v[196:199], v[20:23]
	v_mfma_f32_16x16x32_bf16 v[16:19], v[176:179], v[196:199], v[16:19]
	v_mfma_f32_16x16x32_bf16 v[12:15], v[168:171], v[204:207], v[12:15]
	v_mfma_f32_16x16x32_bf16 v[8:11], v[176:179], v[204:207], v[8:11]
	v_mfma_f32_16x16x32_bf16 v[4:7], v[168:171], v[212:215], v[4:7]
	v_mfma_f32_16x16x32_bf16 v[0:3], v[176:179], v[212:215], v[0:3]
	v_mfma_f32_16x16x32_bf16 v[28:31], v[172:175], v[192:195], v[28:31]
	v_mfma_f32_16x16x32_bf16 v[24:27], v[184:187], v[192:195], v[24:27]
	v_mfma_f32_16x16x32_bf16 v[20:23], v[172:175], v[200:203], v[20:23]
	v_mfma_f32_16x16x32_bf16 v[16:19], v[184:187], v[200:203], v[16:19]
	v_mfma_f32_16x16x32_bf16 v[12:15], v[172:175], v[208:211], v[12:15]
	v_mfma_f32_16x16x32_bf16 v[8:11], v[184:187], v[208:211], v[8:11]
	v_mfma_f32_16x16x32_bf16 v[4:7], v[172:175], v[216:219], v[4:7]
	v_mfma_f32_16x16x32_bf16 v[0:3], v[184:187], v[216:219], v[0:3]
	s_setprio 0
	s_barrier
	s_add_i32 s86, s86, 2
	s_add_u32 s58, s58, 0x100
	s_addc_u32 s59, s59, 0
	s_add_u32 s84, s84, 0x100
	s_addc_u32 s85, s85, 0
	s_cmp_gt_u32 s86, 13
	s_cbranch_scc0 .LBB0_387
	s_and_b64 vcc, exec, s[8:9]
	s_cbranch_vccz .LBB0_390
	s_barrier

.LBB0_600:
	s_ashr_i32 s49, s48, 31
	s_lshl_b64 s[18:19], s[48:49], 19
	s_add_u32 s52, s38, s18
	s_addc_u32 s53, s39, s19
	s_and_b64 s[18:19], s[4:5], exec
	s_cselect_b32 s49, s53, s59
	s_cselect_b32 s84, s52, s58
	s_ashr_i32 s47, s46, 31
	s_lshl_b64 s[18:19], s[46:47], 19
	s_add_u32 s54, s64, s18
	s_addc_u32 s55, s65, s19
	s_and_b64 s[18:19], s[4:5], exec
	s_cselect_b32 s47, s55, s61
	s_cselect_b32 s85, s54, s60
	s_add_u32 s58, s58, 0x40080
	s_addc_u32 s59, s59, 0
	s_add_u32 s86, s60, 0x100
	s_addc_u32 s87, s61, 0
	s_mov_b32 s88, -2
	ds_read_b128 v[152:155], v149
	ds_read_b128 v[156:159], v149 offset:1024
	ds_read_b128 v[160:163], v149 offset:2048
	ds_read_b128 v[164:167], v149 offset:3072
	ds_read_b128 v[168:171], v150
	ds_read_b128 v[172:175], v150 offset:1024
	ds_read_b128 v[176:179], v150 offset:2048
	ds_read_b128 v[184:187], v150 offset:3072
	s_add_u32 s18, s58, 0xfffc0080
	s_addc_u32 s19, s59, -1
	s_cmp_eq_u32 s88, 12
	s_cselect_b32 s63, s49, s19
	s_cselect_b32 s62, s84, s18
	s_cselect_b32 s61, s47, s87
	s_cselect_b32 s60, s85, s86
	v_lshl_add_u64 v[144:145], s[58:59], 0, v[136:137]
	s_add_i32 m0, s57, 0xc000
	ds_read_b128 v[188:191], v151
	ds_read_b128 v[192:195], v151 offset:1024
	ds_read_b128 v[196:199], v151 offset:2048
	ds_read_b128 v[200:203], v151 offset:3072
	ds_read_b128 v[204:207], v151 offset:4096
	ds_read_b128 v[208:211], v151 offset:5120
	ds_read_b128 v[212:215], v151 offset:6144
	ds_read_b128 v[216:219], v151 offset:7168
	global_load_lds_dwordx4 v[144:145], off
	v_lshl_add_u64 v[144:145], s[58:59], 0, v[138:139]
	s_add_i32 m0, s57, 0xe000
	s_nop 0
	global_load_lds_dwordx4 v[144:145], off
	s_waitcnt vmcnt(8)
	s_waitcnt lgkmcnt(0)
	s_barrier
	s_setprio 1
	s_waitcnt lgkmcnt(0)
	v_mfma_f32_16x16x32_bf16 v[124:127], v[152:155], v[188:191], 0
	v_mfma_f32_16x16x32_bf16 v[120:123], v[160:163], v[188:191], 0
	v_mfma_f32_16x16x32_bf16 v[116:119], v[152:155], v[196:199], 0
	v_mfma_f32_16x16x32_bf16 v[108:111], v[160:163], v[196:199], 0
	v_mfma_f32_16x16x32_bf16 v[100:103], v[152:155], v[204:207], 0
	v_mfma_f32_16x16x32_bf16 v[92:95], v[160:163], v[204:207], 0
	v_mfma_f32_16x16x32_bf16 v[84:87], v[152:155], v[212:215], 0
	v_mfma_f32_16x16x32_bf16 v[76:79], v[160:163], v[212:215], 0
	v_mfma_f32_16x16x32_bf16 v[124:127], v[156:159], v[192:195], v[124:127]
	v_mfma_f32_16x16x32_bf16 v[120:123], v[164:167], v[192:195], v[120:123]
	v_mfma_f32_16x16x32_bf16 v[116:119], v[156:159], v[200:203], v[116:119]
	v_mfma_f32_16x16x32_bf16 v[108:111], v[164:167], v[200:203], v[108:111]
	v_mfma_f32_16x16x32_bf16 v[100:103], v[156:159], v[208:211], v[100:103]
	v_mfma_f32_16x16x32_bf16 v[92:95], v[164:167], v[208:211], v[92:95]
	v_mfma_f32_16x16x32_bf16 v[84:87], v[156:159], v[216:219], v[84:87]
	v_mfma_f32_16x16x32_bf16 v[76:79], v[164:167], v[216:219], v[76:79]
	s_setprio 0
	s_setprio 1
	v_mfma_f32_16x16x32_bf16 v[112:115], v[168:171], v[188:191], 0
	v_mfma_f32_16x16x32_bf16 v[104:107], v[176:179], v[188:191], 0
	v_mfma_f32_16x16x32_bf16 v[96:99], v[168:171], v[196:199], 0
	v_mfma_f32_16x16x32_bf16 v[88:91], v[176:179], v[196:199], 0
	v_mfma_f32_16x16x32_bf16 v[80:83], v[168:171], v[204:207], 0
	v_mfma_f32_16x16x32_bf16 v[72:75], v[176:179], v[204:207], 0
	v_mfma_f32_16x16x32_bf16 v[68:71], v[168:171], v[212:215], 0
	v_mfma_f32_16x16x32_bf16 v[64:67], v[176:179], v[212:215], 0
	v_mfma_f32_16x16x32_bf16 v[112:115], v[172:175], v[192:195], v[112:115]
	v_mfma_f32_16x16x32_bf16 v[104:107], v[184:187], v[192:195], v[104:107]
	v_mfma_f32_16x16x32_bf16 v[96:99], v[172:175], v[200:203], v[96:99]
	v_mfma_f32_16x16x32_bf16 v[88:91], v[184:187], v[200:203], v[88:91]
	v_mfma_f32_16x16x32_bf16 v[80:83], v[172:175], v[208:211], v[80:83]
	v_mfma_f32_16x16x32_bf16 v[72:75], v[184:187], v[208:211], v[72:75]
	v_mfma_f32_16x16x32_bf16 v[68:71], v[172:175], v[216:219], v[68:71]
	v_mfma_f32_16x16x32_bf16 v[64:67], v[184:187], v[216:219], v[64:67]
	s_setprio 0
	s_barrier
	s_add_i32 s18, s73, s66
	v_lshl_add_u64 v[144:145], s[60:61], 0, v[130:131]
	s_mov_b32 m0, s18
	ds_read_b128 v[188:191], v151 offset:16384
	ds_read_b128 v[192:195], v151 offset:17408
	ds_read_b128 v[196:199], v151 offset:18432
	ds_read_b128 v[200:203], v151 offset:19456
	ds_read_b128 v[204:207], v151 offset:20480
	ds_read_b128 v[208:211], v151 offset:21504
	ds_read_b128 v[212:215], v151 offset:22528
	ds_read_b128 v[216:219], v151 offset:23552
	global_load_lds_dwordx4 v[144:145], off
	s_add_i32 m0, s18, 0x2000
	s_add_u32 s18, s60, 0x40000
	v_lshl_add_u64 v[220:221], s[60:61], 0, v[134:135]
	s_addc_u32 s19, s61, 0
	s_add_i32 s79, s74, s66
	global_load_lds_dwordx4 v[220:221], off
	v_lshl_add_u64 v[222:223], s[18:19], 0, v[130:131]
	s_mov_b32 m0, s79
	v_lshl_add_u64 v[224:225], s[62:63], 0, v[132:133]
	global_load_lds_dwordx4 v[222:223], off
	v_lshl_add_u64 v[222:223], s[18:19], 0, v[134:135]
	s_add_i32 m0, s79, 0x2000
	s_nop 0
	global_load_lds_dwordx4 v[222:223], off
	v_lshl_add_u64 v[222:223], s[62:63], 0, v[128:129]
	s_mov_b32 m0, s57
	s_nop 0
	global_load_lds_dwordx4 v[222:223], off
	s_mov_b32 m0, s67
	s_nop 0
	global_load_lds_dwordx4 v[224:225], off
	s_waitcnt vmcnt(8)
	s_waitcnt lgkmcnt(0)
	s_barrier
	s_setprio 1
	s_waitcnt lgkmcnt(0)
	v_mfma_f32_16x16x32_bf16 v[60:63], v[152:155], v[188:191], 0
	v_mfma_f32_16x16x32_bf16 v[56:59], v[160:163], v[188:191], 0
	v_mfma_f32_16x16x32_bf16 v[52:55], v[152:155], v[196:199], 0
	v_mfma_f32_16x16x32_bf16 v[44:47], v[160:163], v[196:199], 0
	v_mfma_f32_16x16x32_bf16 v[36:39], v[152:155], v[204:207], 0
	v_mfma_f32_16x16x32_bf16 v[28:31], v[160:163], v[204:207], 0
	v_mfma_f32_16x16x32_bf16 v[20:23], v[152:155], v[212:215], 0
	v_mfma_f32_16x16x32_bf16 v[12:15], v[160:163], v[212:215], 0
	v_mfma_f32_16x16x32_bf16 v[60:63], v[156:159], v[192:195], v[60:63]
	v_mfma_f32_16x16x32_bf16 v[56:59], v[164:167], v[192:195], v[56:59]
	v_mfma_f32_16x16x32_bf16 v[52:55], v[156:159], v[200:203], v[52:55]
	v_mfma_f32_16x16x32_bf16 v[44:47], v[164:167], v[200:203], v[44:47]
	v_mfma_f32_16x16x32_bf16 v[36:39], v[156:159], v[208:211], v[36:39]
	v_mfma_f32_16x16x32_bf16 v[28:31], v[164:167], v[208:211], v[28:31]
	v_mfma_f32_16x16x32_bf16 v[20:23], v[156:159], v[216:219], v[20:23]
	v_mfma_f32_16x16x32_bf16 v[12:15], v[164:167], v[216:219], v[12:15]
	s_setprio 0
	s_setprio 1
	v_mfma_f32_16x16x32_bf16 v[48:51], v[168:171], v[188:191], 0
	v_mfma_f32_16x16x32_bf16 v[40:43], v[176:179], v[188:191], 0
	v_mfma_f32_16x16x32_bf16 v[32:35], v[168:171], v[196:199], 0
	v_mfma_f32_16x16x32_bf16 v[24:27], v[176:179], v[196:199], 0
	v_mfma_f32_16x16x32_bf16 v[16:19], v[168:171], v[204:207], 0
	v_mfma_f32_16x16x32_bf16 v[8:11], v[176:179], v[204:207], 0
	v_mfma_f32_16x16x32_bf16 v[4:7], v[168:171], v[212:215], 0
	v_mfma_f32_16x16x32_bf16 v[0:3], v[176:179], v[212:215], 0
	v_mfma_f32_16x16x32_bf16 v[48:51], v[172:175], v[192:195], v[48:51]
	v_mfma_f32_16x16x32_bf16 v[40:43], v[184:187], v[192:195], v[40:43]
	v_mfma_f32_16x16x32_bf16 v[32:35], v[172:175], v[200:203], v[32:35]
	v_mfma_f32_16x16x32_bf16 v[24:27], v[184:187], v[200:203], v[24:27]
	v_mfma_f32_16x16x32_bf16 v[16:19], v[172:175], v[208:211], v[16:19]
	v_mfma_f32_16x16x32_bf16 v[8:11], v[184:187], v[208:211], v[8:11]
	v_mfma_f32_16x16x32_bf16 v[4:7], v[172:175], v[216:219], v[4:7]
	v_mfma_f32_16x16x32_bf16 v[0:3], v[184:187], v[216:219], v[0:3]
	s_setprio 0
	s_barrier
	s_branch .Lmid_gemm3
.LBB0_601:
	ds_read_b128 v[152:155], v149
	ds_read_b128 v[156:159], v149 offset:1024
	ds_read_b128 v[160:163], v149 offset:2048
	ds_read_b128 v[164:167], v149 offset:3072
	ds_read_b128 v[168:171], v150
	ds_read_b128 v[172:175], v150 offset:1024
	ds_read_b128 v[176:179], v150 offset:2048
	ds_read_b128 v[184:187], v150 offset:3072
	s_add_u32 s18, s58, 0xfffc0080
	s_addc_u32 s19, s59, -1
	s_cmp_eq_u32 s88, 12
	s_cselect_b32 s63, s49, s19
	s_cselect_b32 s62, s84, s18
	s_cselect_b32 s61, s47, s87
	s_cselect_b32 s60, s85, s86
	v_lshl_add_u64 v[144:145], s[58:59], 0, v[136:137]
	s_add_i32 m0, s57, 0xc000
	ds_read_b128 v[188:191], v151
	ds_read_b128 v[192:195], v151 offset:1024
	ds_read_b128 v[196:199], v151 offset:2048
	ds_read_b128 v[200:203], v151 offset:3072
	ds_read_b128 v[204:207], v151 offset:4096
	ds_read_b128 v[208:211], v151 offset:5120
	ds_read_b128 v[212:215], v151 offset:6144
	ds_read_b128 v[216:219], v151 offset:7168
	global_load_lds_dwordx4 v[144:145], off
	v_lshl_add_u64 v[144:145], s[58:59], 0, v[138:139]
	s_add_i32 m0, s57, 0xe000
	s_nop 0
	global_load_lds_dwordx4 v[144:145], off
	s_waitcnt vmcnt(8)
	s_waitcnt lgkmcnt(0)
	s_barrier
	s_setprio 1
	s_waitcnt lgkmcnt(0)
	v_mfma_f32_16x16x32_bf16 v[124:127], v[152:155], v[188:191], v[124:127]
	v_mfma_f32_16x16x32_bf16 v[120:123], v[160:163], v[188:191], v[120:123]
	v_mfma_f32_16x16x32_bf16 v[116:119], v[152:155], v[196:199], v[116:119]
	v_mfma_f32_16x16x32_bf16 v[108:111], v[160:163], v[196:199], v[108:111]
	v_mfma_f32_16x16x32_bf16 v[100:103], v[152:155], v[204:207], v[100:103]
	v_mfma_f32_16x16x32_bf16 v[92:95], v[160:163], v[204:207], v[92:95]
	v_mfma_f32_16x16x32_bf16 v[84:87], v[152:155], v[212:215], v[84:87]
	v_mfma_f32_16x16x32_bf16 v[76:79], v[160:163], v[212:215], v[76:79]
	v_mfma_f32_16x16x32_bf16 v[124:127], v[156:159], v[192:195], v[124:127]
	v_mfma_f32_16x16x32_bf16 v[120:123], v[164:167], v[192:195], v[120:123]
	v_mfma_f32_16x16x32_bf16 v[116:119], v[156:159], v[200:203], v[116:119]
	v_mfma_f32_16x16x32_bf16 v[108:111], v[164:167], v[200:203], v[108:111]
	v_mfma_f32_16x16x32_bf16 v[100:103], v[156:159], v[208:211], v[100:103]
	v_mfma_f32_16x16x32_bf16 v[92:95], v[164:167], v[208:211], v[92:95]
	v_mfma_f32_16x16x32_bf16 v[84:87], v[156:159], v[216:219], v[84:87]
	v_mfma_f32_16x16x32_bf16 v[76:79], v[164:167], v[216:219], v[76:79]
	s_setprio 0
	s_setprio 1
	v_mfma_f32_16x16x32_bf16 v[112:115], v[168:171], v[188:191], v[112:115]
	v_mfma_f32_16x16x32_bf16 v[104:107], v[176:179], v[188:191], v[104:107]
	v_mfma_f32_16x16x32_bf16 v[96:99], v[168:171], v[196:199], v[96:99]
	v_mfma_f32_16x16x32_bf16 v[88:91], v[176:179], v[196:199], v[88:91]
	v_mfma_f32_16x16x32_bf16 v[80:83], v[168:171], v[204:207], v[80:83]
	v_mfma_f32_16x16x32_bf16 v[72:75], v[176:179], v[204:207], v[72:75]
	v_mfma_f32_16x16x32_bf16 v[68:71], v[168:171], v[212:215], v[68:71]
	v_mfma_f32_16x16x32_bf16 v[64:67], v[176:179], v[212:215], v[64:67]
	v_mfma_f32_16x16x32_bf16 v[112:115], v[172:175], v[192:195], v[112:115]
	v_mfma_f32_16x16x32_bf16 v[104:107], v[184:187], v[192:195], v[104:107]
	v_mfma_f32_16x16x32_bf16 v[96:99], v[172:175], v[200:203], v[96:99]
	v_mfma_f32_16x16x32_bf16 v[88:91], v[184:187], v[200:203], v[88:91]
	v_mfma_f32_16x16x32_bf16 v[80:83], v[172:175], v[208:211], v[80:83]
	v_mfma_f32_16x16x32_bf16 v[72:75], v[184:187], v[208:211], v[72:75]
	v_mfma_f32_16x16x32_bf16 v[68:71], v[172:175], v[216:219], v[68:71]
	v_mfma_f32_16x16x32_bf16 v[64:67], v[184:187], v[216:219], v[64:67]
	s_setprio 0
	s_barrier
	s_add_i32 s18, s73, s66
	v_lshl_add_u64 v[144:145], s[60:61], 0, v[130:131]
	s_mov_b32 m0, s18
	ds_read_b128 v[188:191], v151 offset:16384
	ds_read_b128 v[192:195], v151 offset:17408
	ds_read_b128 v[196:199], v151 offset:18432
	ds_read_b128 v[200:203], v151 offset:19456
	ds_read_b128 v[204:207], v151 offset:20480
	ds_read_b128 v[208:211], v151 offset:21504
	ds_read_b128 v[212:215], v151 offset:22528
	ds_read_b128 v[216:219], v151 offset:23552
	global_load_lds_dwordx4 v[144:145], off
	s_add_i32 m0, s18, 0x2000
	s_add_u32 s18, s60, 0x40000
	v_lshl_add_u64 v[220:221], s[60:61], 0, v[134:135]
	s_addc_u32 s19, s61, 0
	s_add_i32 s79, s74, s66
	global_load_lds_dwordx4 v[220:221], off
	v_lshl_add_u64 v[222:223], s[18:19], 0, v[130:131]
	s_mov_b32 m0, s79
	v_lshl_add_u64 v[224:225], s[62:63], 0, v[132:133]
	global_load_lds_dwordx4 v[222:223], off
	v_lshl_add_u64 v[222:223], s[18:19], 0, v[134:135]
	s_add_i32 m0, s79, 0x2000
	s_nop 0
	global_load_lds_dwordx4 v[222:223], off
	v_lshl_add_u64 v[222:223], s[62:63], 0, v[128:129]
	s_mov_b32 m0, s57
	s_nop 0
	global_load_lds_dwordx4 v[222:223], off
	s_mov_b32 m0, s67
	s_nop 0
	global_load_lds_dwordx4 v[224:225], off
	s_waitcnt vmcnt(8)
	s_waitcnt lgkmcnt(0)
	s_barrier
	s_setprio 1
	s_waitcnt lgkmcnt(0)
	v_mfma_f32_16x16x32_bf16 v[60:63], v[152:155], v[188:191], v[60:63]
	v_mfma_f32_16x16x32_bf16 v[56:59], v[160:163], v[188:191], v[56:59]
	v_mfma_f32_16x16x32_bf16 v[52:55], v[152:155], v[196:199], v[52:55]
	v_mfma_f32_16x16x32_bf16 v[44:47], v[160:163], v[196:199], v[44:47]
	v_mfma_f32_16x16x32_bf16 v[36:39], v[152:155], v[204:207], v[36:39]
	v_mfma_f32_16x16x32_bf16 v[28:31], v[160:163], v[204:207], v[28:31]
	v_mfma_f32_16x16x32_bf16 v[20:23], v[152:155], v[212:215], v[20:23]
	v_mfma_f32_16x16x32_bf16 v[12:15], v[160:163], v[212:215], v[12:15]
	v_mfma_f32_16x16x32_bf16 v[60:63], v[156:159], v[192:195], v[60:63]
	v_mfma_f32_16x16x32_bf16 v[56:59], v[164:167], v[192:195], v[56:59]
	v_mfma_f32_16x16x32_bf16 v[52:55], v[156:159], v[200:203], v[52:55]
	v_mfma_f32_16x16x32_bf16 v[44:47], v[164:167], v[200:203], v[44:47]
	v_mfma_f32_16x16x32_bf16 v[36:39], v[156:159], v[208:211], v[36:39]
	v_mfma_f32_16x16x32_bf16 v[28:31], v[164:167], v[208:211], v[28:31]
	v_mfma_f32_16x16x32_bf16 v[20:23], v[156:159], v[216:219], v[20:23]
	v_mfma_f32_16x16x32_bf16 v[12:15], v[164:167], v[216:219], v[12:15]
	s_setprio 0
	s_setprio 1
	v_mfma_f32_16x16x32_bf16 v[48:51], v[168:171], v[188:191], v[48:51]
	v_mfma_f32_16x16x32_bf16 v[40:43], v[176:179], v[188:191], v[40:43]
	v_mfma_f32_16x16x32_bf16 v[32:35], v[168:171], v[196:199], v[32:35]
	v_mfma_f32_16x16x32_bf16 v[24:27], v[176:179], v[196:199], v[24:27]
	v_mfma_f32_16x16x32_bf16 v[16:19], v[168:171], v[204:207], v[16:19]
	v_mfma_f32_16x16x32_bf16 v[8:11], v[176:179], v[204:207], v[8:11]
	v_mfma_f32_16x16x32_bf16 v[4:7], v[168:171], v[212:215], v[4:7]
	v_mfma_f32_16x16x32_bf16 v[0:3], v[176:179], v[212:215], v[0:3]
	v_mfma_f32_16x16x32_bf16 v[48:51], v[172:175], v[192:195], v[48:51]
	v_mfma_f32_16x16x32_bf16 v[40:43], v[184:187], v[192:195], v[40:43]
	v_mfma_f32_16x16x32_bf16 v[32:35], v[172:175], v[200:203], v[32:35]
	v_mfma_f32_16x16x32_bf16 v[24:27], v[184:187], v[200:203], v[24:27]
	v_mfma_f32_16x16x32_bf16 v[16:19], v[172:175], v[208:211], v[16:19]
	v_mfma_f32_16x16x32_bf16 v[8:11], v[184:187], v[208:211], v[8:11]
	v_mfma_f32_16x16x32_bf16 v[4:7], v[172:175], v[216:219], v[4:7]
	v_mfma_f32_16x16x32_bf16 v[0:3], v[184:187], v[216:219], v[0:3]
	s_setprio 0
	s_barrier
.Lmid_gemm3:
	s_add_i32 s79, 0, 0x18000
	s_add_i32 s89, 0, 0x1c000
	v_add_u32_e32 v164, s79, v147
	v_add_u32_e32 v181, s89, v147
	ds_read_b128 v[152:155], v164
	ds_read_b128 v[156:159], v164 offset:1024
	ds_read_b128 v[160:163], v164 offset:2048
	ds_read_b128 v[164:167], v164 offset:3072
	ds_read_b128 v[168:171], v181
	ds_read_b128 v[172:175], v181 offset:1024
	ds_read_b128 v[176:179], v181 offset:2048
	ds_read_b128 v[184:187], v181 offset:3072
	s_add_u32 s18, s62, 0x40000
	s_addc_u32 s19, s63, 0
	s_mov_b32 m0, s68
	v_lshl_add_u64 v[226:227], s[18:19], 0, v[128:129]
	ds_read_b128 v[188:191], v151 offset:32768
	ds_read_b128 v[192:195], v151 offset:33792
	ds_read_b128 v[196:199], v151 offset:34816
	ds_read_b128 v[200:203], v151 offset:35840
	ds_read_b128 v[204:207], v151 offset:36864
	ds_read_b128 v[208:211], v151 offset:37888
	ds_read_b128 v[212:215], v151 offset:38912
	ds_read_b128 v[216:219], v151 offset:39936
	global_load_lds_dwordx4 v[226:227], off
	v_lshl_add_u64 v[226:227], s[18:19], 0, v[132:133]
	s_mov_b32 m0, s69
	s_nop 0
	global_load_lds_dwordx4 v[226:227], off
	s_waitcnt vmcnt(8)
	s_waitcnt lgkmcnt(0)
	s_barrier
	s_setprio 1
	s_waitcnt lgkmcnt(0)
	v_mfma_f32_16x16x32_bf16 v[124:127], v[152:155], v[188:191], v[124:127]
	v_mfma_f32_16x16x32_bf16 v[120:123], v[160:163], v[188:191], v[120:123]
	v_mfma_f32_16x16x32_bf16 v[116:119], v[152:155], v[196:199], v[116:119]
	v_mfma_f32_16x16x32_bf16 v[108:111], v[160:163], v[196:199], v[108:111]
	v_mfma_f32_16x16x32_bf16 v[100:103], v[152:155], v[204:207], v[100:103]
	v_mfma_f32_16x16x32_bf16 v[92:95], v[160:163], v[204:207], v[92:95]
	v_mfma_f32_16x16x32_bf16 v[84:87], v[152:155], v[212:215], v[84:87]
	v_mfma_f32_16x16x32_bf16 v[76:79], v[160:163], v[212:215], v[76:79]
	v_mfma_f32_16x16x32_bf16 v[124:127], v[156:159], v[192:195], v[124:127]
	v_mfma_f32_16x16x32_bf16 v[120:123], v[164:167], v[192:195], v[120:123]
	v_mfma_f32_16x16x32_bf16 v[116:119], v[156:159], v[200:203], v[116:119]
	v_mfma_f32_16x16x32_bf16 v[108:111], v[164:167], v[200:203], v[108:111]
	v_mfma_f32_16x16x32_bf16 v[100:103], v[156:159], v[208:211], v[100:103]
	v_mfma_f32_16x16x32_bf16 v[92:95], v[164:167], v[208:211], v[92:95]
	v_mfma_f32_16x16x32_bf16 v[84:87], v[156:159], v[216:219], v[84:87]
	v_mfma_f32_16x16x32_bf16 v[76:79], v[164:167], v[216:219], v[76:79]
	s_setprio 0
	s_setprio 1
	v_mfma_f32_16x16x32_bf16 v[112:115], v[168:171], v[188:191], v[112:115]
	v_mfma_f32_16x16x32_bf16 v[104:107], v[176:179], v[188:191], v[104:107]
	v_mfma_f32_16x16x32_bf16 v[96:99], v[168:171], v[196:199], v[96:99]
	v_mfma_f32_16x16x32_bf16 v[88:91], v[176:179], v[196:199], v[88:91]
	v_mfma_f32_16x16x32_bf16 v[80:83], v[168:171], v[204:207], v[80:83]
	v_mfma_f32_16x16x32_bf16 v[72:75], v[176:179], v[204:207], v[72:75]
	v_mfma_f32_16x16x32_bf16 v[68:71], v[168:171], v[212:215], v[68:71]
	v_mfma_f32_16x16x32_bf16 v[64:67], v[176:179], v[212:215], v[64:67]
	v_mfma_f32_16x16x32_bf16 v[112:115], v[172:175], v[192:195], v[112:115]
	v_mfma_f32_16x16x32_bf16 v[104:107], v[184:187], v[192:195], v[104:107]
	v_mfma_f32_16x16x32_bf16 v[96:99], v[172:175], v[200:203], v[96:99]
	v_mfma_f32_16x16x32_bf16 v[88:91], v[184:187], v[200:203], v[88:91]
	v_mfma_f32_16x16x32_bf16 v[80:83], v[172:175], v[208:211], v[80:83]
	v_mfma_f32_16x16x32_bf16 v[72:75], v[184:187], v[208:211], v[72:75]
	v_mfma_f32_16x16x32_bf16 v[68:71], v[172:175], v[216:219], v[68:71]
	v_mfma_f32_16x16x32_bf16 v[64:67], v[184:187], v[216:219], v[64:67]
	s_setprio 0
	s_barrier
	s_add_i32 s18, s79, s66
	v_lshl_add_u64 v[144:145], v[144:145], 0, s[10:11]
	s_mov_b32 m0, s18
	ds_read_b128 v[188:191], v151 offset:49152
	ds_read_b128 v[192:195], v151 offset:50176
	ds_read_b128 v[196:199], v151 offset:51200
	ds_read_b128 v[200:203], v151 offset:52224
	ds_read_b128 v[204:207], v151 offset:53248
	ds_read_b128 v[208:211], v151 offset:54272
	ds_read_b128 v[212:215], v151 offset:55296
	ds_read_b128 v[216:219], v151 offset:56320
	global_load_lds_dwordx4 v[144:145], off
	s_add_i32 m0, s18, 0x2000
	s_add_u32 s18, s60, 0x40080
	v_lshl_add_u64 v[144:145], v[220:221], 0, s[10:11]
	s_addc_u32 s19, s61, 0
	s_add_i32 s60, s89, s66
	global_load_lds_dwordx4 v[144:145], off
	v_lshl_add_u64 v[144:145], s[18:19], 0, v[130:131]
	s_mov_b32 m0, s60
	s_nop 0
	global_load_lds_dwordx4 v[144:145], off
	v_lshl_add_u64 v[144:145], s[18:19], 0, v[134:135]
	s_add_i32 m0, s60, 0x2000
	s_nop 0
	global_load_lds_dwordx4 v[144:145], off
	v_lshl_add_u64 v[144:145], v[222:223], 0, s[10:11]
	s_mov_b32 m0, s71
	s_nop 0
	global_load_lds_dwordx4 v[144:145], off
	v_lshl_add_u64 v[144:145], v[224:225], 0, s[10:11]
	s_mov_b32 m0, s72
	s_nop 0
	global_load_lds_dwordx4 v[144:145], off
	s_waitcnt vmcnt(8)
	s_waitcnt lgkmcnt(0)
	s_barrier
	s_setprio 1
	s_waitcnt lgkmcnt(0)
	v_mfma_f32_16x16x32_bf16 v[60:63], v[152:155], v[188:191], v[60:63]
	v_mfma_f32_16x16x32_bf16 v[56:59], v[160:163], v[188:191], v[56:59]
	v_mfma_f32_16x16x32_bf16 v[52:55], v[152:155], v[196:199], v[52:55]
	v_mfma_f32_16x16x32_bf16 v[44:47], v[160:163], v[196:199], v[44:47]
	v_mfma_f32_16x16x32_bf16 v[36:39], v[152:155], v[204:207], v[36:39]
	v_mfma_f32_16x16x32_bf16 v[28:31], v[160:163], v[204:207], v[28:31]
	v_mfma_f32_16x16x32_bf16 v[20:23], v[152:155], v[212:215], v[20:23]
	v_mfma_f32_16x16x32_bf16 v[12:15], v[160:163], v[212:215], v[12:15]
	v_mfma_f32_16x16x32_bf16 v[60:63], v[156:159], v[192:195], v[60:63]
	v_mfma_f32_16x16x32_bf16 v[56:59], v[164:167], v[192:195], v[56:59]
	v_mfma_f32_16x16x32_bf16 v[52:55], v[156:159], v[200:203], v[52:55]
	v_mfma_f32_16x16x32_bf16 v[44:47], v[164:167], v[200:203], v[44:47]
	v_mfma_f32_16x16x32_bf16 v[36:39], v[156:159], v[208:211], v[36:39]
	v_mfma_f32_16x16x32_bf16 v[28:31], v[164:167], v[208:211], v[28:31]
	v_mfma_f32_16x16x32_bf16 v[20:23], v[156:159], v[216:219], v[20:23]
	v_mfma_f32_16x16x32_bf16 v[12:15], v[164:167], v[216:219], v[12:15]
	s_setprio 0
	s_setprio 1
	v_mfma_f32_16x16x32_bf16 v[48:51], v[168:171], v[188:191], v[48:51]
	v_mfma_f32_16x16x32_bf16 v[40:43], v[176:179], v[188:191], v[40:43]
	v_mfma_f32_16x16x32_bf16 v[32:35], v[168:171], v[196:199], v[32:35]
	v_mfma_f32_16x16x32_bf16 v[24:27], v[176:179], v[196:199], v[24:27]
	v_mfma_f32_16x16x32_bf16 v[16:19], v[168:171], v[204:207], v[16:19]
	v_mfma_f32_16x16x32_bf16 v[8:11], v[176:179], v[204:207], v[8:11]
	v_mfma_f32_16x16x32_bf16 v[4:7], v[168:171], v[212:215], v[4:7]
	v_mfma_f32_16x16x32_bf16 v[0:3], v[176:179], v[212:215], v[0:3]
	v_mfma_f32_16x16x32_bf16 v[48:51], v[172:175], v[192:195], v[48:51]
	v_mfma_f32_16x16x32_bf16 v[40:43], v[184:187], v[192:195], v[40:43]
	v_mfma_f32_16x16x32_bf16 v[32:35], v[172:175], v[200:203], v[32:35]
	v_mfma_f32_16x16x32_bf16 v[24:27], v[184:187], v[200:203], v[24:27]
	v_mfma_f32_16x16x32_bf16 v[16:19], v[172:175], v[208:211], v[16:19]
	v_mfma_f32_16x16x32_bf16 v[8:11], v[184:187], v[208:211], v[8:11]
	v_mfma_f32_16x16x32_bf16 v[4:7], v[172:175], v[216:219], v[4:7]
	v_mfma_f32_16x16x32_bf16 v[0:3], v[184:187], v[216:219], v[0:3]
	s_setprio 0
	s_barrier
	s_add_i32 s88, s88, 2
	s_add_u32 s58, s58, 0x100
	s_addc_u32 s59, s59, 0
	s_add_u32 s86, s86, 0x100
	s_addc_u32 s87, s87, 0
	s_cmp_gt_u32 s88, 13
	s_cbranch_scc0 .LBB0_601
	s_and_b64 vcc, exec, s[12:13]
	s_cbranch_vccz .LBB0_604
	s_barrier

.LBB0_723:
	s_ashr_i32 s31, s30, 31
	s_lshl_b64 s[36:37], s[30:31], 19
	s_add_u32 s36, s80, s36
	s_addc_u32 s37, s81, s37
	s_and_b64 s[44:45], s[10:11], exec
	s_cselect_b32 s31, s37, s49
	s_cselect_b32 s70, s36, s48
	s_ashr_i32 s19, s18, 31
	s_lshl_b64 s[44:45], s[18:19], 19
	s_add_u32 s44, s56, s44
	s_addc_u32 s45, s57, s45
	s_and_b64 s[54:55], s[10:11], exec
	s_cselect_b32 s19, s45, s53
	s_cselect_b32 s71, s44, s52
	s_add_u32 s48, s48, 0x40080
	s_addc_u32 s49, s49, 0
	s_add_u32 s72, s52, 0x100
	s_addc_u32 s73, s53, 0
	s_mov_b32 s74, -2
	ds_read_b128 v[140:143], v147
	ds_read_b128 v[150:153], v147 offset:1024
	ds_read_b128 v[154:157], v147 offset:2048
	ds_read_b128 v[158:161], v147 offset:3072
	ds_read_b128 v[162:165], v148
	ds_read_b128 v[166:169], v148 offset:1024
	ds_read_b128 v[170:173], v148 offset:2048
	ds_read_b128 v[174:177], v148 offset:3072
	s_add_u32 s52, s48, 0xfffc0080
	s_addc_u32 s53, s49, -1
	s_cmp_eq_u32 s74, 12
	s_cselect_b32 s55, s31, s53
	s_cselect_b32 s54, s70, s52
	s_cselect_b32 s53, s19, s73
	s_cselect_b32 s52, s71, s72
	v_lshl_add_u64 v[178:179], s[48:49], 0, v[132:133]
	s_add_i32 m0, s47, 0xc000
	ds_read_b128 v[184:187], v149
	ds_read_b128 v[188:191], v149 offset:1024
	ds_read_b128 v[192:195], v149 offset:2048
	ds_read_b128 v[196:199], v149 offset:3072
	ds_read_b128 v[200:203], v149 offset:4096
	ds_read_b128 v[204:207], v149 offset:5120
	ds_read_b128 v[208:211], v149 offset:6144
	ds_read_b128 v[212:215], v149 offset:7168
	global_load_lds_dwordx4 v[178:179], off
	v_lshl_add_u64 v[178:179], s[48:49], 0, v[134:135]
	s_add_i32 m0, s47, 0xe000
	s_nop 0
	global_load_lds_dwordx4 v[178:179], off
	s_waitcnt vmcnt(8)
	s_waitcnt lgkmcnt(0)
	s_barrier
	s_setprio 1
	s_waitcnt lgkmcnt(0)
	v_mfma_f32_16x16x32_bf16 v[124:127], v[140:143], v[184:187], 0
	v_mfma_f32_16x16x32_bf16 v[120:123], v[154:157], v[184:187], 0
	v_mfma_f32_16x16x32_bf16 v[108:111], v[140:143], v[192:195], 0
	v_mfma_f32_16x16x32_bf16 v[104:107], v[154:157], v[192:195], 0
	v_mfma_f32_16x16x32_bf16 v[92:95], v[140:143], v[200:203], 0
	v_mfma_f32_16x16x32_bf16 v[88:91], v[154:157], v[200:203], 0
	v_mfma_f32_16x16x32_bf16 v[76:79], v[140:143], v[208:211], 0
	v_mfma_f32_16x16x32_bf16 v[72:75], v[154:157], v[208:211], 0
	v_mfma_f32_16x16x32_bf16 v[124:127], v[150:153], v[188:191], v[124:127]
	v_mfma_f32_16x16x32_bf16 v[120:123], v[158:161], v[188:191], v[120:123]
	v_mfma_f32_16x16x32_bf16 v[108:111], v[150:153], v[196:199], v[108:111]
	v_mfma_f32_16x16x32_bf16 v[104:107], v[158:161], v[196:199], v[104:107]
	v_mfma_f32_16x16x32_bf16 v[92:95], v[150:153], v[204:207], v[92:95]
	v_mfma_f32_16x16x32_bf16 v[88:91], v[158:161], v[204:207], v[88:91]
	v_mfma_f32_16x16x32_bf16 v[76:79], v[150:153], v[212:215], v[76:79]
	v_mfma_f32_16x16x32_bf16 v[72:75], v[158:161], v[212:215], v[72:75]
	s_setprio 0
	s_setprio 1
	v_mfma_f32_16x16x32_bf16 v[116:119], v[162:165], v[184:187], 0
	v_mfma_f32_16x16x32_bf16 v[112:115], v[170:173], v[184:187], 0
	v_mfma_f32_16x16x32_bf16 v[100:103], v[162:165], v[192:195], 0
	v_mfma_f32_16x16x32_bf16 v[96:99], v[170:173], v[192:195], 0
	v_mfma_f32_16x16x32_bf16 v[84:87], v[162:165], v[200:203], 0
	v_mfma_f32_16x16x32_bf16 v[80:83], v[170:173], v[200:203], 0
	v_mfma_f32_16x16x32_bf16 v[68:71], v[162:165], v[208:211], 0
	v_mfma_f32_16x16x32_bf16 v[64:67], v[170:173], v[208:211], 0
	v_mfma_f32_16x16x32_bf16 v[116:119], v[166:169], v[188:191], v[116:119]
	v_mfma_f32_16x16x32_bf16 v[112:115], v[174:177], v[188:191], v[112:115]
	v_mfma_f32_16x16x32_bf16 v[100:103], v[166:169], v[196:199], v[100:103]
	v_mfma_f32_16x16x32_bf16 v[96:99], v[174:177], v[196:199], v[96:99]
	v_mfma_f32_16x16x32_bf16 v[84:87], v[166:169], v[204:207], v[84:87]
	v_mfma_f32_16x16x32_bf16 v[80:83], v[174:177], v[204:207], v[80:83]
	v_mfma_f32_16x16x32_bf16 v[68:71], v[166:169], v[212:215], v[68:71]
	v_mfma_f32_16x16x32_bf16 v[64:67], v[174:177], v[212:215], v[64:67]
	s_setprio 0
	s_barrier
	s_add_i32 s75, s66, s58
	v_lshl_add_u64 v[178:179], s[52:53], 0, v[130:131]
	s_mov_b32 m0, s75
	ds_read_b128 v[184:187], v149 offset:16384
	ds_read_b128 v[188:191], v149 offset:17408
	ds_read_b128 v[192:195], v149 offset:18432
	ds_read_b128 v[196:199], v149 offset:19456
	ds_read_b128 v[200:203], v149 offset:20480
	ds_read_b128 v[204:207], v149 offset:21504
	ds_read_b128 v[208:211], v149 offset:22528
	ds_read_b128 v[212:215], v149 offset:23552
	global_load_lds_dwordx4 v[178:179], off
	s_add_i32 m0, s75, 0x2000
	s_add_u32 s76, s52, 0x40000
	v_lshl_add_u64 v[216:217], s[52:53], 0, v[128:129]
	s_addc_u32 s77, s53, 0
	s_add_i32 s75, s67, s58
	global_load_lds_dwordx4 v[216:217], off
	v_lshl_add_u64 v[218:219], s[76:77], 0, v[130:131]
	s_mov_b32 m0, s75
	v_lshl_add_u64 v[220:221], s[54:55], 0, v[128:129]
	global_load_lds_dwordx4 v[218:219], off
	v_lshl_add_u64 v[218:219], s[76:77], 0, v[128:129]
	s_add_i32 m0, s75, 0x2000
	s_nop 0
	global_load_lds_dwordx4 v[218:219], off
	v_lshl_add_u64 v[218:219], s[54:55], 0, v[130:131]
	s_mov_b32 m0, s47
	s_nop 0
	global_load_lds_dwordx4 v[218:219], off
	s_mov_b32 m0, s60
	s_nop 0
	global_load_lds_dwordx4 v[220:221], off
	s_waitcnt vmcnt(8)
	s_waitcnt lgkmcnt(0)
	s_barrier
	s_setprio 1
	s_waitcnt lgkmcnt(0)
	v_mfma_f32_16x16x32_bf16 v[60:63], v[140:143], v[184:187], 0
	v_mfma_f32_16x16x32_bf16 v[56:59], v[154:157], v[184:187], 0
	v_mfma_f32_16x16x32_bf16 v[44:47], v[140:143], v[192:195], 0
	v_mfma_f32_16x16x32_bf16 v[40:43], v[154:157], v[192:195], 0
	v_mfma_f32_16x16x32_bf16 v[28:31], v[140:143], v[200:203], 0
	v_mfma_f32_16x16x32_bf16 v[24:27], v[154:157], v[200:203], 0
	v_mfma_f32_16x16x32_bf16 v[12:15], v[140:143], v[208:211], 0
	v_mfma_f32_16x16x32_bf16 v[8:11], v[154:157], v[208:211], 0
	v_mfma_f32_16x16x32_bf16 v[60:63], v[150:153], v[188:191], v[60:63]
	v_mfma_f32_16x16x32_bf16 v[56:59], v[158:161], v[188:191], v[56:59]
	v_mfma_f32_16x16x32_bf16 v[44:47], v[150:153], v[196:199], v[44:47]
	v_mfma_f32_16x16x32_bf16 v[40:43], v[158:161], v[196:199], v[40:43]
	v_mfma_f32_16x16x32_bf16 v[28:31], v[150:153], v[204:207], v[28:31]
	v_mfma_f32_16x16x32_bf16 v[24:27], v[158:161], v[204:207], v[24:27]
	v_mfma_f32_16x16x32_bf16 v[12:15], v[150:153], v[212:215], v[12:15]
	v_mfma_f32_16x16x32_bf16 v[8:11], v[158:161], v[212:215], v[8:11]
	s_setprio 0
	s_setprio 1
	v_mfma_f32_16x16x32_bf16 v[52:55], v[162:165], v[184:187], 0
	v_mfma_f32_16x16x32_bf16 v[48:51], v[170:173], v[184:187], 0
	v_mfma_f32_16x16x32_bf16 v[36:39], v[162:165], v[192:195], 0
	v_mfma_f32_16x16x32_bf16 v[32:35], v[170:173], v[192:195], 0
	v_mfma_f32_16x16x32_bf16 v[20:23], v[162:165], v[200:203], 0
	v_mfma_f32_16x16x32_bf16 v[16:19], v[170:173], v[200:203], 0
	v_mfma_f32_16x16x32_bf16 v[4:7], v[162:165], v[208:211], 0
	v_mfma_f32_16x16x32_bf16 v[0:3], v[170:173], v[208:211], 0
	v_mfma_f32_16x16x32_bf16 v[52:55], v[166:169], v[188:191], v[52:55]
	v_mfma_f32_16x16x32_bf16 v[48:51], v[174:177], v[188:191], v[48:51]
	v_mfma_f32_16x16x32_bf16 v[36:39], v[166:169], v[196:199], v[36:39]
	v_mfma_f32_16x16x32_bf16 v[32:35], v[174:177], v[196:199], v[32:35]
	v_mfma_f32_16x16x32_bf16 v[20:23], v[166:169], v[204:207], v[20:23]
	v_mfma_f32_16x16x32_bf16 v[16:19], v[174:177], v[204:207], v[16:19]
	v_mfma_f32_16x16x32_bf16 v[4:7], v[166:169], v[212:215], v[4:7]
	v_mfma_f32_16x16x32_bf16 v[0:3], v[174:177], v[212:215], v[0:3]
	s_setprio 0
	s_barrier
	s_branch .Lmid_gemm4
.LBB0_724:
	ds_read_b128 v[140:143], v147
	ds_read_b128 v[150:153], v147 offset:1024
	ds_read_b128 v[154:157], v147 offset:2048
	ds_read_b128 v[158:161], v147 offset:3072
	ds_read_b128 v[162:165], v148
	ds_read_b128 v[166:169], v148 offset:1024
	ds_read_b128 v[170:173], v148 offset:2048
	ds_read_b128 v[174:177], v148 offset:3072
	s_add_u32 s52, s48, 0xfffc0080
	s_addc_u32 s53, s49, -1
	s_cmp_eq_u32 s74, 12
	s_cselect_b32 s55, s31, s53
	s_cselect_b32 s54, s70, s52
	s_cselect_b32 s53, s19, s73
	s_cselect_b32 s52, s71, s72
	v_lshl_add_u64 v[178:179], s[48:49], 0, v[132:133]
	s_add_i32 m0, s47, 0xc000
	ds_read_b128 v[184:187], v149
	ds_read_b128 v[188:191], v149 offset:1024
	ds_read_b128 v[192:195], v149 offset:2048
	ds_read_b128 v[196:199], v149 offset:3072
	ds_read_b128 v[200:203], v149 offset:4096
	ds_read_b128 v[204:207], v149 offset:5120
	ds_read_b128 v[208:211], v149 offset:6144
	ds_read_b128 v[212:215], v149 offset:7168
	global_load_lds_dwordx4 v[178:179], off
	v_lshl_add_u64 v[178:179], s[48:49], 0, v[134:135]
	s_add_i32 m0, s47, 0xe000
	s_nop 0
	global_load_lds_dwordx4 v[178:179], off
	s_waitcnt vmcnt(8)
	s_waitcnt lgkmcnt(0)
	s_barrier
	s_setprio 1
	s_waitcnt lgkmcnt(0)
	v_mfma_f32_16x16x32_bf16 v[124:127], v[140:143], v[184:187], v[124:127]
	v_mfma_f32_16x16x32_bf16 v[120:123], v[154:157], v[184:187], v[120:123]
	v_mfma_f32_16x16x32_bf16 v[108:111], v[140:143], v[192:195], v[108:111]
	v_mfma_f32_16x16x32_bf16 v[104:107], v[154:157], v[192:195], v[104:107]
	v_mfma_f32_16x16x32_bf16 v[92:95], v[140:143], v[200:203], v[92:95]
	v_mfma_f32_16x16x32_bf16 v[88:91], v[154:157], v[200:203], v[88:91]
	v_mfma_f32_16x16x32_bf16 v[76:79], v[140:143], v[208:211], v[76:79]
	v_mfma_f32_16x16x32_bf16 v[72:75], v[154:157], v[208:211], v[72:75]
	v_mfma_f32_16x16x32_bf16 v[124:127], v[150:153], v[188:191], v[124:127]
	v_mfma_f32_16x16x32_bf16 v[120:123], v[158:161], v[188:191], v[120:123]
	v_mfma_f32_16x16x32_bf16 v[108:111], v[150:153], v[196:199], v[108:111]
	v_mfma_f32_16x16x32_bf16 v[104:107], v[158:161], v[196:199], v[104:107]
	v_mfma_f32_16x16x32_bf16 v[92:95], v[150:153], v[204:207], v[92:95]
	v_mfma_f32_16x16x32_bf16 v[88:91], v[158:161], v[204:207], v[88:91]
	v_mfma_f32_16x16x32_bf16 v[76:79], v[150:153], v[212:215], v[76:79]
	v_mfma_f32_16x16x32_bf16 v[72:75], v[158:161], v[212:215], v[72:75]
	s_setprio 0
	s_setprio 1
	v_mfma_f32_16x16x32_bf16 v[116:119], v[162:165], v[184:187], v[116:119]
	v_mfma_f32_16x16x32_bf16 v[112:115], v[170:173], v[184:187], v[112:115]
	v_mfma_f32_16x16x32_bf16 v[100:103], v[162:165], v[192:195], v[100:103]
	v_mfma_f32_16x16x32_bf16 v[96:99], v[170:173], v[192:195], v[96:99]
	v_mfma_f32_16x16x32_bf16 v[84:87], v[162:165], v[200:203], v[84:87]
	v_mfma_f32_16x16x32_bf16 v[80:83], v[170:173], v[200:203], v[80:83]
	v_mfma_f32_16x16x32_bf16 v[68:71], v[162:165], v[208:211], v[68:71]
	v_mfma_f32_16x16x32_bf16 v[64:67], v[170:173], v[208:211], v[64:67]
	v_mfma_f32_16x16x32_bf16 v[116:119], v[166:169], v[188:191], v[116:119]
	v_mfma_f32_16x16x32_bf16 v[112:115], v[174:177], v[188:191], v[112:115]
	v_mfma_f32_16x16x32_bf16 v[100:103], v[166:169], v[196:199], v[100:103]
	v_mfma_f32_16x16x32_bf16 v[96:99], v[174:177], v[196:199], v[96:99]
	v_mfma_f32_16x16x32_bf16 v[84:87], v[166:169], v[204:207], v[84:87]
	v_mfma_f32_16x16x32_bf16 v[80:83], v[174:177], v[204:207], v[80:83]
	v_mfma_f32_16x16x32_bf16 v[68:71], v[166:169], v[212:215], v[68:71]
	v_mfma_f32_16x16x32_bf16 v[64:67], v[174:177], v[212:215], v[64:67]
	s_setprio 0
	s_barrier
	s_add_i32 s75, s66, s58
	v_lshl_add_u64 v[178:179], s[52:53], 0, v[130:131]
	s_mov_b32 m0, s75
	ds_read_b128 v[184:187], v149 offset:16384
	ds_read_b128 v[188:191], v149 offset:17408
	ds_read_b128 v[192:195], v149 offset:18432
	ds_read_b128 v[196:199], v149 offset:19456
	ds_read_b128 v[200:203], v149 offset:20480
	ds_read_b128 v[204:207], v149 offset:21504
	ds_read_b128 v[208:211], v149 offset:22528
	ds_read_b128 v[212:215], v149 offset:23552
	global_load_lds_dwordx4 v[178:179], off
	s_add_i32 m0, s75, 0x2000
	s_add_u32 s76, s52, 0x40000
	v_lshl_add_u64 v[216:217], s[52:53], 0, v[128:129]
	s_addc_u32 s77, s53, 0
	s_add_i32 s75, s67, s58
	global_load_lds_dwordx4 v[216:217], off
	v_lshl_add_u64 v[218:219], s[76:77], 0, v[130:131]
	s_mov_b32 m0, s75
	v_lshl_add_u64 v[220:221], s[54:55], 0, v[128:129]
	global_load_lds_dwordx4 v[218:219], off
	v_lshl_add_u64 v[218:219], s[76:77], 0, v[128:129]
	s_add_i32 m0, s75, 0x2000
	s_nop 0
	global_load_lds_dwordx4 v[218:219], off
	v_lshl_add_u64 v[218:219], s[54:55], 0, v[130:131]
	s_mov_b32 m0, s47
	s_nop 0
	global_load_lds_dwordx4 v[218:219], off
	s_mov_b32 m0, s60
	s_nop 0
	global_load_lds_dwordx4 v[220:221], off
	s_waitcnt vmcnt(8)
	s_waitcnt lgkmcnt(0)
	s_barrier
	s_setprio 1
	s_waitcnt lgkmcnt(0)
	v_mfma_f32_16x16x32_bf16 v[60:63], v[140:143], v[184:187], v[60:63]
	v_mfma_f32_16x16x32_bf16 v[56:59], v[154:157], v[184:187], v[56:59]
	v_mfma_f32_16x16x32_bf16 v[44:47], v[140:143], v[192:195], v[44:47]
	v_mfma_f32_16x16x32_bf16 v[40:43], v[154:157], v[192:195], v[40:43]
	v_mfma_f32_16x16x32_bf16 v[28:31], v[140:143], v[200:203], v[28:31]
	v_mfma_f32_16x16x32_bf16 v[24:27], v[154:157], v[200:203], v[24:27]
	v_mfma_f32_16x16x32_bf16 v[12:15], v[140:143], v[208:211], v[12:15]
	v_mfma_f32_16x16x32_bf16 v[8:11], v[154:157], v[208:211], v[8:11]
	v_mfma_f32_16x16x32_bf16 v[60:63], v[150:153], v[188:191], v[60:63]
	v_mfma_f32_16x16x32_bf16 v[56:59], v[158:161], v[188:191], v[56:59]
	v_mfma_f32_16x16x32_bf16 v[44:47], v[150:153], v[196:199], v[44:47]
	v_mfma_f32_16x16x32_bf16 v[40:43], v[158:161], v[196:199], v[40:43]
	v_mfma_f32_16x16x32_bf16 v[28:31], v[150:153], v[204:207], v[28:31]
	v_mfma_f32_16x16x32_bf16 v[24:27], v[158:161], v[204:207], v[24:27]
	v_mfma_f32_16x16x32_bf16 v[12:15], v[150:153], v[212:215], v[12:15]
	v_mfma_f32_16x16x32_bf16 v[8:11], v[158:161], v[212:215], v[8:11]
	s_setprio 0
	s_setprio 1
	v_mfma_f32_16x16x32_bf16 v[52:55], v[162:165], v[184:187], v[52:55]
	v_mfma_f32_16x16x32_bf16 v[48:51], v[170:173], v[184:187], v[48:51]
	v_mfma_f32_16x16x32_bf16 v[36:39], v[162:165], v[192:195], v[36:39]
	v_mfma_f32_16x16x32_bf16 v[32:35], v[170:173], v[192:195], v[32:35]
	v_mfma_f32_16x16x32_bf16 v[20:23], v[162:165], v[200:203], v[20:23]
	v_mfma_f32_16x16x32_bf16 v[16:19], v[170:173], v[200:203], v[16:19]
	v_mfma_f32_16x16x32_bf16 v[4:7], v[162:165], v[208:211], v[4:7]
	v_mfma_f32_16x16x32_bf16 v[0:3], v[170:173], v[208:211], v[0:3]
	v_mfma_f32_16x16x32_bf16 v[52:55], v[166:169], v[188:191], v[52:55]
	v_mfma_f32_16x16x32_bf16 v[48:51], v[174:177], v[188:191], v[48:51]
	v_mfma_f32_16x16x32_bf16 v[36:39], v[166:169], v[196:199], v[36:39]
	v_mfma_f32_16x16x32_bf16 v[32:35], v[174:177], v[196:199], v[32:35]
	v_mfma_f32_16x16x32_bf16 v[20:23], v[166:169], v[204:207], v[20:23]
	v_mfma_f32_16x16x32_bf16 v[16:19], v[174:177], v[204:207], v[16:19]
	v_mfma_f32_16x16x32_bf16 v[4:7], v[166:169], v[212:215], v[4:7]
	v_mfma_f32_16x16x32_bf16 v[0:3], v[174:177], v[212:215], v[0:3]
	s_setprio 0
	s_barrier
.Lmid_gemm4:
	s_add_i32 s75, 0, 0x18000
	s_add_i32 s76, 0, 0x1c000
	v_add_u32_e32 v158, s75, v145
	v_add_u32_e32 v174, s76, v145
	ds_read_b128 v[140:143], v158
	ds_read_b128 v[150:153], v158 offset:1024
	ds_read_b128 v[154:157], v158 offset:2048
	ds_read_b128 v[158:161], v158 offset:3072
	ds_read_b128 v[162:165], v174
	ds_read_b128 v[166:169], v174 offset:1024
	ds_read_b128 v[170:173], v174 offset:2048
	ds_read_b128 v[174:177], v174 offset:3072
	s_add_u32 s54, s54, 0x40000
	s_addc_u32 s55, s55, 0
	s_mov_b32 m0, s61
	v_lshl_add_u64 v[222:223], s[54:55], 0, v[130:131]
	ds_read_b128 v[184:187], v149 offset:32768
	ds_read_b128 v[188:191], v149 offset:33792
	ds_read_b128 v[192:195], v149 offset:34816
	ds_read_b128 v[196:199], v149 offset:35840
	ds_read_b128 v[200:203], v149 offset:36864
	ds_read_b128 v[204:207], v149 offset:37888
	ds_read_b128 v[208:211], v149 offset:38912
	ds_read_b128 v[212:215], v149 offset:39936
	global_load_lds_dwordx4 v[222:223], off
	v_lshl_add_u64 v[222:223], s[54:55], 0, v[128:129]
	s_mov_b32 m0, s62
	s_nop 0
	global_load_lds_dwordx4 v[222:223], off
	s_waitcnt vmcnt(8)
	s_waitcnt lgkmcnt(0)
	s_barrier
	s_setprio 1
	s_waitcnt lgkmcnt(0)
	v_mfma_f32_16x16x32_bf16 v[124:127], v[140:143], v[184:187], v[124:127]
	v_mfma_f32_16x16x32_bf16 v[120:123], v[154:157], v[184:187], v[120:123]
	v_mfma_f32_16x16x32_bf16 v[108:111], v[140:143], v[192:195], v[108:111]
	v_mfma_f32_16x16x32_bf16 v[104:107], v[154:157], v[192:195], v[104:107]
	v_mfma_f32_16x16x32_bf16 v[92:95], v[140:143], v[200:203], v[92:95]
	v_mfma_f32_16x16x32_bf16 v[88:91], v[154:157], v[200:203], v[88:91]
	v_mfma_f32_16x16x32_bf16 v[76:79], v[140:143], v[208:211], v[76:79]
	v_mfma_f32_16x16x32_bf16 v[72:75], v[154:157], v[208:211], v[72:75]
	v_mfma_f32_16x16x32_bf16 v[124:127], v[150:153], v[188:191], v[124:127]
	v_mfma_f32_16x16x32_bf16 v[120:123], v[158:161], v[188:191], v[120:123]
	v_mfma_f32_16x16x32_bf16 v[108:111], v[150:153], v[196:199], v[108:111]
	v_mfma_f32_16x16x32_bf16 v[104:107], v[158:161], v[196:199], v[104:107]
	v_mfma_f32_16x16x32_bf16 v[92:95], v[150:153], v[204:207], v[92:95]
	v_mfma_f32_16x16x32_bf16 v[88:91], v[158:161], v[204:207], v[88:91]
	v_mfma_f32_16x16x32_bf16 v[76:79], v[150:153], v[212:215], v[76:79]
	v_mfma_f32_16x16x32_bf16 v[72:75], v[158:161], v[212:215], v[72:75]
	s_setprio 0
	s_setprio 1
	v_mfma_f32_16x16x32_bf16 v[116:119], v[162:165], v[184:187], v[116:119]
	v_mfma_f32_16x16x32_bf16 v[112:115], v[170:173], v[184:187], v[112:115]
	v_mfma_f32_16x16x32_bf16 v[100:103], v[162:165], v[192:195], v[100:103]
	v_mfma_f32_16x16x32_bf16 v[96:99], v[170:173], v[192:195], v[96:99]
	v_mfma_f32_16x16x32_bf16 v[84:87], v[162:165], v[200:203], v[84:87]
	v_mfma_f32_16x16x32_bf16 v[80:83], v[170:173], v[200:203], v[80:83]
	v_mfma_f32_16x16x32_bf16 v[68:71], v[162:165], v[208:211], v[68:71]
	v_mfma_f32_16x16x32_bf16 v[64:67], v[170:173], v[208:211], v[64:67]
	v_mfma_f32_16x16x32_bf16 v[116:119], v[166:169], v[188:191], v[116:119]
	v_mfma_f32_16x16x32_bf16 v[112:115], v[174:177], v[188:191], v[112:115]
	v_mfma_f32_16x16x32_bf16 v[100:103], v[166:169], v[196:199], v[100:103]
	v_mfma_f32_16x16x32_bf16 v[96:99], v[174:177], v[196:199], v[96:99]
	v_mfma_f32_16x16x32_bf16 v[84:87], v[166:169], v[204:207], v[84:87]
	v_mfma_f32_16x16x32_bf16 v[80:83], v[174:177], v[204:207], v[80:83]
	v_mfma_f32_16x16x32_bf16 v[68:71], v[166:169], v[212:215], v[68:71]
	v_mfma_f32_16x16x32_bf16 v[64:67], v[174:177], v[212:215], v[64:67]
	s_setprio 0
	s_barrier
	s_add_i32 s54, s75, s58
	v_lshl_add_u64 v[178:179], v[178:179], 0, s[12:13]
	s_mov_b32 m0, s54
	ds_read_b128 v[184:187], v149 offset:49152
	ds_read_b128 v[188:191], v149 offset:50176
	ds_read_b128 v[192:195], v149 offset:51200
	ds_read_b128 v[196:199], v149 offset:52224
	ds_read_b128 v[200:203], v149 offset:53248
	ds_read_b128 v[204:207], v149 offset:54272
	ds_read_b128 v[208:211], v149 offset:55296
	ds_read_b128 v[212:215], v149 offset:56320
	global_load_lds_dwordx4 v[178:179], off
	s_add_i32 m0, s54, 0x2000
	s_add_u32 s52, s52, 0x40080
	v_lshl_add_u64 v[178:179], v[216:217], 0, s[12:13]
	s_addc_u32 s53, s53, 0
	s_add_i32 s54, s76, s58
	global_load_lds_dwordx4 v[178:179], off
	v_lshl_add_u64 v[178:179], s[52:53], 0, v[130:131]
	s_mov_b32 m0, s54
	s_nop 0
	global_load_lds_dwordx4 v[178:179], off
	v_lshl_add_u64 v[178:179], s[52:53], 0, v[128:129]
	s_add_i32 m0, s54, 0x2000
	s_nop 0
	global_load_lds_dwordx4 v[178:179], off
	v_lshl_add_u64 v[178:179], v[218:219], 0, s[12:13]
	s_mov_b32 m0, s64
	s_nop 0
	global_load_lds_dwordx4 v[178:179], off
	v_lshl_add_u64 v[178:179], v[220:221], 0, s[12:13]
	s_mov_b32 m0, s65
	s_nop 0
	global_load_lds_dwordx4 v[178:179], off
	s_waitcnt vmcnt(8)
	s_waitcnt lgkmcnt(0)
	s_barrier
	s_setprio 1
	s_waitcnt lgkmcnt(0)
	v_mfma_f32_16x16x32_bf16 v[60:63], v[140:143], v[184:187], v[60:63]
	v_mfma_f32_16x16x32_bf16 v[56:59], v[154:157], v[184:187], v[56:59]
	v_mfma_f32_16x16x32_bf16 v[44:47], v[140:143], v[192:195], v[44:47]
	v_mfma_f32_16x16x32_bf16 v[40:43], v[154:157], v[192:195], v[40:43]
	v_mfma_f32_16x16x32_bf16 v[28:31], v[140:143], v[200:203], v[28:31]
	v_mfma_f32_16x16x32_bf16 v[24:27], v[154:157], v[200:203], v[24:27]
	v_mfma_f32_16x16x32_bf16 v[12:15], v[140:143], v[208:211], v[12:15]
	v_mfma_f32_16x16x32_bf16 v[8:11], v[154:157], v[208:211], v[8:11]
	v_mfma_f32_16x16x32_bf16 v[60:63], v[150:153], v[188:191], v[60:63]
	v_mfma_f32_16x16x32_bf16 v[56:59], v[158:161], v[188:191], v[56:59]
	v_mfma_f32_16x16x32_bf16 v[44:47], v[150:153], v[196:199], v[44:47]
	v_mfma_f32_16x16x32_bf16 v[40:43], v[158:161], v[196:199], v[40:43]
	v_mfma_f32_16x16x32_bf16 v[28:31], v[150:153], v[204:207], v[28:31]
	v_mfma_f32_16x16x32_bf16 v[24:27], v[158:161], v[204:207], v[24:27]
	v_mfma_f32_16x16x32_bf16 v[12:15], v[150:153], v[212:215], v[12:15]
	v_mfma_f32_16x16x32_bf16 v[8:11], v[158:161], v[212:215], v[8:11]
	s_setprio 0
	s_setprio 1
	v_mfma_f32_16x16x32_bf16 v[52:55], v[162:165], v[184:187], v[52:55]
	v_mfma_f32_16x16x32_bf16 v[48:51], v[170:173], v[184:187], v[48:51]
	v_mfma_f32_16x16x32_bf16 v[36:39], v[162:165], v[192:195], v[36:39]
	v_mfma_f32_16x16x32_bf16 v[32:35], v[170:173], v[192:195], v[32:35]
	v_mfma_f32_16x16x32_bf16 v[20:23], v[162:165], v[200:203], v[20:23]
	v_mfma_f32_16x16x32_bf16 v[16:19], v[170:173], v[200:203], v[16:19]
	v_mfma_f32_16x16x32_bf16 v[4:7], v[162:165], v[208:211], v[4:7]
	v_mfma_f32_16x16x32_bf16 v[0:3], v[170:173], v[208:211], v[0:3]
	v_mfma_f32_16x16x32_bf16 v[52:55], v[166:169], v[188:191], v[52:55]
	v_mfma_f32_16x16x32_bf16 v[48:51], v[174:177], v[188:191], v[48:51]
	v_mfma_f32_16x16x32_bf16 v[36:39], v[166:169], v[196:199], v[36:39]
	v_mfma_f32_16x16x32_bf16 v[32:35], v[174:177], v[196:199], v[32:35]
	v_mfma_f32_16x16x32_bf16 v[20:23], v[166:169], v[204:207], v[20:23]
	v_mfma_f32_16x16x32_bf16 v[16:19], v[174:177], v[204:207], v[16:19]
	v_mfma_f32_16x16x32_bf16 v[4:7], v[166:169], v[212:215], v[4:7]
	v_mfma_f32_16x16x32_bf16 v[0:3], v[174:177], v[212:215], v[0:3]
	s_setprio 0
	s_barrier
	s_add_i32 s74, s74, 2
	s_add_u32 s48, s48, 0x100
	s_addc_u32 s49, s49, 0
	s_add_u32 s72, s72, 0x100
	s_addc_u32 s73, s73, 0
	s_cmp_gt_u32 s74, 13
	s_cbranch_scc0 .LBB0_724
	s_and_b64 vcc, exec, s[16:17]
	s_cbranch_vccz .LBB0_727
	s_barrier

.LBB0_803:
	s_add_u32 s84, s54, 0x100
	s_addc_u32 s85, s55, 0
	s_mov_b32 s86, -2
	ds_read_b128 v[152:155], v149
	ds_read_b128 v[156:159], v149 offset:1024
	ds_read_b128 v[160:163], v149 offset:2048
	ds_read_b128 v[164:167], v149 offset:3072
	ds_read_b128 v[168:171], v150
	ds_read_b128 v[172:175], v150 offset:1024
	ds_read_b128 v[176:179], v150 offset:2048
	ds_read_b128 v[184:187], v150 offset:3072
	s_add_u32 s54, s52, 0x100
	s_addc_u32 s55, s53, 0
	s_cmp_eq_u32 s86, 40
	s_cselect_b32 s59, s13, s55
	s_cselect_b32 s58, s12, s54
	s_cselect_b32 s57, s49, s85
	s_cselect_b32 s56, s48, s84
	v_lshl_add_u64 v[144:145], s[52:53], 0, v[136:137]
	s_add_i32 m0, s63, 0xc000
	ds_read_b128 v[188:191], v151
	ds_read_b128 v[192:195], v151 offset:1024
	ds_read_b128 v[196:199], v151 offset:2048
	ds_read_b128 v[200:203], v151 offset:3072
	ds_read_b128 v[204:207], v151 offset:4096
	ds_read_b128 v[208:211], v151 offset:5120
	ds_read_b128 v[212:215], v151 offset:6144
	ds_read_b128 v[216:219], v151 offset:7168
	global_load_lds_dwordx4 v[144:145], off
	v_lshl_add_u64 v[144:145], s[52:53], 0, v[138:139]
	s_add_i32 m0, s63, 0xe000
	s_nop 0
	global_load_lds_dwordx4 v[144:145], off
	s_waitcnt vmcnt(8)
	s_waitcnt lgkmcnt(0)
	s_barrier
	s_setprio 1
	s_waitcnt lgkmcnt(0)
	v_mfma_f32_16x16x32_bf16 v[124:127], v[152:155], v[188:191], 0
	v_mfma_f32_16x16x32_bf16 v[120:123], v[160:163], v[188:191], 0
	v_mfma_f32_16x16x32_bf16 v[116:119], v[152:155], v[196:199], 0
	v_mfma_f32_16x16x32_bf16 v[108:111], v[160:163], v[196:199], 0
	v_mfma_f32_16x16x32_bf16 v[100:103], v[152:155], v[204:207], 0
	v_mfma_f32_16x16x32_bf16 v[92:95], v[160:163], v[204:207], 0
	v_mfma_f32_16x16x32_bf16 v[84:87], v[152:155], v[212:215], 0
	v_mfma_f32_16x16x32_bf16 v[76:79], v[160:163], v[212:215], 0
	v_mfma_f32_16x16x32_bf16 v[124:127], v[156:159], v[192:195], v[124:127]
	v_mfma_f32_16x16x32_bf16 v[120:123], v[164:167], v[192:195], v[120:123]
	v_mfma_f32_16x16x32_bf16 v[116:119], v[156:159], v[200:203], v[116:119]
	v_mfma_f32_16x16x32_bf16 v[108:111], v[164:167], v[200:203], v[108:111]
	v_mfma_f32_16x16x32_bf16 v[100:103], v[156:159], v[208:211], v[100:103]
	v_mfma_f32_16x16x32_bf16 v[92:95], v[164:167], v[208:211], v[92:95]
	v_mfma_f32_16x16x32_bf16 v[84:87], v[156:159], v[216:219], v[84:87]
	v_mfma_f32_16x16x32_bf16 v[76:79], v[164:167], v[216:219], v[76:79]
	s_setprio 0
	s_setprio 1
	v_mfma_f32_16x16x32_bf16 v[112:115], v[168:171], v[188:191], 0
	v_mfma_f32_16x16x32_bf16 v[104:107], v[176:179], v[188:191], 0
	v_mfma_f32_16x16x32_bf16 v[96:99], v[168:171], v[196:199], 0
	v_mfma_f32_16x16x32_bf16 v[88:91], v[176:179], v[196:199], 0
	v_mfma_f32_16x16x32_bf16 v[80:83], v[168:171], v[204:207], 0
	v_mfma_f32_16x16x32_bf16 v[72:75], v[176:179], v[204:207], 0
	v_mfma_f32_16x16x32_bf16 v[68:71], v[168:171], v[212:215], 0
	v_mfma_f32_16x16x32_bf16 v[64:67], v[176:179], v[212:215], 0
	v_mfma_f32_16x16x32_bf16 v[112:115], v[172:175], v[192:195], v[112:115]
	v_mfma_f32_16x16x32_bf16 v[104:107], v[184:187], v[192:195], v[104:107]
	v_mfma_f32_16x16x32_bf16 v[96:99], v[172:175], v[200:203], v[96:99]
	v_mfma_f32_16x16x32_bf16 v[88:91], v[184:187], v[200:203], v[88:91]
	v_mfma_f32_16x16x32_bf16 v[80:83], v[172:175], v[208:211], v[80:83]
	v_mfma_f32_16x16x32_bf16 v[72:75], v[184:187], v[208:211], v[72:75]
	v_mfma_f32_16x16x32_bf16 v[68:71], v[172:175], v[216:219], v[68:71]
	v_mfma_f32_16x16x32_bf16 v[64:67], v[184:187], v[216:219], v[64:67]
	s_setprio 0
	s_barrier
	s_add_i32 s52, s70, s62
	v_lshl_add_u64 v[144:145], s[56:57], 0, v[130:131]
	s_mov_b32 m0, s52
	ds_read_b128 v[188:191], v151 offset:16384
	ds_read_b128 v[192:195], v151 offset:17408
	ds_read_b128 v[196:199], v151 offset:18432
	ds_read_b128 v[200:203], v151 offset:19456
	ds_read_b128 v[204:207], v151 offset:20480
	ds_read_b128 v[208:211], v151 offset:21504
	ds_read_b128 v[212:215], v151 offset:22528
	ds_read_b128 v[216:219], v151 offset:23552
	global_load_lds_dwordx4 v[144:145], off
	s_add_i32 m0, s52, 0x2000
	s_add_u32 s52, s56, 0xb0000
	v_lshl_add_u64 v[220:221], s[56:57], 0, v[134:135]
	s_addc_u32 s53, s57, 0
	s_add_i32 s79, s71, s62
	global_load_lds_dwordx4 v[220:221], off
	v_lshl_add_u64 v[222:223], s[52:53], 0, v[130:131]
	s_mov_b32 m0, s79
	v_lshl_add_u64 v[224:225], s[58:59], 0, v[132:133]
	global_load_lds_dwordx4 v[222:223], off
	v_lshl_add_u64 v[222:223], s[52:53], 0, v[134:135]
	s_add_i32 m0, s79, 0x2000
	s_nop 0
	global_load_lds_dwordx4 v[222:223], off
	v_lshl_add_u64 v[222:223], s[58:59], 0, v[128:129]
	s_mov_b32 m0, s63
	s_nop 0
	global_load_lds_dwordx4 v[222:223], off
	s_mov_b32 m0, s64
	s_nop 0
	global_load_lds_dwordx4 v[224:225], off
	s_waitcnt vmcnt(8)
	s_waitcnt lgkmcnt(0)
	s_barrier
	s_setprio 1
	s_waitcnt lgkmcnt(0)
	v_mfma_f32_16x16x32_bf16 v[60:63], v[152:155], v[188:191], 0
	v_mfma_f32_16x16x32_bf16 v[56:59], v[160:163], v[188:191], 0
	v_mfma_f32_16x16x32_bf16 v[52:55], v[152:155], v[196:199], 0
	v_mfma_f32_16x16x32_bf16 v[44:47], v[160:163], v[196:199], 0
	v_mfma_f32_16x16x32_bf16 v[36:39], v[152:155], v[204:207], 0
	v_mfma_f32_16x16x32_bf16 v[28:31], v[160:163], v[204:207], 0
	v_mfma_f32_16x16x32_bf16 v[20:23], v[152:155], v[212:215], 0
	v_mfma_f32_16x16x32_bf16 v[12:15], v[160:163], v[212:215], 0
	v_mfma_f32_16x16x32_bf16 v[60:63], v[156:159], v[192:195], v[60:63]
	v_mfma_f32_16x16x32_bf16 v[56:59], v[164:167], v[192:195], v[56:59]
	v_mfma_f32_16x16x32_bf16 v[52:55], v[156:159], v[200:203], v[52:55]
	v_mfma_f32_16x16x32_bf16 v[44:47], v[164:167], v[200:203], v[44:47]
	v_mfma_f32_16x16x32_bf16 v[36:39], v[156:159], v[208:211], v[36:39]
	v_mfma_f32_16x16x32_bf16 v[28:31], v[164:167], v[208:211], v[28:31]
	v_mfma_f32_16x16x32_bf16 v[20:23], v[156:159], v[216:219], v[20:23]
	v_mfma_f32_16x16x32_bf16 v[12:15], v[164:167], v[216:219], v[12:15]
	s_setprio 0
	s_setprio 1
	v_mfma_f32_16x16x32_bf16 v[48:51], v[168:171], v[188:191], 0
	v_mfma_f32_16x16x32_bf16 v[40:43], v[176:179], v[188:191], 0
	v_mfma_f32_16x16x32_bf16 v[32:35], v[168:171], v[196:199], 0
	v_mfma_f32_16x16x32_bf16 v[24:27], v[176:179], v[196:199], 0
	v_mfma_f32_16x16x32_bf16 v[16:19], v[168:171], v[204:207], 0
	v_mfma_f32_16x16x32_bf16 v[8:11], v[176:179], v[204:207], 0
	v_mfma_f32_16x16x32_bf16 v[4:7], v[168:171], v[212:215], 0
	v_mfma_f32_16x16x32_bf16 v[0:3], v[176:179], v[212:215], 0
	v_mfma_f32_16x16x32_bf16 v[48:51], v[172:175], v[192:195], v[48:51]
	v_mfma_f32_16x16x32_bf16 v[40:43], v[184:187], v[192:195], v[40:43]
	v_mfma_f32_16x16x32_bf16 v[32:35], v[172:175], v[200:203], v[32:35]
	v_mfma_f32_16x16x32_bf16 v[24:27], v[184:187], v[200:203], v[24:27]
	v_mfma_f32_16x16x32_bf16 v[16:19], v[172:175], v[208:211], v[16:19]
	v_mfma_f32_16x16x32_bf16 v[8:11], v[184:187], v[208:211], v[8:11]
	v_mfma_f32_16x16x32_bf16 v[4:7], v[172:175], v[216:219], v[4:7]
	v_mfma_f32_16x16x32_bf16 v[0:3], v[184:187], v[216:219], v[0:3]
	s_setprio 0
	s_barrier
	s_branch .Lmid_gemm5
.LBB0_804:
	ds_read_b128 v[152:155], v149
	ds_read_b128 v[156:159], v149 offset:1024
	ds_read_b128 v[160:163], v149 offset:2048
	ds_read_b128 v[164:167], v149 offset:3072
	ds_read_b128 v[168:171], v150
	ds_read_b128 v[172:175], v150 offset:1024
	ds_read_b128 v[176:179], v150 offset:2048
	ds_read_b128 v[184:187], v150 offset:3072
	s_add_u32 s54, s52, 0x100
	s_addc_u32 s55, s53, 0
	s_cmp_eq_u32 s86, 40
	s_cselect_b32 s59, s13, s55
	s_cselect_b32 s58, s12, s54
	s_cselect_b32 s57, s49, s85
	s_cselect_b32 s56, s48, s84
	v_lshl_add_u64 v[144:145], s[52:53], 0, v[136:137]
	s_add_i32 m0, s63, 0xc000
	ds_read_b128 v[188:191], v151
	ds_read_b128 v[192:195], v151 offset:1024
	ds_read_b128 v[196:199], v151 offset:2048
	ds_read_b128 v[200:203], v151 offset:3072
	ds_read_b128 v[204:207], v151 offset:4096
	ds_read_b128 v[208:211], v151 offset:5120
	ds_read_b128 v[212:215], v151 offset:6144
	ds_read_b128 v[216:219], v151 offset:7168
	global_load_lds_dwordx4 v[144:145], off
	v_lshl_add_u64 v[144:145], s[52:53], 0, v[138:139]
	s_add_i32 m0, s63, 0xe000
	s_nop 0
	global_load_lds_dwordx4 v[144:145], off
	s_waitcnt vmcnt(8)
	s_waitcnt lgkmcnt(0)
	s_barrier
	s_setprio 1
	s_waitcnt lgkmcnt(0)
	v_mfma_f32_16x16x32_bf16 v[124:127], v[152:155], v[188:191], v[124:127]
	v_mfma_f32_16x16x32_bf16 v[120:123], v[160:163], v[188:191], v[120:123]
	v_mfma_f32_16x16x32_bf16 v[116:119], v[152:155], v[196:199], v[116:119]
	v_mfma_f32_16x16x32_bf16 v[108:111], v[160:163], v[196:199], v[108:111]
	v_mfma_f32_16x16x32_bf16 v[100:103], v[152:155], v[204:207], v[100:103]
	v_mfma_f32_16x16x32_bf16 v[92:95], v[160:163], v[204:207], v[92:95]
	v_mfma_f32_16x16x32_bf16 v[84:87], v[152:155], v[212:215], v[84:87]
	v_mfma_f32_16x16x32_bf16 v[76:79], v[160:163], v[212:215], v[76:79]
	v_mfma_f32_16x16x32_bf16 v[124:127], v[156:159], v[192:195], v[124:127]
	v_mfma_f32_16x16x32_bf16 v[120:123], v[164:167], v[192:195], v[120:123]
	v_mfma_f32_16x16x32_bf16 v[116:119], v[156:159], v[200:203], v[116:119]
	v_mfma_f32_16x16x32_bf16 v[108:111], v[164:167], v[200:203], v[108:111]
	v_mfma_f32_16x16x32_bf16 v[100:103], v[156:159], v[208:211], v[100:103]
	v_mfma_f32_16x16x32_bf16 v[92:95], v[164:167], v[208:211], v[92:95]
	v_mfma_f32_16x16x32_bf16 v[84:87], v[156:159], v[216:219], v[84:87]
	v_mfma_f32_16x16x32_bf16 v[76:79], v[164:167], v[216:219], v[76:79]
	s_setprio 0
	s_setprio 1
	v_mfma_f32_16x16x32_bf16 v[112:115], v[168:171], v[188:191], v[112:115]
	v_mfma_f32_16x16x32_bf16 v[104:107], v[176:179], v[188:191], v[104:107]
	v_mfma_f32_16x16x32_bf16 v[96:99], v[168:171], v[196:199], v[96:99]
	v_mfma_f32_16x16x32_bf16 v[88:91], v[176:179], v[196:199], v[88:91]
	v_mfma_f32_16x16x32_bf16 v[80:83], v[168:171], v[204:207], v[80:83]
	v_mfma_f32_16x16x32_bf16 v[72:75], v[176:179], v[204:207], v[72:75]
	v_mfma_f32_16x16x32_bf16 v[68:71], v[168:171], v[212:215], v[68:71]
	v_mfma_f32_16x16x32_bf16 v[64:67], v[176:179], v[212:215], v[64:67]
	v_mfma_f32_16x16x32_bf16 v[112:115], v[172:175], v[192:195], v[112:115]
	v_mfma_f32_16x16x32_bf16 v[104:107], v[184:187], v[192:195], v[104:107]
	v_mfma_f32_16x16x32_bf16 v[96:99], v[172:175], v[200:203], v[96:99]
	v_mfma_f32_16x16x32_bf16 v[88:91], v[184:187], v[200:203], v[88:91]
	v_mfma_f32_16x16x32_bf16 v[80:83], v[172:175], v[208:211], v[80:83]
	v_mfma_f32_16x16x32_bf16 v[72:75], v[184:187], v[208:211], v[72:75]
	v_mfma_f32_16x16x32_bf16 v[68:71], v[172:175], v[216:219], v[68:71]
	v_mfma_f32_16x16x32_bf16 v[64:67], v[184:187], v[216:219], v[64:67]
	s_setprio 0
	s_barrier
	s_add_i32 s52, s70, s62
	v_lshl_add_u64 v[144:145], s[56:57], 0, v[130:131]
	s_mov_b32 m0, s52
	ds_read_b128 v[188:191], v151 offset:16384
	ds_read_b128 v[192:195], v151 offset:17408
	ds_read_b128 v[196:199], v151 offset:18432
	ds_read_b128 v[200:203], v151 offset:19456
	ds_read_b128 v[204:207], v151 offset:20480
	ds_read_b128 v[208:211], v151 offset:21504
	ds_read_b128 v[212:215], v151 offset:22528
	ds_read_b128 v[216:219], v151 offset:23552
	global_load_lds_dwordx4 v[144:145], off
	s_add_i32 m0, s52, 0x2000
	s_add_u32 s52, s56, 0xb0000
	v_lshl_add_u64 v[220:221], s[56:57], 0, v[134:135]
	s_addc_u32 s53, s57, 0
	s_add_i32 s79, s71, s62
	global_load_lds_dwordx4 v[220:221], off
	v_lshl_add_u64 v[222:223], s[52:53], 0, v[130:131]
	s_mov_b32 m0, s79
	v_lshl_add_u64 v[224:225], s[58:59], 0, v[132:133]
	global_load_lds_dwordx4 v[222:223], off
	v_lshl_add_u64 v[222:223], s[52:53], 0, v[134:135]
	s_add_i32 m0, s79, 0x2000
	s_nop 0
	global_load_lds_dwordx4 v[222:223], off
	v_lshl_add_u64 v[222:223], s[58:59], 0, v[128:129]
	s_mov_b32 m0, s63
	s_nop 0
	global_load_lds_dwordx4 v[222:223], off
	s_mov_b32 m0, s64
	s_nop 0
	global_load_lds_dwordx4 v[224:225], off
	s_waitcnt vmcnt(8)
	s_waitcnt lgkmcnt(0)
	s_barrier
	s_setprio 1
	s_waitcnt lgkmcnt(0)
	v_mfma_f32_16x16x32_bf16 v[60:63], v[152:155], v[188:191], v[60:63]
	v_mfma_f32_16x16x32_bf16 v[56:59], v[160:163], v[188:191], v[56:59]
	v_mfma_f32_16x16x32_bf16 v[52:55], v[152:155], v[196:199], v[52:55]
	v_mfma_f32_16x16x32_bf16 v[44:47], v[160:163], v[196:199], v[44:47]
	v_mfma_f32_16x16x32_bf16 v[36:39], v[152:155], v[204:207], v[36:39]
	v_mfma_f32_16x16x32_bf16 v[28:31], v[160:163], v[204:207], v[28:31]
	v_mfma_f32_16x16x32_bf16 v[20:23], v[152:155], v[212:215], v[20:23]
	v_mfma_f32_16x16x32_bf16 v[12:15], v[160:163], v[212:215], v[12:15]
	v_mfma_f32_16x16x32_bf16 v[60:63], v[156:159], v[192:195], v[60:63]
	v_mfma_f32_16x16x32_bf16 v[56:59], v[164:167], v[192:195], v[56:59]
	v_mfma_f32_16x16x32_bf16 v[52:55], v[156:159], v[200:203], v[52:55]
	v_mfma_f32_16x16x32_bf16 v[44:47], v[164:167], v[200:203], v[44:47]
	v_mfma_f32_16x16x32_bf16 v[36:39], v[156:159], v[208:211], v[36:39]
	v_mfma_f32_16x16x32_bf16 v[28:31], v[164:167], v[208:211], v[28:31]
	v_mfma_f32_16x16x32_bf16 v[20:23], v[156:159], v[216:219], v[20:23]
	v_mfma_f32_16x16x32_bf16 v[12:15], v[164:167], v[216:219], v[12:15]
	s_setprio 0
	s_setprio 1
	v_mfma_f32_16x16x32_bf16 v[48:51], v[168:171], v[188:191], v[48:51]
	v_mfma_f32_16x16x32_bf16 v[40:43], v[176:179], v[188:191], v[40:43]
	v_mfma_f32_16x16x32_bf16 v[32:35], v[168:171], v[196:199], v[32:35]
	v_mfma_f32_16x16x32_bf16 v[24:27], v[176:179], v[196:199], v[24:27]
	v_mfma_f32_16x16x32_bf16 v[16:19], v[168:171], v[204:207], v[16:19]
	v_mfma_f32_16x16x32_bf16 v[8:11], v[176:179], v[204:207], v[8:11]
	v_mfma_f32_16x16x32_bf16 v[4:7], v[168:171], v[212:215], v[4:7]
	v_mfma_f32_16x16x32_bf16 v[0:3], v[176:179], v[212:215], v[0:3]
	v_mfma_f32_16x16x32_bf16 v[48:51], v[172:175], v[192:195], v[48:51]
	v_mfma_f32_16x16x32_bf16 v[40:43], v[184:187], v[192:195], v[40:43]
	v_mfma_f32_16x16x32_bf16 v[32:35], v[172:175], v[200:203], v[32:35]
	v_mfma_f32_16x16x32_bf16 v[24:27], v[184:187], v[200:203], v[24:27]
	v_mfma_f32_16x16x32_bf16 v[16:19], v[172:175], v[208:211], v[16:19]
	v_mfma_f32_16x16x32_bf16 v[8:11], v[184:187], v[208:211], v[8:11]
	v_mfma_f32_16x16x32_bf16 v[4:7], v[172:175], v[216:219], v[4:7]
	v_mfma_f32_16x16x32_bf16 v[0:3], v[184:187], v[216:219], v[0:3]
	s_setprio 0
	s_barrier
.Lmid_gemm5:
	s_add_i32 s79, 0, 0x18000
	s_add_i32 s87, 0, 0x1c000
	v_add_u32_e32 v164, s79, v147
	v_add_u32_e32 v181, s87, v147
	ds_read_b128 v[152:155], v164
	ds_read_b128 v[156:159], v164 offset:1024
	ds_read_b128 v[160:163], v164 offset:2048
	ds_read_b128 v[164:167], v164 offset:3072
	ds_read_b128 v[168:171], v181
	ds_read_b128 v[172:175], v181 offset:1024
	ds_read_b128 v[176:179], v181 offset:2048
	ds_read_b128 v[184:187], v181 offset:3072
	s_add_u32 s52, s58, 0xb0000
	s_addc_u32 s53, s59, 0
	s_mov_b32 m0, s65
	v_lshl_add_u64 v[226:227], s[52:53], 0, v[128:129]
	ds_read_b128 v[188:191], v151 offset:32768
	ds_read_b128 v[192:195], v151 offset:33792
	ds_read_b128 v[196:199], v151 offset:34816
	ds_read_b128 v[200:203], v151 offset:35840
	ds_read_b128 v[204:207], v151 offset:36864
	ds_read_b128 v[208:211], v151 offset:37888
	ds_read_b128 v[212:215], v151 offset:38912
	ds_read_b128 v[216:219], v151 offset:39936
	global_load_lds_dwordx4 v[226:227], off
	v_lshl_add_u64 v[226:227], s[52:53], 0, v[132:133]
	s_mov_b32 m0, s66
	s_nop 0
	global_load_lds_dwordx4 v[226:227], off
	s_waitcnt vmcnt(8)
	s_waitcnt lgkmcnt(0)
	s_barrier
	s_setprio 1
	s_waitcnt lgkmcnt(0)
	v_mfma_f32_16x16x32_bf16 v[124:127], v[152:155], v[188:191], v[124:127]
	v_mfma_f32_16x16x32_bf16 v[120:123], v[160:163], v[188:191], v[120:123]
	v_mfma_f32_16x16x32_bf16 v[116:119], v[152:155], v[196:199], v[116:119]
	v_mfma_f32_16x16x32_bf16 v[108:111], v[160:163], v[196:199], v[108:111]
	v_mfma_f32_16x16x32_bf16 v[100:103], v[152:155], v[204:207], v[100:103]
	v_mfma_f32_16x16x32_bf16 v[92:95], v[160:163], v[204:207], v[92:95]
	v_mfma_f32_16x16x32_bf16 v[84:87], v[152:155], v[212:215], v[84:87]
	v_mfma_f32_16x16x32_bf16 v[76:79], v[160:163], v[212:215], v[76:79]
	v_mfma_f32_16x16x32_bf16 v[124:127], v[156:159], v[192:195], v[124:127]
	v_mfma_f32_16x16x32_bf16 v[120:123], v[164:167], v[192:195], v[120:123]
	v_mfma_f32_16x16x32_bf16 v[116:119], v[156:159], v[200:203], v[116:119]
	v_mfma_f32_16x16x32_bf16 v[108:111], v[164:167], v[200:203], v[108:111]
	v_mfma_f32_16x16x32_bf16 v[100:103], v[156:159], v[208:211], v[100:103]
	v_mfma_f32_16x16x32_bf16 v[92:95], v[164:167], v[208:211], v[92:95]
	v_mfma_f32_16x16x32_bf16 v[84:87], v[156:159], v[216:219], v[84:87]
	v_mfma_f32_16x16x32_bf16 v[76:79], v[164:167], v[216:219], v[76:79]
	s_setprio 0
	s_setprio 1
	v_mfma_f32_16x16x32_bf16 v[112:115], v[168:171], v[188:191], v[112:115]
	v_mfma_f32_16x16x32_bf16 v[104:107], v[176:179], v[188:191], v[104:107]
	v_mfma_f32_16x16x32_bf16 v[96:99], v[168:171], v[196:199], v[96:99]
	v_mfma_f32_16x16x32_bf16 v[88:91], v[176:179], v[196:199], v[88:91]
	v_mfma_f32_16x16x32_bf16 v[80:83], v[168:171], v[204:207], v[80:83]
	v_mfma_f32_16x16x32_bf16 v[72:75], v[176:179], v[204:207], v[72:75]
	v_mfma_f32_16x16x32_bf16 v[68:71], v[168:171], v[212:215], v[68:71]
	v_mfma_f32_16x16x32_bf16 v[64:67], v[176:179], v[212:215], v[64:67]
	v_mfma_f32_16x16x32_bf16 v[112:115], v[172:175], v[192:195], v[112:115]
	v_mfma_f32_16x16x32_bf16 v[104:107], v[184:187], v[192:195], v[104:107]
	v_mfma_f32_16x16x32_bf16 v[96:99], v[172:175], v[200:203], v[96:99]
	v_mfma_f32_16x16x32_bf16 v[88:91], v[184:187], v[200:203], v[88:91]
	v_mfma_f32_16x16x32_bf16 v[80:83], v[172:175], v[208:211], v[80:83]
	v_mfma_f32_16x16x32_bf16 v[72:75], v[184:187], v[208:211], v[72:75]
	v_mfma_f32_16x16x32_bf16 v[68:71], v[172:175], v[216:219], v[68:71]
	v_mfma_f32_16x16x32_bf16 v[64:67], v[184:187], v[216:219], v[64:67]
	s_setprio 0
	s_barrier
	s_add_i32 s52, s79, s62
	v_lshl_add_u64 v[144:145], v[144:145], 0, s[16:17]
	s_mov_b32 m0, s52
	ds_read_b128 v[188:191], v151 offset:49152
	ds_read_b128 v[192:195], v151 offset:50176
	ds_read_b128 v[196:199], v151 offset:51200
	ds_read_b128 v[200:203], v151 offset:52224
	ds_read_b128 v[204:207], v151 offset:53248
	ds_read_b128 v[208:211], v151 offset:54272
	ds_read_b128 v[212:215], v151 offset:55296
	ds_read_b128 v[216:219], v151 offset:56320
	global_load_lds_dwordx4 v[144:145], off
	s_add_i32 m0, s52, 0x2000
	s_add_u32 s52, s56, 0xb0080
	v_lshl_add_u64 v[144:145], v[220:221], 0, s[16:17]
	s_addc_u32 s53, s57, 0
	s_add_i32 s56, s87, s62
	global_load_lds_dwordx4 v[144:145], off
	v_lshl_add_u64 v[144:145], s[52:53], 0, v[130:131]
	s_mov_b32 m0, s56
	s_nop 0
	global_load_lds_dwordx4 v[144:145], off
	v_lshl_add_u64 v[144:145], s[52:53], 0, v[134:135]
	s_add_i32 m0, s56, 0x2000
	s_nop 0
	global_load_lds_dwordx4 v[144:145], off
	v_lshl_add_u64 v[144:145], v[222:223], 0, s[16:17]
	s_mov_b32 m0, s68
	s_nop 0
	global_load_lds_dwordx4 v[144:145], off
	v_lshl_add_u64 v[144:145], v[224:225], 0, s[16:17]
	s_mov_b32 m0, s69
	s_nop 0
	global_load_lds_dwordx4 v[144:145], off
	s_waitcnt vmcnt(8)
	s_waitcnt lgkmcnt(0)
	s_barrier
	s_setprio 1
	s_waitcnt lgkmcnt(0)
	v_mfma_f32_16x16x32_bf16 v[60:63], v[152:155], v[188:191], v[60:63]
	v_mfma_f32_16x16x32_bf16 v[56:59], v[160:163], v[188:191], v[56:59]
	v_mfma_f32_16x16x32_bf16 v[52:55], v[152:155], v[196:199], v[52:55]
	v_mfma_f32_16x16x32_bf16 v[44:47], v[160:163], v[196:199], v[44:47]
	v_mfma_f32_16x16x32_bf16 v[36:39], v[152:155], v[204:207], v[36:39]
	v_mfma_f32_16x16x32_bf16 v[28:31], v[160:163], v[204:207], v[28:31]
	v_mfma_f32_16x16x32_bf16 v[20:23], v[152:155], v[212:215], v[20:23]
	v_mfma_f32_16x16x32_bf16 v[12:15], v[160:163], v[212:215], v[12:15]
	v_mfma_f32_16x16x32_bf16 v[60:63], v[156:159], v[192:195], v[60:63]
	v_mfma_f32_16x16x32_bf16 v[56:59], v[164:167], v[192:195], v[56:59]
	v_mfma_f32_16x16x32_bf16 v[52:55], v[156:159], v[200:203], v[52:55]
	v_mfma_f32_16x16x32_bf16 v[44:47], v[164:167], v[200:203], v[44:47]
	v_mfma_f32_16x16x32_bf16 v[36:39], v[156:159], v[208:211], v[36:39]
	v_mfma_f32_16x16x32_bf16 v[28:31], v[164:167], v[208:211], v[28:31]
	v_mfma_f32_16x16x32_bf16 v[20:23], v[156:159], v[216:219], v[20:23]
	v_mfma_f32_16x16x32_bf16 v[12:15], v[164:167], v[216:219], v[12:15]
	s_setprio 0
	s_setprio 1
	v_mfma_f32_16x16x32_bf16 v[48:51], v[168:171], v[188:191], v[48:51]
	v_mfma_f32_16x16x32_bf16 v[40:43], v[176:179], v[188:191], v[40:43]
	v_mfma_f32_16x16x32_bf16 v[32:35], v[168:171], v[196:199], v[32:35]
	v_mfma_f32_16x16x32_bf16 v[24:27], v[176:179], v[196:199], v[24:27]
	v_mfma_f32_16x16x32_bf16 v[16:19], v[168:171], v[204:207], v[16:19]
	v_mfma_f32_16x16x32_bf16 v[8:11], v[176:179], v[204:207], v[8:11]
	v_mfma_f32_16x16x32_bf16 v[4:7], v[168:171], v[212:215], v[4:7]
	v_mfma_f32_16x16x32_bf16 v[0:3], v[176:179], v[212:215], v[0:3]
	v_mfma_f32_16x16x32_bf16 v[48:51], v[172:175], v[192:195], v[48:51]
	v_mfma_f32_16x16x32_bf16 v[40:43], v[184:187], v[192:195], v[40:43]
	v_mfma_f32_16x16x32_bf16 v[32:35], v[172:175], v[200:203], v[32:35]
	v_mfma_f32_16x16x32_bf16 v[24:27], v[184:187], v[200:203], v[24:27]
	v_mfma_f32_16x16x32_bf16 v[16:19], v[172:175], v[208:211], v[16:19]
	v_mfma_f32_16x16x32_bf16 v[8:11], v[184:187], v[208:211], v[8:11]
	v_mfma_f32_16x16x32_bf16 v[4:7], v[172:175], v[216:219], v[4:7]
	v_mfma_f32_16x16x32_bf16 v[0:3], v[184:187], v[216:219], v[0:3]
	s_setprio 0
	s_barrier
	s_add_i32 s86, s86, 2
	s_add_u32 s84, s84, 0x100
	s_addc_u32 s85, s85, 0
	s_cmp_gt_u32 s86, 41
	s_mov_b64 s[52:53], s[54:55]
	s_cbranch_scc0 .LBB0_804
	s_and_b64 vcc, exec, s[18:19]
	s_cbranch_vccz .LBB0_807
	s_barrier

.LBB0_934:
	s_ashr_i32 s53, s52, 31
	s_lshl_b64 s[54:55], s[52:53], 19
	s_add_u32 s54, s80, s54
	s_addc_u32 s55, s81, s55
	s_and_b64 s[56:57], s[10:11], exec
	s_cselect_b32 s53, s55, s61
	s_cselect_b32 s83, s54, s60
	s_ashr_i32 s49, s48, 31
	s_lshl_b64 s[56:57], s[48:49], 19
	s_add_u32 s56, s66, s56
	s_addc_u32 s57, s67, s57
	s_and_b64 s[64:65], s[10:11], exec
	s_cselect_b32 s49, s57, s63
	s_cselect_b32 s84, s56, s62
	s_add_u32 s60, s60, 0x40080
	s_addc_u32 s61, s61, 0
	s_add_u32 s85, s62, 0x100
	s_addc_u32 s86, s63, 0
	s_mov_b32 s87, -2
	ds_read_b128 v[152:155], v148
	ds_read_b128 v[156:159], v148 offset:1024
	ds_read_b128 v[160:163], v148 offset:2048
	ds_read_b128 v[164:167], v148 offset:3072
	ds_read_b128 v[168:171], v149
	ds_read_b128 v[172:175], v149 offset:1024
	ds_read_b128 v[176:179], v149 offset:2048
	ds_read_b128 v[184:187], v149 offset:3072
	s_add_u32 s62, s60, 0xfffc0080
	s_addc_u32 s63, s61, -1
	s_cmp_eq_u32 s87, 12
	s_cselect_b32 s65, s53, s63
	s_cselect_b32 s64, s83, s62
	s_cselect_b32 s63, s49, s86
	s_cselect_b32 s62, s84, s85
	v_lshl_add_u64 v[220:221], s[60:61], 0, v[138:139]
	s_add_i32 m0, s69, 0xc000
	ds_read_b128 v[188:191], v150
	ds_read_b128 v[192:195], v150 offset:1024
	ds_read_b128 v[196:199], v150 offset:2048
	ds_read_b128 v[200:203], v150 offset:3072
	ds_read_b128 v[204:207], v150 offset:4096
	ds_read_b128 v[208:211], v150 offset:5120
	ds_read_b128 v[212:215], v150 offset:6144
	ds_read_b128 v[216:219], v150 offset:7168
	global_load_lds_dwordx4 v[220:221], off
	v_lshl_add_u64 v[220:221], s[60:61], 0, v[140:141]
	s_add_i32 m0, s69, 0xe000
	s_nop 0
	global_load_lds_dwordx4 v[220:221], off
	s_waitcnt vmcnt(8)
	s_waitcnt lgkmcnt(0)
	s_barrier
	s_setprio 1
	s_waitcnt lgkmcnt(0)
	v_mfma_f32_16x16x32_bf16 v[124:127], v[152:155], v[188:191], 0
	v_mfma_f32_16x16x32_bf16 v[120:123], v[160:163], v[188:191], 0
	v_mfma_f32_16x16x32_bf16 v[116:119], v[152:155], v[196:199], 0
	v_mfma_f32_16x16x32_bf16 v[112:115], v[160:163], v[196:199], 0
	v_mfma_f32_16x16x32_bf16 v[108:111], v[152:155], v[204:207], 0
	v_mfma_f32_16x16x32_bf16 v[104:107], v[160:163], v[204:207], 0
	v_mfma_f32_16x16x32_bf16 v[100:103], v[152:155], v[212:215], 0
	v_mfma_f32_16x16x32_bf16 v[96:99], v[160:163], v[212:215], 0
	v_mfma_f32_16x16x32_bf16 v[124:127], v[156:159], v[192:195], v[124:127]
	v_mfma_f32_16x16x32_bf16 v[120:123], v[164:167], v[192:195], v[120:123]
	v_mfma_f32_16x16x32_bf16 v[116:119], v[156:159], v[200:203], v[116:119]
	v_mfma_f32_16x16x32_bf16 v[112:115], v[164:167], v[200:203], v[112:115]
	v_mfma_f32_16x16x32_bf16 v[108:111], v[156:159], v[208:211], v[108:111]
	v_mfma_f32_16x16x32_bf16 v[104:107], v[164:167], v[208:211], v[104:107]
	v_mfma_f32_16x16x32_bf16 v[100:103], v[156:159], v[216:219], v[100:103]
	v_mfma_f32_16x16x32_bf16 v[96:99], v[164:167], v[216:219], v[96:99]
	s_setprio 0
	s_setprio 1
	v_mfma_f32_16x16x32_bf16 v[76:79], v[168:171], v[188:191], 0
	v_mfma_f32_16x16x32_bf16 v[68:71], v[176:179], v[188:191], 0
	v_mfma_f32_16x16x32_bf16 v[60:63], v[168:171], v[196:199], 0
	v_mfma_f32_16x16x32_bf16 v[52:55], v[176:179], v[196:199], 0
	v_mfma_f32_16x16x32_bf16 v[44:47], v[168:171], v[204:207], 0
	v_mfma_f32_16x16x32_bf16 v[40:43], v[176:179], v[204:207], 0
	v_mfma_f32_16x16x32_bf16 v[36:39], v[168:171], v[212:215], 0
	v_mfma_f32_16x16x32_bf16 v[32:35], v[176:179], v[212:215], 0
	v_mfma_f32_16x16x32_bf16 v[76:79], v[172:175], v[192:195], v[76:79]
	v_mfma_f32_16x16x32_bf16 v[68:71], v[184:187], v[192:195], v[68:71]
	v_mfma_f32_16x16x32_bf16 v[60:63], v[172:175], v[200:203], v[60:63]
	v_mfma_f32_16x16x32_bf16 v[52:55], v[184:187], v[200:203], v[52:55]
	v_mfma_f32_16x16x32_bf16 v[44:47], v[172:175], v[208:211], v[44:47]
	v_mfma_f32_16x16x32_bf16 v[40:43], v[184:187], v[208:211], v[40:43]
	v_mfma_f32_16x16x32_bf16 v[36:39], v[172:175], v[216:219], v[36:39]
	v_mfma_f32_16x16x32_bf16 v[32:35], v[184:187], v[216:219], v[32:35]
	s_setprio 0
	s_barrier
	s_add_i32 s79, s77, s68
	v_lshl_add_u64 v[220:221], s[62:63], 0, v[130:131]
	s_mov_b32 m0, s79
	ds_read_b128 v[188:191], v150 offset:16384
	ds_read_b128 v[192:195], v150 offset:17408
	ds_read_b128 v[196:199], v150 offset:18432
	ds_read_b128 v[200:203], v150 offset:19456
	ds_read_b128 v[204:207], v150 offset:20480
	ds_read_b128 v[208:211], v150 offset:21504
	ds_read_b128 v[212:215], v150 offset:22528
	ds_read_b128 v[216:219], v150 offset:23552
	global_load_lds_dwordx4 v[220:221], off
	s_add_i32 m0, s79, 0x2000
	s_add_u32 s88, s62, 0x40000
	v_lshl_add_u64 v[222:223], s[62:63], 0, v[134:135]
	s_addc_u32 s89, s63, 0
	s_add_i32 s79, s82, s68
	global_load_lds_dwordx4 v[222:223], off
	v_lshl_add_u64 v[224:225], s[88:89], 0, v[130:131]
	s_mov_b32 m0, s79
	v_lshl_add_u64 v[226:227], s[64:65], 0, v[132:133]
	global_load_lds_dwordx4 v[224:225], off
	v_lshl_add_u64 v[224:225], s[88:89], 0, v[134:135]
	s_add_i32 m0, s79, 0x2000
	s_nop 0
	global_load_lds_dwordx4 v[224:225], off
	v_lshl_add_u64 v[224:225], s[64:65], 0, v[128:129]
	s_mov_b32 m0, s69
	s_nop 0
	global_load_lds_dwordx4 v[224:225], off
	s_mov_b32 m0, s70
	s_nop 0
	global_load_lds_dwordx4 v[226:227], off
	s_waitcnt vmcnt(8)
	s_waitcnt lgkmcnt(0)
	s_barrier
	s_setprio 1
	s_waitcnt lgkmcnt(0)
	v_mfma_f32_16x16x32_bf16 v[92:95], v[152:155], v[188:191], 0
	v_mfma_f32_16x16x32_bf16 v[88:91], v[160:163], v[188:191], 0
	v_mfma_f32_16x16x32_bf16 v[84:87], v[152:155], v[196:199], 0
	v_mfma_f32_16x16x32_bf16 v[80:83], v[160:163], v[196:199], 0
	v_mfma_f32_16x16x32_bf16 v[72:75], v[152:155], v[204:207], 0
	v_mfma_f32_16x16x32_bf16 v[64:67], v[160:163], v[204:207], 0
	v_mfma_f32_16x16x32_bf16 v[56:59], v[152:155], v[212:215], 0
	v_mfma_f32_16x16x32_bf16 v[48:51], v[160:163], v[212:215], 0
	v_mfma_f32_16x16x32_bf16 v[92:95], v[156:159], v[192:195], v[92:95]
	v_mfma_f32_16x16x32_bf16 v[88:91], v[164:167], v[192:195], v[88:91]
	v_mfma_f32_16x16x32_bf16 v[84:87], v[156:159], v[200:203], v[84:87]
	v_mfma_f32_16x16x32_bf16 v[80:83], v[164:167], v[200:203], v[80:83]
	v_mfma_f32_16x16x32_bf16 v[72:75], v[156:159], v[208:211], v[72:75]
	v_mfma_f32_16x16x32_bf16 v[64:67], v[164:167], v[208:211], v[64:67]
	v_mfma_f32_16x16x32_bf16 v[56:59], v[156:159], v[216:219], v[56:59]
	v_mfma_f32_16x16x32_bf16 v[48:51], v[164:167], v[216:219], v[48:51]
	s_setprio 0
	s_setprio 1
	v_mfma_f32_16x16x32_bf16 v[28:31], v[168:171], v[188:191], 0
	v_mfma_f32_16x16x32_bf16 v[24:27], v[176:179], v[188:191], 0
	v_mfma_f32_16x16x32_bf16 v[20:23], v[168:171], v[196:199], 0
	v_mfma_f32_16x16x32_bf16 v[16:19], v[176:179], v[196:199], 0
	v_mfma_f32_16x16x32_bf16 v[12:15], v[168:171], v[204:207], 0
	v_mfma_f32_16x16x32_bf16 v[8:11], v[176:179], v[204:207], 0
	v_mfma_f32_16x16x32_bf16 v[4:7], v[168:171], v[212:215], 0
	v_mfma_f32_16x16x32_bf16 v[0:3], v[176:179], v[212:215], 0
	v_mfma_f32_16x16x32_bf16 v[28:31], v[172:175], v[192:195], v[28:31]
	v_mfma_f32_16x16x32_bf16 v[24:27], v[184:187], v[192:195], v[24:27]
	v_mfma_f32_16x16x32_bf16 v[20:23], v[172:175], v[200:203], v[20:23]
	v_mfma_f32_16x16x32_bf16 v[16:19], v[184:187], v[200:203], v[16:19]
	v_mfma_f32_16x16x32_bf16 v[12:15], v[172:175], v[208:211], v[12:15]
	v_mfma_f32_16x16x32_bf16 v[8:11], v[184:187], v[208:211], v[8:11]
	v_mfma_f32_16x16x32_bf16 v[4:7], v[172:175], v[216:219], v[4:7]
	v_mfma_f32_16x16x32_bf16 v[0:3], v[184:187], v[216:219], v[0:3]
	s_setprio 0
	s_barrier
	s_branch .Lmid_gemm6
.LBB0_935:
	ds_read_b128 v[152:155], v148
	ds_read_b128 v[156:159], v148 offset:1024
	ds_read_b128 v[160:163], v148 offset:2048
	ds_read_b128 v[164:167], v148 offset:3072
	ds_read_b128 v[168:171], v149
	ds_read_b128 v[172:175], v149 offset:1024
	ds_read_b128 v[176:179], v149 offset:2048
	ds_read_b128 v[184:187], v149 offset:3072
	s_add_u32 s62, s60, 0xfffc0080
	s_addc_u32 s63, s61, -1
	s_cmp_eq_u32 s87, 12
	s_cselect_b32 s65, s53, s63
	s_cselect_b32 s64, s83, s62
	s_cselect_b32 s63, s49, s86
	s_cselect_b32 s62, s84, s85
	v_lshl_add_u64 v[220:221], s[60:61], 0, v[138:139]
	s_add_i32 m0, s69, 0xc000
	ds_read_b128 v[188:191], v150
	ds_read_b128 v[192:195], v150 offset:1024
	ds_read_b128 v[196:199], v150 offset:2048
	ds_read_b128 v[200:203], v150 offset:3072
	ds_read_b128 v[204:207], v150 offset:4096
	ds_read_b128 v[208:211], v150 offset:5120
	ds_read_b128 v[212:215], v150 offset:6144
	ds_read_b128 v[216:219], v150 offset:7168
	global_load_lds_dwordx4 v[220:221], off
	v_lshl_add_u64 v[220:221], s[60:61], 0, v[140:141]
	s_add_i32 m0, s69, 0xe000
	s_nop 0
	global_load_lds_dwordx4 v[220:221], off
	s_waitcnt vmcnt(8)
	s_waitcnt lgkmcnt(0)
	s_barrier
	s_setprio 1
	s_waitcnt lgkmcnt(0)
	v_mfma_f32_16x16x32_bf16 v[124:127], v[152:155], v[188:191], v[124:127]
	v_mfma_f32_16x16x32_bf16 v[120:123], v[160:163], v[188:191], v[120:123]
	v_mfma_f32_16x16x32_bf16 v[116:119], v[152:155], v[196:199], v[116:119]
	v_mfma_f32_16x16x32_bf16 v[112:115], v[160:163], v[196:199], v[112:115]
	v_mfma_f32_16x16x32_bf16 v[108:111], v[152:155], v[204:207], v[108:111]
	v_mfma_f32_16x16x32_bf16 v[104:107], v[160:163], v[204:207], v[104:107]
	v_mfma_f32_16x16x32_bf16 v[100:103], v[152:155], v[212:215], v[100:103]
	v_mfma_f32_16x16x32_bf16 v[96:99], v[160:163], v[212:215], v[96:99]
	v_mfma_f32_16x16x32_bf16 v[124:127], v[156:159], v[192:195], v[124:127]
	v_mfma_f32_16x16x32_bf16 v[120:123], v[164:167], v[192:195], v[120:123]
	v_mfma_f32_16x16x32_bf16 v[116:119], v[156:159], v[200:203], v[116:119]
	v_mfma_f32_16x16x32_bf16 v[112:115], v[164:167], v[200:203], v[112:115]
	v_mfma_f32_16x16x32_bf16 v[108:111], v[156:159], v[208:211], v[108:111]
	v_mfma_f32_16x16x32_bf16 v[104:107], v[164:167], v[208:211], v[104:107]
	v_mfma_f32_16x16x32_bf16 v[100:103], v[156:159], v[216:219], v[100:103]
	v_mfma_f32_16x16x32_bf16 v[96:99], v[164:167], v[216:219], v[96:99]
	s_setprio 0
	s_setprio 1
	v_mfma_f32_16x16x32_bf16 v[76:79], v[168:171], v[188:191], v[76:79]
	v_mfma_f32_16x16x32_bf16 v[68:71], v[176:179], v[188:191], v[68:71]
	v_mfma_f32_16x16x32_bf16 v[60:63], v[168:171], v[196:199], v[60:63]
	v_mfma_f32_16x16x32_bf16 v[52:55], v[176:179], v[196:199], v[52:55]
	v_mfma_f32_16x16x32_bf16 v[44:47], v[168:171], v[204:207], v[44:47]
	v_mfma_f32_16x16x32_bf16 v[40:43], v[176:179], v[204:207], v[40:43]
	v_mfma_f32_16x16x32_bf16 v[36:39], v[168:171], v[212:215], v[36:39]
	v_mfma_f32_16x16x32_bf16 v[32:35], v[176:179], v[212:215], v[32:35]
	v_mfma_f32_16x16x32_bf16 v[76:79], v[172:175], v[192:195], v[76:79]
	v_mfma_f32_16x16x32_bf16 v[68:71], v[184:187], v[192:195], v[68:71]
	v_mfma_f32_16x16x32_bf16 v[60:63], v[172:175], v[200:203], v[60:63]
	v_mfma_f32_16x16x32_bf16 v[52:55], v[184:187], v[200:203], v[52:55]
	v_mfma_f32_16x16x32_bf16 v[44:47], v[172:175], v[208:211], v[44:47]
	v_mfma_f32_16x16x32_bf16 v[40:43], v[184:187], v[208:211], v[40:43]
	v_mfma_f32_16x16x32_bf16 v[36:39], v[172:175], v[216:219], v[36:39]
	v_mfma_f32_16x16x32_bf16 v[32:35], v[184:187], v[216:219], v[32:35]
	s_setprio 0
	s_barrier
	s_add_i32 s79, s77, s68
	v_lshl_add_u64 v[220:221], s[62:63], 0, v[130:131]
	s_mov_b32 m0, s79
	ds_read_b128 v[188:191], v150 offset:16384
	ds_read_b128 v[192:195], v150 offset:17408
	ds_read_b128 v[196:199], v150 offset:18432
	ds_read_b128 v[200:203], v150 offset:19456
	ds_read_b128 v[204:207], v150 offset:20480
	ds_read_b128 v[208:211], v150 offset:21504
	ds_read_b128 v[212:215], v150 offset:22528
	ds_read_b128 v[216:219], v150 offset:23552
	global_load_lds_dwordx4 v[220:221], off
	s_add_i32 m0, s79, 0x2000
	s_add_u32 s88, s62, 0x40000
	v_lshl_add_u64 v[222:223], s[62:63], 0, v[134:135]
	s_addc_u32 s89, s63, 0
	s_add_i32 s79, s82, s68
	global_load_lds_dwordx4 v[222:223], off
	v_lshl_add_u64 v[224:225], s[88:89], 0, v[130:131]
	s_mov_b32 m0, s79
	v_lshl_add_u64 v[226:227], s[64:65], 0, v[132:133]
	global_load_lds_dwordx4 v[224:225], off
	v_lshl_add_u64 v[224:225], s[88:89], 0, v[134:135]
	s_add_i32 m0, s79, 0x2000
	s_nop 0
	global_load_lds_dwordx4 v[224:225], off
	v_lshl_add_u64 v[224:225], s[64:65], 0, v[128:129]
	s_mov_b32 m0, s69
	s_nop 0
	global_load_lds_dwordx4 v[224:225], off
	s_mov_b32 m0, s70
	s_nop 0
	global_load_lds_dwordx4 v[226:227], off
	s_waitcnt vmcnt(8)
	s_waitcnt lgkmcnt(0)
	s_barrier
	s_setprio 1
	s_waitcnt lgkmcnt(0)
	v_mfma_f32_16x16x32_bf16 v[92:95], v[152:155], v[188:191], v[92:95]
	v_mfma_f32_16x16x32_bf16 v[88:91], v[160:163], v[188:191], v[88:91]
	v_mfma_f32_16x16x32_bf16 v[84:87], v[152:155], v[196:199], v[84:87]
	v_mfma_f32_16x16x32_bf16 v[80:83], v[160:163], v[196:199], v[80:83]
	v_mfma_f32_16x16x32_bf16 v[72:75], v[152:155], v[204:207], v[72:75]
	v_mfma_f32_16x16x32_bf16 v[64:67], v[160:163], v[204:207], v[64:67]
	v_mfma_f32_16x16x32_bf16 v[56:59], v[152:155], v[212:215], v[56:59]
	v_mfma_f32_16x16x32_bf16 v[48:51], v[160:163], v[212:215], v[48:51]
	v_mfma_f32_16x16x32_bf16 v[92:95], v[156:159], v[192:195], v[92:95]
	v_mfma_f32_16x16x32_bf16 v[88:91], v[164:167], v[192:195], v[88:91]
	v_mfma_f32_16x16x32_bf16 v[84:87], v[156:159], v[200:203], v[84:87]
	v_mfma_f32_16x16x32_bf16 v[80:83], v[164:167], v[200:203], v[80:83]
	v_mfma_f32_16x16x32_bf16 v[72:75], v[156:159], v[208:211], v[72:75]
	v_mfma_f32_16x16x32_bf16 v[64:67], v[164:167], v[208:211], v[64:67]
	v_mfma_f32_16x16x32_bf16 v[56:59], v[156:159], v[216:219], v[56:59]
	v_mfma_f32_16x16x32_bf16 v[48:51], v[164:167], v[216:219], v[48:51]
	s_setprio 0
	s_setprio 1
	v_mfma_f32_16x16x32_bf16 v[28:31], v[168:171], v[188:191], v[28:31]
	v_mfma_f32_16x16x32_bf16 v[24:27], v[176:179], v[188:191], v[24:27]
	v_mfma_f32_16x16x32_bf16 v[20:23], v[168:171], v[196:199], v[20:23]
	v_mfma_f32_16x16x32_bf16 v[16:19], v[176:179], v[196:199], v[16:19]
	v_mfma_f32_16x16x32_bf16 v[12:15], v[168:171], v[204:207], v[12:15]
	v_mfma_f32_16x16x32_bf16 v[8:11], v[176:179], v[204:207], v[8:11]
	v_mfma_f32_16x16x32_bf16 v[4:7], v[168:171], v[212:215], v[4:7]
	v_mfma_f32_16x16x32_bf16 v[0:3], v[176:179], v[212:215], v[0:3]
	v_mfma_f32_16x16x32_bf16 v[28:31], v[172:175], v[192:195], v[28:31]
	v_mfma_f32_16x16x32_bf16 v[24:27], v[184:187], v[192:195], v[24:27]
	v_mfma_f32_16x16x32_bf16 v[20:23], v[172:175], v[200:203], v[20:23]
	v_mfma_f32_16x16x32_bf16 v[16:19], v[184:187], v[200:203], v[16:19]
	v_mfma_f32_16x16x32_bf16 v[12:15], v[172:175], v[208:211], v[12:15]
	v_mfma_f32_16x16x32_bf16 v[8:11], v[184:187], v[208:211], v[8:11]
	v_mfma_f32_16x16x32_bf16 v[4:7], v[172:175], v[216:219], v[4:7]
	v_mfma_f32_16x16x32_bf16 v[0:3], v[184:187], v[216:219], v[0:3]
	s_setprio 0
	s_barrier
.Lmid_gemm6:
	s_add_i32 s79, 0, 0x18000
	v_add_u32_e32 v151, s79, v147
	s_add_i32 s88, 0, 0x1c000
	ds_read_b128 v[152:155], v151
	ds_read_b128 v[156:159], v151 offset:1024
	ds_read_b128 v[160:163], v151 offset:2048
	ds_read_b128 v[164:167], v151 offset:3072
	v_add_u32_e32 v151, s88, v147
	ds_read_b128 v[168:171], v151
	ds_read_b128 v[172:175], v151 offset:1024
	ds_read_b128 v[176:179], v151 offset:2048
	ds_read_b128 v[184:187], v151 offset:3072
	s_add_u32 s64, s64, 0x40000
	s_addc_u32 s65, s65, 0
	s_mov_b32 m0, s71
	v_lshl_add_u64 v[228:229], s[64:65], 0, v[128:129]
	ds_read_b128 v[188:191], v150 offset:32768
	ds_read_b128 v[192:195], v150 offset:33792
	ds_read_b128 v[196:199], v150 offset:34816
	ds_read_b128 v[200:203], v150 offset:35840
	ds_read_b128 v[204:207], v150 offset:36864
	ds_read_b128 v[208:211], v150 offset:37888
	ds_read_b128 v[212:215], v150 offset:38912
	ds_read_b128 v[216:219], v150 offset:39936
	global_load_lds_dwordx4 v[228:229], off
	v_lshl_add_u64 v[228:229], s[64:65], 0, v[132:133]
	s_mov_b32 m0, s72
	s_nop 0
	global_load_lds_dwordx4 v[228:229], off
	s_waitcnt vmcnt(8)
	s_waitcnt lgkmcnt(0)
	s_barrier
	s_setprio 1
	s_waitcnt lgkmcnt(0)
	v_mfma_f32_16x16x32_bf16 v[124:127], v[152:155], v[188:191], v[124:127]
	v_mfma_f32_16x16x32_bf16 v[120:123], v[160:163], v[188:191], v[120:123]
	v_mfma_f32_16x16x32_bf16 v[116:119], v[152:155], v[196:199], v[116:119]
	v_mfma_f32_16x16x32_bf16 v[112:115], v[160:163], v[196:199], v[112:115]
	v_mfma_f32_16x16x32_bf16 v[108:111], v[152:155], v[204:207], v[108:111]
	v_mfma_f32_16x16x32_bf16 v[104:107], v[160:163], v[204:207], v[104:107]
	v_mfma_f32_16x16x32_bf16 v[100:103], v[152:155], v[212:215], v[100:103]
	v_mfma_f32_16x16x32_bf16 v[96:99], v[160:163], v[212:215], v[96:99]
	v_mfma_f32_16x16x32_bf16 v[124:127], v[156:159], v[192:195], v[124:127]
	v_mfma_f32_16x16x32_bf16 v[120:123], v[164:167], v[192:195], v[120:123]
	v_mfma_f32_16x16x32_bf16 v[116:119], v[156:159], v[200:203], v[116:119]
	v_mfma_f32_16x16x32_bf16 v[112:115], v[164:167], v[200:203], v[112:115]
	v_mfma_f32_16x16x32_bf16 v[108:111], v[156:159], v[208:211], v[108:111]
	v_mfma_f32_16x16x32_bf16 v[104:107], v[164:167], v[208:211], v[104:107]
	v_mfma_f32_16x16x32_bf16 v[100:103], v[156:159], v[216:219], v[100:103]
	v_mfma_f32_16x16x32_bf16 v[96:99], v[164:167], v[216:219], v[96:99]
	s_setprio 0
	s_setprio 1
	v_mfma_f32_16x16x32_bf16 v[76:79], v[168:171], v[188:191], v[76:79]
	v_mfma_f32_16x16x32_bf16 v[68:71], v[176:179], v[188:191], v[68:71]
	v_mfma_f32_16x16x32_bf16 v[60:63], v[168:171], v[196:199], v[60:63]
	v_mfma_f32_16x16x32_bf16 v[52:55], v[176:179], v[196:199], v[52:55]
	v_mfma_f32_16x16x32_bf16 v[44:47], v[168:171], v[204:207], v[44:47]
	v_mfma_f32_16x16x32_bf16 v[40:43], v[176:179], v[204:207], v[40:43]
	v_mfma_f32_16x16x32_bf16 v[36:39], v[168:171], v[212:215], v[36:39]
	v_mfma_f32_16x16x32_bf16 v[32:35], v[176:179], v[212:215], v[32:35]
	v_mfma_f32_16x16x32_bf16 v[76:79], v[172:175], v[192:195], v[76:79]
	v_mfma_f32_16x16x32_bf16 v[68:71], v[184:187], v[192:195], v[68:71]
	v_mfma_f32_16x16x32_bf16 v[60:63], v[172:175], v[200:203], v[60:63]
	v_mfma_f32_16x16x32_bf16 v[52:55], v[184:187], v[200:203], v[52:55]
	v_mfma_f32_16x16x32_bf16 v[44:47], v[172:175], v[208:211], v[44:47]
	v_mfma_f32_16x16x32_bf16 v[40:43], v[184:187], v[208:211], v[40:43]
	v_mfma_f32_16x16x32_bf16 v[36:39], v[172:175], v[216:219], v[36:39]
	v_mfma_f32_16x16x32_bf16 v[32:35], v[184:187], v[216:219], v[32:35]
	s_setprio 0
	s_barrier
	s_add_i32 s64, s79, s68
	v_lshl_add_u64 v[220:221], v[220:221], 0, s[12:13]
	s_mov_b32 m0, s64
	ds_read_b128 v[188:191], v150 offset:49152
	ds_read_b128 v[192:195], v150 offset:50176
	ds_read_b128 v[196:199], v150 offset:51200
	ds_read_b128 v[200:203], v150 offset:52224
	ds_read_b128 v[204:207], v150 offset:53248
	ds_read_b128 v[208:211], v150 offset:54272
	ds_read_b128 v[212:215], v150 offset:55296
	ds_read_b128 v[216:219], v150 offset:56320
	global_load_lds_dwordx4 v[220:221], off
	s_add_i32 m0, s64, 0x2000
	s_add_u32 s62, s62, 0x40080
	v_lshl_add_u64 v[220:221], v[222:223], 0, s[12:13]
	s_addc_u32 s63, s63, 0
	s_add_i32 s64, s88, s68
	global_load_lds_dwordx4 v[220:221], off
	v_lshl_add_u64 v[220:221], s[62:63], 0, v[130:131]
	s_mov_b32 m0, s64
	s_nop 0
	global_load_lds_dwordx4 v[220:221], off
	v_lshl_add_u64 v[220:221], s[62:63], 0, v[134:135]
	s_add_i32 m0, s64, 0x2000
	s_nop 0
	global_load_lds_dwordx4 v[220:221], off
	v_lshl_add_u64 v[220:221], v[224:225], 0, s[12:13]
	s_mov_b32 m0, s75
	s_nop 0
	global_load_lds_dwordx4 v[220:221], off
	v_lshl_add_u64 v[220:221], v[226:227], 0, s[12:13]
	s_mov_b32 m0, s76
	s_nop 0
	global_load_lds_dwordx4 v[220:221], off
	s_waitcnt vmcnt(8)
	s_waitcnt lgkmcnt(0)
	s_barrier
	s_setprio 1
	s_waitcnt lgkmcnt(0)
	v_mfma_f32_16x16x32_bf16 v[92:95], v[152:155], v[188:191], v[92:95]
	v_mfma_f32_16x16x32_bf16 v[88:91], v[160:163], v[188:191], v[88:91]
	v_mfma_f32_16x16x32_bf16 v[84:87], v[152:155], v[196:199], v[84:87]
	v_mfma_f32_16x16x32_bf16 v[80:83], v[160:163], v[196:199], v[80:83]
	v_mfma_f32_16x16x32_bf16 v[72:75], v[152:155], v[204:207], v[72:75]
	v_mfma_f32_16x16x32_bf16 v[64:67], v[160:163], v[204:207], v[64:67]
	v_mfma_f32_16x16x32_bf16 v[56:59], v[152:155], v[212:215], v[56:59]
	v_mfma_f32_16x16x32_bf16 v[48:51], v[160:163], v[212:215], v[48:51]
	v_mfma_f32_16x16x32_bf16 v[92:95], v[156:159], v[192:195], v[92:95]
	v_mfma_f32_16x16x32_bf16 v[88:91], v[164:167], v[192:195], v[88:91]
	v_mfma_f32_16x16x32_bf16 v[84:87], v[156:159], v[200:203], v[84:87]
	v_mfma_f32_16x16x32_bf16 v[80:83], v[164:167], v[200:203], v[80:83]
	v_mfma_f32_16x16x32_bf16 v[72:75], v[156:159], v[208:211], v[72:75]
	v_mfma_f32_16x16x32_bf16 v[64:67], v[164:167], v[208:211], v[64:67]
	v_mfma_f32_16x16x32_bf16 v[56:59], v[156:159], v[216:219], v[56:59]
	v_mfma_f32_16x16x32_bf16 v[48:51], v[164:167], v[216:219], v[48:51]
	s_setprio 0
	s_setprio 1
	v_mfma_f32_16x16x32_bf16 v[28:31], v[168:171], v[188:191], v[28:31]
	v_mfma_f32_16x16x32_bf16 v[24:27], v[176:179], v[188:191], v[24:27]
	v_mfma_f32_16x16x32_bf16 v[20:23], v[168:171], v[196:199], v[20:23]
	v_mfma_f32_16x16x32_bf16 v[16:19], v[176:179], v[196:199], v[16:19]
	v_mfma_f32_16x16x32_bf16 v[12:15], v[168:171], v[204:207], v[12:15]
	v_mfma_f32_16x16x32_bf16 v[8:11], v[176:179], v[204:207], v[8:11]
	v_mfma_f32_16x16x32_bf16 v[4:7], v[168:171], v[212:215], v[4:7]
	v_mfma_f32_16x16x32_bf16 v[0:3], v[176:179], v[212:215], v[0:3]
	v_mfma_f32_16x16x32_bf16 v[28:31], v[172:175], v[192:195], v[28:31]
	v_mfma_f32_16x16x32_bf16 v[24:27], v[184:187], v[192:195], v[24:27]
	v_mfma_f32_16x16x32_bf16 v[20:23], v[172:175], v[200:203], v[20:23]
	v_mfma_f32_16x16x32_bf16 v[16:19], v[184:187], v[200:203], v[16:19]
	v_mfma_f32_16x16x32_bf16 v[12:15], v[172:175], v[208:211], v[12:15]
	v_mfma_f32_16x16x32_bf16 v[8:11], v[184:187], v[208:211], v[8:11]
	v_mfma_f32_16x16x32_bf16 v[4:7], v[172:175], v[216:219], v[4:7]
	v_mfma_f32_16x16x32_bf16 v[0:3], v[184:187], v[216:219], v[0:3]
	s_setprio 0
	s_barrier
	s_add_i32 s87, s87, 2
	s_add_u32 s60, s60, 0x100
	s_addc_u32 s61, s61, 0
	s_add_u32 s85, s85, 0x100
	s_addc_u32 s86, s86, 0
	s_cmp_gt_u32 s87, 13
	s_cbranch_scc0 .LBB0_935
	s_and_b64 vcc, exec, s[16:17]
	s_cbranch_vccz .LBB0_938
	s_barrier

.LBB0_950:
	s_ashr_i32 s37, s36, 31
	s_lshl_b64 s[44:45], s[36:37], 19
	s_add_u32 s44, s80, s44
	s_addc_u32 s45, s81, s45
	s_and_b64 s[46:47], s[10:11], exec
	s_cselect_b32 s37, s45, s53
	s_cselect_b32 s72, s44, s52
	s_ashr_i32 s19, s18, 31
	s_lshl_b64 s[46:47], s[18:19], 19
	s_add_u32 s46, s58, s46
	s_addc_u32 s47, s59, s47
	s_and_b64 s[56:57], s[10:11], exec
	s_cselect_b32 s19, s47, s55
	s_cselect_b32 s73, s46, s54
	s_add_u32 s52, s52, 0x40080
	s_addc_u32 s53, s53, 0
	s_add_u32 s74, s54, 0x100
	s_addc_u32 s75, s55, 0
	s_mov_b32 s76, -2
	ds_read_b128 v[140:143], v147
	ds_read_b128 v[150:153], v147 offset:1024
	ds_read_b128 v[154:157], v147 offset:2048
	ds_read_b128 v[158:161], v147 offset:3072
	ds_read_b128 v[162:165], v148
	ds_read_b128 v[166:169], v148 offset:1024
	ds_read_b128 v[170:173], v148 offset:2048
	ds_read_b128 v[174:177], v148 offset:3072
	s_add_u32 s54, s52, 0xfffc0080
	s_addc_u32 s55, s53, -1
	s_cmp_eq_u32 s76, 12
	s_cselect_b32 s57, s37, s55
	s_cselect_b32 s56, s72, s54
	s_cselect_b32 s55, s19, s75
	s_cselect_b32 s54, s73, s74
	v_lshl_add_u64 v[178:179], s[52:53], 0, v[132:133]
	s_add_i32 m0, s49, 0xc000
	ds_read_b128 v[184:187], v149
	ds_read_b128 v[188:191], v149 offset:1024
	ds_read_b128 v[192:195], v149 offset:2048
	ds_read_b128 v[196:199], v149 offset:3072
	ds_read_b128 v[200:203], v149 offset:4096
	ds_read_b128 v[204:207], v149 offset:5120
	ds_read_b128 v[208:211], v149 offset:6144
	ds_read_b128 v[212:215], v149 offset:7168
	global_load_lds_dwordx4 v[178:179], off
	v_lshl_add_u64 v[178:179], s[52:53], 0, v[134:135]
	s_add_i32 m0, s49, 0xe000
	s_nop 0
	global_load_lds_dwordx4 v[178:179], off
	s_waitcnt vmcnt(8)
	s_waitcnt lgkmcnt(0)
	s_barrier
	s_setprio 1
	s_waitcnt lgkmcnt(0)
	v_mfma_f32_16x16x32_bf16 v[124:127], v[140:143], v[184:187], 0
	v_mfma_f32_16x16x32_bf16 v[120:123], v[154:157], v[184:187], 0
	v_mfma_f32_16x16x32_bf16 v[108:111], v[140:143], v[192:195], 0
	v_mfma_f32_16x16x32_bf16 v[104:107], v[154:157], v[192:195], 0
	v_mfma_f32_16x16x32_bf16 v[92:95], v[140:143], v[200:203], 0
	v_mfma_f32_16x16x32_bf16 v[88:91], v[154:157], v[200:203], 0
	v_mfma_f32_16x16x32_bf16 v[76:79], v[140:143], v[208:211], 0
	v_mfma_f32_16x16x32_bf16 v[72:75], v[154:157], v[208:211], 0
	v_mfma_f32_16x16x32_bf16 v[124:127], v[150:153], v[188:191], v[124:127]
	v_mfma_f32_16x16x32_bf16 v[120:123], v[158:161], v[188:191], v[120:123]
	v_mfma_f32_16x16x32_bf16 v[108:111], v[150:153], v[196:199], v[108:111]
	v_mfma_f32_16x16x32_bf16 v[104:107], v[158:161], v[196:199], v[104:107]
	v_mfma_f32_16x16x32_bf16 v[92:95], v[150:153], v[204:207], v[92:95]
	v_mfma_f32_16x16x32_bf16 v[88:91], v[158:161], v[204:207], v[88:91]
	v_mfma_f32_16x16x32_bf16 v[76:79], v[150:153], v[212:215], v[76:79]
	v_mfma_f32_16x16x32_bf16 v[72:75], v[158:161], v[212:215], v[72:75]
	s_setprio 0
	s_setprio 1
	v_mfma_f32_16x16x32_bf16 v[116:119], v[162:165], v[184:187], 0
	v_mfma_f32_16x16x32_bf16 v[112:115], v[170:173], v[184:187], 0
	v_mfma_f32_16x16x32_bf16 v[100:103], v[162:165], v[192:195], 0
	v_mfma_f32_16x16x32_bf16 v[96:99], v[170:173], v[192:195], 0
	v_mfma_f32_16x16x32_bf16 v[84:87], v[162:165], v[200:203], 0
	v_mfma_f32_16x16x32_bf16 v[80:83], v[170:173], v[200:203], 0
	v_mfma_f32_16x16x32_bf16 v[68:71], v[162:165], v[208:211], 0
	v_mfma_f32_16x16x32_bf16 v[64:67], v[170:173], v[208:211], 0
	v_mfma_f32_16x16x32_bf16 v[116:119], v[166:169], v[188:191], v[116:119]
	v_mfma_f32_16x16x32_bf16 v[112:115], v[174:177], v[188:191], v[112:115]
	v_mfma_f32_16x16x32_bf16 v[100:103], v[166:169], v[196:199], v[100:103]
	v_mfma_f32_16x16x32_bf16 v[96:99], v[174:177], v[196:199], v[96:99]
	v_mfma_f32_16x16x32_bf16 v[84:87], v[166:169], v[204:207], v[84:87]
	v_mfma_f32_16x16x32_bf16 v[80:83], v[174:177], v[204:207], v[80:83]
	v_mfma_f32_16x16x32_bf16 v[68:71], v[166:169], v[212:215], v[68:71]
	v_mfma_f32_16x16x32_bf16 v[64:67], v[174:177], v[212:215], v[64:67]
	s_setprio 0
	s_barrier
	s_add_i32 s77, s68, s60
	v_lshl_add_u64 v[178:179], s[54:55], 0, v[130:131]
	s_mov_b32 m0, s77
	ds_read_b128 v[184:187], v149 offset:16384
	ds_read_b128 v[188:191], v149 offset:17408
	ds_read_b128 v[192:195], v149 offset:18432
	ds_read_b128 v[196:199], v149 offset:19456
	ds_read_b128 v[200:203], v149 offset:20480
	ds_read_b128 v[204:207], v149 offset:21504
	ds_read_b128 v[208:211], v149 offset:22528
	ds_read_b128 v[212:215], v149 offset:23552
	global_load_lds_dwordx4 v[178:179], off
	s_add_i32 m0, s77, 0x2000
	s_add_u32 s82, s54, 0x40000
	v_lshl_add_u64 v[216:217], s[54:55], 0, v[128:129]
	s_addc_u32 s83, s55, 0
	s_add_i32 s77, s69, s60
	global_load_lds_dwordx4 v[216:217], off
	v_lshl_add_u64 v[218:219], s[82:83], 0, v[130:131]
	s_mov_b32 m0, s77
	v_lshl_add_u64 v[220:221], s[56:57], 0, v[128:129]
	global_load_lds_dwordx4 v[218:219], off
	v_lshl_add_u64 v[218:219], s[82:83], 0, v[128:129]
	s_add_i32 m0, s77, 0x2000
	s_nop 0
	global_load_lds_dwordx4 v[218:219], off
	v_lshl_add_u64 v[218:219], s[56:57], 0, v[130:131]
	s_mov_b32 m0, s49
	s_nop 0
	global_load_lds_dwordx4 v[218:219], off
	s_mov_b32 m0, s62
	s_nop 0
	global_load_lds_dwordx4 v[220:221], off
	s_waitcnt vmcnt(8)
	s_waitcnt lgkmcnt(0)
	s_barrier
	s_setprio 1
	s_waitcnt lgkmcnt(0)
	v_mfma_f32_16x16x32_bf16 v[60:63], v[140:143], v[184:187], 0
	v_mfma_f32_16x16x32_bf16 v[56:59], v[154:157], v[184:187], 0
	v_mfma_f32_16x16x32_bf16 v[44:47], v[140:143], v[192:195], 0
	v_mfma_f32_16x16x32_bf16 v[40:43], v[154:157], v[192:195], 0
	v_mfma_f32_16x16x32_bf16 v[28:31], v[140:143], v[200:203], 0
	v_mfma_f32_16x16x32_bf16 v[24:27], v[154:157], v[200:203], 0
	v_mfma_f32_16x16x32_bf16 v[12:15], v[140:143], v[208:211], 0
	v_mfma_f32_16x16x32_bf16 v[8:11], v[154:157], v[208:211], 0
	v_mfma_f32_16x16x32_bf16 v[60:63], v[150:153], v[188:191], v[60:63]
	v_mfma_f32_16x16x32_bf16 v[56:59], v[158:161], v[188:191], v[56:59]
	v_mfma_f32_16x16x32_bf16 v[44:47], v[150:153], v[196:199], v[44:47]
	v_mfma_f32_16x16x32_bf16 v[40:43], v[158:161], v[196:199], v[40:43]
	v_mfma_f32_16x16x32_bf16 v[28:31], v[150:153], v[204:207], v[28:31]
	v_mfma_f32_16x16x32_bf16 v[24:27], v[158:161], v[204:207], v[24:27]
	v_mfma_f32_16x16x32_bf16 v[12:15], v[150:153], v[212:215], v[12:15]
	v_mfma_f32_16x16x32_bf16 v[8:11], v[158:161], v[212:215], v[8:11]
	s_setprio 0
	s_setprio 1
	v_mfma_f32_16x16x32_bf16 v[52:55], v[162:165], v[184:187], 0
	v_mfma_f32_16x16x32_bf16 v[48:51], v[170:173], v[184:187], 0
	v_mfma_f32_16x16x32_bf16 v[36:39], v[162:165], v[192:195], 0
	v_mfma_f32_16x16x32_bf16 v[32:35], v[170:173], v[192:195], 0
	v_mfma_f32_16x16x32_bf16 v[20:23], v[162:165], v[200:203], 0
	v_mfma_f32_16x16x32_bf16 v[16:19], v[170:173], v[200:203], 0
	v_mfma_f32_16x16x32_bf16 v[4:7], v[162:165], v[208:211], 0
	v_mfma_f32_16x16x32_bf16 v[0:3], v[170:173], v[208:211], 0
	v_mfma_f32_16x16x32_bf16 v[52:55], v[166:169], v[188:191], v[52:55]
	v_mfma_f32_16x16x32_bf16 v[48:51], v[174:177], v[188:191], v[48:51]
	v_mfma_f32_16x16x32_bf16 v[36:39], v[166:169], v[196:199], v[36:39]
	v_mfma_f32_16x16x32_bf16 v[32:35], v[174:177], v[196:199], v[32:35]
	v_mfma_f32_16x16x32_bf16 v[20:23], v[166:169], v[204:207], v[20:23]
	v_mfma_f32_16x16x32_bf16 v[16:19], v[174:177], v[204:207], v[16:19]
	v_mfma_f32_16x16x32_bf16 v[4:7], v[166:169], v[212:215], v[4:7]
	v_mfma_f32_16x16x32_bf16 v[0:3], v[174:177], v[212:215], v[0:3]
	s_setprio 0
	s_barrier
	s_branch .Lmid_gemm7
.LBB0_951:
	ds_read_b128 v[140:143], v147
	ds_read_b128 v[150:153], v147 offset:1024
	ds_read_b128 v[154:157], v147 offset:2048
	ds_read_b128 v[158:161], v147 offset:3072
	ds_read_b128 v[162:165], v148
	ds_read_b128 v[166:169], v148 offset:1024
	ds_read_b128 v[170:173], v148 offset:2048
	ds_read_b128 v[174:177], v148 offset:3072
	s_add_u32 s54, s52, 0xfffc0080
	s_addc_u32 s55, s53, -1
	s_cmp_eq_u32 s76, 12
	s_cselect_b32 s57, s37, s55
	s_cselect_b32 s56, s72, s54
	s_cselect_b32 s55, s19, s75
	s_cselect_b32 s54, s73, s74
	v_lshl_add_u64 v[178:179], s[52:53], 0, v[132:133]
	s_add_i32 m0, s49, 0xc000
	ds_read_b128 v[184:187], v149
	ds_read_b128 v[188:191], v149 offset:1024
	ds_read_b128 v[192:195], v149 offset:2048
	ds_read_b128 v[196:199], v149 offset:3072
	ds_read_b128 v[200:203], v149 offset:4096
	ds_read_b128 v[204:207], v149 offset:5120
	ds_read_b128 v[208:211], v149 offset:6144
	ds_read_b128 v[212:215], v149 offset:7168
	global_load_lds_dwordx4 v[178:179], off
	v_lshl_add_u64 v[178:179], s[52:53], 0, v[134:135]
	s_add_i32 m0, s49, 0xe000
	s_nop 0
	global_load_lds_dwordx4 v[178:179], off
	s_waitcnt vmcnt(8)
	s_waitcnt lgkmcnt(0)
	s_barrier
	s_setprio 1
	s_waitcnt lgkmcnt(0)
	v_mfma_f32_16x16x32_bf16 v[124:127], v[140:143], v[184:187], v[124:127]
	v_mfma_f32_16x16x32_bf16 v[120:123], v[154:157], v[184:187], v[120:123]
	v_mfma_f32_16x16x32_bf16 v[108:111], v[140:143], v[192:195], v[108:111]
	v_mfma_f32_16x16x32_bf16 v[104:107], v[154:157], v[192:195], v[104:107]
	v_mfma_f32_16x16x32_bf16 v[92:95], v[140:143], v[200:203], v[92:95]
	v_mfma_f32_16x16x32_bf16 v[88:91], v[154:157], v[200:203], v[88:91]
	v_mfma_f32_16x16x32_bf16 v[76:79], v[140:143], v[208:211], v[76:79]
	v_mfma_f32_16x16x32_bf16 v[72:75], v[154:157], v[208:211], v[72:75]
	v_mfma_f32_16x16x32_bf16 v[124:127], v[150:153], v[188:191], v[124:127]
	v_mfma_f32_16x16x32_bf16 v[120:123], v[158:161], v[188:191], v[120:123]
	v_mfma_f32_16x16x32_bf16 v[108:111], v[150:153], v[196:199], v[108:111]
	v_mfma_f32_16x16x32_bf16 v[104:107], v[158:161], v[196:199], v[104:107]
	v_mfma_f32_16x16x32_bf16 v[92:95], v[150:153], v[204:207], v[92:95]
	v_mfma_f32_16x16x32_bf16 v[88:91], v[158:161], v[204:207], v[88:91]
	v_mfma_f32_16x16x32_bf16 v[76:79], v[150:153], v[212:215], v[76:79]
	v_mfma_f32_16x16x32_bf16 v[72:75], v[158:161], v[212:215], v[72:75]
	s_setprio 0
	s_setprio 1
	v_mfma_f32_16x16x32_bf16 v[116:119], v[162:165], v[184:187], v[116:119]
	v_mfma_f32_16x16x32_bf16 v[112:115], v[170:173], v[184:187], v[112:115]
	v_mfma_f32_16x16x32_bf16 v[100:103], v[162:165], v[192:195], v[100:103]
	v_mfma_f32_16x16x32_bf16 v[96:99], v[170:173], v[192:195], v[96:99]
	v_mfma_f32_16x16x32_bf16 v[84:87], v[162:165], v[200:203], v[84:87]
	v_mfma_f32_16x16x32_bf16 v[80:83], v[170:173], v[200:203], v[80:83]
	v_mfma_f32_16x16x32_bf16 v[68:71], v[162:165], v[208:211], v[68:71]
	v_mfma_f32_16x16x32_bf16 v[64:67], v[170:173], v[208:211], v[64:67]
	v_mfma_f32_16x16x32_bf16 v[116:119], v[166:169], v[188:191], v[116:119]
	v_mfma_f32_16x16x32_bf16 v[112:115], v[174:177], v[188:191], v[112:115]
	v_mfma_f32_16x16x32_bf16 v[100:103], v[166:169], v[196:199], v[100:103]
	v_mfma_f32_16x16x32_bf16 v[96:99], v[174:177], v[196:199], v[96:99]
	v_mfma_f32_16x16x32_bf16 v[84:87], v[166:169], v[204:207], v[84:87]
	v_mfma_f32_16x16x32_bf16 v[80:83], v[174:177], v[204:207], v[80:83]
	v_mfma_f32_16x16x32_bf16 v[68:71], v[166:169], v[212:215], v[68:71]
	v_mfma_f32_16x16x32_bf16 v[64:67], v[174:177], v[212:215], v[64:67]
	s_setprio 0
	s_barrier
	s_add_i32 s77, s68, s60
	v_lshl_add_u64 v[178:179], s[54:55], 0, v[130:131]
	s_mov_b32 m0, s77
	ds_read_b128 v[184:187], v149 offset:16384
	ds_read_b128 v[188:191], v149 offset:17408
	ds_read_b128 v[192:195], v149 offset:18432
	ds_read_b128 v[196:199], v149 offset:19456
	ds_read_b128 v[200:203], v149 offset:20480
	ds_read_b128 v[204:207], v149 offset:21504
	ds_read_b128 v[208:211], v149 offset:22528
	ds_read_b128 v[212:215], v149 offset:23552
	global_load_lds_dwordx4 v[178:179], off
	s_add_i32 m0, s77, 0x2000
	s_add_u32 s82, s54, 0x40000
	v_lshl_add_u64 v[216:217], s[54:55], 0, v[128:129]
	s_addc_u32 s83, s55, 0
	s_add_i32 s77, s69, s60
	global_load_lds_dwordx4 v[216:217], off
	v_lshl_add_u64 v[218:219], s[82:83], 0, v[130:131]
	s_mov_b32 m0, s77
	v_lshl_add_u64 v[220:221], s[56:57], 0, v[128:129]
	global_load_lds_dwordx4 v[218:219], off
	v_lshl_add_u64 v[218:219], s[82:83], 0, v[128:129]
	s_add_i32 m0, s77, 0x2000
	s_nop 0
	global_load_lds_dwordx4 v[218:219], off
	v_lshl_add_u64 v[218:219], s[56:57], 0, v[130:131]
	s_mov_b32 m0, s49
	s_nop 0
	global_load_lds_dwordx4 v[218:219], off
	s_mov_b32 m0, s62
	s_nop 0
	global_load_lds_dwordx4 v[220:221], off
	s_waitcnt vmcnt(8)
	s_waitcnt lgkmcnt(0)
	s_barrier
	s_setprio 1
	s_waitcnt lgkmcnt(0)
	v_mfma_f32_16x16x32_bf16 v[60:63], v[140:143], v[184:187], v[60:63]
	v_mfma_f32_16x16x32_bf16 v[56:59], v[154:157], v[184:187], v[56:59]
	v_mfma_f32_16x16x32_bf16 v[44:47], v[140:143], v[192:195], v[44:47]
	v_mfma_f32_16x16x32_bf16 v[40:43], v[154:157], v[192:195], v[40:43]
	v_mfma_f32_16x16x32_bf16 v[28:31], v[140:143], v[200:203], v[28:31]
	v_mfma_f32_16x16x32_bf16 v[24:27], v[154:157], v[200:203], v[24:27]
	v_mfma_f32_16x16x32_bf16 v[12:15], v[140:143], v[208:211], v[12:15]
	v_mfma_f32_16x16x32_bf16 v[8:11], v[154:157], v[208:211], v[8:11]
	v_mfma_f32_16x16x32_bf16 v[60:63], v[150:153], v[188:191], v[60:63]
	v_mfma_f32_16x16x32_bf16 v[56:59], v[158:161], v[188:191], v[56:59]
	v_mfma_f32_16x16x32_bf16 v[44:47], v[150:153], v[196:199], v[44:47]
	v_mfma_f32_16x16x32_bf16 v[40:43], v[158:161], v[196:199], v[40:43]
	v_mfma_f32_16x16x32_bf16 v[28:31], v[150:153], v[204:207], v[28:31]
	v_mfma_f32_16x16x32_bf16 v[24:27], v[158:161], v[204:207], v[24:27]
	v_mfma_f32_16x16x32_bf16 v[12:15], v[150:153], v[212:215], v[12:15]
	v_mfma_f32_16x16x32_bf16 v[8:11], v[158:161], v[212:215], v[8:11]
	s_setprio 0
	s_setprio 1
	v_mfma_f32_16x16x32_bf16 v[52:55], v[162:165], v[184:187], v[52:55]
	v_mfma_f32_16x16x32_bf16 v[48:51], v[170:173], v[184:187], v[48:51]
	v_mfma_f32_16x16x32_bf16 v[36:39], v[162:165], v[192:195], v[36:39]
	v_mfma_f32_16x16x32_bf16 v[32:35], v[170:173], v[192:195], v[32:35]
	v_mfma_f32_16x16x32_bf16 v[20:23], v[162:165], v[200:203], v[20:23]
	v_mfma_f32_16x16x32_bf16 v[16:19], v[170:173], v[200:203], v[16:19]
	v_mfma_f32_16x16x32_bf16 v[4:7], v[162:165], v[208:211], v[4:7]
	v_mfma_f32_16x16x32_bf16 v[0:3], v[170:173], v[208:211], v[0:3]
	v_mfma_f32_16x16x32_bf16 v[52:55], v[166:169], v[188:191], v[52:55]
	v_mfma_f32_16x16x32_bf16 v[48:51], v[174:177], v[188:191], v[48:51]
	v_mfma_f32_16x16x32_bf16 v[36:39], v[166:169], v[196:199], v[36:39]
	v_mfma_f32_16x16x32_bf16 v[32:35], v[174:177], v[196:199], v[32:35]
	v_mfma_f32_16x16x32_bf16 v[20:23], v[166:169], v[204:207], v[20:23]
	v_mfma_f32_16x16x32_bf16 v[16:19], v[174:177], v[204:207], v[16:19]
	v_mfma_f32_16x16x32_bf16 v[4:7], v[166:169], v[212:215], v[4:7]
	v_mfma_f32_16x16x32_bf16 v[0:3], v[174:177], v[212:215], v[0:3]
	s_setprio 0
	s_barrier
.Lmid_gemm7:
	s_add_i32 s77, 0, 0x18000
	s_add_i32 s79, 0, 0x1c000
	v_add_u32_e32 v158, s77, v145
	v_add_u32_e32 v174, s79, v145
	ds_read_b128 v[140:143], v158
	ds_read_b128 v[150:153], v158 offset:1024
	ds_read_b128 v[154:157], v158 offset:2048
	ds_read_b128 v[158:161], v158 offset:3072
	ds_read_b128 v[162:165], v174
	ds_read_b128 v[166:169], v174 offset:1024
	ds_read_b128 v[170:173], v174 offset:2048
	ds_read_b128 v[174:177], v174 offset:3072
	s_add_u32 s56, s56, 0x40000
	s_addc_u32 s57, s57, 0
	s_mov_b32 m0, s63
	v_lshl_add_u64 v[222:223], s[56:57], 0, v[130:131]
	ds_read_b128 v[184:187], v149 offset:32768
	ds_read_b128 v[188:191], v149 offset:33792
	ds_read_b128 v[192:195], v149 offset:34816
	ds_read_b128 v[196:199], v149 offset:35840
	ds_read_b128 v[200:203], v149 offset:36864
	ds_read_b128 v[204:207], v149 offset:37888
	ds_read_b128 v[208:211], v149 offset:38912
	ds_read_b128 v[212:215], v149 offset:39936
	global_load_lds_dwordx4 v[222:223], off
	v_lshl_add_u64 v[222:223], s[56:57], 0, v[128:129]
	s_mov_b32 m0, s64
	s_nop 0
	global_load_lds_dwordx4 v[222:223], off
	s_waitcnt vmcnt(8)
	s_waitcnt lgkmcnt(0)
	s_barrier
	s_setprio 1
	s_waitcnt lgkmcnt(0)
	v_mfma_f32_16x16x32_bf16 v[124:127], v[140:143], v[184:187], v[124:127]
	v_mfma_f32_16x16x32_bf16 v[120:123], v[154:157], v[184:187], v[120:123]
	v_mfma_f32_16x16x32_bf16 v[108:111], v[140:143], v[192:195], v[108:111]
	v_mfma_f32_16x16x32_bf16 v[104:107], v[154:157], v[192:195], v[104:107]
	v_mfma_f32_16x16x32_bf16 v[92:95], v[140:143], v[200:203], v[92:95]
	v_mfma_f32_16x16x32_bf16 v[88:91], v[154:157], v[200:203], v[88:91]
	v_mfma_f32_16x16x32_bf16 v[76:79], v[140:143], v[208:211], v[76:79]
	v_mfma_f32_16x16x32_bf16 v[72:75], v[154:157], v[208:211], v[72:75]
	v_mfma_f32_16x16x32_bf16 v[124:127], v[150:153], v[188:191], v[124:127]
	v_mfma_f32_16x16x32_bf16 v[120:123], v[158:161], v[188:191], v[120:123]
	v_mfma_f32_16x16x32_bf16 v[108:111], v[150:153], v[196:199], v[108:111]
	v_mfma_f32_16x16x32_bf16 v[104:107], v[158:161], v[196:199], v[104:107]
	v_mfma_f32_16x16x32_bf16 v[92:95], v[150:153], v[204:207], v[92:95]
	v_mfma_f32_16x16x32_bf16 v[88:91], v[158:161], v[204:207], v[88:91]
	v_mfma_f32_16x16x32_bf16 v[76:79], v[150:153], v[212:215], v[76:79]
	v_mfma_f32_16x16x32_bf16 v[72:75], v[158:161], v[212:215], v[72:75]
	s_setprio 0
	s_setprio 1
	v_mfma_f32_16x16x32_bf16 v[116:119], v[162:165], v[184:187], v[116:119]
	v_mfma_f32_16x16x32_bf16 v[112:115], v[170:173], v[184:187], v[112:115]
	v_mfma_f32_16x16x32_bf16 v[100:103], v[162:165], v[192:195], v[100:103]
	v_mfma_f32_16x16x32_bf16 v[96:99], v[170:173], v[192:195], v[96:99]
	v_mfma_f32_16x16x32_bf16 v[84:87], v[162:165], v[200:203], v[84:87]
	v_mfma_f32_16x16x32_bf16 v[80:83], v[170:173], v[200:203], v[80:83]
	v_mfma_f32_16x16x32_bf16 v[68:71], v[162:165], v[208:211], v[68:71]
	v_mfma_f32_16x16x32_bf16 v[64:67], v[170:173], v[208:211], v[64:67]
	v_mfma_f32_16x16x32_bf16 v[116:119], v[166:169], v[188:191], v[116:119]
	v_mfma_f32_16x16x32_bf16 v[112:115], v[174:177], v[188:191], v[112:115]
	v_mfma_f32_16x16x32_bf16 v[100:103], v[166:169], v[196:199], v[100:103]
	v_mfma_f32_16x16x32_bf16 v[96:99], v[174:177], v[196:199], v[96:99]
	v_mfma_f32_16x16x32_bf16 v[84:87], v[166:169], v[204:207], v[84:87]
	v_mfma_f32_16x16x32_bf16 v[80:83], v[174:177], v[204:207], v[80:83]
	v_mfma_f32_16x16x32_bf16 v[68:71], v[166:169], v[212:215], v[68:71]
	v_mfma_f32_16x16x32_bf16 v[64:67], v[174:177], v[212:215], v[64:67]
	s_setprio 0
	s_barrier
	s_add_i32 s56, s77, s60
	v_lshl_add_u64 v[178:179], v[178:179], 0, s[12:13]
	s_mov_b32 m0, s56
	ds_read_b128 v[184:187], v149 offset:49152
	ds_read_b128 v[188:191], v149 offset:50176
	ds_read_b128 v[192:195], v149 offset:51200
	ds_read_b128 v[196:199], v149 offset:52224
	ds_read_b128 v[200:203], v149 offset:53248
	ds_read_b128 v[204:207], v149 offset:54272
	ds_read_b128 v[208:211], v149 offset:55296
	ds_read_b128 v[212:215], v149 offset:56320
	global_load_lds_dwordx4 v[178:179], off
	s_add_i32 m0, s56, 0x2000
	s_add_u32 s54, s54, 0x40080
	v_lshl_add_u64 v[178:179], v[216:217], 0, s[12:13]
	s_addc_u32 s55, s55, 0
	s_add_i32 s56, s79, s60
	global_load_lds_dwordx4 v[178:179], off
	v_lshl_add_u64 v[178:179], s[54:55], 0, v[130:131]
	s_mov_b32 m0, s56
	s_nop 0
	global_load_lds_dwordx4 v[178:179], off
	v_lshl_add_u64 v[178:179], s[54:55], 0, v[128:129]
	s_add_i32 m0, s56, 0x2000
	s_nop 0
	global_load_lds_dwordx4 v[178:179], off
	v_lshl_add_u64 v[178:179], v[218:219], 0, s[12:13]
	s_mov_b32 m0, s66
	s_nop 0
	global_load_lds_dwordx4 v[178:179], off
	v_lshl_add_u64 v[178:179], v[220:221], 0, s[12:13]
	s_mov_b32 m0, s67
	s_nop 0
	global_load_lds_dwordx4 v[178:179], off
	s_waitcnt vmcnt(8)
	s_waitcnt lgkmcnt(0)
	s_barrier
	s_setprio 1
	s_waitcnt lgkmcnt(0)
	v_mfma_f32_16x16x32_bf16 v[60:63], v[140:143], v[184:187], v[60:63]
	v_mfma_f32_16x16x32_bf16 v[56:59], v[154:157], v[184:187], v[56:59]
	v_mfma_f32_16x16x32_bf16 v[44:47], v[140:143], v[192:195], v[44:47]
	v_mfma_f32_16x16x32_bf16 v[40:43], v[154:157], v[192:195], v[40:43]
	v_mfma_f32_16x16x32_bf16 v[28:31], v[140:143], v[200:203], v[28:31]
	v_mfma_f32_16x16x32_bf16 v[24:27], v[154:157], v[200:203], v[24:27]
	v_mfma_f32_16x16x32_bf16 v[12:15], v[140:143], v[208:211], v[12:15]
	v_mfma_f32_16x16x32_bf16 v[8:11], v[154:157], v[208:211], v[8:11]
	v_mfma_f32_16x16x32_bf16 v[60:63], v[150:153], v[188:191], v[60:63]
	v_mfma_f32_16x16x32_bf16 v[56:59], v[158:161], v[188:191], v[56:59]
	v_mfma_f32_16x16x32_bf16 v[44:47], v[150:153], v[196:199], v[44:47]
	v_mfma_f32_16x16x32_bf16 v[40:43], v[158:161], v[196:199], v[40:43]
	v_mfma_f32_16x16x32_bf16 v[28:31], v[150:153], v[204:207], v[28:31]
	v_mfma_f32_16x16x32_bf16 v[24:27], v[158:161], v[204:207], v[24:27]
	v_mfma_f32_16x16x32_bf16 v[12:15], v[150:153], v[212:215], v[12:15]
	v_mfma_f32_16x16x32_bf16 v[8:11], v[158:161], v[212:215], v[8:11]
	s_setprio 0
	s_setprio 1
	v_mfma_f32_16x16x32_bf16 v[52:55], v[162:165], v[184:187], v[52:55]
	v_mfma_f32_16x16x32_bf16 v[48:51], v[170:173], v[184:187], v[48:51]
	v_mfma_f32_16x16x32_bf16 v[36:39], v[162:165], v[192:195], v[36:39]
	v_mfma_f32_16x16x32_bf16 v[32:35], v[170:173], v[192:195], v[32:35]
	v_mfma_f32_16x16x32_bf16 v[20:23], v[162:165], v[200:203], v[20:23]
	v_mfma_f32_16x16x32_bf16 v[16:19], v[170:173], v[200:203], v[16:19]
	v_mfma_f32_16x16x32_bf16 v[4:7], v[162:165], v[208:211], v[4:7]
	v_mfma_f32_16x16x32_bf16 v[0:3], v[170:173], v[208:211], v[0:3]
	v_mfma_f32_16x16x32_bf16 v[52:55], v[166:169], v[188:191], v[52:55]
	v_mfma_f32_16x16x32_bf16 v[48:51], v[174:177], v[188:191], v[48:51]
	v_mfma_f32_16x16x32_bf16 v[36:39], v[166:169], v[196:199], v[36:39]
	v_mfma_f32_16x16x32_bf16 v[32:35], v[174:177], v[196:199], v[32:35]
	v_mfma_f32_16x16x32_bf16 v[20:23], v[166:169], v[204:207], v[20:23]
	v_mfma_f32_16x16x32_bf16 v[16:19], v[174:177], v[204:207], v[16:19]
	v_mfma_f32_16x16x32_bf16 v[4:7], v[166:169], v[212:215], v[4:7]
	v_mfma_f32_16x16x32_bf16 v[0:3], v[174:177], v[212:215], v[0:3]
	s_setprio 0
	s_barrier
	s_add_i32 s76, s76, 2
	s_add_u32 s52, s52, 0x100
	s_addc_u32 s53, s53, 0
	s_add_u32 s74, s74, 0x100
	s_addc_u32 s75, s75, 0
	s_cmp_gt_u32 s76, 13
	s_cbranch_scc0 .LBB0_951
	s_and_b64 vcc, exec, s[16:17]
	s_cbranch_vccz .LBB0_954
	s_barrier

.LBB0_1030:
	s_add_u32 s86, s56, 0x100
	s_addc_u32 s87, s57, 0
	s_mov_b32 s88, -2
	ds_read_b128 v[152:155], v149
	ds_read_b128 v[156:159], v149 offset:1024
	ds_read_b128 v[160:163], v149 offset:2048
	ds_read_b128 v[164:167], v149 offset:3072
	ds_read_b128 v[168:171], v150
	ds_read_b128 v[172:175], v150 offset:1024
	ds_read_b128 v[176:179], v150 offset:2048
	ds_read_b128 v[184:187], v150 offset:3072
	s_add_u32 s56, s54, 0x100
	s_addc_u32 s57, s55, 0
	s_cmp_eq_u32 s88, 40
	s_cselect_b32 s61, s13, s57
	s_cselect_b32 s60, s12, s56
	s_cselect_b32 s59, s53, s87
	s_cselect_b32 s58, s52, s86
	v_lshl_add_u64 v[144:145], s[54:55], 0, v[136:137]
	s_add_i32 m0, s65, 0xc000
	ds_read_b128 v[188:191], v151
	ds_read_b128 v[192:195], v151 offset:1024
	ds_read_b128 v[196:199], v151 offset:2048
	ds_read_b128 v[200:203], v151 offset:3072
	ds_read_b128 v[204:207], v151 offset:4096
	ds_read_b128 v[208:211], v151 offset:5120
	ds_read_b128 v[212:215], v151 offset:6144
	ds_read_b128 v[216:219], v151 offset:7168
	global_load_lds_dwordx4 v[144:145], off
	v_lshl_add_u64 v[144:145], s[54:55], 0, v[138:139]
	s_add_i32 m0, s65, 0xe000
	s_nop 0
	global_load_lds_dwordx4 v[144:145], off
	s_waitcnt vmcnt(8)
	s_waitcnt lgkmcnt(0)
	s_barrier
	s_setprio 1
	s_waitcnt lgkmcnt(0)
	v_mfma_f32_16x16x32_bf16 v[124:127], v[152:155], v[188:191], 0
	v_mfma_f32_16x16x32_bf16 v[120:123], v[160:163], v[188:191], 0
	v_mfma_f32_16x16x32_bf16 v[116:119], v[152:155], v[196:199], 0
	v_mfma_f32_16x16x32_bf16 v[108:111], v[160:163], v[196:199], 0
	v_mfma_f32_16x16x32_bf16 v[100:103], v[152:155], v[204:207], 0
	v_mfma_f32_16x16x32_bf16 v[92:95], v[160:163], v[204:207], 0
	v_mfma_f32_16x16x32_bf16 v[84:87], v[152:155], v[212:215], 0
	v_mfma_f32_16x16x32_bf16 v[76:79], v[160:163], v[212:215], 0
	v_mfma_f32_16x16x32_bf16 v[124:127], v[156:159], v[192:195], v[124:127]
	v_mfma_f32_16x16x32_bf16 v[120:123], v[164:167], v[192:195], v[120:123]
	v_mfma_f32_16x16x32_bf16 v[116:119], v[156:159], v[200:203], v[116:119]
	v_mfma_f32_16x16x32_bf16 v[108:111], v[164:167], v[200:203], v[108:111]
	v_mfma_f32_16x16x32_bf16 v[100:103], v[156:159], v[208:211], v[100:103]
	v_mfma_f32_16x16x32_bf16 v[92:95], v[164:167], v[208:211], v[92:95]
	v_mfma_f32_16x16x32_bf16 v[84:87], v[156:159], v[216:219], v[84:87]
	v_mfma_f32_16x16x32_bf16 v[76:79], v[164:167], v[216:219], v[76:79]
	s_setprio 0
	s_setprio 1
	v_mfma_f32_16x16x32_bf16 v[112:115], v[168:171], v[188:191], 0
	v_mfma_f32_16x16x32_bf16 v[104:107], v[176:179], v[188:191], 0
	v_mfma_f32_16x16x32_bf16 v[96:99], v[168:171], v[196:199], 0
	v_mfma_f32_16x16x32_bf16 v[88:91], v[176:179], v[196:199], 0
	v_mfma_f32_16x16x32_bf16 v[80:83], v[168:171], v[204:207], 0
	v_mfma_f32_16x16x32_bf16 v[72:75], v[176:179], v[204:207], 0
	v_mfma_f32_16x16x32_bf16 v[68:71], v[168:171], v[212:215], 0
	v_mfma_f32_16x16x32_bf16 v[64:67], v[176:179], v[212:215], 0
	v_mfma_f32_16x16x32_bf16 v[112:115], v[172:175], v[192:195], v[112:115]
	v_mfma_f32_16x16x32_bf16 v[104:107], v[184:187], v[192:195], v[104:107]
	v_mfma_f32_16x16x32_bf16 v[96:99], v[172:175], v[200:203], v[96:99]
	v_mfma_f32_16x16x32_bf16 v[88:91], v[184:187], v[200:203], v[88:91]
	v_mfma_f32_16x16x32_bf16 v[80:83], v[172:175], v[208:211], v[80:83]
	v_mfma_f32_16x16x32_bf16 v[72:75], v[184:187], v[208:211], v[72:75]
	v_mfma_f32_16x16x32_bf16 v[68:71], v[172:175], v[216:219], v[68:71]
	v_mfma_f32_16x16x32_bf16 v[64:67], v[184:187], v[216:219], v[64:67]
	s_setprio 0
	s_barrier
	s_add_i32 s54, s72, s64
	v_lshl_add_u64 v[144:145], s[58:59], 0, v[130:131]
	s_mov_b32 m0, s54
	ds_read_b128 v[188:191], v151 offset:16384
	ds_read_b128 v[192:195], v151 offset:17408
	ds_read_b128 v[196:199], v151 offset:18432
	ds_read_b128 v[200:203], v151 offset:19456
	ds_read_b128 v[204:207], v151 offset:20480
	ds_read_b128 v[208:211], v151 offset:21504
	ds_read_b128 v[212:215], v151 offset:22528
	ds_read_b128 v[216:219], v151 offset:23552
	global_load_lds_dwordx4 v[144:145], off
	s_add_i32 m0, s54, 0x2000
	s_add_u32 s54, s58, 0xb0000
	v_lshl_add_u64 v[220:221], s[58:59], 0, v[134:135]
	s_addc_u32 s55, s59, 0
	s_add_i32 s79, s73, s64
	global_load_lds_dwordx4 v[220:221], off
	v_lshl_add_u64 v[222:223], s[54:55], 0, v[130:131]
	s_mov_b32 m0, s79
	v_lshl_add_u64 v[224:225], s[60:61], 0, v[132:133]
	global_load_lds_dwordx4 v[222:223], off
	v_lshl_add_u64 v[222:223], s[54:55], 0, v[134:135]
	s_add_i32 m0, s79, 0x2000
	s_nop 0
	global_load_lds_dwordx4 v[222:223], off
	v_lshl_add_u64 v[222:223], s[60:61], 0, v[128:129]
	s_mov_b32 m0, s65
	s_nop 0
	global_load_lds_dwordx4 v[222:223], off
	s_mov_b32 m0, s66
	s_nop 0
	global_load_lds_dwordx4 v[224:225], off
	s_waitcnt vmcnt(8)
	s_waitcnt lgkmcnt(0)
	s_barrier
	s_setprio 1
	s_waitcnt lgkmcnt(0)
	v_mfma_f32_16x16x32_bf16 v[60:63], v[152:155], v[188:191], 0
	v_mfma_f32_16x16x32_bf16 v[56:59], v[160:163], v[188:191], 0
	v_mfma_f32_16x16x32_bf16 v[52:55], v[152:155], v[196:199], 0
	v_mfma_f32_16x16x32_bf16 v[44:47], v[160:163], v[196:199], 0
	v_mfma_f32_16x16x32_bf16 v[36:39], v[152:155], v[204:207], 0
	v_mfma_f32_16x16x32_bf16 v[28:31], v[160:163], v[204:207], 0
	v_mfma_f32_16x16x32_bf16 v[20:23], v[152:155], v[212:215], 0
	v_mfma_f32_16x16x32_bf16 v[12:15], v[160:163], v[212:215], 0
	v_mfma_f32_16x16x32_bf16 v[60:63], v[156:159], v[192:195], v[60:63]
	v_mfma_f32_16x16x32_bf16 v[56:59], v[164:167], v[192:195], v[56:59]
	v_mfma_f32_16x16x32_bf16 v[52:55], v[156:159], v[200:203], v[52:55]
	v_mfma_f32_16x16x32_bf16 v[44:47], v[164:167], v[200:203], v[44:47]
	v_mfma_f32_16x16x32_bf16 v[36:39], v[156:159], v[208:211], v[36:39]
	v_mfma_f32_16x16x32_bf16 v[28:31], v[164:167], v[208:211], v[28:31]
	v_mfma_f32_16x16x32_bf16 v[20:23], v[156:159], v[216:219], v[20:23]
	v_mfma_f32_16x16x32_bf16 v[12:15], v[164:167], v[216:219], v[12:15]
	s_setprio 0
	s_setprio 1
	v_mfma_f32_16x16x32_bf16 v[48:51], v[168:171], v[188:191], 0
	v_mfma_f32_16x16x32_bf16 v[40:43], v[176:179], v[188:191], 0
	v_mfma_f32_16x16x32_bf16 v[32:35], v[168:171], v[196:199], 0
	v_mfma_f32_16x16x32_bf16 v[24:27], v[176:179], v[196:199], 0
	v_mfma_f32_16x16x32_bf16 v[16:19], v[168:171], v[204:207], 0
	v_mfma_f32_16x16x32_bf16 v[8:11], v[176:179], v[204:207], 0
	v_mfma_f32_16x16x32_bf16 v[4:7], v[168:171], v[212:215], 0
	v_mfma_f32_16x16x32_bf16 v[0:3], v[176:179], v[212:215], 0
	v_mfma_f32_16x16x32_bf16 v[48:51], v[172:175], v[192:195], v[48:51]
	v_mfma_f32_16x16x32_bf16 v[40:43], v[184:187], v[192:195], v[40:43]
	v_mfma_f32_16x16x32_bf16 v[32:35], v[172:175], v[200:203], v[32:35]
	v_mfma_f32_16x16x32_bf16 v[24:27], v[184:187], v[200:203], v[24:27]
	v_mfma_f32_16x16x32_bf16 v[16:19], v[172:175], v[208:211], v[16:19]
	v_mfma_f32_16x16x32_bf16 v[8:11], v[184:187], v[208:211], v[8:11]
	v_mfma_f32_16x16x32_bf16 v[4:7], v[172:175], v[216:219], v[4:7]
	v_mfma_f32_16x16x32_bf16 v[0:3], v[184:187], v[216:219], v[0:3]
	s_setprio 0
	s_barrier
	s_branch .Lmid_gemm8
.LBB0_1031:
	ds_read_b128 v[152:155], v149
	ds_read_b128 v[156:159], v149 offset:1024
	ds_read_b128 v[160:163], v149 offset:2048
	ds_read_b128 v[164:167], v149 offset:3072
	ds_read_b128 v[168:171], v150
	ds_read_b128 v[172:175], v150 offset:1024
	ds_read_b128 v[176:179], v150 offset:2048
	ds_read_b128 v[184:187], v150 offset:3072
	s_add_u32 s56, s54, 0x100
	s_addc_u32 s57, s55, 0
	s_cmp_eq_u32 s88, 40
	s_cselect_b32 s61, s13, s57
	s_cselect_b32 s60, s12, s56
	s_cselect_b32 s59, s53, s87
	s_cselect_b32 s58, s52, s86
	v_lshl_add_u64 v[144:145], s[54:55], 0, v[136:137]
	s_add_i32 m0, s65, 0xc000
	ds_read_b128 v[188:191], v151
	ds_read_b128 v[192:195], v151 offset:1024
	ds_read_b128 v[196:199], v151 offset:2048
	ds_read_b128 v[200:203], v151 offset:3072
	ds_read_b128 v[204:207], v151 offset:4096
	ds_read_b128 v[208:211], v151 offset:5120
	ds_read_b128 v[212:215], v151 offset:6144
	ds_read_b128 v[216:219], v151 offset:7168
	global_load_lds_dwordx4 v[144:145], off
	v_lshl_add_u64 v[144:145], s[54:55], 0, v[138:139]
	s_add_i32 m0, s65, 0xe000
	s_nop 0
	global_load_lds_dwordx4 v[144:145], off
	s_waitcnt vmcnt(8)
	s_waitcnt lgkmcnt(0)
	s_barrier
	s_setprio 1
	s_waitcnt lgkmcnt(0)
	v_mfma_f32_16x16x32_bf16 v[124:127], v[152:155], v[188:191], v[124:127]
	v_mfma_f32_16x16x32_bf16 v[120:123], v[160:163], v[188:191], v[120:123]
	v_mfma_f32_16x16x32_bf16 v[116:119], v[152:155], v[196:199], v[116:119]
	v_mfma_f32_16x16x32_bf16 v[108:111], v[160:163], v[196:199], v[108:111]
	v_mfma_f32_16x16x32_bf16 v[100:103], v[152:155], v[204:207], v[100:103]
	v_mfma_f32_16x16x32_bf16 v[92:95], v[160:163], v[204:207], v[92:95]
	v_mfma_f32_16x16x32_bf16 v[84:87], v[152:155], v[212:215], v[84:87]
	v_mfma_f32_16x16x32_bf16 v[76:79], v[160:163], v[212:215], v[76:79]
	v_mfma_f32_16x16x32_bf16 v[124:127], v[156:159], v[192:195], v[124:127]
	v_mfma_f32_16x16x32_bf16 v[120:123], v[164:167], v[192:195], v[120:123]
	v_mfma_f32_16x16x32_bf16 v[116:119], v[156:159], v[200:203], v[116:119]
	v_mfma_f32_16x16x32_bf16 v[108:111], v[164:167], v[200:203], v[108:111]
	v_mfma_f32_16x16x32_bf16 v[100:103], v[156:159], v[208:211], v[100:103]
	v_mfma_f32_16x16x32_bf16 v[92:95], v[164:167], v[208:211], v[92:95]
	v_mfma_f32_16x16x32_bf16 v[84:87], v[156:159], v[216:219], v[84:87]
	v_mfma_f32_16x16x32_bf16 v[76:79], v[164:167], v[216:219], v[76:79]
	s_setprio 0
	s_setprio 1
	v_mfma_f32_16x16x32_bf16 v[112:115], v[168:171], v[188:191], v[112:115]
	v_mfma_f32_16x16x32_bf16 v[104:107], v[176:179], v[188:191], v[104:107]
	v_mfma_f32_16x16x32_bf16 v[96:99], v[168:171], v[196:199], v[96:99]
	v_mfma_f32_16x16x32_bf16 v[88:91], v[176:179], v[196:199], v[88:91]
	v_mfma_f32_16x16x32_bf16 v[80:83], v[168:171], v[204:207], v[80:83]
	v_mfma_f32_16x16x32_bf16 v[72:75], v[176:179], v[204:207], v[72:75]
	v_mfma_f32_16x16x32_bf16 v[68:71], v[168:171], v[212:215], v[68:71]
	v_mfma_f32_16x16x32_bf16 v[64:67], v[176:179], v[212:215], v[64:67]
	v_mfma_f32_16x16x32_bf16 v[112:115], v[172:175], v[192:195], v[112:115]
	v_mfma_f32_16x16x32_bf16 v[104:107], v[184:187], v[192:195], v[104:107]
	v_mfma_f32_16x16x32_bf16 v[96:99], v[172:175], v[200:203], v[96:99]
	v_mfma_f32_16x16x32_bf16 v[88:91], v[184:187], v[200:203], v[88:91]
	v_mfma_f32_16x16x32_bf16 v[80:83], v[172:175], v[208:211], v[80:83]
	v_mfma_f32_16x16x32_bf16 v[72:75], v[184:187], v[208:211], v[72:75]
	v_mfma_f32_16x16x32_bf16 v[68:71], v[172:175], v[216:219], v[68:71]
	v_mfma_f32_16x16x32_bf16 v[64:67], v[184:187], v[216:219], v[64:67]
	s_setprio 0
	s_barrier
	s_add_i32 s54, s72, s64
	v_lshl_add_u64 v[144:145], s[58:59], 0, v[130:131]
	s_mov_b32 m0, s54
	ds_read_b128 v[188:191], v151 offset:16384
	ds_read_b128 v[192:195], v151 offset:17408
	ds_read_b128 v[196:199], v151 offset:18432
	ds_read_b128 v[200:203], v151 offset:19456
	ds_read_b128 v[204:207], v151 offset:20480
	ds_read_b128 v[208:211], v151 offset:21504
	ds_read_b128 v[212:215], v151 offset:22528
	ds_read_b128 v[216:219], v151 offset:23552
	global_load_lds_dwordx4 v[144:145], off
	s_add_i32 m0, s54, 0x2000
	s_add_u32 s54, s58, 0xb0000
	v_lshl_add_u64 v[220:221], s[58:59], 0, v[134:135]
	s_addc_u32 s55, s59, 0
	s_add_i32 s79, s73, s64
	global_load_lds_dwordx4 v[220:221], off
	v_lshl_add_u64 v[222:223], s[54:55], 0, v[130:131]
	s_mov_b32 m0, s79
	v_lshl_add_u64 v[224:225], s[60:61], 0, v[132:133]
	global_load_lds_dwordx4 v[222:223], off
	v_lshl_add_u64 v[222:223], s[54:55], 0, v[134:135]
	s_add_i32 m0, s79, 0x2000
	s_nop 0
	global_load_lds_dwordx4 v[222:223], off
	v_lshl_add_u64 v[222:223], s[60:61], 0, v[128:129]
	s_mov_b32 m0, s65
	s_nop 0
	global_load_lds_dwordx4 v[222:223], off
	s_mov_b32 m0, s66
	s_nop 0
	global_load_lds_dwordx4 v[224:225], off
	s_waitcnt vmcnt(8)
	s_waitcnt lgkmcnt(0)
	s_barrier
	s_setprio 1
	s_waitcnt lgkmcnt(0)
	v_mfma_f32_16x16x32_bf16 v[60:63], v[152:155], v[188:191], v[60:63]
	v_mfma_f32_16x16x32_bf16 v[56:59], v[160:163], v[188:191], v[56:59]
	v_mfma_f32_16x16x32_bf16 v[52:55], v[152:155], v[196:199], v[52:55]
	v_mfma_f32_16x16x32_bf16 v[44:47], v[160:163], v[196:199], v[44:47]
	v_mfma_f32_16x16x32_bf16 v[36:39], v[152:155], v[204:207], v[36:39]
	v_mfma_f32_16x16x32_bf16 v[28:31], v[160:163], v[204:207], v[28:31]
	v_mfma_f32_16x16x32_bf16 v[20:23], v[152:155], v[212:215], v[20:23]
	v_mfma_f32_16x16x32_bf16 v[12:15], v[160:163], v[212:215], v[12:15]
	v_mfma_f32_16x16x32_bf16 v[60:63], v[156:159], v[192:195], v[60:63]
	v_mfma_f32_16x16x32_bf16 v[56:59], v[164:167], v[192:195], v[56:59]
	v_mfma_f32_16x16x32_bf16 v[52:55], v[156:159], v[200:203], v[52:55]
	v_mfma_f32_16x16x32_bf16 v[44:47], v[164:167], v[200:203], v[44:47]
	v_mfma_f32_16x16x32_bf16 v[36:39], v[156:159], v[208:211], v[36:39]
	v_mfma_f32_16x16x32_bf16 v[28:31], v[164:167], v[208:211], v[28:31]
	v_mfma_f32_16x16x32_bf16 v[20:23], v[156:159], v[216:219], v[20:23]
	v_mfma_f32_16x16x32_bf16 v[12:15], v[164:167], v[216:219], v[12:15]
	s_setprio 0
	s_setprio 1
	v_mfma_f32_16x16x32_bf16 v[48:51], v[168:171], v[188:191], v[48:51]
	v_mfma_f32_16x16x32_bf16 v[40:43], v[176:179], v[188:191], v[40:43]
	v_mfma_f32_16x16x32_bf16 v[32:35], v[168:171], v[196:199], v[32:35]
	v_mfma_f32_16x16x32_bf16 v[24:27], v[176:179], v[196:199], v[24:27]
	v_mfma_f32_16x16x32_bf16 v[16:19], v[168:171], v[204:207], v[16:19]
	v_mfma_f32_16x16x32_bf16 v[8:11], v[176:179], v[204:207], v[8:11]
	v_mfma_f32_16x16x32_bf16 v[4:7], v[168:171], v[212:215], v[4:7]
	v_mfma_f32_16x16x32_bf16 v[0:3], v[176:179], v[212:215], v[0:3]
	v_mfma_f32_16x16x32_bf16 v[48:51], v[172:175], v[192:195], v[48:51]
	v_mfma_f32_16x16x32_bf16 v[40:43], v[184:187], v[192:195], v[40:43]
	v_mfma_f32_16x16x32_bf16 v[32:35], v[172:175], v[200:203], v[32:35]
	v_mfma_f32_16x16x32_bf16 v[24:27], v[184:187], v[200:203], v[24:27]
	v_mfma_f32_16x16x32_bf16 v[16:19], v[172:175], v[208:211], v[16:19]
	v_mfma_f32_16x16x32_bf16 v[8:11], v[184:187], v[208:211], v[8:11]
	v_mfma_f32_16x16x32_bf16 v[4:7], v[172:175], v[216:219], v[4:7]
	v_mfma_f32_16x16x32_bf16 v[0:3], v[184:187], v[216:219], v[0:3]
	s_setprio 0
	s_barrier
.Lmid_gemm8:
	s_add_i32 s79, 0, 0x18000
	s_add_i32 s89, 0, 0x1c000
	v_add_u32_e32 v164, s79, v147
	v_add_u32_e32 v181, s89, v147
	ds_read_b128 v[152:155], v164
	ds_read_b128 v[156:159], v164 offset:1024
	ds_read_b128 v[160:163], v164 offset:2048
	ds_read_b128 v[164:167], v164 offset:3072
	ds_read_b128 v[168:171], v181
	ds_read_b128 v[172:175], v181 offset:1024
	ds_read_b128 v[176:179], v181 offset:2048
	ds_read_b128 v[184:187], v181 offset:3072
	s_add_u32 s54, s60, 0xb0000
	s_addc_u32 s55, s61, 0
	s_mov_b32 m0, s67
	v_lshl_add_u64 v[226:227], s[54:55], 0, v[128:129]
	ds_read_b128 v[188:191], v151 offset:32768
	ds_read_b128 v[192:195], v151 offset:33792
	ds_read_b128 v[196:199], v151 offset:34816
	ds_read_b128 v[200:203], v151 offset:35840
	ds_read_b128 v[204:207], v151 offset:36864
	ds_read_b128 v[208:211], v151 offset:37888
	ds_read_b128 v[212:215], v151 offset:38912
	ds_read_b128 v[216:219], v151 offset:39936
	global_load_lds_dwordx4 v[226:227], off
	v_lshl_add_u64 v[226:227], s[54:55], 0, v[132:133]
	s_mov_b32 m0, s68
	s_nop 0
	global_load_lds_dwordx4 v[226:227], off
	s_waitcnt vmcnt(8)
	s_waitcnt lgkmcnt(0)
	s_barrier
	s_setprio 1
	s_waitcnt lgkmcnt(0)
	v_mfma_f32_16x16x32_bf16 v[124:127], v[152:155], v[188:191], v[124:127]
	v_mfma_f32_16x16x32_bf16 v[120:123], v[160:163], v[188:191], v[120:123]
	v_mfma_f32_16x16x32_bf16 v[116:119], v[152:155], v[196:199], v[116:119]
	v_mfma_f32_16x16x32_bf16 v[108:111], v[160:163], v[196:199], v[108:111]
	v_mfma_f32_16x16x32_bf16 v[100:103], v[152:155], v[204:207], v[100:103]
	v_mfma_f32_16x16x32_bf16 v[92:95], v[160:163], v[204:207], v[92:95]
	v_mfma_f32_16x16x32_bf16 v[84:87], v[152:155], v[212:215], v[84:87]
	v_mfma_f32_16x16x32_bf16 v[76:79], v[160:163], v[212:215], v[76:79]
	v_mfma_f32_16x16x32_bf16 v[124:127], v[156:159], v[192:195], v[124:127]
	v_mfma_f32_16x16x32_bf16 v[120:123], v[164:167], v[192:195], v[120:123]
	v_mfma_f32_16x16x32_bf16 v[116:119], v[156:159], v[200:203], v[116:119]
	v_mfma_f32_16x16x32_bf16 v[108:111], v[164:167], v[200:203], v[108:111]
	v_mfma_f32_16x16x32_bf16 v[100:103], v[156:159], v[208:211], v[100:103]
	v_mfma_f32_16x16x32_bf16 v[92:95], v[164:167], v[208:211], v[92:95]
	v_mfma_f32_16x16x32_bf16 v[84:87], v[156:159], v[216:219], v[84:87]
	v_mfma_f32_16x16x32_bf16 v[76:79], v[164:167], v[216:219], v[76:79]
	s_setprio 0
	s_setprio 1
	v_mfma_f32_16x16x32_bf16 v[112:115], v[168:171], v[188:191], v[112:115]
	v_mfma_f32_16x16x32_bf16 v[104:107], v[176:179], v[188:191], v[104:107]
	v_mfma_f32_16x16x32_bf16 v[96:99], v[168:171], v[196:199], v[96:99]
	v_mfma_f32_16x16x32_bf16 v[88:91], v[176:179], v[196:199], v[88:91]
	v_mfma_f32_16x16x32_bf16 v[80:83], v[168:171], v[204:207], v[80:83]
	v_mfma_f32_16x16x32_bf16 v[72:75], v[176:179], v[204:207], v[72:75]
	v_mfma_f32_16x16x32_bf16 v[68:71], v[168:171], v[212:215], v[68:71]
	v_mfma_f32_16x16x32_bf16 v[64:67], v[176:179], v[212:215], v[64:67]
	v_mfma_f32_16x16x32_bf16 v[112:115], v[172:175], v[192:195], v[112:115]
	v_mfma_f32_16x16x32_bf16 v[104:107], v[184:187], v[192:195], v[104:107]
	v_mfma_f32_16x16x32_bf16 v[96:99], v[172:175], v[200:203], v[96:99]
	v_mfma_f32_16x16x32_bf16 v[88:91], v[184:187], v[200:203], v[88:91]
	v_mfma_f32_16x16x32_bf16 v[80:83], v[172:175], v[208:211], v[80:83]
	v_mfma_f32_16x16x32_bf16 v[72:75], v[184:187], v[208:211], v[72:75]
	v_mfma_f32_16x16x32_bf16 v[68:71], v[172:175], v[216:219], v[68:71]
	v_mfma_f32_16x16x32_bf16 v[64:67], v[184:187], v[216:219], v[64:67]
	s_setprio 0
	s_barrier
	s_add_i32 s54, s79, s64
	v_lshl_add_u64 v[144:145], v[144:145], 0, s[16:17]
	s_mov_b32 m0, s54
	ds_read_b128 v[188:191], v151 offset:49152
	ds_read_b128 v[192:195], v151 offset:50176
	ds_read_b128 v[196:199], v151 offset:51200
	ds_read_b128 v[200:203], v151 offset:52224
	ds_read_b128 v[204:207], v151 offset:53248
	ds_read_b128 v[208:211], v151 offset:54272
	ds_read_b128 v[212:215], v151 offset:55296
	ds_read_b128 v[216:219], v151 offset:56320
	global_load_lds_dwordx4 v[144:145], off
	s_add_i32 m0, s54, 0x2000
	s_add_u32 s54, s58, 0xb0080
	v_lshl_add_u64 v[144:145], v[220:221], 0, s[16:17]
	s_addc_u32 s55, s59, 0
	s_add_i32 s58, s89, s64
	global_load_lds_dwordx4 v[144:145], off
	v_lshl_add_u64 v[144:145], s[54:55], 0, v[130:131]
	s_mov_b32 m0, s58
	s_nop 0
	global_load_lds_dwordx4 v[144:145], off
	v_lshl_add_u64 v[144:145], s[54:55], 0, v[134:135]
	s_add_i32 m0, s58, 0x2000
	s_nop 0
	global_load_lds_dwordx4 v[144:145], off
	v_lshl_add_u64 v[144:145], v[222:223], 0, s[16:17]
	s_mov_b32 m0, s70
	s_nop 0
	global_load_lds_dwordx4 v[144:145], off
	v_lshl_add_u64 v[144:145], v[224:225], 0, s[16:17]
	s_mov_b32 m0, s71
	s_nop 0
	global_load_lds_dwordx4 v[144:145], off
	s_waitcnt vmcnt(8)
	s_waitcnt lgkmcnt(0)
	s_barrier
	s_setprio 1
	s_waitcnt lgkmcnt(0)
	v_mfma_f32_16x16x32_bf16 v[60:63], v[152:155], v[188:191], v[60:63]
	v_mfma_f32_16x16x32_bf16 v[56:59], v[160:163], v[188:191], v[56:59]
	v_mfma_f32_16x16x32_bf16 v[52:55], v[152:155], v[196:199], v[52:55]
	v_mfma_f32_16x16x32_bf16 v[44:47], v[160:163], v[196:199], v[44:47]
	v_mfma_f32_16x16x32_bf16 v[36:39], v[152:155], v[204:207], v[36:39]
	v_mfma_f32_16x16x32_bf16 v[28:31], v[160:163], v[204:207], v[28:31]
	v_mfma_f32_16x16x32_bf16 v[20:23], v[152:155], v[212:215], v[20:23]
	v_mfma_f32_16x16x32_bf16 v[12:15], v[160:163], v[212:215], v[12:15]
	v_mfma_f32_16x16x32_bf16 v[60:63], v[156:159], v[192:195], v[60:63]
	v_mfma_f32_16x16x32_bf16 v[56:59], v[164:167], v[192:195], v[56:59]
	v_mfma_f32_16x16x32_bf16 v[52:55], v[156:159], v[200:203], v[52:55]
	v_mfma_f32_16x16x32_bf16 v[44:47], v[164:167], v[200:203], v[44:47]
	v_mfma_f32_16x16x32_bf16 v[36:39], v[156:159], v[208:211], v[36:39]
	v_mfma_f32_16x16x32_bf16 v[28:31], v[164:167], v[208:211], v[28:31]
	v_mfma_f32_16x16x32_bf16 v[20:23], v[156:159], v[216:219], v[20:23]
	v_mfma_f32_16x16x32_bf16 v[12:15], v[164:167], v[216:219], v[12:15]
	s_setprio 0
	s_setprio 1
	v_mfma_f32_16x16x32_bf16 v[48:51], v[168:171], v[188:191], v[48:51]
	v_mfma_f32_16x16x32_bf16 v[40:43], v[176:179], v[188:191], v[40:43]
	v_mfma_f32_16x16x32_bf16 v[32:35], v[168:171], v[196:199], v[32:35]
	v_mfma_f32_16x16x32_bf16 v[24:27], v[176:179], v[196:199], v[24:27]
	v_mfma_f32_16x16x32_bf16 v[16:19], v[168:171], v[204:207], v[16:19]
	v_mfma_f32_16x16x32_bf16 v[8:11], v[176:179], v[204:207], v[8:11]
	v_mfma_f32_16x16x32_bf16 v[4:7], v[168:171], v[212:215], v[4:7]
	v_mfma_f32_16x16x32_bf16 v[0:3], v[176:179], v[212:215], v[0:3]
	v_mfma_f32_16x16x32_bf16 v[48:51], v[172:175], v[192:195], v[48:51]
	v_mfma_f32_16x16x32_bf16 v[40:43], v[184:187], v[192:195], v[40:43]
	v_mfma_f32_16x16x32_bf16 v[32:35], v[172:175], v[200:203], v[32:35]
	v_mfma_f32_16x16x32_bf16 v[24:27], v[184:187], v[200:203], v[24:27]
	v_mfma_f32_16x16x32_bf16 v[16:19], v[172:175], v[208:211], v[16:19]
	v_mfma_f32_16x16x32_bf16 v[8:11], v[184:187], v[208:211], v[8:11]
	v_mfma_f32_16x16x32_bf16 v[4:7], v[172:175], v[216:219], v[4:7]
	v_mfma_f32_16x16x32_bf16 v[0:3], v[184:187], v[216:219], v[0:3]
	s_setprio 0
	s_barrier
	s_add_i32 s88, s88, 2
	s_add_u32 s86, s86, 0x100
	s_addc_u32 s87, s87, 0
	s_cmp_gt_u32 s88, 41
	s_mov_b64 s[54:55], s[56:57]
	s_cbranch_scc0 .LBB0_1031
	s_and_b64 vcc, exec, s[18:19]
	s_cbranch_vccz .LBB0_1034
	s_barrier

.LBB0_1161:
	s_ashr_i32 s53, s52, 31
	s_lshl_b64 s[54:55], s[52:53], 19
	s_add_u32 s54, s80, s54
	s_addc_u32 s55, s81, s55
	s_and_b64 s[56:57], s[10:11], exec
	s_cselect_b32 s53, s55, s61
	s_cselect_b32 s83, s54, s60
	s_ashr_i32 s49, s48, 31
	s_lshl_b64 s[56:57], s[48:49], 19
	s_add_u32 s56, s66, s56
	s_addc_u32 s57, s67, s57
	s_and_b64 s[64:65], s[10:11], exec
	s_cselect_b32 s49, s57, s63
	s_cselect_b32 s84, s56, s62
	s_add_u32 s60, s60, 0x40080
	s_addc_u32 s61, s61, 0
	s_add_u32 s85, s62, 0x100
	s_addc_u32 s86, s63, 0
	s_mov_b32 s87, -2
	ds_read_b128 v[152:155], v148
	ds_read_b128 v[156:159], v148 offset:1024
	ds_read_b128 v[160:163], v148 offset:2048
	ds_read_b128 v[164:167], v148 offset:3072
	ds_read_b128 v[168:171], v149
	ds_read_b128 v[172:175], v149 offset:1024
	ds_read_b128 v[176:179], v149 offset:2048
	ds_read_b128 v[184:187], v149 offset:3072
	s_add_u32 s62, s60, 0xfffc0080
	s_addc_u32 s63, s61, -1
	s_cmp_eq_u32 s87, 12
	s_cselect_b32 s65, s53, s63
	s_cselect_b32 s64, s83, s62
	s_cselect_b32 s63, s49, s86
	s_cselect_b32 s62, s84, s85
	v_lshl_add_u64 v[220:221], s[60:61], 0, v[138:139]
	s_add_i32 m0, s69, 0xc000
	ds_read_b128 v[188:191], v150
	ds_read_b128 v[192:195], v150 offset:1024
	ds_read_b128 v[196:199], v150 offset:2048
	ds_read_b128 v[200:203], v150 offset:3072
	ds_read_b128 v[204:207], v150 offset:4096
	ds_read_b128 v[208:211], v150 offset:5120
	ds_read_b128 v[212:215], v150 offset:6144
	ds_read_b128 v[216:219], v150 offset:7168
	global_load_lds_dwordx4 v[220:221], off
	v_lshl_add_u64 v[220:221], s[60:61], 0, v[140:141]
	s_add_i32 m0, s69, 0xe000
	s_nop 0
	global_load_lds_dwordx4 v[220:221], off
	s_waitcnt vmcnt(8)
	s_waitcnt lgkmcnt(0)
	s_barrier
	s_setprio 1
	s_waitcnt lgkmcnt(0)
	v_mfma_f32_16x16x32_bf16 v[124:127], v[152:155], v[188:191], 0
	v_mfma_f32_16x16x32_bf16 v[120:123], v[160:163], v[188:191], 0
	v_mfma_f32_16x16x32_bf16 v[116:119], v[152:155], v[196:199], 0
	v_mfma_f32_16x16x32_bf16 v[112:115], v[160:163], v[196:199], 0
	v_mfma_f32_16x16x32_bf16 v[108:111], v[152:155], v[204:207], 0
	v_mfma_f32_16x16x32_bf16 v[104:107], v[160:163], v[204:207], 0
	v_mfma_f32_16x16x32_bf16 v[100:103], v[152:155], v[212:215], 0
	v_mfma_f32_16x16x32_bf16 v[96:99], v[160:163], v[212:215], 0
	v_mfma_f32_16x16x32_bf16 v[124:127], v[156:159], v[192:195], v[124:127]
	v_mfma_f32_16x16x32_bf16 v[120:123], v[164:167], v[192:195], v[120:123]
	v_mfma_f32_16x16x32_bf16 v[116:119], v[156:159], v[200:203], v[116:119]
	v_mfma_f32_16x16x32_bf16 v[112:115], v[164:167], v[200:203], v[112:115]
	v_mfma_f32_16x16x32_bf16 v[108:111], v[156:159], v[208:211], v[108:111]
	v_mfma_f32_16x16x32_bf16 v[104:107], v[164:167], v[208:211], v[104:107]
	v_mfma_f32_16x16x32_bf16 v[100:103], v[156:159], v[216:219], v[100:103]
	v_mfma_f32_16x16x32_bf16 v[96:99], v[164:167], v[216:219], v[96:99]
	s_setprio 0
	s_setprio 1
	v_mfma_f32_16x16x32_bf16 v[68:71], v[168:171], v[188:191], 0
	v_mfma_f32_16x16x32_bf16 v[64:67], v[176:179], v[188:191], 0
	v_mfma_f32_16x16x32_bf16 v[52:55], v[168:171], v[196:199], 0
	v_mfma_f32_16x16x32_bf16 v[48:51], v[176:179], v[196:199], 0
	v_mfma_f32_16x16x32_bf16 v[44:47], v[168:171], v[204:207], 0
	v_mfma_f32_16x16x32_bf16 v[40:43], v[176:179], v[204:207], 0
	v_mfma_f32_16x16x32_bf16 v[36:39], v[168:171], v[212:215], 0
	v_mfma_f32_16x16x32_bf16 v[32:35], v[176:179], v[212:215], 0
	v_mfma_f32_16x16x32_bf16 v[68:71], v[172:175], v[192:195], v[68:71]
	v_mfma_f32_16x16x32_bf16 v[64:67], v[184:187], v[192:195], v[64:67]
	v_mfma_f32_16x16x32_bf16 v[52:55], v[172:175], v[200:203], v[52:55]
	v_mfma_f32_16x16x32_bf16 v[48:51], v[184:187], v[200:203], v[48:51]
	v_mfma_f32_16x16x32_bf16 v[44:47], v[172:175], v[208:211], v[44:47]
	v_mfma_f32_16x16x32_bf16 v[40:43], v[184:187], v[208:211], v[40:43]
	v_mfma_f32_16x16x32_bf16 v[36:39], v[172:175], v[216:219], v[36:39]
	v_mfma_f32_16x16x32_bf16 v[32:35], v[184:187], v[216:219], v[32:35]
	s_setprio 0
	s_barrier
	s_add_i32 s79, s77, s68
	v_lshl_add_u64 v[220:221], s[62:63], 0, v[130:131]
	s_mov_b32 m0, s79
	ds_read_b128 v[188:191], v150 offset:16384
	ds_read_b128 v[192:195], v150 offset:17408
	ds_read_b128 v[196:199], v150 offset:18432
	ds_read_b128 v[200:203], v150 offset:19456
	ds_read_b128 v[204:207], v150 offset:20480
	ds_read_b128 v[208:211], v150 offset:21504
	ds_read_b128 v[212:215], v150 offset:22528
	ds_read_b128 v[216:219], v150 offset:23552
	global_load_lds_dwordx4 v[220:221], off
	s_add_i32 m0, s79, 0x2000
	s_add_u32 s88, s62, 0x40000
	v_lshl_add_u64 v[222:223], s[62:63], 0, v[134:135]
	s_addc_u32 s89, s63, 0
	s_add_i32 s79, s82, s68
	global_load_lds_dwordx4 v[222:223], off
	v_lshl_add_u64 v[224:225], s[88:89], 0, v[130:131]
	s_mov_b32 m0, s79
	v_lshl_add_u64 v[226:227], s[64:65], 0, v[132:133]
	global_load_lds_dwordx4 v[224:225], off
	v_lshl_add_u64 v[224:225], s[88:89], 0, v[134:135]
	s_add_i32 m0, s79, 0x2000
	s_nop 0
	global_load_lds_dwordx4 v[224:225], off
	v_lshl_add_u64 v[224:225], s[64:65], 0, v[128:129]
	s_mov_b32 m0, s69
	s_nop 0
	global_load_lds_dwordx4 v[224:225], off
	s_mov_b32 m0, s70
	s_nop 0
	global_load_lds_dwordx4 v[226:227], off
	s_waitcnt vmcnt(8)
	s_waitcnt lgkmcnt(0)
	s_barrier
	s_setprio 1
	s_waitcnt lgkmcnt(0)
	v_mfma_f32_16x16x32_bf16 v[92:95], v[152:155], v[188:191], 0
	v_mfma_f32_16x16x32_bf16 v[88:91], v[160:163], v[188:191], 0
	v_mfma_f32_16x16x32_bf16 v[84:87], v[152:155], v[196:199], 0
	v_mfma_f32_16x16x32_bf16 v[80:83], v[160:163], v[196:199], 0
	v_mfma_f32_16x16x32_bf16 v[76:79], v[152:155], v[204:207], 0
	v_mfma_f32_16x16x32_bf16 v[72:75], v[160:163], v[204:207], 0
	v_mfma_f32_16x16x32_bf16 v[60:63], v[152:155], v[212:215], 0
	v_mfma_f32_16x16x32_bf16 v[56:59], v[160:163], v[212:215], 0
	v_mfma_f32_16x16x32_bf16 v[92:95], v[156:159], v[192:195], v[92:95]
	v_mfma_f32_16x16x32_bf16 v[88:91], v[164:167], v[192:195], v[88:91]
	v_mfma_f32_16x16x32_bf16 v[84:87], v[156:159], v[200:203], v[84:87]
	v_mfma_f32_16x16x32_bf16 v[80:83], v[164:167], v[200:203], v[80:83]
	v_mfma_f32_16x16x32_bf16 v[76:79], v[156:159], v[208:211], v[76:79]
	v_mfma_f32_16x16x32_bf16 v[72:75], v[164:167], v[208:211], v[72:75]
	v_mfma_f32_16x16x32_bf16 v[60:63], v[156:159], v[216:219], v[60:63]
	v_mfma_f32_16x16x32_bf16 v[56:59], v[164:167], v[216:219], v[56:59]
	s_setprio 0
	s_setprio 1
	v_mfma_f32_16x16x32_bf16 v[28:31], v[168:171], v[188:191], 0
	v_mfma_f32_16x16x32_bf16 v[24:27], v[176:179], v[188:191], 0
	v_mfma_f32_16x16x32_bf16 v[20:23], v[168:171], v[196:199], 0
	v_mfma_f32_16x16x32_bf16 v[16:19], v[176:179], v[196:199], 0
	v_mfma_f32_16x16x32_bf16 v[12:15], v[168:171], v[204:207], 0
	v_mfma_f32_16x16x32_bf16 v[8:11], v[176:179], v[204:207], 0
	v_mfma_f32_16x16x32_bf16 v[4:7], v[168:171], v[212:215], 0
	v_mfma_f32_16x16x32_bf16 v[0:3], v[176:179], v[212:215], 0
	v_mfma_f32_16x16x32_bf16 v[28:31], v[172:175], v[192:195], v[28:31]
	v_mfma_f32_16x16x32_bf16 v[24:27], v[184:187], v[192:195], v[24:27]
	v_mfma_f32_16x16x32_bf16 v[20:23], v[172:175], v[200:203], v[20:23]
	v_mfma_f32_16x16x32_bf16 v[16:19], v[184:187], v[200:203], v[16:19]
	v_mfma_f32_16x16x32_bf16 v[12:15], v[172:175], v[208:211], v[12:15]
	v_mfma_f32_16x16x32_bf16 v[8:11], v[184:187], v[208:211], v[8:11]
	v_mfma_f32_16x16x32_bf16 v[4:7], v[172:175], v[216:219], v[4:7]
	v_mfma_f32_16x16x32_bf16 v[0:3], v[184:187], v[216:219], v[0:3]
	s_setprio 0
	s_barrier
	s_branch .Lmid_gemm9
.LBB0_1162:
	ds_read_b128 v[152:155], v148
	ds_read_b128 v[156:159], v148 offset:1024
	ds_read_b128 v[160:163], v148 offset:2048
	ds_read_b128 v[164:167], v148 offset:3072
	ds_read_b128 v[168:171], v149
	ds_read_b128 v[172:175], v149 offset:1024
	ds_read_b128 v[176:179], v149 offset:2048
	ds_read_b128 v[184:187], v149 offset:3072
	s_add_u32 s62, s60, 0xfffc0080
	s_addc_u32 s63, s61, -1
	s_cmp_eq_u32 s87, 12
	s_cselect_b32 s65, s53, s63
	s_cselect_b32 s64, s83, s62
	s_cselect_b32 s63, s49, s86
	s_cselect_b32 s62, s84, s85
	v_lshl_add_u64 v[220:221], s[60:61], 0, v[138:139]
	s_add_i32 m0, s69, 0xc000
	ds_read_b128 v[188:191], v150
	ds_read_b128 v[192:195], v150 offset:1024
	ds_read_b128 v[196:199], v150 offset:2048
	ds_read_b128 v[200:203], v150 offset:3072
	ds_read_b128 v[204:207], v150 offset:4096
	ds_read_b128 v[208:211], v150 offset:5120
	ds_read_b128 v[212:215], v150 offset:6144
	ds_read_b128 v[216:219], v150 offset:7168
	global_load_lds_dwordx4 v[220:221], off
	v_lshl_add_u64 v[220:221], s[60:61], 0, v[140:141]
	s_add_i32 m0, s69, 0xe000
	s_nop 0
	global_load_lds_dwordx4 v[220:221], off
	s_waitcnt vmcnt(8)
	s_waitcnt lgkmcnt(0)
	s_barrier
	s_setprio 1
	s_waitcnt lgkmcnt(0)
	v_mfma_f32_16x16x32_bf16 v[124:127], v[152:155], v[188:191], v[124:127]
	v_mfma_f32_16x16x32_bf16 v[120:123], v[160:163], v[188:191], v[120:123]
	v_mfma_f32_16x16x32_bf16 v[116:119], v[152:155], v[196:199], v[116:119]
	v_mfma_f32_16x16x32_bf16 v[112:115], v[160:163], v[196:199], v[112:115]
	v_mfma_f32_16x16x32_bf16 v[108:111], v[152:155], v[204:207], v[108:111]
	v_mfma_f32_16x16x32_bf16 v[104:107], v[160:163], v[204:207], v[104:107]
	v_mfma_f32_16x16x32_bf16 v[100:103], v[152:155], v[212:215], v[100:103]
	v_mfma_f32_16x16x32_bf16 v[96:99], v[160:163], v[212:215], v[96:99]
	v_mfma_f32_16x16x32_bf16 v[124:127], v[156:159], v[192:195], v[124:127]
	v_mfma_f32_16x16x32_bf16 v[120:123], v[164:167], v[192:195], v[120:123]
	v_mfma_f32_16x16x32_bf16 v[116:119], v[156:159], v[200:203], v[116:119]
	v_mfma_f32_16x16x32_bf16 v[112:115], v[164:167], v[200:203], v[112:115]
	v_mfma_f32_16x16x32_bf16 v[108:111], v[156:159], v[208:211], v[108:111]
	v_mfma_f32_16x16x32_bf16 v[104:107], v[164:167], v[208:211], v[104:107]
	v_mfma_f32_16x16x32_bf16 v[100:103], v[156:159], v[216:219], v[100:103]
	v_mfma_f32_16x16x32_bf16 v[96:99], v[164:167], v[216:219], v[96:99]
	s_setprio 0
	s_setprio 1
	v_mfma_f32_16x16x32_bf16 v[68:71], v[168:171], v[188:191], v[68:71]
	v_mfma_f32_16x16x32_bf16 v[64:67], v[176:179], v[188:191], v[64:67]
	v_mfma_f32_16x16x32_bf16 v[52:55], v[168:171], v[196:199], v[52:55]
	v_mfma_f32_16x16x32_bf16 v[48:51], v[176:179], v[196:199], v[48:51]
	v_mfma_f32_16x16x32_bf16 v[44:47], v[168:171], v[204:207], v[44:47]
	v_mfma_f32_16x16x32_bf16 v[40:43], v[176:179], v[204:207], v[40:43]
	v_mfma_f32_16x16x32_bf16 v[36:39], v[168:171], v[212:215], v[36:39]
	v_mfma_f32_16x16x32_bf16 v[32:35], v[176:179], v[212:215], v[32:35]
	v_mfma_f32_16x16x32_bf16 v[68:71], v[172:175], v[192:195], v[68:71]
	v_mfma_f32_16x16x32_bf16 v[64:67], v[184:187], v[192:195], v[64:67]
	v_mfma_f32_16x16x32_bf16 v[52:55], v[172:175], v[200:203], v[52:55]
	v_mfma_f32_16x16x32_bf16 v[48:51], v[184:187], v[200:203], v[48:51]
	v_mfma_f32_16x16x32_bf16 v[44:47], v[172:175], v[208:211], v[44:47]
	v_mfma_f32_16x16x32_bf16 v[40:43], v[184:187], v[208:211], v[40:43]
	v_mfma_f32_16x16x32_bf16 v[36:39], v[172:175], v[216:219], v[36:39]
	v_mfma_f32_16x16x32_bf16 v[32:35], v[184:187], v[216:219], v[32:35]
	s_setprio 0
	s_barrier
	s_add_i32 s79, s77, s68
	v_lshl_add_u64 v[220:221], s[62:63], 0, v[130:131]
	s_mov_b32 m0, s79
	ds_read_b128 v[188:191], v150 offset:16384
	ds_read_b128 v[192:195], v150 offset:17408
	ds_read_b128 v[196:199], v150 offset:18432
	ds_read_b128 v[200:203], v150 offset:19456
	ds_read_b128 v[204:207], v150 offset:20480
	ds_read_b128 v[208:211], v150 offset:21504
	ds_read_b128 v[212:215], v150 offset:22528
	ds_read_b128 v[216:219], v150 offset:23552
	global_load_lds_dwordx4 v[220:221], off
	s_add_i32 m0, s79, 0x2000
	s_add_u32 s88, s62, 0x40000
	v_lshl_add_u64 v[222:223], s[62:63], 0, v[134:135]
	s_addc_u32 s89, s63, 0
	s_add_i32 s79, s82, s68
	global_load_lds_dwordx4 v[222:223], off
	v_lshl_add_u64 v[224:225], s[88:89], 0, v[130:131]
	s_mov_b32 m0, s79
	v_lshl_add_u64 v[226:227], s[64:65], 0, v[132:133]
	global_load_lds_dwordx4 v[224:225], off
	v_lshl_add_u64 v[224:225], s[88:89], 0, v[134:135]
	s_add_i32 m0, s79, 0x2000
	s_nop 0
	global_load_lds_dwordx4 v[224:225], off
	v_lshl_add_u64 v[224:225], s[64:65], 0, v[128:129]
	s_mov_b32 m0, s69
	s_nop 0
	global_load_lds_dwordx4 v[224:225], off
	s_mov_b32 m0, s70
	s_nop 0
	global_load_lds_dwordx4 v[226:227], off
	s_waitcnt vmcnt(8)
	s_waitcnt lgkmcnt(0)
	s_barrier
	s_setprio 1
	s_waitcnt lgkmcnt(0)
	v_mfma_f32_16x16x32_bf16 v[92:95], v[152:155], v[188:191], v[92:95]
	v_mfma_f32_16x16x32_bf16 v[88:91], v[160:163], v[188:191], v[88:91]
	v_mfma_f32_16x16x32_bf16 v[84:87], v[152:155], v[196:199], v[84:87]
	v_mfma_f32_16x16x32_bf16 v[80:83], v[160:163], v[196:199], v[80:83]
	v_mfma_f32_16x16x32_bf16 v[76:79], v[152:155], v[204:207], v[76:79]
	v_mfma_f32_16x16x32_bf16 v[72:75], v[160:163], v[204:207], v[72:75]
	v_mfma_f32_16x16x32_bf16 v[60:63], v[152:155], v[212:215], v[60:63]
	v_mfma_f32_16x16x32_bf16 v[56:59], v[160:163], v[212:215], v[56:59]
	v_mfma_f32_16x16x32_bf16 v[92:95], v[156:159], v[192:195], v[92:95]
	v_mfma_f32_16x16x32_bf16 v[88:91], v[164:167], v[192:195], v[88:91]
	v_mfma_f32_16x16x32_bf16 v[84:87], v[156:159], v[200:203], v[84:87]
	v_mfma_f32_16x16x32_bf16 v[80:83], v[164:167], v[200:203], v[80:83]
	v_mfma_f32_16x16x32_bf16 v[76:79], v[156:159], v[208:211], v[76:79]
	v_mfma_f32_16x16x32_bf16 v[72:75], v[164:167], v[208:211], v[72:75]
	v_mfma_f32_16x16x32_bf16 v[60:63], v[156:159], v[216:219], v[60:63]
	v_mfma_f32_16x16x32_bf16 v[56:59], v[164:167], v[216:219], v[56:59]
	s_setprio 0
	s_setprio 1
	v_mfma_f32_16x16x32_bf16 v[28:31], v[168:171], v[188:191], v[28:31]
	v_mfma_f32_16x16x32_bf16 v[24:27], v[176:179], v[188:191], v[24:27]
	v_mfma_f32_16x16x32_bf16 v[20:23], v[168:171], v[196:199], v[20:23]
	v_mfma_f32_16x16x32_bf16 v[16:19], v[176:179], v[196:199], v[16:19]
	v_mfma_f32_16x16x32_bf16 v[12:15], v[168:171], v[204:207], v[12:15]
	v_mfma_f32_16x16x32_bf16 v[8:11], v[176:179], v[204:207], v[8:11]
	v_mfma_f32_16x16x32_bf16 v[4:7], v[168:171], v[212:215], v[4:7]
	v_mfma_f32_16x16x32_bf16 v[0:3], v[176:179], v[212:215], v[0:3]
	v_mfma_f32_16x16x32_bf16 v[28:31], v[172:175], v[192:195], v[28:31]
	v_mfma_f32_16x16x32_bf16 v[24:27], v[184:187], v[192:195], v[24:27]
	v_mfma_f32_16x16x32_bf16 v[20:23], v[172:175], v[200:203], v[20:23]
	v_mfma_f32_16x16x32_bf16 v[16:19], v[184:187], v[200:203], v[16:19]
	v_mfma_f32_16x16x32_bf16 v[12:15], v[172:175], v[208:211], v[12:15]
	v_mfma_f32_16x16x32_bf16 v[8:11], v[184:187], v[208:211], v[8:11]
	v_mfma_f32_16x16x32_bf16 v[4:7], v[172:175], v[216:219], v[4:7]
	v_mfma_f32_16x16x32_bf16 v[0:3], v[184:187], v[216:219], v[0:3]
	s_setprio 0
	s_barrier
.Lmid_gemm9:
	s_add_i32 s79, 0, 0x18000
	s_add_i32 s88, 0, 0x1c000
	v_add_u32_e32 v164, s79, v147
	v_add_u32_e32 v181, s88, v147
	ds_read_b128 v[152:155], v164
	ds_read_b128 v[156:159], v164 offset:1024
	ds_read_b128 v[160:163], v164 offset:2048
	ds_read_b128 v[164:167], v164 offset:3072
	ds_read_b128 v[168:171], v181
	ds_read_b128 v[172:175], v181 offset:1024
	ds_read_b128 v[176:179], v181 offset:2048
	ds_read_b128 v[184:187], v181 offset:3072
	s_add_u32 s64, s64, 0x40000
	s_addc_u32 s65, s65, 0
	s_mov_b32 m0, s71
	v_lshl_add_u64 v[228:229], s[64:65], 0, v[128:129]
	ds_read_b128 v[188:191], v150 offset:32768
	ds_read_b128 v[192:195], v150 offset:33792
	ds_read_b128 v[196:199], v150 offset:34816
	ds_read_b128 v[200:203], v150 offset:35840
	ds_read_b128 v[204:207], v150 offset:36864
	ds_read_b128 v[208:211], v150 offset:37888
	ds_read_b128 v[212:215], v150 offset:38912
	ds_read_b128 v[216:219], v150 offset:39936
	global_load_lds_dwordx4 v[228:229], off
	v_lshl_add_u64 v[228:229], s[64:65], 0, v[132:133]
	s_mov_b32 m0, s72
	s_nop 0
	global_load_lds_dwordx4 v[228:229], off
	s_waitcnt vmcnt(8)
	s_waitcnt lgkmcnt(0)
	s_barrier
	s_setprio 1
	s_waitcnt lgkmcnt(0)
	v_mfma_f32_16x16x32_bf16 v[124:127], v[152:155], v[188:191], v[124:127]
	v_mfma_f32_16x16x32_bf16 v[120:123], v[160:163], v[188:191], v[120:123]
	v_mfma_f32_16x16x32_bf16 v[116:119], v[152:155], v[196:199], v[116:119]
	v_mfma_f32_16x16x32_bf16 v[112:115], v[160:163], v[196:199], v[112:115]
	v_mfma_f32_16x16x32_bf16 v[108:111], v[152:155], v[204:207], v[108:111]
	v_mfma_f32_16x16x32_bf16 v[104:107], v[160:163], v[204:207], v[104:107]
	v_mfma_f32_16x16x32_bf16 v[100:103], v[152:155], v[212:215], v[100:103]
	v_mfma_f32_16x16x32_bf16 v[96:99], v[160:163], v[212:215], v[96:99]
	v_mfma_f32_16x16x32_bf16 v[124:127], v[156:159], v[192:195], v[124:127]
	v_mfma_f32_16x16x32_bf16 v[120:123], v[164:167], v[192:195], v[120:123]
	v_mfma_f32_16x16x32_bf16 v[116:119], v[156:159], v[200:203], v[116:119]
	v_mfma_f32_16x16x32_bf16 v[112:115], v[164:167], v[200:203], v[112:115]
	v_mfma_f32_16x16x32_bf16 v[108:111], v[156:159], v[208:211], v[108:111]
	v_mfma_f32_16x16x32_bf16 v[104:107], v[164:167], v[208:211], v[104:107]
	v_mfma_f32_16x16x32_bf16 v[100:103], v[156:159], v[216:219], v[100:103]
	v_mfma_f32_16x16x32_bf16 v[96:99], v[164:167], v[216:219], v[96:99]
	s_setprio 0
	s_setprio 1
	v_mfma_f32_16x16x32_bf16 v[68:71], v[168:171], v[188:191], v[68:71]
	v_mfma_f32_16x16x32_bf16 v[64:67], v[176:179], v[188:191], v[64:67]
	v_mfma_f32_16x16x32_bf16 v[52:55], v[168:171], v[196:199], v[52:55]
	v_mfma_f32_16x16x32_bf16 v[48:51], v[176:179], v[196:199], v[48:51]
	v_mfma_f32_16x16x32_bf16 v[44:47], v[168:171], v[204:207], v[44:47]
	v_mfma_f32_16x16x32_bf16 v[40:43], v[176:179], v[204:207], v[40:43]
	v_mfma_f32_16x16x32_bf16 v[36:39], v[168:171], v[212:215], v[36:39]
	v_mfma_f32_16x16x32_bf16 v[32:35], v[176:179], v[212:215], v[32:35]
	v_mfma_f32_16x16x32_bf16 v[68:71], v[172:175], v[192:195], v[68:71]
	v_mfma_f32_16x16x32_bf16 v[64:67], v[184:187], v[192:195], v[64:67]
	v_mfma_f32_16x16x32_bf16 v[52:55], v[172:175], v[200:203], v[52:55]
	v_mfma_f32_16x16x32_bf16 v[48:51], v[184:187], v[200:203], v[48:51]
	v_mfma_f32_16x16x32_bf16 v[44:47], v[172:175], v[208:211], v[44:47]
	v_mfma_f32_16x16x32_bf16 v[40:43], v[184:187], v[208:211], v[40:43]
	v_mfma_f32_16x16x32_bf16 v[36:39], v[172:175], v[216:219], v[36:39]
	v_mfma_f32_16x16x32_bf16 v[32:35], v[184:187], v[216:219], v[32:35]
	s_setprio 0
	s_barrier
	s_add_i32 s64, s79, s68
	v_lshl_add_u64 v[220:221], v[220:221], 0, s[12:13]
	s_mov_b32 m0, s64
	ds_read_b128 v[188:191], v150 offset:49152
	ds_read_b128 v[192:195], v150 offset:50176
	ds_read_b128 v[196:199], v150 offset:51200
	ds_read_b128 v[200:203], v150 offset:52224
	ds_read_b128 v[204:207], v150 offset:53248
	ds_read_b128 v[208:211], v150 offset:54272
	ds_read_b128 v[212:215], v150 offset:55296
	ds_read_b128 v[216:219], v150 offset:56320
	global_load_lds_dwordx4 v[220:221], off
	s_add_i32 m0, s64, 0x2000
	s_add_u32 s62, s62, 0x40080
	v_lshl_add_u64 v[220:221], v[222:223], 0, s[12:13]
	s_addc_u32 s63, s63, 0
	s_add_i32 s64, s88, s68
	global_load_lds_dwordx4 v[220:221], off
	v_lshl_add_u64 v[220:221], s[62:63], 0, v[130:131]
	s_mov_b32 m0, s64
	s_nop 0
	global_load_lds_dwordx4 v[220:221], off
	v_lshl_add_u64 v[220:221], s[62:63], 0, v[134:135]
	s_add_i32 m0, s64, 0x2000
	s_nop 0
	global_load_lds_dwordx4 v[220:221], off
	v_lshl_add_u64 v[220:221], v[224:225], 0, s[12:13]
	s_mov_b32 m0, s75
	s_nop 0
	global_load_lds_dwordx4 v[220:221], off
	v_lshl_add_u64 v[220:221], v[226:227], 0, s[12:13]
	s_mov_b32 m0, s76
	s_nop 0
	global_load_lds_dwordx4 v[220:221], off
	s_waitcnt vmcnt(8)
	s_waitcnt lgkmcnt(0)
	s_barrier
	s_setprio 1
	s_waitcnt lgkmcnt(0)
	v_mfma_f32_16x16x32_bf16 v[92:95], v[152:155], v[188:191], v[92:95]
	v_mfma_f32_16x16x32_bf16 v[88:91], v[160:163], v[188:191], v[88:91]
	v_mfma_f32_16x16x32_bf16 v[84:87], v[152:155], v[196:199], v[84:87]
	v_mfma_f32_16x16x32_bf16 v[80:83], v[160:163], v[196:199], v[80:83]
	v_mfma_f32_16x16x32_bf16 v[76:79], v[152:155], v[204:207], v[76:79]
	v_mfma_f32_16x16x32_bf16 v[72:75], v[160:163], v[204:207], v[72:75]
	v_mfma_f32_16x16x32_bf16 v[60:63], v[152:155], v[212:215], v[60:63]
	v_mfma_f32_16x16x32_bf16 v[56:59], v[160:163], v[212:215], v[56:59]
	v_mfma_f32_16x16x32_bf16 v[92:95], v[156:159], v[192:195], v[92:95]
	v_mfma_f32_16x16x32_bf16 v[88:91], v[164:167], v[192:195], v[88:91]
	v_mfma_f32_16x16x32_bf16 v[84:87], v[156:159], v[200:203], v[84:87]
	v_mfma_f32_16x16x32_bf16 v[80:83], v[164:167], v[200:203], v[80:83]
	v_mfma_f32_16x16x32_bf16 v[76:79], v[156:159], v[208:211], v[76:79]
	v_mfma_f32_16x16x32_bf16 v[72:75], v[164:167], v[208:211], v[72:75]
	v_mfma_f32_16x16x32_bf16 v[60:63], v[156:159], v[216:219], v[60:63]
	v_mfma_f32_16x16x32_bf16 v[56:59], v[164:167], v[216:219], v[56:59]
	s_setprio 0
	s_setprio 1
	v_mfma_f32_16x16x32_bf16 v[28:31], v[168:171], v[188:191], v[28:31]
	v_mfma_f32_16x16x32_bf16 v[24:27], v[176:179], v[188:191], v[24:27]
	v_mfma_f32_16x16x32_bf16 v[20:23], v[168:171], v[196:199], v[20:23]
	v_mfma_f32_16x16x32_bf16 v[16:19], v[176:179], v[196:199], v[16:19]
	v_mfma_f32_16x16x32_bf16 v[12:15], v[168:171], v[204:207], v[12:15]
	v_mfma_f32_16x16x32_bf16 v[8:11], v[176:179], v[204:207], v[8:11]
	v_mfma_f32_16x16x32_bf16 v[4:7], v[168:171], v[212:215], v[4:7]
	v_mfma_f32_16x16x32_bf16 v[0:3], v[176:179], v[212:215], v[0:3]
	v_mfma_f32_16x16x32_bf16 v[28:31], v[172:175], v[192:195], v[28:31]
	v_mfma_f32_16x16x32_bf16 v[24:27], v[184:187], v[192:195], v[24:27]
	v_mfma_f32_16x16x32_bf16 v[20:23], v[172:175], v[200:203], v[20:23]
	v_mfma_f32_16x16x32_bf16 v[16:19], v[184:187], v[200:203], v[16:19]
	v_mfma_f32_16x16x32_bf16 v[12:15], v[172:175], v[208:211], v[12:15]
	v_mfma_f32_16x16x32_bf16 v[8:11], v[184:187], v[208:211], v[8:11]
	v_mfma_f32_16x16x32_bf16 v[4:7], v[172:175], v[216:219], v[4:7]
	v_mfma_f32_16x16x32_bf16 v[0:3], v[184:187], v[216:219], v[0:3]
	s_setprio 0
	s_barrier
	s_add_i32 s87, s87, 2
	s_add_u32 s60, s60, 0x100
	s_addc_u32 s61, s61, 0
	s_add_u32 s85, s85, 0x100
	s_addc_u32 s86, s86, 0
	s_cmp_gt_u32 s87, 13
	s_cbranch_scc0 .LBB0_1162
	s_and_b64 vcc, exec, s[16:17]
	s_cbranch_vccz .LBB0_1165
	s_barrier

.LBB0_1310:
	s_ashr_i32 s49, s48, 31
	s_lshl_b64 s[50:51], s[48:49], 19
	s_add_u32 s50, s38, s50
	s_addc_u32 s51, s39, s51
	s_and_b64 s[52:53], s[10:11], exec
	s_cselect_b32 s49, s51, s57
	s_cselect_b32 s82, s50, s56
	s_ashr_i32 s47, s46, 31
	s_lshl_b64 s[52:53], s[46:47], 19
	s_add_u32 s52, s62, s52
	s_addc_u32 s53, s63, s53
	s_and_b64 s[60:61], s[10:11], exec
	s_cselect_b32 s47, s53, s59
	s_cselect_b32 s83, s52, s58
	s_add_u32 s56, s56, 0x40080
	s_addc_u32 s57, s57, 0
	s_add_u32 s84, s58, 0x100
	s_addc_u32 s85, s59, 0
	s_mov_b32 s86, -2
	ds_read_b128 v[152:155], v149
	ds_read_b128 v[156:159], v149 offset:1024
	ds_read_b128 v[160:163], v149 offset:2048
	ds_read_b128 v[164:167], v149 offset:3072
	ds_read_b128 v[168:171], v150
	ds_read_b128 v[172:175], v150 offset:1024
	ds_read_b128 v[176:179], v150 offset:2048
	ds_read_b128 v[184:187], v150 offset:3072
	s_add_u32 s58, s56, 0xfffc0080
	s_addc_u32 s59, s57, -1
	s_cmp_eq_u32 s86, 12
	s_cselect_b32 s61, s49, s59
	s_cselect_b32 s60, s82, s58
	s_cselect_b32 s59, s47, s85
	s_cselect_b32 s58, s83, s84
	v_lshl_add_u64 v[144:145], s[56:57], 0, v[136:137]
	s_add_i32 m0, s55, 0xc000
	ds_read_b128 v[188:191], v151
	ds_read_b128 v[192:195], v151 offset:1024
	ds_read_b128 v[196:199], v151 offset:2048
	ds_read_b128 v[200:203], v151 offset:3072
	ds_read_b128 v[204:207], v151 offset:4096
	ds_read_b128 v[208:211], v151 offset:5120
	ds_read_b128 v[212:215], v151 offset:6144
	ds_read_b128 v[216:219], v151 offset:7168
	global_load_lds_dwordx4 v[144:145], off
	v_lshl_add_u64 v[144:145], s[56:57], 0, v[138:139]
	s_add_i32 m0, s55, 0xe000
	s_nop 0
	global_load_lds_dwordx4 v[144:145], off
	s_waitcnt vmcnt(8)
	s_waitcnt lgkmcnt(0)
	s_barrier
	s_setprio 1
	s_waitcnt lgkmcnt(0)
	v_mfma_f32_16x16x32_bf16 v[124:127], v[152:155], v[188:191], 0
	v_mfma_f32_16x16x32_bf16 v[120:123], v[160:163], v[188:191], 0
	v_mfma_f32_16x16x32_bf16 v[116:119], v[152:155], v[196:199], 0
	v_mfma_f32_16x16x32_bf16 v[108:111], v[160:163], v[196:199], 0
	v_mfma_f32_16x16x32_bf16 v[100:103], v[152:155], v[204:207], 0
	v_mfma_f32_16x16x32_bf16 v[92:95], v[160:163], v[204:207], 0
	v_mfma_f32_16x16x32_bf16 v[84:87], v[152:155], v[212:215], 0
	v_mfma_f32_16x16x32_bf16 v[76:79], v[160:163], v[212:215], 0
	v_mfma_f32_16x16x32_bf16 v[124:127], v[156:159], v[192:195], v[124:127]
	v_mfma_f32_16x16x32_bf16 v[120:123], v[164:167], v[192:195], v[120:123]
	v_mfma_f32_16x16x32_bf16 v[116:119], v[156:159], v[200:203], v[116:119]
	v_mfma_f32_16x16x32_bf16 v[108:111], v[164:167], v[200:203], v[108:111]
	v_mfma_f32_16x16x32_bf16 v[100:103], v[156:159], v[208:211], v[100:103]
	v_mfma_f32_16x16x32_bf16 v[92:95], v[164:167], v[208:211], v[92:95]
	v_mfma_f32_16x16x32_bf16 v[84:87], v[156:159], v[216:219], v[84:87]
	v_mfma_f32_16x16x32_bf16 v[76:79], v[164:167], v[216:219], v[76:79]
	s_setprio 0
	s_setprio 1
	v_mfma_f32_16x16x32_bf16 v[112:115], v[168:171], v[188:191], 0
	v_mfma_f32_16x16x32_bf16 v[104:107], v[176:179], v[188:191], 0
	v_mfma_f32_16x16x32_bf16 v[96:99], v[168:171], v[196:199], 0
	v_mfma_f32_16x16x32_bf16 v[88:91], v[176:179], v[196:199], 0
	v_mfma_f32_16x16x32_bf16 v[80:83], v[168:171], v[204:207], 0
	v_mfma_f32_16x16x32_bf16 v[72:75], v[176:179], v[204:207], 0
	v_mfma_f32_16x16x32_bf16 v[68:71], v[168:171], v[212:215], 0
	v_mfma_f32_16x16x32_bf16 v[64:67], v[176:179], v[212:215], 0
	v_mfma_f32_16x16x32_bf16 v[112:115], v[172:175], v[192:195], v[112:115]
	v_mfma_f32_16x16x32_bf16 v[104:107], v[184:187], v[192:195], v[104:107]
	v_mfma_f32_16x16x32_bf16 v[96:99], v[172:175], v[200:203], v[96:99]
	v_mfma_f32_16x16x32_bf16 v[88:91], v[184:187], v[200:203], v[88:91]
	v_mfma_f32_16x16x32_bf16 v[80:83], v[172:175], v[208:211], v[80:83]
	v_mfma_f32_16x16x32_bf16 v[72:75], v[184:187], v[208:211], v[72:75]
	v_mfma_f32_16x16x32_bf16 v[68:71], v[172:175], v[216:219], v[68:71]
	v_mfma_f32_16x16x32_bf16 v[64:67], v[184:187], v[216:219], v[64:67]
	s_setprio 0
	s_barrier
	s_add_i32 s79, s71, s64
	v_lshl_add_u64 v[144:145], s[58:59], 0, v[130:131]
	s_mov_b32 m0, s79
	ds_read_b128 v[188:191], v151 offset:16384
	ds_read_b128 v[192:195], v151 offset:17408
	ds_read_b128 v[196:199], v151 offset:18432
	ds_read_b128 v[200:203], v151 offset:19456
	ds_read_b128 v[204:207], v151 offset:20480
	ds_read_b128 v[208:211], v151 offset:21504
	ds_read_b128 v[212:215], v151 offset:22528
	ds_read_b128 v[216:219], v151 offset:23552
	global_load_lds_dwordx4 v[144:145], off
	s_add_i32 m0, s79, 0x2000
	s_add_u32 s88, s58, 0x40000
	v_lshl_add_u64 v[220:221], s[58:59], 0, v[134:135]
	s_addc_u32 s89, s59, 0
	s_add_i32 s79, s72, s64
	global_load_lds_dwordx4 v[220:221], off
	v_lshl_add_u64 v[222:223], s[88:89], 0, v[130:131]
	s_mov_b32 m0, s79
	v_lshl_add_u64 v[224:225], s[60:61], 0, v[132:133]
	global_load_lds_dwordx4 v[222:223], off
	v_lshl_add_u64 v[222:223], s[88:89], 0, v[134:135]
	s_add_i32 m0, s79, 0x2000
	s_nop 0
	global_load_lds_dwordx4 v[222:223], off
	v_lshl_add_u64 v[222:223], s[60:61], 0, v[128:129]
	s_mov_b32 m0, s55
	s_nop 0
	global_load_lds_dwordx4 v[222:223], off
	s_mov_b32 m0, s65
	s_nop 0
	global_load_lds_dwordx4 v[224:225], off
	s_waitcnt vmcnt(8)
	s_waitcnt lgkmcnt(0)
	s_barrier
	s_setprio 1
	s_waitcnt lgkmcnt(0)
	v_mfma_f32_16x16x32_bf16 v[60:63], v[152:155], v[188:191], 0
	v_mfma_f32_16x16x32_bf16 v[56:59], v[160:163], v[188:191], 0
	v_mfma_f32_16x16x32_bf16 v[52:55], v[152:155], v[196:199], 0
	v_mfma_f32_16x16x32_bf16 v[44:47], v[160:163], v[196:199], 0
	v_mfma_f32_16x16x32_bf16 v[36:39], v[152:155], v[204:207], 0
	v_mfma_f32_16x16x32_bf16 v[28:31], v[160:163], v[204:207], 0
	v_mfma_f32_16x16x32_bf16 v[20:23], v[152:155], v[212:215], 0
	v_mfma_f32_16x16x32_bf16 v[12:15], v[160:163], v[212:215], 0
	v_mfma_f32_16x16x32_bf16 v[60:63], v[156:159], v[192:195], v[60:63]
	v_mfma_f32_16x16x32_bf16 v[56:59], v[164:167], v[192:195], v[56:59]
	v_mfma_f32_16x16x32_bf16 v[52:55], v[156:159], v[200:203], v[52:55]
	v_mfma_f32_16x16x32_bf16 v[44:47], v[164:167], v[200:203], v[44:47]
	v_mfma_f32_16x16x32_bf16 v[36:39], v[156:159], v[208:211], v[36:39]
	v_mfma_f32_16x16x32_bf16 v[28:31], v[164:167], v[208:211], v[28:31]
	v_mfma_f32_16x16x32_bf16 v[20:23], v[156:159], v[216:219], v[20:23]
	v_mfma_f32_16x16x32_bf16 v[12:15], v[164:167], v[216:219], v[12:15]
	s_setprio 0
	s_setprio 1
	v_mfma_f32_16x16x32_bf16 v[48:51], v[168:171], v[188:191], 0
	v_mfma_f32_16x16x32_bf16 v[40:43], v[176:179], v[188:191], 0
	v_mfma_f32_16x16x32_bf16 v[32:35], v[168:171], v[196:199], 0
	v_mfma_f32_16x16x32_bf16 v[24:27], v[176:179], v[196:199], 0
	v_mfma_f32_16x16x32_bf16 v[16:19], v[168:171], v[204:207], 0
	v_mfma_f32_16x16x32_bf16 v[8:11], v[176:179], v[204:207], 0
	v_mfma_f32_16x16x32_bf16 v[4:7], v[168:171], v[212:215], 0
	v_mfma_f32_16x16x32_bf16 v[0:3], v[176:179], v[212:215], 0
	v_mfma_f32_16x16x32_bf16 v[48:51], v[172:175], v[192:195], v[48:51]
	v_mfma_f32_16x16x32_bf16 v[40:43], v[184:187], v[192:195], v[40:43]
	v_mfma_f32_16x16x32_bf16 v[32:35], v[172:175], v[200:203], v[32:35]
	v_mfma_f32_16x16x32_bf16 v[24:27], v[184:187], v[200:203], v[24:27]
	v_mfma_f32_16x16x32_bf16 v[16:19], v[172:175], v[208:211], v[16:19]
	v_mfma_f32_16x16x32_bf16 v[8:11], v[184:187], v[208:211], v[8:11]
	v_mfma_f32_16x16x32_bf16 v[4:7], v[172:175], v[216:219], v[4:7]
	v_mfma_f32_16x16x32_bf16 v[0:3], v[184:187], v[216:219], v[0:3]
	s_setprio 0
	s_barrier
	s_branch .Lmid_gemm10
.LBB0_1311:
	ds_read_b128 v[152:155], v149
	ds_read_b128 v[156:159], v149 offset:1024
	ds_read_b128 v[160:163], v149 offset:2048
	ds_read_b128 v[164:167], v149 offset:3072
	ds_read_b128 v[168:171], v150
	ds_read_b128 v[172:175], v150 offset:1024
	ds_read_b128 v[176:179], v150 offset:2048
	ds_read_b128 v[184:187], v150 offset:3072
	s_add_u32 s58, s56, 0xfffc0080
	s_addc_u32 s59, s57, -1
	s_cmp_eq_u32 s86, 12
	s_cselect_b32 s61, s49, s59
	s_cselect_b32 s60, s82, s58
	s_cselect_b32 s59, s47, s85
	s_cselect_b32 s58, s83, s84
	v_lshl_add_u64 v[144:145], s[56:57], 0, v[136:137]
	s_add_i32 m0, s55, 0xc000
	ds_read_b128 v[188:191], v151
	ds_read_b128 v[192:195], v151 offset:1024
	ds_read_b128 v[196:199], v151 offset:2048
	ds_read_b128 v[200:203], v151 offset:3072
	ds_read_b128 v[204:207], v151 offset:4096
	ds_read_b128 v[208:211], v151 offset:5120
	ds_read_b128 v[212:215], v151 offset:6144
	ds_read_b128 v[216:219], v151 offset:7168
	global_load_lds_dwordx4 v[144:145], off
	v_lshl_add_u64 v[144:145], s[56:57], 0, v[138:139]
	s_add_i32 m0, s55, 0xe000
	s_nop 0
	global_load_lds_dwordx4 v[144:145], off
	s_waitcnt vmcnt(8)
	s_waitcnt lgkmcnt(0)
	s_barrier
	s_setprio 1
	s_waitcnt lgkmcnt(0)
	v_mfma_f32_16x16x32_bf16 v[124:127], v[152:155], v[188:191], v[124:127]
	v_mfma_f32_16x16x32_bf16 v[120:123], v[160:163], v[188:191], v[120:123]
	v_mfma_f32_16x16x32_bf16 v[116:119], v[152:155], v[196:199], v[116:119]
	v_mfma_f32_16x16x32_bf16 v[108:111], v[160:163], v[196:199], v[108:111]
	v_mfma_f32_16x16x32_bf16 v[100:103], v[152:155], v[204:207], v[100:103]
	v_mfma_f32_16x16x32_bf16 v[92:95], v[160:163], v[204:207], v[92:95]
	v_mfma_f32_16x16x32_bf16 v[84:87], v[152:155], v[212:215], v[84:87]
	v_mfma_f32_16x16x32_bf16 v[76:79], v[160:163], v[212:215], v[76:79]
	v_mfma_f32_16x16x32_bf16 v[124:127], v[156:159], v[192:195], v[124:127]
	v_mfma_f32_16x16x32_bf16 v[120:123], v[164:167], v[192:195], v[120:123]
	v_mfma_f32_16x16x32_bf16 v[116:119], v[156:159], v[200:203], v[116:119]
	v_mfma_f32_16x16x32_bf16 v[108:111], v[164:167], v[200:203], v[108:111]
	v_mfma_f32_16x16x32_bf16 v[100:103], v[156:159], v[208:211], v[100:103]
	v_mfma_f32_16x16x32_bf16 v[92:95], v[164:167], v[208:211], v[92:95]
	v_mfma_f32_16x16x32_bf16 v[84:87], v[156:159], v[216:219], v[84:87]
	v_mfma_f32_16x16x32_bf16 v[76:79], v[164:167], v[216:219], v[76:79]
	s_setprio 0
	s_setprio 1
	v_mfma_f32_16x16x32_bf16 v[112:115], v[168:171], v[188:191], v[112:115]
	v_mfma_f32_16x16x32_bf16 v[104:107], v[176:179], v[188:191], v[104:107]
	v_mfma_f32_16x16x32_bf16 v[96:99], v[168:171], v[196:199], v[96:99]
	v_mfma_f32_16x16x32_bf16 v[88:91], v[176:179], v[196:199], v[88:91]
	v_mfma_f32_16x16x32_bf16 v[80:83], v[168:171], v[204:207], v[80:83]
	v_mfma_f32_16x16x32_bf16 v[72:75], v[176:179], v[204:207], v[72:75]
	v_mfma_f32_16x16x32_bf16 v[68:71], v[168:171], v[212:215], v[68:71]
	v_mfma_f32_16x16x32_bf16 v[64:67], v[176:179], v[212:215], v[64:67]
	v_mfma_f32_16x16x32_bf16 v[112:115], v[172:175], v[192:195], v[112:115]
	v_mfma_f32_16x16x32_bf16 v[104:107], v[184:187], v[192:195], v[104:107]
	v_mfma_f32_16x16x32_bf16 v[96:99], v[172:175], v[200:203], v[96:99]
	v_mfma_f32_16x16x32_bf16 v[88:91], v[184:187], v[200:203], v[88:91]
	v_mfma_f32_16x16x32_bf16 v[80:83], v[172:175], v[208:211], v[80:83]
	v_mfma_f32_16x16x32_bf16 v[72:75], v[184:187], v[208:211], v[72:75]
	v_mfma_f32_16x16x32_bf16 v[68:71], v[172:175], v[216:219], v[68:71]
	v_mfma_f32_16x16x32_bf16 v[64:67], v[184:187], v[216:219], v[64:67]
	s_setprio 0
	s_barrier
	s_add_i32 s79, s71, s64
	v_lshl_add_u64 v[144:145], s[58:59], 0, v[130:131]
	s_mov_b32 m0, s79
	ds_read_b128 v[188:191], v151 offset:16384
	ds_read_b128 v[192:195], v151 offset:17408
	ds_read_b128 v[196:199], v151 offset:18432
	ds_read_b128 v[200:203], v151 offset:19456
	ds_read_b128 v[204:207], v151 offset:20480
	ds_read_b128 v[208:211], v151 offset:21504
	ds_read_b128 v[212:215], v151 offset:22528
	ds_read_b128 v[216:219], v151 offset:23552
	global_load_lds_dwordx4 v[144:145], off
	s_add_i32 m0, s79, 0x2000
	s_add_u32 s88, s58, 0x40000
	v_lshl_add_u64 v[220:221], s[58:59], 0, v[134:135]
	s_addc_u32 s89, s59, 0
	s_add_i32 s79, s72, s64
	global_load_lds_dwordx4 v[220:221], off
	v_lshl_add_u64 v[222:223], s[88:89], 0, v[130:131]
	s_mov_b32 m0, s79
	v_lshl_add_u64 v[224:225], s[60:61], 0, v[132:133]
	global_load_lds_dwordx4 v[222:223], off
	v_lshl_add_u64 v[222:223], s[88:89], 0, v[134:135]
	s_add_i32 m0, s79, 0x2000
	s_nop 0
	global_load_lds_dwordx4 v[222:223], off
	v_lshl_add_u64 v[222:223], s[60:61], 0, v[128:129]
	s_mov_b32 m0, s55
	s_nop 0
	global_load_lds_dwordx4 v[222:223], off
	s_mov_b32 m0, s65
	s_nop 0
	global_load_lds_dwordx4 v[224:225], off
	s_waitcnt vmcnt(8)
	s_waitcnt lgkmcnt(0)
	s_barrier
	s_setprio 1
	s_waitcnt lgkmcnt(0)
	v_mfma_f32_16x16x32_bf16 v[60:63], v[152:155], v[188:191], v[60:63]
	v_mfma_f32_16x16x32_bf16 v[56:59], v[160:163], v[188:191], v[56:59]
	v_mfma_f32_16x16x32_bf16 v[52:55], v[152:155], v[196:199], v[52:55]
	v_mfma_f32_16x16x32_bf16 v[44:47], v[160:163], v[196:199], v[44:47]
	v_mfma_f32_16x16x32_bf16 v[36:39], v[152:155], v[204:207], v[36:39]
	v_mfma_f32_16x16x32_bf16 v[28:31], v[160:163], v[204:207], v[28:31]
	v_mfma_f32_16x16x32_bf16 v[20:23], v[152:155], v[212:215], v[20:23]
	v_mfma_f32_16x16x32_bf16 v[12:15], v[160:163], v[212:215], v[12:15]
	v_mfma_f32_16x16x32_bf16 v[60:63], v[156:159], v[192:195], v[60:63]
	v_mfma_f32_16x16x32_bf16 v[56:59], v[164:167], v[192:195], v[56:59]
	v_mfma_f32_16x16x32_bf16 v[52:55], v[156:159], v[200:203], v[52:55]
	v_mfma_f32_16x16x32_bf16 v[44:47], v[164:167], v[200:203], v[44:47]
	v_mfma_f32_16x16x32_bf16 v[36:39], v[156:159], v[208:211], v[36:39]
	v_mfma_f32_16x16x32_bf16 v[28:31], v[164:167], v[208:211], v[28:31]
	v_mfma_f32_16x16x32_bf16 v[20:23], v[156:159], v[216:219], v[20:23]
	v_mfma_f32_16x16x32_bf16 v[12:15], v[164:167], v[216:219], v[12:15]
	s_setprio 0
	s_setprio 1
	v_mfma_f32_16x16x32_bf16 v[48:51], v[168:171], v[188:191], v[48:51]
	v_mfma_f32_16x16x32_bf16 v[40:43], v[176:179], v[188:191], v[40:43]
	v_mfma_f32_16x16x32_bf16 v[32:35], v[168:171], v[196:199], v[32:35]
	v_mfma_f32_16x16x32_bf16 v[24:27], v[176:179], v[196:199], v[24:27]
	v_mfma_f32_16x16x32_bf16 v[16:19], v[168:171], v[204:207], v[16:19]
	v_mfma_f32_16x16x32_bf16 v[8:11], v[176:179], v[204:207], v[8:11]
	v_mfma_f32_16x16x32_bf16 v[4:7], v[168:171], v[212:215], v[4:7]
	v_mfma_f32_16x16x32_bf16 v[0:3], v[176:179], v[212:215], v[0:3]
	v_mfma_f32_16x16x32_bf16 v[48:51], v[172:175], v[192:195], v[48:51]
	v_mfma_f32_16x16x32_bf16 v[40:43], v[184:187], v[192:195], v[40:43]
	v_mfma_f32_16x16x32_bf16 v[32:35], v[172:175], v[200:203], v[32:35]
	v_mfma_f32_16x16x32_bf16 v[24:27], v[184:187], v[200:203], v[24:27]
	v_mfma_f32_16x16x32_bf16 v[16:19], v[172:175], v[208:211], v[16:19]
	v_mfma_f32_16x16x32_bf16 v[8:11], v[184:187], v[208:211], v[8:11]
	v_mfma_f32_16x16x32_bf16 v[4:7], v[172:175], v[216:219], v[4:7]
	v_mfma_f32_16x16x32_bf16 v[0:3], v[184:187], v[216:219], v[0:3]
	s_setprio 0
	s_barrier
.Lmid_gemm10:
	s_add_i32 s79, 0, 0x18000
	s_add_i32 s87, 0, 0x1c000
	v_add_u32_e32 v164, s79, v147
	v_add_u32_e32 v181, s87, v147
	ds_read_b128 v[152:155], v164
	ds_read_b128 v[156:159], v164 offset:1024
	ds_read_b128 v[160:163], v164 offset:2048
	ds_read_b128 v[164:167], v164 offset:3072
	ds_read_b128 v[168:171], v181
	ds_read_b128 v[172:175], v181 offset:1024
	ds_read_b128 v[176:179], v181 offset:2048
	ds_read_b128 v[184:187], v181 offset:3072
	s_add_u32 s60, s60, 0x40000
	s_addc_u32 s61, s61, 0
	s_mov_b32 m0, s66
	v_lshl_add_u64 v[226:227], s[60:61], 0, v[128:129]
	ds_read_b128 v[188:191], v151 offset:32768
	ds_read_b128 v[192:195], v151 offset:33792
	ds_read_b128 v[196:199], v151 offset:34816
	ds_read_b128 v[200:203], v151 offset:35840
	ds_read_b128 v[204:207], v151 offset:36864
	ds_read_b128 v[208:211], v151 offset:37888
	ds_read_b128 v[212:215], v151 offset:38912
	ds_read_b128 v[216:219], v151 offset:39936
	global_load_lds_dwordx4 v[226:227], off
	v_lshl_add_u64 v[226:227], s[60:61], 0, v[132:133]
	s_mov_b32 m0, s67
	s_nop 0
	global_load_lds_dwordx4 v[226:227], off
	s_waitcnt vmcnt(8)
	s_waitcnt lgkmcnt(0)
	s_barrier
	s_setprio 1
	s_waitcnt lgkmcnt(0)
	v_mfma_f32_16x16x32_bf16 v[124:127], v[152:155], v[188:191], v[124:127]
	v_mfma_f32_16x16x32_bf16 v[120:123], v[160:163], v[188:191], v[120:123]
	v_mfma_f32_16x16x32_bf16 v[116:119], v[152:155], v[196:199], v[116:119]
	v_mfma_f32_16x16x32_bf16 v[108:111], v[160:163], v[196:199], v[108:111]
	v_mfma_f32_16x16x32_bf16 v[100:103], v[152:155], v[204:207], v[100:103]
	v_mfma_f32_16x16x32_bf16 v[92:95], v[160:163], v[204:207], v[92:95]
	v_mfma_f32_16x16x32_bf16 v[84:87], v[152:155], v[212:215], v[84:87]
	v_mfma_f32_16x16x32_bf16 v[76:79], v[160:163], v[212:215], v[76:79]
	v_mfma_f32_16x16x32_bf16 v[124:127], v[156:159], v[192:195], v[124:127]
	v_mfma_f32_16x16x32_bf16 v[120:123], v[164:167], v[192:195], v[120:123]
	v_mfma_f32_16x16x32_bf16 v[116:119], v[156:159], v[200:203], v[116:119]
	v_mfma_f32_16x16x32_bf16 v[108:111], v[164:167], v[200:203], v[108:111]
	v_mfma_f32_16x16x32_bf16 v[100:103], v[156:159], v[208:211], v[100:103]
	v_mfma_f32_16x16x32_bf16 v[92:95], v[164:167], v[208:211], v[92:95]
	v_mfma_f32_16x16x32_bf16 v[84:87], v[156:159], v[216:219], v[84:87]
	v_mfma_f32_16x16x32_bf16 v[76:79], v[164:167], v[216:219], v[76:79]
	s_setprio 0
	s_setprio 1
	v_mfma_f32_16x16x32_bf16 v[112:115], v[168:171], v[188:191], v[112:115]
	v_mfma_f32_16x16x32_bf16 v[104:107], v[176:179], v[188:191], v[104:107]
	v_mfma_f32_16x16x32_bf16 v[96:99], v[168:171], v[196:199], v[96:99]
	v_mfma_f32_16x16x32_bf16 v[88:91], v[176:179], v[196:199], v[88:91]
	v_mfma_f32_16x16x32_bf16 v[80:83], v[168:171], v[204:207], v[80:83]
	v_mfma_f32_16x16x32_bf16 v[72:75], v[176:179], v[204:207], v[72:75]
	v_mfma_f32_16x16x32_bf16 v[68:71], v[168:171], v[212:215], v[68:71]
	v_mfma_f32_16x16x32_bf16 v[64:67], v[176:179], v[212:215], v[64:67]
	v_mfma_f32_16x16x32_bf16 v[112:115], v[172:175], v[192:195], v[112:115]
	v_mfma_f32_16x16x32_bf16 v[104:107], v[184:187], v[192:195], v[104:107]
	v_mfma_f32_16x16x32_bf16 v[96:99], v[172:175], v[200:203], v[96:99]
	v_mfma_f32_16x16x32_bf16 v[88:91], v[184:187], v[200:203], v[88:91]
	v_mfma_f32_16x16x32_bf16 v[80:83], v[172:175], v[208:211], v[80:83]
	v_mfma_f32_16x16x32_bf16 v[72:75], v[184:187], v[208:211], v[72:75]
	v_mfma_f32_16x16x32_bf16 v[68:71], v[172:175], v[216:219], v[68:71]
	v_mfma_f32_16x16x32_bf16 v[64:67], v[184:187], v[216:219], v[64:67]
	s_setprio 0
	s_barrier
	s_add_i32 s60, s79, s64
	v_lshl_add_u64 v[144:145], v[144:145], 0, s[16:17]
	s_mov_b32 m0, s60
	ds_read_b128 v[188:191], v151 offset:49152
	ds_read_b128 v[192:195], v151 offset:50176
	ds_read_b128 v[196:199], v151 offset:51200
	ds_read_b128 v[200:203], v151 offset:52224
	ds_read_b128 v[204:207], v151 offset:53248
	ds_read_b128 v[208:211], v151 offset:54272
	ds_read_b128 v[212:215], v151 offset:55296
	ds_read_b128 v[216:219], v151 offset:56320
	global_load_lds_dwordx4 v[144:145], off
	s_add_i32 m0, s60, 0x2000
	s_add_u32 s58, s58, 0x40080
	v_lshl_add_u64 v[144:145], v[220:221], 0, s[16:17]
	s_addc_u32 s59, s59, 0
	s_add_i32 s60, s87, s64
	global_load_lds_dwordx4 v[144:145], off
	v_lshl_add_u64 v[144:145], s[58:59], 0, v[130:131]
	s_mov_b32 m0, s60
	s_nop 0
	global_load_lds_dwordx4 v[144:145], off
	v_lshl_add_u64 v[144:145], s[58:59], 0, v[134:135]
	s_add_i32 m0, s60, 0x2000
	s_nop 0
	global_load_lds_dwordx4 v[144:145], off
	v_lshl_add_u64 v[144:145], v[222:223], 0, s[16:17]
	s_mov_b32 m0, s69
	s_nop 0
	global_load_lds_dwordx4 v[144:145], off
	v_lshl_add_u64 v[144:145], v[224:225], 0, s[16:17]
	s_mov_b32 m0, s70
	s_nop 0
	global_load_lds_dwordx4 v[144:145], off
	s_waitcnt vmcnt(8)
	s_waitcnt lgkmcnt(0)
	s_barrier
	s_setprio 1
	s_waitcnt lgkmcnt(0)
	v_mfma_f32_16x16x32_bf16 v[60:63], v[152:155], v[188:191], v[60:63]
	v_mfma_f32_16x16x32_bf16 v[56:59], v[160:163], v[188:191], v[56:59]
	v_mfma_f32_16x16x32_bf16 v[52:55], v[152:155], v[196:199], v[52:55]
	v_mfma_f32_16x16x32_bf16 v[44:47], v[160:163], v[196:199], v[44:47]
	v_mfma_f32_16x16x32_bf16 v[36:39], v[152:155], v[204:207], v[36:39]
	v_mfma_f32_16x16x32_bf16 v[28:31], v[160:163], v[204:207], v[28:31]
	v_mfma_f32_16x16x32_bf16 v[20:23], v[152:155], v[212:215], v[20:23]
	v_mfma_f32_16x16x32_bf16 v[12:15], v[160:163], v[212:215], v[12:15]
	v_mfma_f32_16x16x32_bf16 v[60:63], v[156:159], v[192:195], v[60:63]
	v_mfma_f32_16x16x32_bf16 v[56:59], v[164:167], v[192:195], v[56:59]
	v_mfma_f32_16x16x32_bf16 v[52:55], v[156:159], v[200:203], v[52:55]
	v_mfma_f32_16x16x32_bf16 v[44:47], v[164:167], v[200:203], v[44:47]
	v_mfma_f32_16x16x32_bf16 v[36:39], v[156:159], v[208:211], v[36:39]
	v_mfma_f32_16x16x32_bf16 v[28:31], v[164:167], v[208:211], v[28:31]
	v_mfma_f32_16x16x32_bf16 v[20:23], v[156:159], v[216:219], v[20:23]
	v_mfma_f32_16x16x32_bf16 v[12:15], v[164:167], v[216:219], v[12:15]
	s_setprio 0
	s_setprio 1
	v_mfma_f32_16x16x32_bf16 v[48:51], v[168:171], v[188:191], v[48:51]
	v_mfma_f32_16x16x32_bf16 v[40:43], v[176:179], v[188:191], v[40:43]
	v_mfma_f32_16x16x32_bf16 v[32:35], v[168:171], v[196:199], v[32:35]
	v_mfma_f32_16x16x32_bf16 v[24:27], v[176:179], v[196:199], v[24:27]
	v_mfma_f32_16x16x32_bf16 v[16:19], v[168:171], v[204:207], v[16:19]
	v_mfma_f32_16x16x32_bf16 v[8:11], v[176:179], v[204:207], v[8:11]
	v_mfma_f32_16x16x32_bf16 v[4:7], v[168:171], v[212:215], v[4:7]
	v_mfma_f32_16x16x32_bf16 v[0:3], v[176:179], v[212:215], v[0:3]
	v_mfma_f32_16x16x32_bf16 v[48:51], v[172:175], v[192:195], v[48:51]
	v_mfma_f32_16x16x32_bf16 v[40:43], v[184:187], v[192:195], v[40:43]
	v_mfma_f32_16x16x32_bf16 v[32:35], v[172:175], v[200:203], v[32:35]
	v_mfma_f32_16x16x32_bf16 v[24:27], v[184:187], v[200:203], v[24:27]
	v_mfma_f32_16x16x32_bf16 v[16:19], v[172:175], v[208:211], v[16:19]
	v_mfma_f32_16x16x32_bf16 v[8:11], v[184:187], v[208:211], v[8:11]
	v_mfma_f32_16x16x32_bf16 v[4:7], v[172:175], v[216:219], v[4:7]
	v_mfma_f32_16x16x32_bf16 v[0:3], v[184:187], v[216:219], v[0:3]
	s_setprio 0
	s_barrier
	s_add_i32 s86, s86, 2
	s_add_u32 s56, s56, 0x100
	s_addc_u32 s57, s57, 0
	s_add_u32 s84, s84, 0x100
	s_addc_u32 s85, s85, 0
	s_cmp_gt_u32 s86, 13
	s_cbranch_scc0 .LBB0_1311
	s_and_b64 vcc, exec, s[18:19]
	s_cbranch_vccz .LBB0_1314
	s_barrier

.LBB0_1433:
	s_ashr_i32 s19, s18, 31
	s_lshl_b64 s[30:31], s[18:19], 19
	s_add_u32 s30, s80, s30
	s_addc_u32 s31, s81, s31
	s_and_b64 s[36:37], s[8:9], exec
	s_cselect_b32 s19, s31, s47
	s_cselect_b32 s66, s30, s46
	s_ashr_i32 s17, s16, 31
	s_lshl_b64 s[36:37], s[16:17], 19
	s_add_u32 s36, s52, s36
	s_addc_u32 s37, s53, s37
	s_and_b64 s[50:51], s[8:9], exec
	s_cselect_b32 s17, s37, s49
	s_cselect_b32 s67, s36, s48
	s_add_u32 s46, s46, 0x40080
	s_addc_u32 s47, s47, 0
	s_add_u32 s68, s48, 0x100
	s_addc_u32 s69, s49, 0
	s_mov_b32 s70, -2
	ds_read_b128 v[140:143], v147
	ds_read_b128 v[150:153], v147 offset:1024
	ds_read_b128 v[154:157], v147 offset:2048
	ds_read_b128 v[158:161], v147 offset:3072
	ds_read_b128 v[162:165], v148
	ds_read_b128 v[166:169], v148 offset:1024
	ds_read_b128 v[170:173], v148 offset:2048
	ds_read_b128 v[174:177], v148 offset:3072
	s_add_u32 s48, s46, 0xfffc0080
	s_addc_u32 s49, s47, -1
	s_cmp_eq_u32 s70, 12
	s_cselect_b32 s51, s19, s49
	s_cselect_b32 s50, s66, s48
	s_cselect_b32 s49, s17, s69
	s_cselect_b32 s48, s67, s68
	v_lshl_add_u64 v[178:179], s[46:47], 0, v[132:133]
	s_add_i32 m0, s45, 0xc000
	ds_read_b128 v[184:187], v149
	ds_read_b128 v[188:191], v149 offset:1024
	ds_read_b128 v[192:195], v149 offset:2048
	ds_read_b128 v[196:199], v149 offset:3072
	ds_read_b128 v[200:203], v149 offset:4096
	ds_read_b128 v[204:207], v149 offset:5120
	ds_read_b128 v[208:211], v149 offset:6144
	ds_read_b128 v[212:215], v149 offset:7168
	global_load_lds_dwordx4 v[178:179], off
	v_lshl_add_u64 v[178:179], s[46:47], 0, v[134:135]
	s_add_i32 m0, s45, 0xe000
	s_nop 0
	global_load_lds_dwordx4 v[178:179], off
	s_waitcnt vmcnt(8)
	s_waitcnt lgkmcnt(0)
	s_barrier
	s_setprio 1
	s_waitcnt lgkmcnt(0)
	v_mfma_f32_16x16x32_bf16 v[124:127], v[140:143], v[184:187], 0
	v_mfma_f32_16x16x32_bf16 v[120:123], v[154:157], v[184:187], 0
	v_mfma_f32_16x16x32_bf16 v[108:111], v[140:143], v[192:195], 0
	v_mfma_f32_16x16x32_bf16 v[104:107], v[154:157], v[192:195], 0
	v_mfma_f32_16x16x32_bf16 v[92:95], v[140:143], v[200:203], 0
	v_mfma_f32_16x16x32_bf16 v[88:91], v[154:157], v[200:203], 0
	v_mfma_f32_16x16x32_bf16 v[76:79], v[140:143], v[208:211], 0
	v_mfma_f32_16x16x32_bf16 v[72:75], v[154:157], v[208:211], 0
	v_mfma_f32_16x16x32_bf16 v[124:127], v[150:153], v[188:191], v[124:127]
	v_mfma_f32_16x16x32_bf16 v[120:123], v[158:161], v[188:191], v[120:123]
	v_mfma_f32_16x16x32_bf16 v[108:111], v[150:153], v[196:199], v[108:111]
	v_mfma_f32_16x16x32_bf16 v[104:107], v[158:161], v[196:199], v[104:107]
	v_mfma_f32_16x16x32_bf16 v[92:95], v[150:153], v[204:207], v[92:95]
	v_mfma_f32_16x16x32_bf16 v[88:91], v[158:161], v[204:207], v[88:91]
	v_mfma_f32_16x16x32_bf16 v[76:79], v[150:153], v[212:215], v[76:79]
	v_mfma_f32_16x16x32_bf16 v[72:75], v[158:161], v[212:215], v[72:75]
	s_setprio 0
	s_setprio 1
	v_mfma_f32_16x16x32_bf16 v[116:119], v[162:165], v[184:187], 0
	v_mfma_f32_16x16x32_bf16 v[112:115], v[170:173], v[184:187], 0
	v_mfma_f32_16x16x32_bf16 v[100:103], v[162:165], v[192:195], 0
	v_mfma_f32_16x16x32_bf16 v[96:99], v[170:173], v[192:195], 0
	v_mfma_f32_16x16x32_bf16 v[84:87], v[162:165], v[200:203], 0
	v_mfma_f32_16x16x32_bf16 v[80:83], v[170:173], v[200:203], 0
	v_mfma_f32_16x16x32_bf16 v[68:71], v[162:165], v[208:211], 0
	v_mfma_f32_16x16x32_bf16 v[64:67], v[170:173], v[208:211], 0
	v_mfma_f32_16x16x32_bf16 v[116:119], v[166:169], v[188:191], v[116:119]
	v_mfma_f32_16x16x32_bf16 v[112:115], v[174:177], v[188:191], v[112:115]
	v_mfma_f32_16x16x32_bf16 v[100:103], v[166:169], v[196:199], v[100:103]
	v_mfma_f32_16x16x32_bf16 v[96:99], v[174:177], v[196:199], v[96:99]
	v_mfma_f32_16x16x32_bf16 v[84:87], v[166:169], v[204:207], v[84:87]
	v_mfma_f32_16x16x32_bf16 v[80:83], v[174:177], v[204:207], v[80:83]
	v_mfma_f32_16x16x32_bf16 v[68:71], v[166:169], v[212:215], v[68:71]
	v_mfma_f32_16x16x32_bf16 v[64:67], v[174:177], v[212:215], v[64:67]
	s_setprio 0
	s_barrier
	s_add_i32 s71, s62, s54
	v_lshl_add_u64 v[178:179], s[48:49], 0, v[130:131]
	s_mov_b32 m0, s71
	ds_read_b128 v[184:187], v149 offset:16384
	ds_read_b128 v[188:191], v149 offset:17408
	ds_read_b128 v[192:195], v149 offset:18432
	ds_read_b128 v[196:199], v149 offset:19456
	ds_read_b128 v[200:203], v149 offset:20480
	ds_read_b128 v[204:207], v149 offset:21504
	ds_read_b128 v[208:211], v149 offset:22528
	ds_read_b128 v[212:215], v149 offset:23552
	global_load_lds_dwordx4 v[178:179], off
	s_add_i32 m0, s71, 0x2000
	s_add_u32 s72, s48, 0x40000
	v_lshl_add_u64 v[216:217], s[48:49], 0, v[128:129]
	s_addc_u32 s73, s49, 0
	s_add_i32 s71, s63, s54
	global_load_lds_dwordx4 v[216:217], off
	v_lshl_add_u64 v[218:219], s[72:73], 0, v[130:131]
	s_mov_b32 m0, s71
	v_lshl_add_u64 v[220:221], s[50:51], 0, v[128:129]
	global_load_lds_dwordx4 v[218:219], off
	v_lshl_add_u64 v[218:219], s[72:73], 0, v[128:129]
	s_add_i32 m0, s71, 0x2000
	s_nop 0
	global_load_lds_dwordx4 v[218:219], off
	v_lshl_add_u64 v[218:219], s[50:51], 0, v[130:131]
	s_mov_b32 m0, s45
	s_nop 0
	global_load_lds_dwordx4 v[218:219], off
	s_mov_b32 m0, s56
	s_nop 0
	global_load_lds_dwordx4 v[220:221], off
	s_waitcnt vmcnt(8)
	s_waitcnt lgkmcnt(0)
	s_barrier
	s_setprio 1
	s_waitcnt lgkmcnt(0)
	v_mfma_f32_16x16x32_bf16 v[60:63], v[140:143], v[184:187], 0
	v_mfma_f32_16x16x32_bf16 v[56:59], v[154:157], v[184:187], 0
	v_mfma_f32_16x16x32_bf16 v[44:47], v[140:143], v[192:195], 0
	v_mfma_f32_16x16x32_bf16 v[40:43], v[154:157], v[192:195], 0
	v_mfma_f32_16x16x32_bf16 v[28:31], v[140:143], v[200:203], 0
	v_mfma_f32_16x16x32_bf16 v[24:27], v[154:157], v[200:203], 0
	v_mfma_f32_16x16x32_bf16 v[12:15], v[140:143], v[208:211], 0
	v_mfma_f32_16x16x32_bf16 v[8:11], v[154:157], v[208:211], 0
	v_mfma_f32_16x16x32_bf16 v[60:63], v[150:153], v[188:191], v[60:63]
	v_mfma_f32_16x16x32_bf16 v[56:59], v[158:161], v[188:191], v[56:59]
	v_mfma_f32_16x16x32_bf16 v[44:47], v[150:153], v[196:199], v[44:47]
	v_mfma_f32_16x16x32_bf16 v[40:43], v[158:161], v[196:199], v[40:43]
	v_mfma_f32_16x16x32_bf16 v[28:31], v[150:153], v[204:207], v[28:31]
	v_mfma_f32_16x16x32_bf16 v[24:27], v[158:161], v[204:207], v[24:27]
	v_mfma_f32_16x16x32_bf16 v[12:15], v[150:153], v[212:215], v[12:15]
	v_mfma_f32_16x16x32_bf16 v[8:11], v[158:161], v[212:215], v[8:11]
	s_setprio 0
	s_setprio 1
	v_mfma_f32_16x16x32_bf16 v[52:55], v[162:165], v[184:187], 0
	v_mfma_f32_16x16x32_bf16 v[48:51], v[170:173], v[184:187], 0
	v_mfma_f32_16x16x32_bf16 v[36:39], v[162:165], v[192:195], 0
	v_mfma_f32_16x16x32_bf16 v[32:35], v[170:173], v[192:195], 0
	v_mfma_f32_16x16x32_bf16 v[20:23], v[162:165], v[200:203], 0
	v_mfma_f32_16x16x32_bf16 v[16:19], v[170:173], v[200:203], 0
	v_mfma_f32_16x16x32_bf16 v[4:7], v[162:165], v[208:211], 0
	v_mfma_f32_16x16x32_bf16 v[0:3], v[170:173], v[208:211], 0
	v_mfma_f32_16x16x32_bf16 v[52:55], v[166:169], v[188:191], v[52:55]
	v_mfma_f32_16x16x32_bf16 v[48:51], v[174:177], v[188:191], v[48:51]
	v_mfma_f32_16x16x32_bf16 v[36:39], v[166:169], v[196:199], v[36:39]
	v_mfma_f32_16x16x32_bf16 v[32:35], v[174:177], v[196:199], v[32:35]
	v_mfma_f32_16x16x32_bf16 v[20:23], v[166:169], v[204:207], v[20:23]
	v_mfma_f32_16x16x32_bf16 v[16:19], v[174:177], v[204:207], v[16:19]
	v_mfma_f32_16x16x32_bf16 v[4:7], v[166:169], v[212:215], v[4:7]
	v_mfma_f32_16x16x32_bf16 v[0:3], v[174:177], v[212:215], v[0:3]
	s_setprio 0
	s_barrier
	s_branch .Lmid_gemm11
.LBB0_1434:
	ds_read_b128 v[140:143], v147
	ds_read_b128 v[150:153], v147 offset:1024
	ds_read_b128 v[154:157], v147 offset:2048
	ds_read_b128 v[158:161], v147 offset:3072
	ds_read_b128 v[162:165], v148
	ds_read_b128 v[166:169], v148 offset:1024
	ds_read_b128 v[170:173], v148 offset:2048
	ds_read_b128 v[174:177], v148 offset:3072
	s_add_u32 s48, s46, 0xfffc0080
	s_addc_u32 s49, s47, -1
	s_cmp_eq_u32 s70, 12
	s_cselect_b32 s51, s19, s49
	s_cselect_b32 s50, s66, s48
	s_cselect_b32 s49, s17, s69
	s_cselect_b32 s48, s67, s68
	v_lshl_add_u64 v[178:179], s[46:47], 0, v[132:133]
	s_add_i32 m0, s45, 0xc000
	ds_read_b128 v[184:187], v149
	ds_read_b128 v[188:191], v149 offset:1024
	ds_read_b128 v[192:195], v149 offset:2048
	ds_read_b128 v[196:199], v149 offset:3072
	ds_read_b128 v[200:203], v149 offset:4096
	ds_read_b128 v[204:207], v149 offset:5120
	ds_read_b128 v[208:211], v149 offset:6144
	ds_read_b128 v[212:215], v149 offset:7168
	global_load_lds_dwordx4 v[178:179], off
	v_lshl_add_u64 v[178:179], s[46:47], 0, v[134:135]
	s_add_i32 m0, s45, 0xe000
	s_nop 0
	global_load_lds_dwordx4 v[178:179], off
	s_waitcnt vmcnt(8)
	s_waitcnt lgkmcnt(0)
	s_barrier
	s_setprio 1
	s_waitcnt lgkmcnt(0)
	v_mfma_f32_16x16x32_bf16 v[124:127], v[140:143], v[184:187], v[124:127]
	v_mfma_f32_16x16x32_bf16 v[120:123], v[154:157], v[184:187], v[120:123]
	v_mfma_f32_16x16x32_bf16 v[108:111], v[140:143], v[192:195], v[108:111]
	v_mfma_f32_16x16x32_bf16 v[104:107], v[154:157], v[192:195], v[104:107]
	v_mfma_f32_16x16x32_bf16 v[92:95], v[140:143], v[200:203], v[92:95]
	v_mfma_f32_16x16x32_bf16 v[88:91], v[154:157], v[200:203], v[88:91]
	v_mfma_f32_16x16x32_bf16 v[76:79], v[140:143], v[208:211], v[76:79]
	v_mfma_f32_16x16x32_bf16 v[72:75], v[154:157], v[208:211], v[72:75]
	v_mfma_f32_16x16x32_bf16 v[124:127], v[150:153], v[188:191], v[124:127]
	v_mfma_f32_16x16x32_bf16 v[120:123], v[158:161], v[188:191], v[120:123]
	v_mfma_f32_16x16x32_bf16 v[108:111], v[150:153], v[196:199], v[108:111]
	v_mfma_f32_16x16x32_bf16 v[104:107], v[158:161], v[196:199], v[104:107]
	v_mfma_f32_16x16x32_bf16 v[92:95], v[150:153], v[204:207], v[92:95]
	v_mfma_f32_16x16x32_bf16 v[88:91], v[158:161], v[204:207], v[88:91]
	v_mfma_f32_16x16x32_bf16 v[76:79], v[150:153], v[212:215], v[76:79]
	v_mfma_f32_16x16x32_bf16 v[72:75], v[158:161], v[212:215], v[72:75]
	s_setprio 0
	s_setprio 1
	v_mfma_f32_16x16x32_bf16 v[116:119], v[162:165], v[184:187], v[116:119]
	v_mfma_f32_16x16x32_bf16 v[112:115], v[170:173], v[184:187], v[112:115]
	v_mfma_f32_16x16x32_bf16 v[100:103], v[162:165], v[192:195], v[100:103]
	v_mfma_f32_16x16x32_bf16 v[96:99], v[170:173], v[192:195], v[96:99]
	v_mfma_f32_16x16x32_bf16 v[84:87], v[162:165], v[200:203], v[84:87]
	v_mfma_f32_16x16x32_bf16 v[80:83], v[170:173], v[200:203], v[80:83]
	v_mfma_f32_16x16x32_bf16 v[68:71], v[162:165], v[208:211], v[68:71]
	v_mfma_f32_16x16x32_bf16 v[64:67], v[170:173], v[208:211], v[64:67]
	v_mfma_f32_16x16x32_bf16 v[116:119], v[166:169], v[188:191], v[116:119]
	v_mfma_f32_16x16x32_bf16 v[112:115], v[174:177], v[188:191], v[112:115]
	v_mfma_f32_16x16x32_bf16 v[100:103], v[166:169], v[196:199], v[100:103]
	v_mfma_f32_16x16x32_bf16 v[96:99], v[174:177], v[196:199], v[96:99]
	v_mfma_f32_16x16x32_bf16 v[84:87], v[166:169], v[204:207], v[84:87]
	v_mfma_f32_16x16x32_bf16 v[80:83], v[174:177], v[204:207], v[80:83]
	v_mfma_f32_16x16x32_bf16 v[68:71], v[166:169], v[212:215], v[68:71]
	v_mfma_f32_16x16x32_bf16 v[64:67], v[174:177], v[212:215], v[64:67]
	s_setprio 0
	s_barrier
	s_add_i32 s71, s62, s54
	v_lshl_add_u64 v[178:179], s[48:49], 0, v[130:131]
	s_mov_b32 m0, s71
	ds_read_b128 v[184:187], v149 offset:16384
	ds_read_b128 v[188:191], v149 offset:17408
	ds_read_b128 v[192:195], v149 offset:18432
	ds_read_b128 v[196:199], v149 offset:19456
	ds_read_b128 v[200:203], v149 offset:20480
	ds_read_b128 v[204:207], v149 offset:21504
	ds_read_b128 v[208:211], v149 offset:22528
	ds_read_b128 v[212:215], v149 offset:23552
	global_load_lds_dwordx4 v[178:179], off
	s_add_i32 m0, s71, 0x2000
	s_add_u32 s72, s48, 0x40000
	v_lshl_add_u64 v[216:217], s[48:49], 0, v[128:129]
	s_addc_u32 s73, s49, 0
	s_add_i32 s71, s63, s54
	global_load_lds_dwordx4 v[216:217], off
	v_lshl_add_u64 v[218:219], s[72:73], 0, v[130:131]
	s_mov_b32 m0, s71
	v_lshl_add_u64 v[220:221], s[50:51], 0, v[128:129]
	global_load_lds_dwordx4 v[218:219], off
	v_lshl_add_u64 v[218:219], s[72:73], 0, v[128:129]
	s_add_i32 m0, s71, 0x2000
	s_nop 0
	global_load_lds_dwordx4 v[218:219], off
	v_lshl_add_u64 v[218:219], s[50:51], 0, v[130:131]
	s_mov_b32 m0, s45
	s_nop 0
	global_load_lds_dwordx4 v[218:219], off
	s_mov_b32 m0, s56
	s_nop 0
	global_load_lds_dwordx4 v[220:221], off
	s_waitcnt vmcnt(8)
	s_waitcnt lgkmcnt(0)
	s_barrier
	s_setprio 1
	s_waitcnt lgkmcnt(0)
	v_mfma_f32_16x16x32_bf16 v[60:63], v[140:143], v[184:187], v[60:63]
	v_mfma_f32_16x16x32_bf16 v[56:59], v[154:157], v[184:187], v[56:59]
	v_mfma_f32_16x16x32_bf16 v[44:47], v[140:143], v[192:195], v[44:47]
	v_mfma_f32_16x16x32_bf16 v[40:43], v[154:157], v[192:195], v[40:43]
	v_mfma_f32_16x16x32_bf16 v[28:31], v[140:143], v[200:203], v[28:31]
	v_mfma_f32_16x16x32_bf16 v[24:27], v[154:157], v[200:203], v[24:27]
	v_mfma_f32_16x16x32_bf16 v[12:15], v[140:143], v[208:211], v[12:15]
	v_mfma_f32_16x16x32_bf16 v[8:11], v[154:157], v[208:211], v[8:11]
	v_mfma_f32_16x16x32_bf16 v[60:63], v[150:153], v[188:191], v[60:63]
	v_mfma_f32_16x16x32_bf16 v[56:59], v[158:161], v[188:191], v[56:59]
	v_mfma_f32_16x16x32_bf16 v[44:47], v[150:153], v[196:199], v[44:47]
	v_mfma_f32_16x16x32_bf16 v[40:43], v[158:161], v[196:199], v[40:43]
	v_mfma_f32_16x16x32_bf16 v[28:31], v[150:153], v[204:207], v[28:31]
	v_mfma_f32_16x16x32_bf16 v[24:27], v[158:161], v[204:207], v[24:27]
	v_mfma_f32_16x16x32_bf16 v[12:15], v[150:153], v[212:215], v[12:15]
	v_mfma_f32_16x16x32_bf16 v[8:11], v[158:161], v[212:215], v[8:11]
	s_setprio 0
	s_setprio 1
	v_mfma_f32_16x16x32_bf16 v[52:55], v[162:165], v[184:187], v[52:55]
	v_mfma_f32_16x16x32_bf16 v[48:51], v[170:173], v[184:187], v[48:51]
	v_mfma_f32_16x16x32_bf16 v[36:39], v[162:165], v[192:195], v[36:39]
	v_mfma_f32_16x16x32_bf16 v[32:35], v[170:173], v[192:195], v[32:35]
	v_mfma_f32_16x16x32_bf16 v[20:23], v[162:165], v[200:203], v[20:23]
	v_mfma_f32_16x16x32_bf16 v[16:19], v[170:173], v[200:203], v[16:19]
	v_mfma_f32_16x16x32_bf16 v[4:7], v[162:165], v[208:211], v[4:7]
	v_mfma_f32_16x16x32_bf16 v[0:3], v[170:173], v[208:211], v[0:3]
	v_mfma_f32_16x16x32_bf16 v[52:55], v[166:169], v[188:191], v[52:55]
	v_mfma_f32_16x16x32_bf16 v[48:51], v[174:177], v[188:191], v[48:51]
	v_mfma_f32_16x16x32_bf16 v[36:39], v[166:169], v[196:199], v[36:39]
	v_mfma_f32_16x16x32_bf16 v[32:35], v[174:177], v[196:199], v[32:35]
	v_mfma_f32_16x16x32_bf16 v[20:23], v[166:169], v[204:207], v[20:23]
	v_mfma_f32_16x16x32_bf16 v[16:19], v[174:177], v[204:207], v[16:19]
	v_mfma_f32_16x16x32_bf16 v[4:7], v[166:169], v[212:215], v[4:7]
	v_mfma_f32_16x16x32_bf16 v[0:3], v[174:177], v[212:215], v[0:3]
	s_setprio 0
	s_barrier
.Lmid_gemm11:
	s_add_i32 s71, 0, 0x18000
	s_add_i32 s72, 0, 0x1c000
	v_add_u32_e32 v158, s71, v145
	v_add_u32_e32 v174, s72, v145
	ds_read_b128 v[140:143], v158
	ds_read_b128 v[150:153], v158 offset:1024
	ds_read_b128 v[154:157], v158 offset:2048
	ds_read_b128 v[158:161], v158 offset:3072
	ds_read_b128 v[162:165], v174
	ds_read_b128 v[166:169], v174 offset:1024
	ds_read_b128 v[170:173], v174 offset:2048
	ds_read_b128 v[174:177], v174 offset:3072
	s_add_u32 s50, s50, 0x40000
	s_addc_u32 s51, s51, 0
	s_mov_b32 m0, s57
	v_lshl_add_u64 v[222:223], s[50:51], 0, v[130:131]
	ds_read_b128 v[184:187], v149 offset:32768
	ds_read_b128 v[188:191], v149 offset:33792
	ds_read_b128 v[192:195], v149 offset:34816
	ds_read_b128 v[196:199], v149 offset:35840
	ds_read_b128 v[200:203], v149 offset:36864
	ds_read_b128 v[204:207], v149 offset:37888
	ds_read_b128 v[208:211], v149 offset:38912
	ds_read_b128 v[212:215], v149 offset:39936
	global_load_lds_dwordx4 v[222:223], off
	v_lshl_add_u64 v[222:223], s[50:51], 0, v[128:129]
	s_mov_b32 m0, s58
	s_nop 0
	global_load_lds_dwordx4 v[222:223], off
	s_waitcnt vmcnt(8)
	s_waitcnt lgkmcnt(0)
	s_barrier
	s_setprio 1
	s_waitcnt lgkmcnt(0)
	v_mfma_f32_16x16x32_bf16 v[124:127], v[140:143], v[184:187], v[124:127]
	v_mfma_f32_16x16x32_bf16 v[120:123], v[154:157], v[184:187], v[120:123]
	v_mfma_f32_16x16x32_bf16 v[108:111], v[140:143], v[192:195], v[108:111]
	v_mfma_f32_16x16x32_bf16 v[104:107], v[154:157], v[192:195], v[104:107]
	v_mfma_f32_16x16x32_bf16 v[92:95], v[140:143], v[200:203], v[92:95]
	v_mfma_f32_16x16x32_bf16 v[88:91], v[154:157], v[200:203], v[88:91]
	v_mfma_f32_16x16x32_bf16 v[76:79], v[140:143], v[208:211], v[76:79]
	v_mfma_f32_16x16x32_bf16 v[72:75], v[154:157], v[208:211], v[72:75]
	v_mfma_f32_16x16x32_bf16 v[124:127], v[150:153], v[188:191], v[124:127]
	v_mfma_f32_16x16x32_bf16 v[120:123], v[158:161], v[188:191], v[120:123]
	v_mfma_f32_16x16x32_bf16 v[108:111], v[150:153], v[196:199], v[108:111]
	v_mfma_f32_16x16x32_bf16 v[104:107], v[158:161], v[196:199], v[104:107]
	v_mfma_f32_16x16x32_bf16 v[92:95], v[150:153], v[204:207], v[92:95]
	v_mfma_f32_16x16x32_bf16 v[88:91], v[158:161], v[204:207], v[88:91]
	v_mfma_f32_16x16x32_bf16 v[76:79], v[150:153], v[212:215], v[76:79]
	v_mfma_f32_16x16x32_bf16 v[72:75], v[158:161], v[212:215], v[72:75]
	s_setprio 0
	s_setprio 1
	v_mfma_f32_16x16x32_bf16 v[116:119], v[162:165], v[184:187], v[116:119]
	v_mfma_f32_16x16x32_bf16 v[112:115], v[170:173], v[184:187], v[112:115]
	v_mfma_f32_16x16x32_bf16 v[100:103], v[162:165], v[192:195], v[100:103]
	v_mfma_f32_16x16x32_bf16 v[96:99], v[170:173], v[192:195], v[96:99]
	v_mfma_f32_16x16x32_bf16 v[84:87], v[162:165], v[200:203], v[84:87]
	v_mfma_f32_16x16x32_bf16 v[80:83], v[170:173], v[200:203], v[80:83]
	v_mfma_f32_16x16x32_bf16 v[68:71], v[162:165], v[208:211], v[68:71]
	v_mfma_f32_16x16x32_bf16 v[64:67], v[170:173], v[208:211], v[64:67]
	v_mfma_f32_16x16x32_bf16 v[116:119], v[166:169], v[188:191], v[116:119]
	v_mfma_f32_16x16x32_bf16 v[112:115], v[174:177], v[188:191], v[112:115]
	v_mfma_f32_16x16x32_bf16 v[100:103], v[166:169], v[196:199], v[100:103]
	v_mfma_f32_16x16x32_bf16 v[96:99], v[174:177], v[196:199], v[96:99]
	v_mfma_f32_16x16x32_bf16 v[84:87], v[166:169], v[204:207], v[84:87]
	v_mfma_f32_16x16x32_bf16 v[80:83], v[174:177], v[204:207], v[80:83]
	v_mfma_f32_16x16x32_bf16 v[68:71], v[166:169], v[212:215], v[68:71]
	v_mfma_f32_16x16x32_bf16 v[64:67], v[174:177], v[212:215], v[64:67]
	s_setprio 0
	s_barrier
	s_add_i32 s50, s71, s54
	v_lshl_add_u64 v[178:179], v[178:179], 0, s[10:11]
	s_mov_b32 m0, s50
	ds_read_b128 v[184:187], v149 offset:49152
	ds_read_b128 v[188:191], v149 offset:50176
	ds_read_b128 v[192:195], v149 offset:51200
	ds_read_b128 v[196:199], v149 offset:52224
	ds_read_b128 v[200:203], v149 offset:53248
	ds_read_b128 v[204:207], v149 offset:54272
	ds_read_b128 v[208:211], v149 offset:55296
	ds_read_b128 v[212:215], v149 offset:56320
	global_load_lds_dwordx4 v[178:179], off
	s_add_i32 m0, s50, 0x2000
	s_add_u32 s48, s48, 0x40080
	v_lshl_add_u64 v[178:179], v[216:217], 0, s[10:11]
	s_addc_u32 s49, s49, 0
	s_add_i32 s50, s72, s54
	global_load_lds_dwordx4 v[178:179], off
	v_lshl_add_u64 v[178:179], s[48:49], 0, v[130:131]
	s_mov_b32 m0, s50
	s_nop 0
	global_load_lds_dwordx4 v[178:179], off
	v_lshl_add_u64 v[178:179], s[48:49], 0, v[128:129]
	s_add_i32 m0, s50, 0x2000
	s_nop 0
	global_load_lds_dwordx4 v[178:179], off
	v_lshl_add_u64 v[178:179], v[218:219], 0, s[10:11]
	s_mov_b32 m0, s60
	s_nop 0
	global_load_lds_dwordx4 v[178:179], off
	v_lshl_add_u64 v[178:179], v[220:221], 0, s[10:11]
	s_mov_b32 m0, s61
	s_nop 0
	global_load_lds_dwordx4 v[178:179], off
	s_waitcnt vmcnt(8)
	s_waitcnt lgkmcnt(0)
	s_barrier
	s_setprio 1
	s_waitcnt lgkmcnt(0)
	v_mfma_f32_16x16x32_bf16 v[60:63], v[140:143], v[184:187], v[60:63]
	v_mfma_f32_16x16x32_bf16 v[56:59], v[154:157], v[184:187], v[56:59]
	v_mfma_f32_16x16x32_bf16 v[44:47], v[140:143], v[192:195], v[44:47]
	v_mfma_f32_16x16x32_bf16 v[40:43], v[154:157], v[192:195], v[40:43]
	v_mfma_f32_16x16x32_bf16 v[28:31], v[140:143], v[200:203], v[28:31]
	v_mfma_f32_16x16x32_bf16 v[24:27], v[154:157], v[200:203], v[24:27]
	v_mfma_f32_16x16x32_bf16 v[12:15], v[140:143], v[208:211], v[12:15]
	v_mfma_f32_16x16x32_bf16 v[8:11], v[154:157], v[208:211], v[8:11]
	v_mfma_f32_16x16x32_bf16 v[60:63], v[150:153], v[188:191], v[60:63]
	v_mfma_f32_16x16x32_bf16 v[56:59], v[158:161], v[188:191], v[56:59]
	v_mfma_f32_16x16x32_bf16 v[44:47], v[150:153], v[196:199], v[44:47]
	v_mfma_f32_16x16x32_bf16 v[40:43], v[158:161], v[196:199], v[40:43]
	v_mfma_f32_16x16x32_bf16 v[28:31], v[150:153], v[204:207], v[28:31]
	v_mfma_f32_16x16x32_bf16 v[24:27], v[158:161], v[204:207], v[24:27]
	v_mfma_f32_16x16x32_bf16 v[12:15], v[150:153], v[212:215], v[12:15]
	v_mfma_f32_16x16x32_bf16 v[8:11], v[158:161], v[212:215], v[8:11]
	s_setprio 0
	s_setprio 1
	v_mfma_f32_16x16x32_bf16 v[52:55], v[162:165], v[184:187], v[52:55]
	v_mfma_f32_16x16x32_bf16 v[48:51], v[170:173], v[184:187], v[48:51]
	v_mfma_f32_16x16x32_bf16 v[36:39], v[162:165], v[192:195], v[36:39]
	v_mfma_f32_16x16x32_bf16 v[32:35], v[170:173], v[192:195], v[32:35]
	v_mfma_f32_16x16x32_bf16 v[20:23], v[162:165], v[200:203], v[20:23]
	v_mfma_f32_16x16x32_bf16 v[16:19], v[170:173], v[200:203], v[16:19]
	v_mfma_f32_16x16x32_bf16 v[4:7], v[162:165], v[208:211], v[4:7]
	v_mfma_f32_16x16x32_bf16 v[0:3], v[170:173], v[208:211], v[0:3]
	v_mfma_f32_16x16x32_bf16 v[52:55], v[166:169], v[188:191], v[52:55]
	v_mfma_f32_16x16x32_bf16 v[48:51], v[174:177], v[188:191], v[48:51]
	v_mfma_f32_16x16x32_bf16 v[36:39], v[166:169], v[196:199], v[36:39]
	v_mfma_f32_16x16x32_bf16 v[32:35], v[174:177], v[196:199], v[32:35]
	v_mfma_f32_16x16x32_bf16 v[20:23], v[166:169], v[204:207], v[20:23]
	v_mfma_f32_16x16x32_bf16 v[16:19], v[174:177], v[204:207], v[16:19]
	v_mfma_f32_16x16x32_bf16 v[4:7], v[166:169], v[212:215], v[4:7]
	v_mfma_f32_16x16x32_bf16 v[0:3], v[174:177], v[212:215], v[0:3]
	s_setprio 0
	s_barrier
	s_add_i32 s70, s70, 2
	s_add_u32 s46, s46, 0x100
	s_addc_u32 s47, s47, 0
	s_add_u32 s68, s68, 0x100
	s_addc_u32 s69, s69, 0
	s_cmp_gt_u32 s70, 13
	s_cbranch_scc0 .LBB0_1434
	s_and_b64 vcc, exec, s[12:13]
	s_cbranch_vccz .LBB0_1437
	s_barrier

.LBB0_1513:
	s_add_u32 s74, s48, 0x100
	s_addc_u32 s75, s49, 0
	s_mov_b32 s76, -2
	ds_read_b128 v[152:155], v149
	ds_read_b128 v[156:159], v149 offset:1024
	ds_read_b128 v[160:163], v149 offset:2048
	ds_read_b128 v[164:167], v149 offset:3072
	ds_read_b128 v[168:171], v150
	ds_read_b128 v[172:175], v150 offset:1024
	ds_read_b128 v[176:179], v150 offset:2048
	ds_read_b128 v[184:187], v150 offset:3072
	s_add_u32 s48, s46, 0x100
	s_addc_u32 s49, s47, 0
	s_cmp_eq_u32 s76, 40
	s_cselect_b32 s53, s9, s49
	s_cselect_b32 s52, s8, s48
	s_cselect_b32 s51, s45, s75
	s_cselect_b32 s50, s44, s74
	v_lshl_add_u64 v[144:145], s[46:47], 0, v[136:137]
	s_add_i32 m0, s57, 0xc000
	ds_read_b128 v[188:191], v151
	ds_read_b128 v[192:195], v151 offset:1024
	ds_read_b128 v[196:199], v151 offset:2048
	ds_read_b128 v[200:203], v151 offset:3072
	ds_read_b128 v[204:207], v151 offset:4096
	ds_read_b128 v[208:211], v151 offset:5120
	ds_read_b128 v[212:215], v151 offset:6144
	ds_read_b128 v[216:219], v151 offset:7168
	global_load_lds_dwordx4 v[144:145], off
	v_lshl_add_u64 v[144:145], s[46:47], 0, v[138:139]
	s_add_i32 m0, s57, 0xe000
	s_nop 0
	global_load_lds_dwordx4 v[144:145], off
	s_waitcnt vmcnt(8)
	s_waitcnt lgkmcnt(0)
	s_barrier
	s_setprio 1
	s_waitcnt lgkmcnt(0)
	v_mfma_f32_16x16x32_bf16 v[124:127], v[152:155], v[188:191], 0
	v_mfma_f32_16x16x32_bf16 v[120:123], v[160:163], v[188:191], 0
	v_mfma_f32_16x16x32_bf16 v[116:119], v[152:155], v[196:199], 0
	v_mfma_f32_16x16x32_bf16 v[108:111], v[160:163], v[196:199], 0
	v_mfma_f32_16x16x32_bf16 v[100:103], v[152:155], v[204:207], 0
	v_mfma_f32_16x16x32_bf16 v[92:95], v[160:163], v[204:207], 0
	v_mfma_f32_16x16x32_bf16 v[84:87], v[152:155], v[212:215], 0
	v_mfma_f32_16x16x32_bf16 v[76:79], v[160:163], v[212:215], 0
	v_mfma_f32_16x16x32_bf16 v[124:127], v[156:159], v[192:195], v[124:127]
	v_mfma_f32_16x16x32_bf16 v[120:123], v[164:167], v[192:195], v[120:123]
	v_mfma_f32_16x16x32_bf16 v[116:119], v[156:159], v[200:203], v[116:119]
	v_mfma_f32_16x16x32_bf16 v[108:111], v[164:167], v[200:203], v[108:111]
	v_mfma_f32_16x16x32_bf16 v[100:103], v[156:159], v[208:211], v[100:103]
	v_mfma_f32_16x16x32_bf16 v[92:95], v[164:167], v[208:211], v[92:95]
	v_mfma_f32_16x16x32_bf16 v[84:87], v[156:159], v[216:219], v[84:87]
	v_mfma_f32_16x16x32_bf16 v[76:79], v[164:167], v[216:219], v[76:79]
	s_setprio 0
	s_setprio 1
	v_mfma_f32_16x16x32_bf16 v[112:115], v[168:171], v[188:191], 0
	v_mfma_f32_16x16x32_bf16 v[104:107], v[176:179], v[188:191], 0
	v_mfma_f32_16x16x32_bf16 v[96:99], v[168:171], v[196:199], 0
	v_mfma_f32_16x16x32_bf16 v[88:91], v[176:179], v[196:199], 0
	v_mfma_f32_16x16x32_bf16 v[80:83], v[168:171], v[204:207], 0
	v_mfma_f32_16x16x32_bf16 v[72:75], v[176:179], v[204:207], 0
	v_mfma_f32_16x16x32_bf16 v[68:71], v[168:171], v[212:215], 0
	v_mfma_f32_16x16x32_bf16 v[64:67], v[176:179], v[212:215], 0
	v_mfma_f32_16x16x32_bf16 v[112:115], v[172:175], v[192:195], v[112:115]
	v_mfma_f32_16x16x32_bf16 v[104:107], v[184:187], v[192:195], v[104:107]
	v_mfma_f32_16x16x32_bf16 v[96:99], v[172:175], v[200:203], v[96:99]
	v_mfma_f32_16x16x32_bf16 v[88:91], v[184:187], v[200:203], v[88:91]
	v_mfma_f32_16x16x32_bf16 v[80:83], v[172:175], v[208:211], v[80:83]
	v_mfma_f32_16x16x32_bf16 v[72:75], v[184:187], v[208:211], v[72:75]
	v_mfma_f32_16x16x32_bf16 v[68:71], v[172:175], v[216:219], v[68:71]
	v_mfma_f32_16x16x32_bf16 v[64:67], v[184:187], v[216:219], v[64:67]
	s_setprio 0
	s_barrier
	s_add_i32 s46, s64, s56
	v_lshl_add_u64 v[144:145], s[50:51], 0, v[130:131]
	s_mov_b32 m0, s46
	ds_read_b128 v[188:191], v151 offset:16384
	ds_read_b128 v[192:195], v151 offset:17408
	ds_read_b128 v[196:199], v151 offset:18432
	ds_read_b128 v[200:203], v151 offset:19456
	ds_read_b128 v[204:207], v151 offset:20480
	ds_read_b128 v[208:211], v151 offset:21504
	ds_read_b128 v[212:215], v151 offset:22528
	ds_read_b128 v[216:219], v151 offset:23552
	global_load_lds_dwordx4 v[144:145], off
	s_add_i32 m0, s46, 0x2000
	s_add_u32 s46, s50, 0xb0000
	v_lshl_add_u64 v[220:221], s[50:51], 0, v[134:135]
	s_addc_u32 s47, s51, 0
	s_add_i32 s77, s65, s56
	global_load_lds_dwordx4 v[220:221], off
	v_lshl_add_u64 v[222:223], s[46:47], 0, v[130:131]
	s_mov_b32 m0, s77
	v_lshl_add_u64 v[224:225], s[52:53], 0, v[132:133]
	global_load_lds_dwordx4 v[222:223], off
	v_lshl_add_u64 v[222:223], s[46:47], 0, v[134:135]
	s_add_i32 m0, s77, 0x2000
	s_nop 0
	global_load_lds_dwordx4 v[222:223], off
	v_lshl_add_u64 v[222:223], s[52:53], 0, v[128:129]
	s_mov_b32 m0, s57
	s_nop 0
	global_load_lds_dwordx4 v[222:223], off
	s_mov_b32 m0, s58
	s_nop 0
	global_load_lds_dwordx4 v[224:225], off
	s_waitcnt vmcnt(8)
	s_waitcnt lgkmcnt(0)
	s_barrier
	s_setprio 1
	s_waitcnt lgkmcnt(0)
	v_mfma_f32_16x16x32_bf16 v[60:63], v[152:155], v[188:191], 0
	v_mfma_f32_16x16x32_bf16 v[56:59], v[160:163], v[188:191], 0
	v_mfma_f32_16x16x32_bf16 v[52:55], v[152:155], v[196:199], 0
	v_mfma_f32_16x16x32_bf16 v[44:47], v[160:163], v[196:199], 0
	v_mfma_f32_16x16x32_bf16 v[36:39], v[152:155], v[204:207], 0
	v_mfma_f32_16x16x32_bf16 v[28:31], v[160:163], v[204:207], 0
	v_mfma_f32_16x16x32_bf16 v[20:23], v[152:155], v[212:215], 0
	v_mfma_f32_16x16x32_bf16 v[12:15], v[160:163], v[212:215], 0
	v_mfma_f32_16x16x32_bf16 v[60:63], v[156:159], v[192:195], v[60:63]
	v_mfma_f32_16x16x32_bf16 v[56:59], v[164:167], v[192:195], v[56:59]
	v_mfma_f32_16x16x32_bf16 v[52:55], v[156:159], v[200:203], v[52:55]
	v_mfma_f32_16x16x32_bf16 v[44:47], v[164:167], v[200:203], v[44:47]
	v_mfma_f32_16x16x32_bf16 v[36:39], v[156:159], v[208:211], v[36:39]
	v_mfma_f32_16x16x32_bf16 v[28:31], v[164:167], v[208:211], v[28:31]
	v_mfma_f32_16x16x32_bf16 v[20:23], v[156:159], v[216:219], v[20:23]
	v_mfma_f32_16x16x32_bf16 v[12:15], v[164:167], v[216:219], v[12:15]
	s_setprio 0
	s_setprio 1
	v_mfma_f32_16x16x32_bf16 v[48:51], v[168:171], v[188:191], 0
	v_mfma_f32_16x16x32_bf16 v[40:43], v[176:179], v[188:191], 0
	v_mfma_f32_16x16x32_bf16 v[32:35], v[168:171], v[196:199], 0
	v_mfma_f32_16x16x32_bf16 v[24:27], v[176:179], v[196:199], 0
	v_mfma_f32_16x16x32_bf16 v[16:19], v[168:171], v[204:207], 0
	v_mfma_f32_16x16x32_bf16 v[8:11], v[176:179], v[204:207], 0
	v_mfma_f32_16x16x32_bf16 v[4:7], v[168:171], v[212:215], 0
	v_mfma_f32_16x16x32_bf16 v[0:3], v[176:179], v[212:215], 0
	v_mfma_f32_16x16x32_bf16 v[48:51], v[172:175], v[192:195], v[48:51]
	v_mfma_f32_16x16x32_bf16 v[40:43], v[184:187], v[192:195], v[40:43]
	v_mfma_f32_16x16x32_bf16 v[32:35], v[172:175], v[200:203], v[32:35]
	v_mfma_f32_16x16x32_bf16 v[24:27], v[184:187], v[200:203], v[24:27]
	v_mfma_f32_16x16x32_bf16 v[16:19], v[172:175], v[208:211], v[16:19]
	v_mfma_f32_16x16x32_bf16 v[8:11], v[184:187], v[208:211], v[8:11]
	v_mfma_f32_16x16x32_bf16 v[4:7], v[172:175], v[216:219], v[4:7]
	v_mfma_f32_16x16x32_bf16 v[0:3], v[184:187], v[216:219], v[0:3]
	s_setprio 0
	s_barrier
	s_branch .Lmid_gemm12
.LBB0_1514:
	ds_read_b128 v[152:155], v149
	ds_read_b128 v[156:159], v149 offset:1024
	ds_read_b128 v[160:163], v149 offset:2048
	ds_read_b128 v[164:167], v149 offset:3072
	ds_read_b128 v[168:171], v150
	ds_read_b128 v[172:175], v150 offset:1024
	ds_read_b128 v[176:179], v150 offset:2048
	ds_read_b128 v[184:187], v150 offset:3072
	s_add_u32 s48, s46, 0x100
	s_addc_u32 s49, s47, 0
	s_cmp_eq_u32 s76, 40
	s_cselect_b32 s53, s9, s49
	s_cselect_b32 s52, s8, s48
	s_cselect_b32 s51, s45, s75
	s_cselect_b32 s50, s44, s74
	v_lshl_add_u64 v[144:145], s[46:47], 0, v[136:137]
	s_add_i32 m0, s57, 0xc000
	ds_read_b128 v[188:191], v151
	ds_read_b128 v[192:195], v151 offset:1024
	ds_read_b128 v[196:199], v151 offset:2048
	ds_read_b128 v[200:203], v151 offset:3072
	ds_read_b128 v[204:207], v151 offset:4096
	ds_read_b128 v[208:211], v151 offset:5120
	ds_read_b128 v[212:215], v151 offset:6144
	ds_read_b128 v[216:219], v151 offset:7168
	global_load_lds_dwordx4 v[144:145], off
	v_lshl_add_u64 v[144:145], s[46:47], 0, v[138:139]
	s_add_i32 m0, s57, 0xe000
	s_nop 0
	global_load_lds_dwordx4 v[144:145], off
	s_waitcnt vmcnt(8)
	s_waitcnt lgkmcnt(0)
	s_barrier
	s_setprio 1
	s_waitcnt lgkmcnt(0)
	v_mfma_f32_16x16x32_bf16 v[124:127], v[152:155], v[188:191], v[124:127]
	v_mfma_f32_16x16x32_bf16 v[120:123], v[160:163], v[188:191], v[120:123]
	v_mfma_f32_16x16x32_bf16 v[116:119], v[152:155], v[196:199], v[116:119]
	v_mfma_f32_16x16x32_bf16 v[108:111], v[160:163], v[196:199], v[108:111]
	v_mfma_f32_16x16x32_bf16 v[100:103], v[152:155], v[204:207], v[100:103]
	v_mfma_f32_16x16x32_bf16 v[92:95], v[160:163], v[204:207], v[92:95]
	v_mfma_f32_16x16x32_bf16 v[84:87], v[152:155], v[212:215], v[84:87]
	v_mfma_f32_16x16x32_bf16 v[76:79], v[160:163], v[212:215], v[76:79]
	v_mfma_f32_16x16x32_bf16 v[124:127], v[156:159], v[192:195], v[124:127]
	v_mfma_f32_16x16x32_bf16 v[120:123], v[164:167], v[192:195], v[120:123]
	v_mfma_f32_16x16x32_bf16 v[116:119], v[156:159], v[200:203], v[116:119]
	v_mfma_f32_16x16x32_bf16 v[108:111], v[164:167], v[200:203], v[108:111]
	v_mfma_f32_16x16x32_bf16 v[100:103], v[156:159], v[208:211], v[100:103]
	v_mfma_f32_16x16x32_bf16 v[92:95], v[164:167], v[208:211], v[92:95]
	v_mfma_f32_16x16x32_bf16 v[84:87], v[156:159], v[216:219], v[84:87]
	v_mfma_f32_16x16x32_bf16 v[76:79], v[164:167], v[216:219], v[76:79]
	s_setprio 0
	s_setprio 1
	v_mfma_f32_16x16x32_bf16 v[112:115], v[168:171], v[188:191], v[112:115]
	v_mfma_f32_16x16x32_bf16 v[104:107], v[176:179], v[188:191], v[104:107]
	v_mfma_f32_16x16x32_bf16 v[96:99], v[168:171], v[196:199], v[96:99]
	v_mfma_f32_16x16x32_bf16 v[88:91], v[176:179], v[196:199], v[88:91]
	v_mfma_f32_16x16x32_bf16 v[80:83], v[168:171], v[204:207], v[80:83]
	v_mfma_f32_16x16x32_bf16 v[72:75], v[176:179], v[204:207], v[72:75]
	v_mfma_f32_16x16x32_bf16 v[68:71], v[168:171], v[212:215], v[68:71]
	v_mfma_f32_16x16x32_bf16 v[64:67], v[176:179], v[212:215], v[64:67]
	v_mfma_f32_16x16x32_bf16 v[112:115], v[172:175], v[192:195], v[112:115]
	v_mfma_f32_16x16x32_bf16 v[104:107], v[184:187], v[192:195], v[104:107]
	v_mfma_f32_16x16x32_bf16 v[96:99], v[172:175], v[200:203], v[96:99]
	v_mfma_f32_16x16x32_bf16 v[88:91], v[184:187], v[200:203], v[88:91]
	v_mfma_f32_16x16x32_bf16 v[80:83], v[172:175], v[208:211], v[80:83]
	v_mfma_f32_16x16x32_bf16 v[72:75], v[184:187], v[208:211], v[72:75]
	v_mfma_f32_16x16x32_bf16 v[68:71], v[172:175], v[216:219], v[68:71]
	v_mfma_f32_16x16x32_bf16 v[64:67], v[184:187], v[216:219], v[64:67]
	s_setprio 0
	s_barrier
	s_add_i32 s46, s64, s56
	v_lshl_add_u64 v[144:145], s[50:51], 0, v[130:131]
	s_mov_b32 m0, s46
	ds_read_b128 v[188:191], v151 offset:16384
	ds_read_b128 v[192:195], v151 offset:17408
	ds_read_b128 v[196:199], v151 offset:18432
	ds_read_b128 v[200:203], v151 offset:19456
	ds_read_b128 v[204:207], v151 offset:20480
	ds_read_b128 v[208:211], v151 offset:21504
	ds_read_b128 v[212:215], v151 offset:22528
	ds_read_b128 v[216:219], v151 offset:23552
	global_load_lds_dwordx4 v[144:145], off
	s_add_i32 m0, s46, 0x2000
	s_add_u32 s46, s50, 0xb0000
	v_lshl_add_u64 v[220:221], s[50:51], 0, v[134:135]
	s_addc_u32 s47, s51, 0
	s_add_i32 s77, s65, s56
	global_load_lds_dwordx4 v[220:221], off
	v_lshl_add_u64 v[222:223], s[46:47], 0, v[130:131]
	s_mov_b32 m0, s77
	v_lshl_add_u64 v[224:225], s[52:53], 0, v[132:133]
	global_load_lds_dwordx4 v[222:223], off
	v_lshl_add_u64 v[222:223], s[46:47], 0, v[134:135]
	s_add_i32 m0, s77, 0x2000
	s_nop 0
	global_load_lds_dwordx4 v[222:223], off
	v_lshl_add_u64 v[222:223], s[52:53], 0, v[128:129]
	s_mov_b32 m0, s57
	s_nop 0
	global_load_lds_dwordx4 v[222:223], off
	s_mov_b32 m0, s58
	s_nop 0
	global_load_lds_dwordx4 v[224:225], off
	s_waitcnt vmcnt(8)
	s_waitcnt lgkmcnt(0)
	s_barrier
	s_setprio 1
	s_waitcnt lgkmcnt(0)
	v_mfma_f32_16x16x32_bf16 v[60:63], v[152:155], v[188:191], v[60:63]
	v_mfma_f32_16x16x32_bf16 v[56:59], v[160:163], v[188:191], v[56:59]
	v_mfma_f32_16x16x32_bf16 v[52:55], v[152:155], v[196:199], v[52:55]
	v_mfma_f32_16x16x32_bf16 v[44:47], v[160:163], v[196:199], v[44:47]
	v_mfma_f32_16x16x32_bf16 v[36:39], v[152:155], v[204:207], v[36:39]
	v_mfma_f32_16x16x32_bf16 v[28:31], v[160:163], v[204:207], v[28:31]
	v_mfma_f32_16x16x32_bf16 v[20:23], v[152:155], v[212:215], v[20:23]
	v_mfma_f32_16x16x32_bf16 v[12:15], v[160:163], v[212:215], v[12:15]
	v_mfma_f32_16x16x32_bf16 v[60:63], v[156:159], v[192:195], v[60:63]
	v_mfma_f32_16x16x32_bf16 v[56:59], v[164:167], v[192:195], v[56:59]
	v_mfma_f32_16x16x32_bf16 v[52:55], v[156:159], v[200:203], v[52:55]
	v_mfma_f32_16x16x32_bf16 v[44:47], v[164:167], v[200:203], v[44:47]
	v_mfma_f32_16x16x32_bf16 v[36:39], v[156:159], v[208:211], v[36:39]
	v_mfma_f32_16x16x32_bf16 v[28:31], v[164:167], v[208:211], v[28:31]
	v_mfma_f32_16x16x32_bf16 v[20:23], v[156:159], v[216:219], v[20:23]
	v_mfma_f32_16x16x32_bf16 v[12:15], v[164:167], v[216:219], v[12:15]
	s_setprio 0
	s_setprio 1
	v_mfma_f32_16x16x32_bf16 v[48:51], v[168:171], v[188:191], v[48:51]
	v_mfma_f32_16x16x32_bf16 v[40:43], v[176:179], v[188:191], v[40:43]
	v_mfma_f32_16x16x32_bf16 v[32:35], v[168:171], v[196:199], v[32:35]
	v_mfma_f32_16x16x32_bf16 v[24:27], v[176:179], v[196:199], v[24:27]
	v_mfma_f32_16x16x32_bf16 v[16:19], v[168:171], v[204:207], v[16:19]
	v_mfma_f32_16x16x32_bf16 v[8:11], v[176:179], v[204:207], v[8:11]
	v_mfma_f32_16x16x32_bf16 v[4:7], v[168:171], v[212:215], v[4:7]
	v_mfma_f32_16x16x32_bf16 v[0:3], v[176:179], v[212:215], v[0:3]
	v_mfma_f32_16x16x32_bf16 v[48:51], v[172:175], v[192:195], v[48:51]
	v_mfma_f32_16x16x32_bf16 v[40:43], v[184:187], v[192:195], v[40:43]
	v_mfma_f32_16x16x32_bf16 v[32:35], v[172:175], v[200:203], v[32:35]
	v_mfma_f32_16x16x32_bf16 v[24:27], v[184:187], v[200:203], v[24:27]
	v_mfma_f32_16x16x32_bf16 v[16:19], v[172:175], v[208:211], v[16:19]
	v_mfma_f32_16x16x32_bf16 v[8:11], v[184:187], v[208:211], v[8:11]
	v_mfma_f32_16x16x32_bf16 v[4:7], v[172:175], v[216:219], v[4:7]
	v_mfma_f32_16x16x32_bf16 v[0:3], v[184:187], v[216:219], v[0:3]
	s_setprio 0
	s_barrier
.Lmid_gemm12:
	s_add_i32 s77, 0, 0x18000
	s_add_i32 s79, 0, 0x1c000
	v_add_u32_e32 v164, s77, v147
	v_add_u32_e32 v181, s79, v147
	ds_read_b128 v[152:155], v164
	ds_read_b128 v[156:159], v164 offset:1024
	ds_read_b128 v[160:163], v164 offset:2048
	ds_read_b128 v[164:167], v164 offset:3072
	ds_read_b128 v[168:171], v181
	ds_read_b128 v[172:175], v181 offset:1024
	ds_read_b128 v[176:179], v181 offset:2048
	ds_read_b128 v[184:187], v181 offset:3072
	s_add_u32 s46, s52, 0xb0000
	s_addc_u32 s47, s53, 0
	s_mov_b32 m0, s59
	v_lshl_add_u64 v[226:227], s[46:47], 0, v[128:129]
	ds_read_b128 v[188:191], v151 offset:32768
	ds_read_b128 v[192:195], v151 offset:33792
	ds_read_b128 v[196:199], v151 offset:34816
	ds_read_b128 v[200:203], v151 offset:35840
	ds_read_b128 v[204:207], v151 offset:36864
	ds_read_b128 v[208:211], v151 offset:37888
	ds_read_b128 v[212:215], v151 offset:38912
	ds_read_b128 v[216:219], v151 offset:39936
	global_load_lds_dwordx4 v[226:227], off
	v_lshl_add_u64 v[226:227], s[46:47], 0, v[132:133]
	s_mov_b32 m0, s60
	s_nop 0
	global_load_lds_dwordx4 v[226:227], off
	s_waitcnt vmcnt(8)
	s_waitcnt lgkmcnt(0)
	s_barrier
	s_setprio 1
	s_waitcnt lgkmcnt(0)
	v_mfma_f32_16x16x32_bf16 v[124:127], v[152:155], v[188:191], v[124:127]
	v_mfma_f32_16x16x32_bf16 v[120:123], v[160:163], v[188:191], v[120:123]
	v_mfma_f32_16x16x32_bf16 v[116:119], v[152:155], v[196:199], v[116:119]
	v_mfma_f32_16x16x32_bf16 v[108:111], v[160:163], v[196:199], v[108:111]
	v_mfma_f32_16x16x32_bf16 v[100:103], v[152:155], v[204:207], v[100:103]
	v_mfma_f32_16x16x32_bf16 v[92:95], v[160:163], v[204:207], v[92:95]
	v_mfma_f32_16x16x32_bf16 v[84:87], v[152:155], v[212:215], v[84:87]
	v_mfma_f32_16x16x32_bf16 v[76:79], v[160:163], v[212:215], v[76:79]
	v_mfma_f32_16x16x32_bf16 v[124:127], v[156:159], v[192:195], v[124:127]
	v_mfma_f32_16x16x32_bf16 v[120:123], v[164:167], v[192:195], v[120:123]
	v_mfma_f32_16x16x32_bf16 v[116:119], v[156:159], v[200:203], v[116:119]
	v_mfma_f32_16x16x32_bf16 v[108:111], v[164:167], v[200:203], v[108:111]
	v_mfma_f32_16x16x32_bf16 v[100:103], v[156:159], v[208:211], v[100:103]
	v_mfma_f32_16x16x32_bf16 v[92:95], v[164:167], v[208:211], v[92:95]
	v_mfma_f32_16x16x32_bf16 v[84:87], v[156:159], v[216:219], v[84:87]
	v_mfma_f32_16x16x32_bf16 v[76:79], v[164:167], v[216:219], v[76:79]
	s_setprio 0
	s_setprio 1
	v_mfma_f32_16x16x32_bf16 v[112:115], v[168:171], v[188:191], v[112:115]
	v_mfma_f32_16x16x32_bf16 v[104:107], v[176:179], v[188:191], v[104:107]
	v_mfma_f32_16x16x32_bf16 v[96:99], v[168:171], v[196:199], v[96:99]
	v_mfma_f32_16x16x32_bf16 v[88:91], v[176:179], v[196:199], v[88:91]
	v_mfma_f32_16x16x32_bf16 v[80:83], v[168:171], v[204:207], v[80:83]
	v_mfma_f32_16x16x32_bf16 v[72:75], v[176:179], v[204:207], v[72:75]
	v_mfma_f32_16x16x32_bf16 v[68:71], v[168:171], v[212:215], v[68:71]
	v_mfma_f32_16x16x32_bf16 v[64:67], v[176:179], v[212:215], v[64:67]
	v_mfma_f32_16x16x32_bf16 v[112:115], v[172:175], v[192:195], v[112:115]
	v_mfma_f32_16x16x32_bf16 v[104:107], v[184:187], v[192:195], v[104:107]
	v_mfma_f32_16x16x32_bf16 v[96:99], v[172:175], v[200:203], v[96:99]
	v_mfma_f32_16x16x32_bf16 v[88:91], v[184:187], v[200:203], v[88:91]
	v_mfma_f32_16x16x32_bf16 v[80:83], v[172:175], v[208:211], v[80:83]
	v_mfma_f32_16x16x32_bf16 v[72:75], v[184:187], v[208:211], v[72:75]
	v_mfma_f32_16x16x32_bf16 v[68:71], v[172:175], v[216:219], v[68:71]
	v_mfma_f32_16x16x32_bf16 v[64:67], v[184:187], v[216:219], v[64:67]
	s_setprio 0
	s_barrier
	s_add_i32 s46, s77, s56
	v_lshl_add_u64 v[144:145], v[144:145], 0, s[10:11]
	s_mov_b32 m0, s46
	ds_read_b128 v[188:191], v151 offset:49152
	ds_read_b128 v[192:195], v151 offset:50176
	ds_read_b128 v[196:199], v151 offset:51200
	ds_read_b128 v[200:203], v151 offset:52224
	ds_read_b128 v[204:207], v151 offset:53248
	ds_read_b128 v[208:211], v151 offset:54272
	ds_read_b128 v[212:215], v151 offset:55296
	ds_read_b128 v[216:219], v151 offset:56320
	global_load_lds_dwordx4 v[144:145], off
	s_add_i32 m0, s46, 0x2000
	s_add_u32 s46, s50, 0xb0080
	v_lshl_add_u64 v[144:145], v[220:221], 0, s[10:11]
	s_addc_u32 s47, s51, 0
	s_add_i32 s50, s79, s56
	global_load_lds_dwordx4 v[144:145], off
	v_lshl_add_u64 v[144:145], s[46:47], 0, v[130:131]
	s_mov_b32 m0, s50
	s_nop 0
	global_load_lds_dwordx4 v[144:145], off
	v_lshl_add_u64 v[144:145], s[46:47], 0, v[134:135]
	s_add_i32 m0, s50, 0x2000
	s_nop 0
	global_load_lds_dwordx4 v[144:145], off
	v_lshl_add_u64 v[144:145], v[222:223], 0, s[10:11]
	s_mov_b32 m0, s62
	s_nop 0
	global_load_lds_dwordx4 v[144:145], off
	v_lshl_add_u64 v[144:145], v[224:225], 0, s[10:11]
	s_mov_b32 m0, s63
	s_nop 0
	global_load_lds_dwordx4 v[144:145], off
	s_waitcnt vmcnt(8)
	s_waitcnt lgkmcnt(0)
	s_barrier
	s_setprio 1
	s_waitcnt lgkmcnt(0)
	v_mfma_f32_16x16x32_bf16 v[60:63], v[152:155], v[188:191], v[60:63]
	v_mfma_f32_16x16x32_bf16 v[56:59], v[160:163], v[188:191], v[56:59]
	v_mfma_f32_16x16x32_bf16 v[52:55], v[152:155], v[196:199], v[52:55]
	v_mfma_f32_16x16x32_bf16 v[44:47], v[160:163], v[196:199], v[44:47]
	v_mfma_f32_16x16x32_bf16 v[36:39], v[152:155], v[204:207], v[36:39]
	v_mfma_f32_16x16x32_bf16 v[28:31], v[160:163], v[204:207], v[28:31]
	v_mfma_f32_16x16x32_bf16 v[20:23], v[152:155], v[212:215], v[20:23]
	v_mfma_f32_16x16x32_bf16 v[12:15], v[160:163], v[212:215], v[12:15]
	v_mfma_f32_16x16x32_bf16 v[60:63], v[156:159], v[192:195], v[60:63]
	v_mfma_f32_16x16x32_bf16 v[56:59], v[164:167], v[192:195], v[56:59]
	v_mfma_f32_16x16x32_bf16 v[52:55], v[156:159], v[200:203], v[52:55]
	v_mfma_f32_16x16x32_bf16 v[44:47], v[164:167], v[200:203], v[44:47]
	v_mfma_f32_16x16x32_bf16 v[36:39], v[156:159], v[208:211], v[36:39]
	v_mfma_f32_16x16x32_bf16 v[28:31], v[164:167], v[208:211], v[28:31]
	v_mfma_f32_16x16x32_bf16 v[20:23], v[156:159], v[216:219], v[20:23]
	v_mfma_f32_16x16x32_bf16 v[12:15], v[164:167], v[216:219], v[12:15]
	s_setprio 0
	s_setprio 1
	v_mfma_f32_16x16x32_bf16 v[48:51], v[168:171], v[188:191], v[48:51]
	v_mfma_f32_16x16x32_bf16 v[40:43], v[176:179], v[188:191], v[40:43]
	v_mfma_f32_16x16x32_bf16 v[32:35], v[168:171], v[196:199], v[32:35]
	v_mfma_f32_16x16x32_bf16 v[24:27], v[176:179], v[196:199], v[24:27]
	v_mfma_f32_16x16x32_bf16 v[16:19], v[168:171], v[204:207], v[16:19]
	v_mfma_f32_16x16x32_bf16 v[8:11], v[176:179], v[204:207], v[8:11]
	v_mfma_f32_16x16x32_bf16 v[4:7], v[168:171], v[212:215], v[4:7]
	v_mfma_f32_16x16x32_bf16 v[0:3], v[176:179], v[212:215], v[0:3]
	v_mfma_f32_16x16x32_bf16 v[48:51], v[172:175], v[192:195], v[48:51]
	v_mfma_f32_16x16x32_bf16 v[40:43], v[184:187], v[192:195], v[40:43]
	v_mfma_f32_16x16x32_bf16 v[32:35], v[172:175], v[200:203], v[32:35]
	v_mfma_f32_16x16x32_bf16 v[24:27], v[184:187], v[200:203], v[24:27]
	v_mfma_f32_16x16x32_bf16 v[16:19], v[172:175], v[208:211], v[16:19]
	v_mfma_f32_16x16x32_bf16 v[8:11], v[184:187], v[208:211], v[8:11]
	v_mfma_f32_16x16x32_bf16 v[4:7], v[172:175], v[216:219], v[4:7]
	v_mfma_f32_16x16x32_bf16 v[0:3], v[184:187], v[216:219], v[0:3]
	s_setprio 0
	s_barrier
	s_add_i32 s76, s76, 2
	s_add_u32 s74, s74, 0x100
	s_addc_u32 s75, s75, 0
	s_cmp_gt_u32 s76, 41
	s_mov_b64 s[46:47], s[48:49]
	s_cbranch_scc0 .LBB0_1514
	s_and_b64 vcc, exec, s[12:13]
	s_cbranch_vccz .LBB0_1517
	s_barrier
